# GEMM k-tile boundary rotation: barrier + next tile's first fragment reads hoisted above the tile's last 4 MFMAs (72 sites, all GEMM instances)
# speedup vs baseline: 1.0416x; 1.0363x over previous
; template <bool SWAP>
; DI void gemm_tile(const bf16_t* __restrict__ A, int lda, const bf16_t* __restrict__ Bt, int ldb, int K, f32x16 (&acc)[2][2], bf16_t* As, bf16_t* Bs_unused) {
;     ...
;   auto step = [&](int buf, u32x4 (&ra)[4], u32x4 (&rb)[4], bool do_write, bool do_load, int tload) __attribute__((always_inline)) {
;     const bf16_t* pa = As + buf * 2 * GT_IMG + pao; const bf16_t* pb = As + buf * 2 * GT_IMG + pbo;
;     bf16_t* Ad = As + (buf ^ 1) * 2 * GT_IMG; bf16_t* Bd = Ad + GT_IMG;
;     bf16x8 F0[4], F1[4];
;     frag_read(F0, pa, pb, 0);
;     __builtin_amdgcn_sched_barrier(0);
;     frag_read(F1, pa, pb, 16);
;     mfma4(F0);
;     __builtin_amdgcn_sched_barrier(0);
;     frag_read(F0, pa, pb, 32);
;     mfma4(F1);
;     if (do_write) {
; #pragma unroll
;       for (int i = 0; i < 4; ++i) *(u32x4*)(Ad + (lr + 32 * i) * 72 + lc) = ra[i];
;     }
;     __builtin_amdgcn_sched_barrier(0);
;     frag_read(F1, pa, pb, 48);
;     mfma4(F0);
;     if (do_write) {
; #pragma unroll
;       for (int i = 0; i < 4; ++i) *(u32x4*)(Bd + (lr + 32 * i) * 72 + lc) = rb[i];
;     }
;     __builtin_amdgcn_sched_barrier(0);
;     mfma4(F1);
;     if (do_load) load_stage(ra, rb, tload);
;     __builtin_amdgcn_sched_barrier(0);
;   };
;   const int nk = K >> 6;
;   load_stage(ra0, rb0, 0); load_stage(ra1, rb1, 1);
;   __syncthreads();
;   write_stage(ra0, rb0, 0);
;   load_stage(ra0, rb0, 2);
;   __syncthreads();
;   for (int kt = 0; kt < nk; kt += 2) {
;     step(0, ra1, rb1, true, kt + 3 < nk, kt + 3);
.LBB0_193:
	s_ashr_i32 s7, s6, 31
	s_lshl_b64 s[8:9], s[6:7], 18
	v_mov_b32_e32 v34, v195
	s_add_u32 s8, s63, s8
	s_addc_u32 s9, s70, s9
	v_ashrrev_i32_e32 v32, 3, v34
	s_ashr_i32 s1, s0, 31
	v_ashrrev_i32_e32 v33, 31, v32
	s_lshl_b64 s[14:15], s[0:1], 18
	v_readlane_b32 s1, v235, 57
	v_lshlrev_b64 v[0:1], 11, v[32:33]
	s_waitcnt lgkmcnt(0)
	v_lshlrev_b32_e32 v4, 4, v34
	s_add_u32 s14, s1, s14
	v_readlane_b32 s1, v235, 58
	v_lshl_add_u64 v[2:3], s[8:9], 0, v[0:1]
	v_and_b32_e32 v192, 0x70, v4
	s_addc_u32 s15, s1, s15
	v_lshl_add_u64 v[80:81], v[2:3], 0, v[192:193]
	s_mov_b32 s1, 0x10000
	v_lshl_add_u64 v[0:1], s[14:15], 0, v[0:1]
	v_add_co_u32_e32 v84, vcc, s1, v80
	v_lshl_add_u64 v[82:83], v[0:1], 0, v[192:193]
	s_nop 0
	v_addc_co_u32_e32 v85, vcc, 0, v81, vcc
	v_add_co_u32_e32 v86, vcc, s1, v82
	s_mov_b32 s1, 0x20000
	s_nop 0
	v_addc_co_u32_e32 v87, vcc, 0, v83, vcc
	global_load_dwordx4 v[0:3], v[80:81], off
	global_load_dwordx4 v[4:7], v[82:83], off
	v_add_co_u32_e32 v88, vcc, s1, v80
	global_load_dwordx4 v[8:11], v[84:85], off
	global_load_dwordx4 v[12:15], v[86:87], off
	v_addc_co_u32_e32 v89, vcc, 0, v81, vcc
	v_add_co_u32_e32 v90, vcc, s1, v82
	s_mov_b32 s1, 0x30000
	s_nop 0
	v_addc_co_u32_e32 v91, vcc, 0, v83, vcc
	global_load_dwordx4 v[16:19], v[88:89], off
	global_load_dwordx4 v[20:23], v[90:91], off
	v_add_co_u32_e32 v92, vcc, s1, v80
	v_mul_lo_u32 v32, v32, s71
	s_nop 0
	v_addc_co_u32_e32 v93, vcc, 0, v81, vcc
	global_load_dwordx4 v[24:27], v[92:93], off
	v_add_co_u32_e32 v94, vcc, s1, v82
	v_add3_u32 v100, 32, v32, v192
	s_nop 0
	v_addc_co_u32_e32 v95, vcc, 0, v83, vcc
	global_load_dwordx4 v[28:31], v[94:95], off
	global_load_dwordx4 v[104:107], v[80:81], off offset:128
	global_load_dwordx4 v[108:111], v[82:83], off offset:128
	global_load_dwordx4 v[112:115], v[84:85], off offset:128
	global_load_dwordx4 v[116:119], v[86:87], off offset:128
	global_load_dwordx4 v[120:123], v[88:89], off offset:128
	global_load_dwordx4 v[124:127], v[90:91], off offset:128
	global_load_dwordx4 v[128:131], v[92:93], off offset:128
	global_load_dwordx4 v[132:135], v[94:95], off offset:128
	s_barrier
	v_add_u32_e32 v103, 0xd800, v100
	s_waitcnt vmcnt(15)
	ds_write_b128 v100, v[0:3]
	s_waitcnt vmcnt(14)
	ds_write_b128 v100, v[4:7] offset:18432
	s_waitcnt vmcnt(13)
	ds_write_b128 v100, v[8:11] offset:4608
	s_waitcnt vmcnt(12)
	ds_write_b128 v100, v[12:15] offset:23040
	s_waitcnt vmcnt(11)
	ds_write_b128 v100, v[16:19] offset:9216
	s_waitcnt vmcnt(10)
	ds_write_b128 v100, v[20:23] offset:27648
	s_waitcnt vmcnt(9)
	ds_write_b128 v100, v[24:27] offset:13824
	s_waitcnt vmcnt(8)
	ds_write_b128 v100, v[28:31] offset:32256
	global_load_dwordx4 v[136:139], v[80:81], off offset:256
	global_load_dwordx4 v[64:67], v[82:83], off offset:256
	global_load_dwordx4 v[140:143], v[84:85], off offset:256
	global_load_dwordx4 v[68:71], v[86:87], off offset:256
	global_load_dwordx4 v[144:147], v[88:89], off offset:256
	global_load_dwordx4 v[72:75], v[90:91], off offset:256
	global_load_dwordx4 v[148:151], v[92:93], off offset:256
	global_load_dwordx4 v[76:79], v[94:95], off offset:256
	v_lshrrev_b32_e32 v0, 2, v34
	v_lshrrev_b32_e32 v2, 1, v34
	v_and_b32_e32 v3, 31, v34
	v_and_b32_e32 v1, 0x5f, v34
	v_and_b32_e32 v0, 8, v0
	v_and_or_b32 v2, v2, s80, v3
	v_mad_u64_u32 v[2:3], s[8:9], v2, s72, v[0:1]
	v_lshl_add_u32 v101, v2, 1, 32
	v_mad_u32_u24 v0, v1, s72, v0
	s_waitcnt lgkmcnt(0)
	s_barrier
	v_lshl_add_u32 v102, v0, 1, 32
	ds_read_b128 v[0:3], v101
	ds_read_b128 v[4:7], v102 offset:18432
	ds_read_b128 v[8:11], v102 offset:23040
	ds_read_b128 v[12:15], v101 offset:4608
	ds_read_b128 v[152:155], v102 offset:18464
	ds_read_b128 v[156:159], v102 offset:23072
	ds_read_b128 v[160:163], v101 offset:32
	ds_read_b128 v[164:167], v101 offset:4640
	s_waitcnt lgkmcnt(6)
	v_mfma_f32_32x32x16_bf16 v[48:63], v[0:3], v[4:7], 0
	s_waitcnt lgkmcnt(5)
	v_mfma_f32_32x32x16_bf16 v[32:47], v[0:3], v[8:11], 0
	s_waitcnt lgkmcnt(4)
	v_mfma_f32_32x32x16_bf16 v[16:31], v[12:15], v[4:7], 0
	v_mfma_f32_32x32x16_bf16 v[0:15], v[12:15], v[8:11], 0
	s_waitcnt lgkmcnt(1)
	v_mfma_f32_32x32x16_bf16 v[48:63], v[160:163], v[152:155], v[48:63]
	v_mfma_f32_32x32x16_bf16 v[32:47], v[160:163], v[156:159], v[32:47]
	s_waitcnt lgkmcnt(0)
	v_mfma_f32_32x32x16_bf16 v[16:31], v[164:167], v[152:155], v[16:31]
	ds_read_b128 v[152:155], v102 offset:18496
	ds_read_b128 v[160:163], v102 offset:23104
	ds_read_b128 v[168:171], v101 offset:64
	ds_read_b128 v[172:175], v101 offset:4672
	s_waitcnt vmcnt(15)
	ds_write_b128 v100, v[104:107] offset:36864
	s_waitcnt vmcnt(13)
	ds_write_b128 v100, v[112:115] offset:41472
	s_waitcnt vmcnt(11)
	ds_write_b128 v100, v[120:123] offset:46080
	s_waitcnt vmcnt(9)
	ds_write_b128 v100, v[128:131] offset:50688
	v_mfma_f32_32x32x16_bf16 v[0:15], v[164:167], v[156:159], v[0:15]
	ds_read_b128 v[104:107], v102 offset:18528
	ds_read_b128 v[112:115], v102 offset:23136
	ds_read_b128 v[120:123], v101 offset:96
	ds_read_b128 v[128:131], v101 offset:4704
	s_waitcnt lgkmcnt(9)
	v_mfma_f32_32x32x16_bf16 v[48:63], v[168:171], v[152:155], v[48:63]
	ds_write_b128 v100, v[108:111] offset:55296
	ds_write_b128 v100, v[116:119] offset:59904
	ds_write_b128 v100, v[124:127] offset:64512
	s_waitcnt vmcnt(8)
	ds_write_b128 v103, v[132:135] offset:13824
	v_mfma_f32_32x32x16_bf16 v[32:47], v[168:171], v[160:163], v[32:47]
	s_waitcnt lgkmcnt(12)
	v_mfma_f32_32x32x16_bf16 v[16:31], v[172:175], v[152:155], v[16:31]
	v_mfma_f32_32x32x16_bf16 v[0:15], v[172:175], v[160:163], v[0:15]
	s_waitcnt lgkmcnt(0)
	s_barrier
; template <bool SWAP>
; DI void gemm_tile(const bf16_t* __restrict__ A, int lda, const bf16_t* __restrict__ Bt, int ldb, int K, f32x16 (&acc)[2][2], bf16_t* As, bf16_t* Bs_unused) {
;     ...
;   auto step = [&](int buf, u32x4 (&ra)[4], u32x4 (&rb)[4], bool do_write, bool do_load, int tload) __attribute__((always_inline)) {
;     const bf16_t* pa = As + buf * 2 * GT_IMG + pao; const bf16_t* pb = As + buf * 2 * GT_IMG + pbo;
;     bf16_t* Ad = As + (buf ^ 1) * 2 * GT_IMG; bf16_t* Bd = Ad + GT_IMG;
;     bf16x8 F0[4], F1[4];
;     frag_read(F0, pa, pb, 0);
;     __builtin_amdgcn_sched_barrier(0);
;     frag_read(F1, pa, pb, 16);
;     mfma4(F0);
;     __builtin_amdgcn_sched_barrier(0);
;     frag_read(F0, pa, pb, 32);
;     mfma4(F1);
;     if (do_write) {
; #pragma unroll
;       for (int i = 0; i < 4; ++i) *(u32x4*)(Ad + (lr + 32 * i) * 72 + lc) = ra[i];
;     }
;     __builtin_amdgcn_sched_barrier(0);
;     frag_read(F1, pa, pb, 48);
;     mfma4(F0);
;     if (do_write) {
; #pragma unroll
;       for (int i = 0; i < 4; ++i) *(u32x4*)(Bd + (lr + 32 * i) * 72 + lc) = rb[i];
;     }
;     __builtin_amdgcn_sched_barrier(0);
;     mfma4(F1);
;     if (do_load) load_stage(ra, rb, tload);
;     __builtin_amdgcn_sched_barrier(0);
;   };
;   const int nk = K >> 6;
;   load_stage(ra0, rb0, 0); load_stage(ra1, rb1, 1);
;   __syncthreads();
;   write_stage(ra0, rb0, 0);
;   load_stage(ra0, rb0, 2);
;   __syncthreads();
;   for (int kt = 0; kt < nk; kt += 2) {
;     step(0, ra1, rb1, true, kt + 3 < nk, kt + 3);
;     __syncthreads();
;     step(1, ra0, rb0, kt + 2 < nk, kt + 4 < nk, kt + 4);
;     __syncthreads();
	ds_read_b128 v[152:155], v102 offset:55296
	ds_read_b128 v[156:159], v102 offset:59904
	ds_read_b128 v[160:163], v101 offset:36864
	ds_read_b128 v[164:167], v101 offset:41472
	v_mfma_f32_32x32x16_bf16 v[48:63], v[120:123], v[104:107], v[48:63]
	v_mfma_f32_32x32x16_bf16 v[32:47], v[120:123], v[112:115], v[32:47]
	v_mfma_f32_32x32x16_bf16 v[16:31], v[128:131], v[104:107], v[16:31]
	v_mfma_f32_32x32x16_bf16 v[0:15], v[128:131], v[112:115], v[0:15]
	global_load_dwordx4 v[104:107], v[80:81], off offset:384
	global_load_dwordx4 v[108:111], v[82:83], off offset:384
	global_load_dwordx4 v[112:115], v[84:85], off offset:384
	global_load_dwordx4 v[116:119], v[86:87], off offset:384
	global_load_dwordx4 v[120:123], v[88:89], off offset:384
	global_load_dwordx4 v[124:127], v[90:91], off offset:384
	global_load_dwordx4 v[128:131], v[92:93], off offset:384
	global_load_dwordx4 v[132:135], v[94:95], off offset:384
	s_waitcnt lgkmcnt(1)
	v_mfma_f32_32x32x16_bf16 v[48:63], v[160:163], v[152:155], v[48:63]
	v_mfma_f32_32x32x16_bf16 v[32:47], v[160:163], v[156:159], v[32:47]
	s_waitcnt lgkmcnt(0)
	v_mfma_f32_32x32x16_bf16 v[16:31], v[164:167], v[152:155], v[16:31]
	ds_read_b128 v[152:155], v102 offset:55328
	ds_read_b128 v[160:163], v102 offset:59936
	ds_read_b128 v[168:171], v101 offset:36896
	ds_read_b128 v[172:175], v101 offset:41504
	v_mfma_f32_32x32x16_bf16 v[0:15], v[164:167], v[156:159], v[0:15]
	s_waitcnt lgkmcnt(1)
	v_mfma_f32_32x32x16_bf16 v[48:63], v[168:171], v[152:155], v[48:63]
	v_mfma_f32_32x32x16_bf16 v[32:47], v[168:171], v[160:163], v[32:47]
	s_waitcnt lgkmcnt(0)
	v_mfma_f32_32x32x16_bf16 v[16:31], v[172:175], v[152:155], v[16:31]
	ds_read_b128 v[152:155], v102 offset:55360
	ds_read_b128 v[156:159], v102 offset:59968
	ds_read_b128 v[164:167], v101 offset:36928
	ds_read_b128 v[168:171], v101 offset:41536
	s_waitcnt vmcnt(15)
	ds_write_b128 v100, v[136:139]
	s_waitcnt vmcnt(13)
	ds_write_b128 v100, v[140:143] offset:4608
	s_waitcnt vmcnt(11)
	ds_write_b128 v100, v[144:147] offset:9216
	s_waitcnt vmcnt(9)
	ds_write_b128 v100, v[148:151] offset:13824
	v_mfma_f32_32x32x16_bf16 v[0:15], v[172:175], v[160:163], v[0:15]
	ds_read_b128 v[136:139], v102 offset:55392
	ds_read_b128 v[140:143], v102 offset:60000
	ds_read_b128 v[144:147], v101 offset:36960
	ds_read_b128 v[148:151], v101 offset:41568
	s_waitcnt lgkmcnt(9)
	v_mfma_f32_32x32x16_bf16 v[48:63], v[164:167], v[152:155], v[48:63]
	ds_write_b128 v100, v[64:67] offset:18432
	ds_write_b128 v100, v[68:71] offset:23040
	ds_write_b128 v100, v[72:75] offset:27648
	s_waitcnt vmcnt(8)
	ds_write_b128 v100, v[76:79] offset:32256
	v_mfma_f32_32x32x16_bf16 v[32:47], v[164:167], v[156:159], v[32:47]
	s_waitcnt lgkmcnt(12)
	v_mfma_f32_32x32x16_bf16 v[16:31], v[168:171], v[152:155], v[16:31]
	v_mfma_f32_32x32x16_bf16 v[0:15], v[168:171], v[156:159], v[0:15]
	s_waitcnt lgkmcnt(0)
	s_barrier
	ds_read_b128 v[152:155], v102 offset:18432
	ds_read_b128 v[156:159], v102 offset:23040
	ds_read_b128 v[160:163], v101
	ds_read_b128 v[164:167], v101 offset:4608
	v_mfma_f32_32x32x16_bf16 v[48:63], v[144:147], v[136:139], v[48:63]
	v_mfma_f32_32x32x16_bf16 v[32:47], v[144:147], v[140:143], v[32:47]
	v_mfma_f32_32x32x16_bf16 v[16:31], v[148:151], v[136:139], v[16:31]
	v_mfma_f32_32x32x16_bf16 v[0:15], v[148:151], v[140:143], v[0:15]
	global_load_dwordx4 v[64:67], v[80:81], off offset:512
	global_load_dwordx4 v[68:71], v[82:83], off offset:512
	global_load_dwordx4 v[72:75], v[84:85], off offset:512
	global_load_dwordx4 v[76:79], v[86:87], off offset:512
	global_load_dwordx4 v[136:139], v[88:89], off offset:512
	global_load_dwordx4 v[140:143], v[90:91], off offset:512
	global_load_dwordx4 v[144:147], v[92:93], off offset:512
	global_load_dwordx4 v[148:151], v[94:95], off offset:512
	s_waitcnt lgkmcnt(1)
	v_mfma_f32_32x32x16_bf16 v[48:63], v[160:163], v[152:155], v[48:63]
	v_mfma_f32_32x32x16_bf16 v[32:47], v[160:163], v[156:159], v[32:47]
	s_waitcnt lgkmcnt(0)
	v_mfma_f32_32x32x16_bf16 v[16:31], v[164:167], v[152:155], v[16:31]
	ds_read_b128 v[152:155], v102 offset:18464
	ds_read_b128 v[160:163], v102 offset:23072
	ds_read_b128 v[168:171], v101 offset:32
	ds_read_b128 v[172:175], v101 offset:4640
	v_mfma_f32_32x32x16_bf16 v[0:15], v[164:167], v[156:159], v[0:15]
	s_waitcnt lgkmcnt(1)
	v_mfma_f32_32x32x16_bf16 v[48:63], v[168:171], v[152:155], v[48:63]
	v_mfma_f32_32x32x16_bf16 v[32:47], v[168:171], v[160:163], v[32:47]
	s_waitcnt lgkmcnt(0)
	v_mfma_f32_32x32x16_bf16 v[16:31], v[172:175], v[152:155], v[16:31]
	ds_read_b128 v[152:155], v102 offset:18496
	ds_read_b128 v[156:159], v102 offset:23104
	ds_read_b128 v[164:167], v101 offset:64
	ds_read_b128 v[168:171], v101 offset:4672
	s_waitcnt vmcnt(15)
	ds_write_b128 v100, v[104:107] offset:36864
	s_waitcnt vmcnt(13)
	ds_write_b128 v100, v[112:115] offset:41472
	s_waitcnt vmcnt(11)
	ds_write_b128 v100, v[120:123] offset:46080
	s_waitcnt vmcnt(9)
	ds_write_b128 v100, v[128:131] offset:50688
	v_mfma_f32_32x32x16_bf16 v[0:15], v[172:175], v[160:163], v[0:15]
	ds_read_b128 v[104:107], v102 offset:18528
	ds_read_b128 v[112:115], v102 offset:23136
	ds_read_b128 v[120:123], v101 offset:96
	ds_read_b128 v[128:131], v101 offset:4704
	s_waitcnt lgkmcnt(9)
	v_mfma_f32_32x32x16_bf16 v[48:63], v[164:167], v[152:155], v[48:63]
	ds_write_b128 v100, v[108:111] offset:55296
	ds_write_b128 v100, v[116:119] offset:59904
	ds_write_b128 v100, v[124:127] offset:64512
	s_waitcnt vmcnt(8)
	ds_write_b128 v103, v[132:135] offset:13824
	v_mfma_f32_32x32x16_bf16 v[32:47], v[164:167], v[156:159], v[32:47]
	s_waitcnt lgkmcnt(12)
	v_mfma_f32_32x32x16_bf16 v[16:31], v[168:171], v[152:155], v[16:31]
	v_mfma_f32_32x32x16_bf16 v[0:15], v[168:171], v[156:159], v[0:15]
	s_waitcnt lgkmcnt(0)
	s_barrier
; template <bool SWAP>
; DI void gemm_tile(const bf16_t* __restrict__ A, int lda, const bf16_t* __restrict__ Bt, int ldb, int K, f32x16 (&acc)[2][2], bf16_t* As, bf16_t* Bs_unused) {
;     ...
;   auto step = [&](int buf, u32x4 (&ra)[4], u32x4 (&rb)[4], bool do_write, bool do_load, int tload) __attribute__((always_inline)) {
;     const bf16_t* pa = As + buf * 2 * GT_IMG + pao; const bf16_t* pb = As + buf * 2 * GT_IMG + pbo;
;     bf16_t* Ad = As + (buf ^ 1) * 2 * GT_IMG; bf16_t* Bd = Ad + GT_IMG;
;     bf16x8 F0[4], F1[4];
;     frag_read(F0, pa, pb, 0);
;     __builtin_amdgcn_sched_barrier(0);
;     frag_read(F1, pa, pb, 16);
;     mfma4(F0);
;     __builtin_amdgcn_sched_barrier(0);
;     frag_read(F0, pa, pb, 32);
;     mfma4(F1);
;     if (do_write) {
; #pragma unroll
;       for (int i = 0; i < 4; ++i) *(u32x4*)(Ad + (lr + 32 * i) * 72 + lc) = ra[i];
;     }
;     __builtin_amdgcn_sched_barrier(0);
;     frag_read(F1, pa, pb, 48);
;     mfma4(F0);
;     if (do_write) {
; #pragma unroll
;       for (int i = 0; i < 4; ++i) *(u32x4*)(Bd + (lr + 32 * i) * 72 + lc) = rb[i];
;     }
;     __builtin_amdgcn_sched_barrier(0);
;     mfma4(F1);
;     if (do_load) load_stage(ra, rb, tload);
;     __builtin_amdgcn_sched_barrier(0);
;   };
;   const int nk = K >> 6;
;   load_stage(ra0, rb0, 0); load_stage(ra1, rb1, 1);
;   __syncthreads();
;   write_stage(ra0, rb0, 0);
;   load_stage(ra0, rb0, 2);
;   __syncthreads();
;   for (int kt = 0; kt < nk; kt += 2) {
;     step(0, ra1, rb1, true, kt + 3 < nk, kt + 3);
;     __syncthreads();
;     step(1, ra0, rb0, kt + 2 < nk, kt + 4 < nk, kt + 4);
;     __syncthreads();
	ds_read_b128 v[152:155], v102 offset:55296
	ds_read_b128 v[156:159], v102 offset:59904
	ds_read_b128 v[160:163], v101 offset:36864
	ds_read_b128 v[164:167], v101 offset:41472
	v_mfma_f32_32x32x16_bf16 v[48:63], v[120:123], v[104:107], v[48:63]
	v_mfma_f32_32x32x16_bf16 v[32:47], v[120:123], v[112:115], v[32:47]
	v_mfma_f32_32x32x16_bf16 v[16:31], v[128:131], v[104:107], v[16:31]
	v_mfma_f32_32x32x16_bf16 v[0:15], v[128:131], v[112:115], v[0:15]
	global_load_dwordx4 v[104:107], v[80:81], off offset:640
	global_load_dwordx4 v[108:111], v[82:83], off offset:640
	global_load_dwordx4 v[112:115], v[84:85], off offset:640
	global_load_dwordx4 v[116:119], v[86:87], off offset:640
	global_load_dwordx4 v[120:123], v[88:89], off offset:640
	global_load_dwordx4 v[124:127], v[90:91], off offset:640
	global_load_dwordx4 v[128:131], v[92:93], off offset:640
	global_load_dwordx4 v[132:135], v[94:95], off offset:640
	s_waitcnt lgkmcnt(1)
	v_mfma_f32_32x32x16_bf16 v[48:63], v[160:163], v[152:155], v[48:63]
	v_mfma_f32_32x32x16_bf16 v[32:47], v[160:163], v[156:159], v[32:47]
	s_waitcnt lgkmcnt(0)
	v_mfma_f32_32x32x16_bf16 v[16:31], v[164:167], v[152:155], v[16:31]
	ds_read_b128 v[152:155], v102 offset:55328
	ds_read_b128 v[160:163], v102 offset:59936
	ds_read_b128 v[168:171], v101 offset:36896
	ds_read_b128 v[172:175], v101 offset:41504
	v_mfma_f32_32x32x16_bf16 v[0:15], v[164:167], v[156:159], v[0:15]
	s_waitcnt lgkmcnt(1)
	v_mfma_f32_32x32x16_bf16 v[48:63], v[168:171], v[152:155], v[48:63]
	v_mfma_f32_32x32x16_bf16 v[32:47], v[168:171], v[160:163], v[32:47]
	s_waitcnt lgkmcnt(0)
	v_mfma_f32_32x32x16_bf16 v[16:31], v[172:175], v[152:155], v[16:31]
	ds_read_b128 v[152:155], v102 offset:55360
	ds_read_b128 v[156:159], v102 offset:59968
	ds_read_b128 v[164:167], v101 offset:36928
	ds_read_b128 v[168:171], v101 offset:41536
	s_waitcnt vmcnt(15)
	ds_write_b128 v100, v[64:67]
	s_waitcnt vmcnt(13)
	ds_write_b128 v100, v[72:75] offset:4608
	s_waitcnt vmcnt(11)
	ds_write_b128 v100, v[136:139] offset:9216
	s_waitcnt vmcnt(9)
	ds_write_b128 v100, v[144:147] offset:13824
	v_mfma_f32_32x32x16_bf16 v[0:15], v[172:175], v[160:163], v[0:15]
	ds_read_b128 v[64:67], v102 offset:55392
	ds_read_b128 v[72:75], v102 offset:60000
	ds_read_b128 v[136:139], v101 offset:36960
	ds_read_b128 v[144:147], v101 offset:41568
	s_waitcnt lgkmcnt(9)
	v_mfma_f32_32x32x16_bf16 v[48:63], v[164:167], v[152:155], v[48:63]
	ds_write_b128 v100, v[68:71] offset:18432
	ds_write_b128 v100, v[76:79] offset:23040
	ds_write_b128 v100, v[140:143] offset:27648
	s_waitcnt vmcnt(8)
	ds_write_b128 v100, v[148:151] offset:32256
	v_mfma_f32_32x32x16_bf16 v[32:47], v[164:167], v[156:159], v[32:47]
	s_waitcnt lgkmcnt(12)
	v_mfma_f32_32x32x16_bf16 v[16:31], v[168:171], v[152:155], v[16:31]
	v_mfma_f32_32x32x16_bf16 v[0:15], v[168:171], v[156:159], v[0:15]
	s_waitcnt lgkmcnt(0)
	s_barrier
	ds_read_b128 v[152:155], v102 offset:18432
	ds_read_b128 v[156:159], v102 offset:23040
	ds_read_b128 v[160:163], v101
	ds_read_b128 v[164:167], v101 offset:4608
	v_mfma_f32_32x32x16_bf16 v[48:63], v[136:139], v[64:67], v[48:63]
	v_mfma_f32_32x32x16_bf16 v[32:47], v[136:139], v[72:75], v[32:47]
	v_mfma_f32_32x32x16_bf16 v[16:31], v[144:147], v[64:67], v[16:31]
	v_mfma_f32_32x32x16_bf16 v[0:15], v[144:147], v[72:75], v[0:15]
	global_load_dwordx4 v[64:67], v[80:81], off offset:768
	global_load_dwordx4 v[68:71], v[82:83], off offset:768
	global_load_dwordx4 v[72:75], v[84:85], off offset:768
	global_load_dwordx4 v[76:79], v[86:87], off offset:768
	global_load_dwordx4 v[136:139], v[88:89], off offset:768
	global_load_dwordx4 v[140:143], v[90:91], off offset:768
	global_load_dwordx4 v[144:147], v[92:93], off offset:768
	global_load_dwordx4 v[148:151], v[94:95], off offset:768
	s_waitcnt lgkmcnt(1)
	v_mfma_f32_32x32x16_bf16 v[48:63], v[160:163], v[152:155], v[48:63]
	v_mfma_f32_32x32x16_bf16 v[32:47], v[160:163], v[156:159], v[32:47]
	s_waitcnt lgkmcnt(0)
	v_mfma_f32_32x32x16_bf16 v[16:31], v[164:167], v[152:155], v[16:31]
	ds_read_b128 v[152:155], v102 offset:18464
	ds_read_b128 v[160:163], v102 offset:23072
	ds_read_b128 v[168:171], v101 offset:32
	ds_read_b128 v[172:175], v101 offset:4640
	v_mfma_f32_32x32x16_bf16 v[0:15], v[164:167], v[156:159], v[0:15]
	s_waitcnt lgkmcnt(1)
	v_mfma_f32_32x32x16_bf16 v[48:63], v[168:171], v[152:155], v[48:63]
	v_mfma_f32_32x32x16_bf16 v[32:47], v[168:171], v[160:163], v[32:47]
	s_waitcnt lgkmcnt(0)
	v_mfma_f32_32x32x16_bf16 v[16:31], v[172:175], v[152:155], v[16:31]
	ds_read_b128 v[152:155], v102 offset:18496
	ds_read_b128 v[156:159], v102 offset:23104
	ds_read_b128 v[164:167], v101 offset:64
	ds_read_b128 v[168:171], v101 offset:4672
	s_waitcnt vmcnt(15)
	ds_write_b128 v100, v[104:107] offset:36864
	s_waitcnt vmcnt(13)
	ds_write_b128 v100, v[112:115] offset:41472
	s_waitcnt vmcnt(11)
	ds_write_b128 v100, v[120:123] offset:46080
	s_waitcnt vmcnt(9)
	ds_write_b128 v100, v[128:131] offset:50688
	v_mfma_f32_32x32x16_bf16 v[0:15], v[172:175], v[160:163], v[0:15]
	ds_read_b128 v[104:107], v102 offset:18528
	ds_read_b128 v[112:115], v102 offset:23136
	ds_read_b128 v[120:123], v101 offset:96
	ds_read_b128 v[128:131], v101 offset:4704
	s_waitcnt lgkmcnt(9)
	v_mfma_f32_32x32x16_bf16 v[48:63], v[164:167], v[152:155], v[48:63]
	ds_write_b128 v100, v[108:111] offset:55296
	ds_write_b128 v100, v[116:119] offset:59904
	ds_write_b128 v100, v[124:127] offset:64512
	s_waitcnt vmcnt(8)
	ds_write_b128 v103, v[132:135] offset:13824
	v_mfma_f32_32x32x16_bf16 v[32:47], v[164:167], v[156:159], v[32:47]
	s_waitcnt lgkmcnt(12)
	v_mfma_f32_32x32x16_bf16 v[16:31], v[168:171], v[152:155], v[16:31]
	v_mfma_f32_32x32x16_bf16 v[0:15], v[168:171], v[156:159], v[0:15]
	s_waitcnt lgkmcnt(0)
	s_barrier
; template <bool SWAP>
; DI void gemm_tile(const bf16_t* __restrict__ A, int lda, const bf16_t* __restrict__ Bt, int ldb, int K, f32x16 (&acc)[2][2], bf16_t* As, bf16_t* Bs_unused) {
;     ...
;   auto step = [&](int buf, u32x4 (&ra)[4], u32x4 (&rb)[4], bool do_write, bool do_load, int tload) __attribute__((always_inline)) {
;     const bf16_t* pa = As + buf * 2 * GT_IMG + pao; const bf16_t* pb = As + buf * 2 * GT_IMG + pbo;
;     bf16_t* Ad = As + (buf ^ 1) * 2 * GT_IMG; bf16_t* Bd = Ad + GT_IMG;
;     bf16x8 F0[4], F1[4];
;     frag_read(F0, pa, pb, 0);
;     __builtin_amdgcn_sched_barrier(0);
;     frag_read(F1, pa, pb, 16);
;     mfma4(F0);
;     __builtin_amdgcn_sched_barrier(0);
;     frag_read(F0, pa, pb, 32);
;     mfma4(F1);
;     if (do_write) {
; #pragma unroll
;       for (int i = 0; i < 4; ++i) *(u32x4*)(Ad + (lr + 32 * i) * 72 + lc) = ra[i];
;     }
;     __builtin_amdgcn_sched_barrier(0);
;     frag_read(F1, pa, pb, 48);
;     mfma4(F0);
;     if (do_write) {
; #pragma unroll
;       for (int i = 0; i < 4; ++i) *(u32x4*)(Bd + (lr + 32 * i) * 72 + lc) = rb[i];
;     }
;     __builtin_amdgcn_sched_barrier(0);
;     mfma4(F1);
;     if (do_load) load_stage(ra, rb, tload);
;     __builtin_amdgcn_sched_barrier(0);
;   };
;   const int nk = K >> 6;
;   load_stage(ra0, rb0, 0); load_stage(ra1, rb1, 1);
;   __syncthreads();
;   write_stage(ra0, rb0, 0);
;   load_stage(ra0, rb0, 2);
;   __syncthreads();
;   for (int kt = 0; kt < nk; kt += 2) {
;     step(0, ra1, rb1, true, kt + 3 < nk, kt + 3);
;     __syncthreads();
;     step(1, ra0, rb0, kt + 2 < nk, kt + 4 < nk, kt + 4);
;     __syncthreads();
	ds_read_b128 v[152:155], v102 offset:55296
	ds_read_b128 v[156:159], v102 offset:59904
	ds_read_b128 v[160:163], v101 offset:36864
	ds_read_b128 v[164:167], v101 offset:41472
	v_mfma_f32_32x32x16_bf16 v[48:63], v[120:123], v[104:107], v[48:63]
	v_mfma_f32_32x32x16_bf16 v[32:47], v[120:123], v[112:115], v[32:47]
	v_mfma_f32_32x32x16_bf16 v[16:31], v[128:131], v[104:107], v[16:31]
	v_mfma_f32_32x32x16_bf16 v[0:15], v[128:131], v[112:115], v[0:15]
	global_load_dwordx4 v[104:107], v[80:81], off offset:896
	global_load_dwordx4 v[108:111], v[82:83], off offset:896
	global_load_dwordx4 v[112:115], v[84:85], off offset:896
	global_load_dwordx4 v[116:119], v[86:87], off offset:896
	global_load_dwordx4 v[120:123], v[88:89], off offset:896
	global_load_dwordx4 v[124:127], v[90:91], off offset:896
	global_load_dwordx4 v[128:131], v[92:93], off offset:896
	global_load_dwordx4 v[132:135], v[94:95], off offset:896
	s_waitcnt lgkmcnt(1)
	v_mfma_f32_32x32x16_bf16 v[48:63], v[160:163], v[152:155], v[48:63]
	v_mfma_f32_32x32x16_bf16 v[32:47], v[160:163], v[156:159], v[32:47]
	s_waitcnt lgkmcnt(0)
	v_mfma_f32_32x32x16_bf16 v[16:31], v[164:167], v[152:155], v[16:31]
	ds_read_b128 v[152:155], v102 offset:55328
	ds_read_b128 v[160:163], v102 offset:59936
	ds_read_b128 v[168:171], v101 offset:36896
	ds_read_b128 v[172:175], v101 offset:41504
	v_mfma_f32_32x32x16_bf16 v[0:15], v[164:167], v[156:159], v[0:15]
	s_waitcnt lgkmcnt(1)
	v_mfma_f32_32x32x16_bf16 v[48:63], v[168:171], v[152:155], v[48:63]
	v_mfma_f32_32x32x16_bf16 v[32:47], v[168:171], v[160:163], v[32:47]
	s_waitcnt lgkmcnt(0)
	v_mfma_f32_32x32x16_bf16 v[16:31], v[172:175], v[152:155], v[16:31]
	ds_read_b128 v[152:155], v102 offset:55360
	ds_read_b128 v[156:159], v102 offset:59968
	ds_read_b128 v[164:167], v101 offset:36928
	ds_read_b128 v[168:171], v101 offset:41536
	s_waitcnt vmcnt(15)
	ds_write_b128 v100, v[64:67]
	s_waitcnt vmcnt(13)
	ds_write_b128 v100, v[72:75] offset:4608
	s_waitcnt vmcnt(11)
	ds_write_b128 v100, v[136:139] offset:9216
	s_waitcnt vmcnt(9)
	ds_write_b128 v100, v[144:147] offset:13824
	v_mfma_f32_32x32x16_bf16 v[0:15], v[172:175], v[160:163], v[0:15]
	ds_read_b128 v[64:67], v102 offset:55392
	ds_read_b128 v[72:75], v102 offset:60000
	ds_read_b128 v[136:139], v101 offset:36960
	ds_read_b128 v[144:147], v101 offset:41568
	s_waitcnt lgkmcnt(9)
	v_mfma_f32_32x32x16_bf16 v[48:63], v[164:167], v[152:155], v[48:63]
	ds_write_b128 v100, v[68:71] offset:18432
	ds_write_b128 v100, v[76:79] offset:23040
	ds_write_b128 v100, v[140:143] offset:27648
	s_waitcnt vmcnt(8)
	ds_write_b128 v100, v[148:151] offset:32256
	v_mfma_f32_32x32x16_bf16 v[32:47], v[164:167], v[156:159], v[32:47]
	s_waitcnt lgkmcnt(12)
	v_mfma_f32_32x32x16_bf16 v[16:31], v[168:171], v[152:155], v[16:31]
	v_mfma_f32_32x32x16_bf16 v[0:15], v[168:171], v[156:159], v[0:15]
	s_waitcnt lgkmcnt(0)
	s_barrier
	ds_read_b128 v[152:155], v102 offset:18432
	ds_read_b128 v[156:159], v102 offset:23040
	ds_read_b128 v[160:163], v101
	ds_read_b128 v[164:167], v101 offset:4608
	v_mfma_f32_32x32x16_bf16 v[48:63], v[136:139], v[64:67], v[48:63]
	v_mfma_f32_32x32x16_bf16 v[32:47], v[136:139], v[72:75], v[32:47]
	v_mfma_f32_32x32x16_bf16 v[16:31], v[144:147], v[64:67], v[16:31]
	v_mfma_f32_32x32x16_bf16 v[0:15], v[144:147], v[72:75], v[0:15]
	global_load_dwordx4 v[64:67], v[80:81], off offset:1024
	global_load_dwordx4 v[68:71], v[82:83], off offset:1024
	global_load_dwordx4 v[72:75], v[84:85], off offset:1024
	global_load_dwordx4 v[76:79], v[86:87], off offset:1024
	global_load_dwordx4 v[136:139], v[88:89], off offset:1024
	global_load_dwordx4 v[140:143], v[90:91], off offset:1024
	global_load_dwordx4 v[144:147], v[92:93], off offset:1024
	global_load_dwordx4 v[148:151], v[94:95], off offset:1024
	s_waitcnt lgkmcnt(1)
	v_mfma_f32_32x32x16_bf16 v[48:63], v[160:163], v[152:155], v[48:63]
	v_mfma_f32_32x32x16_bf16 v[32:47], v[160:163], v[156:159], v[32:47]
	s_waitcnt lgkmcnt(0)
	v_mfma_f32_32x32x16_bf16 v[16:31], v[164:167], v[152:155], v[16:31]
	ds_read_b128 v[152:155], v102 offset:18464
	ds_read_b128 v[160:163], v102 offset:23072
	ds_read_b128 v[168:171], v101 offset:32
	ds_read_b128 v[172:175], v101 offset:4640
	v_mfma_f32_32x32x16_bf16 v[0:15], v[164:167], v[156:159], v[0:15]
	s_waitcnt lgkmcnt(1)
	v_mfma_f32_32x32x16_bf16 v[48:63], v[168:171], v[152:155], v[48:63]
	v_mfma_f32_32x32x16_bf16 v[32:47], v[168:171], v[160:163], v[32:47]
	s_waitcnt lgkmcnt(0)
	v_mfma_f32_32x32x16_bf16 v[16:31], v[172:175], v[152:155], v[16:31]
	ds_read_b128 v[152:155], v102 offset:18496
	ds_read_b128 v[156:159], v102 offset:23104
	ds_read_b128 v[164:167], v101 offset:64
	ds_read_b128 v[168:171], v101 offset:4672
	s_waitcnt vmcnt(15)
	ds_write_b128 v100, v[104:107] offset:36864
	s_waitcnt vmcnt(13)
	ds_write_b128 v100, v[112:115] offset:41472
	s_waitcnt vmcnt(11)
	ds_write_b128 v100, v[120:123] offset:46080
	s_waitcnt vmcnt(9)
	ds_write_b128 v100, v[128:131] offset:50688
	v_mfma_f32_32x32x16_bf16 v[0:15], v[172:175], v[160:163], v[0:15]
	ds_read_b128 v[104:107], v102 offset:18528
	ds_read_b128 v[112:115], v102 offset:23136
	ds_read_b128 v[120:123], v101 offset:96
	ds_read_b128 v[128:131], v101 offset:4704
	s_waitcnt lgkmcnt(9)
	v_mfma_f32_32x32x16_bf16 v[48:63], v[164:167], v[152:155], v[48:63]
	ds_write_b128 v100, v[108:111] offset:55296
	ds_write_b128 v100, v[116:119] offset:59904
	ds_write_b128 v100, v[124:127] offset:64512
	s_waitcnt vmcnt(8)
	ds_write_b128 v103, v[132:135] offset:13824
	v_mfma_f32_32x32x16_bf16 v[32:47], v[164:167], v[156:159], v[32:47]
	s_waitcnt lgkmcnt(12)
	v_mfma_f32_32x32x16_bf16 v[16:31], v[168:171], v[152:155], v[16:31]
	v_mfma_f32_32x32x16_bf16 v[0:15], v[168:171], v[156:159], v[0:15]
	s_waitcnt lgkmcnt(0)
	s_barrier
; template <bool SWAP>
; DI void gemm_tile(const bf16_t* __restrict__ A, int lda, const bf16_t* __restrict__ Bt, int ldb, int K, f32x16 (&acc)[2][2], bf16_t* As, bf16_t* Bs_unused) {
;     ...
;   auto step = [&](int buf, u32x4 (&ra)[4], u32x4 (&rb)[4], bool do_write, bool do_load, int tload) __attribute__((always_inline)) {
;     const bf16_t* pa = As + buf * 2 * GT_IMG + pao; const bf16_t* pb = As + buf * 2 * GT_IMG + pbo;
;     bf16_t* Ad = As + (buf ^ 1) * 2 * GT_IMG; bf16_t* Bd = Ad + GT_IMG;
;     bf16x8 F0[4], F1[4];
;     frag_read(F0, pa, pb, 0);
;     __builtin_amdgcn_sched_barrier(0);
;     frag_read(F1, pa, pb, 16);
;     mfma4(F0);
;     __builtin_amdgcn_sched_barrier(0);
;     frag_read(F0, pa, pb, 32);
;     mfma4(F1);
;     if (do_write) {
; #pragma unroll
;       for (int i = 0; i < 4; ++i) *(u32x4*)(Ad + (lr + 32 * i) * 72 + lc) = ra[i];
;     }
;     __builtin_amdgcn_sched_barrier(0);
;     frag_read(F1, pa, pb, 48);
;     mfma4(F0);
;     if (do_write) {
; #pragma unroll
;       for (int i = 0; i < 4; ++i) *(u32x4*)(Bd + (lr + 32 * i) * 72 + lc) = rb[i];
;     }
;     __builtin_amdgcn_sched_barrier(0);
;     mfma4(F1);
;     if (do_load) load_stage(ra, rb, tload);
;     __builtin_amdgcn_sched_barrier(0);
;   };
;   const int nk = K >> 6;
;   load_stage(ra0, rb0, 0); load_stage(ra1, rb1, 1);
;   __syncthreads();
;   write_stage(ra0, rb0, 0);
;   load_stage(ra0, rb0, 2);
;   __syncthreads();
;   for (int kt = 0; kt < nk; kt += 2) {
;     step(0, ra1, rb1, true, kt + 3 < nk, kt + 3);
;     __syncthreads();
;     step(1, ra0, rb0, kt + 2 < nk, kt + 4 < nk, kt + 4);
;     __syncthreads();
	ds_read_b128 v[152:155], v102 offset:55296
	ds_read_b128 v[156:159], v102 offset:59904
	ds_read_b128 v[160:163], v101 offset:36864
	ds_read_b128 v[164:167], v101 offset:41472
	v_mfma_f32_32x32x16_bf16 v[48:63], v[120:123], v[104:107], v[48:63]
	v_mfma_f32_32x32x16_bf16 v[32:47], v[120:123], v[112:115], v[32:47]
	v_mfma_f32_32x32x16_bf16 v[16:31], v[128:131], v[104:107], v[16:31]
	v_mfma_f32_32x32x16_bf16 v[0:15], v[128:131], v[112:115], v[0:15]
	global_load_dwordx4 v[104:107], v[80:81], off offset:1152
	global_load_dwordx4 v[108:111], v[82:83], off offset:1152
	global_load_dwordx4 v[112:115], v[84:85], off offset:1152
	global_load_dwordx4 v[116:119], v[86:87], off offset:1152
	global_load_dwordx4 v[120:123], v[88:89], off offset:1152
	global_load_dwordx4 v[124:127], v[90:91], off offset:1152
	global_load_dwordx4 v[128:131], v[92:93], off offset:1152
	global_load_dwordx4 v[132:135], v[94:95], off offset:1152
	s_waitcnt lgkmcnt(1)
	v_mfma_f32_32x32x16_bf16 v[48:63], v[160:163], v[152:155], v[48:63]
	v_mfma_f32_32x32x16_bf16 v[32:47], v[160:163], v[156:159], v[32:47]
	s_waitcnt lgkmcnt(0)
	v_mfma_f32_32x32x16_bf16 v[16:31], v[164:167], v[152:155], v[16:31]
	ds_read_b128 v[152:155], v102 offset:55328
	ds_read_b128 v[160:163], v102 offset:59936
	ds_read_b128 v[168:171], v101 offset:36896
	ds_read_b128 v[172:175], v101 offset:41504
	v_mfma_f32_32x32x16_bf16 v[0:15], v[164:167], v[156:159], v[0:15]
	s_waitcnt lgkmcnt(1)
	v_mfma_f32_32x32x16_bf16 v[48:63], v[168:171], v[152:155], v[48:63]
	v_mfma_f32_32x32x16_bf16 v[32:47], v[168:171], v[160:163], v[32:47]
	s_waitcnt lgkmcnt(0)
	v_mfma_f32_32x32x16_bf16 v[16:31], v[172:175], v[152:155], v[16:31]
	ds_read_b128 v[152:155], v102 offset:55360
	ds_read_b128 v[156:159], v102 offset:59968
	ds_read_b128 v[164:167], v101 offset:36928
	ds_read_b128 v[168:171], v101 offset:41536
	s_waitcnt vmcnt(15)
	ds_write_b128 v100, v[64:67]
	s_waitcnt vmcnt(13)
	ds_write_b128 v100, v[72:75] offset:4608
	s_waitcnt vmcnt(11)
	ds_write_b128 v100, v[136:139] offset:9216
	s_waitcnt vmcnt(9)
	ds_write_b128 v100, v[144:147] offset:13824
	v_mfma_f32_32x32x16_bf16 v[0:15], v[172:175], v[160:163], v[0:15]
	ds_read_b128 v[64:67], v102 offset:55392
	ds_read_b128 v[72:75], v102 offset:60000
	ds_read_b128 v[136:139], v101 offset:36960
	ds_read_b128 v[144:147], v101 offset:41568
	s_waitcnt lgkmcnt(9)
	v_mfma_f32_32x32x16_bf16 v[48:63], v[164:167], v[152:155], v[48:63]
	ds_write_b128 v100, v[68:71] offset:18432
	ds_write_b128 v100, v[76:79] offset:23040
	ds_write_b128 v100, v[140:143] offset:27648
	s_waitcnt vmcnt(8)
	ds_write_b128 v100, v[148:151] offset:32256
	v_mfma_f32_32x32x16_bf16 v[32:47], v[164:167], v[156:159], v[32:47]
	s_waitcnt lgkmcnt(12)
	v_mfma_f32_32x32x16_bf16 v[16:31], v[168:171], v[152:155], v[16:31]
	v_mfma_f32_32x32x16_bf16 v[0:15], v[168:171], v[156:159], v[0:15]
	s_waitcnt lgkmcnt(0)
	s_barrier
	ds_read_b128 v[152:155], v102 offset:18432
	ds_read_b128 v[156:159], v102 offset:23040
	ds_read_b128 v[160:163], v101
	ds_read_b128 v[164:167], v101 offset:4608
	v_mfma_f32_32x32x16_bf16 v[48:63], v[136:139], v[64:67], v[48:63]
	v_mfma_f32_32x32x16_bf16 v[32:47], v[136:139], v[72:75], v[32:47]
	v_mfma_f32_32x32x16_bf16 v[16:31], v[144:147], v[64:67], v[16:31]
	v_mfma_f32_32x32x16_bf16 v[0:15], v[144:147], v[72:75], v[0:15]
	global_load_dwordx4 v[64:67], v[80:81], off offset:1280
	global_load_dwordx4 v[68:71], v[82:83], off offset:1280
	global_load_dwordx4 v[72:75], v[84:85], off offset:1280
	global_load_dwordx4 v[76:79], v[86:87], off offset:1280
	global_load_dwordx4 v[136:139], v[88:89], off offset:1280
	global_load_dwordx4 v[140:143], v[90:91], off offset:1280
	global_load_dwordx4 v[144:147], v[92:93], off offset:1280
	global_load_dwordx4 v[148:151], v[94:95], off offset:1280
	s_waitcnt lgkmcnt(1)
	v_mfma_f32_32x32x16_bf16 v[48:63], v[160:163], v[152:155], v[48:63]
	v_mfma_f32_32x32x16_bf16 v[32:47], v[160:163], v[156:159], v[32:47]
	s_waitcnt lgkmcnt(0)
	v_mfma_f32_32x32x16_bf16 v[16:31], v[164:167], v[152:155], v[16:31]
	ds_read_b128 v[152:155], v102 offset:18464
	ds_read_b128 v[160:163], v102 offset:23072
	ds_read_b128 v[168:171], v101 offset:32
	ds_read_b128 v[172:175], v101 offset:4640
	v_mfma_f32_32x32x16_bf16 v[0:15], v[164:167], v[156:159], v[0:15]
	s_waitcnt lgkmcnt(1)
	v_mfma_f32_32x32x16_bf16 v[48:63], v[168:171], v[152:155], v[48:63]
	v_mfma_f32_32x32x16_bf16 v[32:47], v[168:171], v[160:163], v[32:47]
	s_waitcnt lgkmcnt(0)
	v_mfma_f32_32x32x16_bf16 v[16:31], v[172:175], v[152:155], v[16:31]
	ds_read_b128 v[152:155], v102 offset:18496
	ds_read_b128 v[156:159], v102 offset:23104
	ds_read_b128 v[164:167], v101 offset:64
	ds_read_b128 v[168:171], v101 offset:4672
	s_waitcnt vmcnt(15)
	ds_write_b128 v100, v[104:107] offset:36864
	s_waitcnt vmcnt(13)
	ds_write_b128 v100, v[112:115] offset:41472
	s_waitcnt vmcnt(11)
	ds_write_b128 v100, v[120:123] offset:46080
	s_waitcnt vmcnt(9)
	ds_write_b128 v100, v[128:131] offset:50688
	v_mfma_f32_32x32x16_bf16 v[0:15], v[172:175], v[160:163], v[0:15]
	ds_read_b128 v[104:107], v102 offset:18528
	ds_read_b128 v[112:115], v102 offset:23136
	ds_read_b128 v[120:123], v101 offset:96
	ds_read_b128 v[128:131], v101 offset:4704
	s_waitcnt lgkmcnt(9)
	v_mfma_f32_32x32x16_bf16 v[48:63], v[164:167], v[152:155], v[48:63]
	ds_write_b128 v100, v[108:111] offset:55296
	ds_write_b128 v100, v[116:119] offset:59904
	ds_write_b128 v100, v[124:127] offset:64512
	s_waitcnt vmcnt(8)
	ds_write_b128 v103, v[132:135] offset:13824
	v_mfma_f32_32x32x16_bf16 v[32:47], v[164:167], v[156:159], v[32:47]
	s_waitcnt lgkmcnt(12)
	v_mfma_f32_32x32x16_bf16 v[16:31], v[168:171], v[152:155], v[16:31]
	v_mfma_f32_32x32x16_bf16 v[0:15], v[168:171], v[156:159], v[0:15]
	s_waitcnt lgkmcnt(0)
	s_barrier
; template <bool SWAP>
; DI void gemm_tile(const bf16_t* __restrict__ A, int lda, const bf16_t* __restrict__ Bt, int ldb, int K, f32x16 (&acc)[2][2], bf16_t* As, bf16_t* Bs_unused) {
;     ...
;   auto step = [&](int buf, u32x4 (&ra)[4], u32x4 (&rb)[4], bool do_write, bool do_load, int tload) __attribute__((always_inline)) {
;     const bf16_t* pa = As + buf * 2 * GT_IMG + pao; const bf16_t* pb = As + buf * 2 * GT_IMG + pbo;
;     bf16_t* Ad = As + (buf ^ 1) * 2 * GT_IMG; bf16_t* Bd = Ad + GT_IMG;
;     bf16x8 F0[4], F1[4];
;     frag_read(F0, pa, pb, 0);
;     __builtin_amdgcn_sched_barrier(0);
;     frag_read(F1, pa, pb, 16);
;     mfma4(F0);
;     __builtin_amdgcn_sched_barrier(0);
;     frag_read(F0, pa, pb, 32);
;     mfma4(F1);
;     if (do_write) {
; #pragma unroll
;       for (int i = 0; i < 4; ++i) *(u32x4*)(Ad + (lr + 32 * i) * 72 + lc) = ra[i];
;     }
;     __builtin_amdgcn_sched_barrier(0);
;     frag_read(F1, pa, pb, 48);
;     mfma4(F0);
;     if (do_write) {
; #pragma unroll
;       for (int i = 0; i < 4; ++i) *(u32x4*)(Bd + (lr + 32 * i) * 72 + lc) = rb[i];
;     }
;     __builtin_amdgcn_sched_barrier(0);
;     mfma4(F1);
;     if (do_load) load_stage(ra, rb, tload);
;     __builtin_amdgcn_sched_barrier(0);
;   };
;   const int nk = K >> 6;
;   load_stage(ra0, rb0, 0); load_stage(ra1, rb1, 1);
;   __syncthreads();
;   write_stage(ra0, rb0, 0);
;   load_stage(ra0, rb0, 2);
;   __syncthreads();
;   for (int kt = 0; kt < nk; kt += 2) {
;     step(0, ra1, rb1, true, kt + 3 < nk, kt + 3);
;     __syncthreads();
;     step(1, ra0, rb0, kt + 2 < nk, kt + 4 < nk, kt + 4);
;     __syncthreads();
	ds_read_b128 v[152:155], v102 offset:55296
	ds_read_b128 v[156:159], v102 offset:59904
	ds_read_b128 v[160:163], v101 offset:36864
	ds_read_b128 v[164:167], v101 offset:41472
	v_mfma_f32_32x32x16_bf16 v[48:63], v[120:123], v[104:107], v[48:63]
	v_mfma_f32_32x32x16_bf16 v[32:47], v[120:123], v[112:115], v[32:47]
	v_mfma_f32_32x32x16_bf16 v[16:31], v[128:131], v[104:107], v[16:31]
	v_mfma_f32_32x32x16_bf16 v[0:15], v[128:131], v[112:115], v[0:15]
	global_load_dwordx4 v[104:107], v[80:81], off offset:1408
	global_load_dwordx4 v[108:111], v[82:83], off offset:1408
	global_load_dwordx4 v[112:115], v[84:85], off offset:1408
	global_load_dwordx4 v[116:119], v[86:87], off offset:1408
	global_load_dwordx4 v[120:123], v[88:89], off offset:1408
	global_load_dwordx4 v[124:127], v[90:91], off offset:1408
	global_load_dwordx4 v[128:131], v[92:93], off offset:1408
	global_load_dwordx4 v[132:135], v[94:95], off offset:1408
	s_waitcnt lgkmcnt(1)
	v_mfma_f32_32x32x16_bf16 v[48:63], v[160:163], v[152:155], v[48:63]
	v_mfma_f32_32x32x16_bf16 v[32:47], v[160:163], v[156:159], v[32:47]
	s_waitcnt lgkmcnt(0)
	v_mfma_f32_32x32x16_bf16 v[16:31], v[164:167], v[152:155], v[16:31]
	ds_read_b128 v[152:155], v102 offset:55328
	ds_read_b128 v[160:163], v102 offset:59936
	ds_read_b128 v[168:171], v101 offset:36896
	ds_read_b128 v[172:175], v101 offset:41504
	v_mfma_f32_32x32x16_bf16 v[0:15], v[164:167], v[156:159], v[0:15]
	s_waitcnt lgkmcnt(1)
	v_mfma_f32_32x32x16_bf16 v[48:63], v[168:171], v[152:155], v[48:63]
	v_mfma_f32_32x32x16_bf16 v[32:47], v[168:171], v[160:163], v[32:47]
	s_waitcnt lgkmcnt(0)
	v_mfma_f32_32x32x16_bf16 v[16:31], v[172:175], v[152:155], v[16:31]
	ds_read_b128 v[152:155], v102 offset:55360
	ds_read_b128 v[156:159], v102 offset:59968
	ds_read_b128 v[164:167], v101 offset:36928
	ds_read_b128 v[168:171], v101 offset:41536
	s_waitcnt vmcnt(15)
	ds_write_b128 v100, v[64:67]
	s_waitcnt vmcnt(13)
	ds_write_b128 v100, v[72:75] offset:4608
	s_waitcnt vmcnt(11)
	ds_write_b128 v100, v[136:139] offset:9216
	s_waitcnt vmcnt(9)
	ds_write_b128 v100, v[144:147] offset:13824
	v_mfma_f32_32x32x16_bf16 v[0:15], v[172:175], v[160:163], v[0:15]
	ds_read_b128 v[64:67], v102 offset:55392
	ds_read_b128 v[72:75], v102 offset:60000
	ds_read_b128 v[136:139], v101 offset:36960
	ds_read_b128 v[144:147], v101 offset:41568
	s_waitcnt lgkmcnt(9)
	v_mfma_f32_32x32x16_bf16 v[48:63], v[164:167], v[152:155], v[48:63]
	ds_write_b128 v100, v[68:71] offset:18432
	ds_write_b128 v100, v[76:79] offset:23040
	ds_write_b128 v100, v[140:143] offset:27648
	s_waitcnt vmcnt(8)
	ds_write_b128 v100, v[148:151] offset:32256
	v_mfma_f32_32x32x16_bf16 v[32:47], v[164:167], v[156:159], v[32:47]
	s_waitcnt lgkmcnt(12)
	v_mfma_f32_32x32x16_bf16 v[16:31], v[168:171], v[152:155], v[16:31]
	v_mfma_f32_32x32x16_bf16 v[0:15], v[168:171], v[156:159], v[0:15]
	s_waitcnt lgkmcnt(0)
	s_barrier
	ds_read_b128 v[152:155], v102 offset:18432
	ds_read_b128 v[156:159], v102 offset:23040
	ds_read_b128 v[160:163], v101
	ds_read_b128 v[164:167], v101 offset:4608
	v_mfma_f32_32x32x16_bf16 v[48:63], v[136:139], v[64:67], v[48:63]
	v_mfma_f32_32x32x16_bf16 v[32:47], v[136:139], v[72:75], v[32:47]
	v_mfma_f32_32x32x16_bf16 v[16:31], v[144:147], v[64:67], v[16:31]
	v_mfma_f32_32x32x16_bf16 v[0:15], v[144:147], v[72:75], v[0:15]
	global_load_dwordx4 v[64:67], v[80:81], off offset:1536
	global_load_dwordx4 v[68:71], v[82:83], off offset:1536
	global_load_dwordx4 v[72:75], v[84:85], off offset:1536
	global_load_dwordx4 v[76:79], v[86:87], off offset:1536
	global_load_dwordx4 v[136:139], v[88:89], off offset:1536
	global_load_dwordx4 v[140:143], v[90:91], off offset:1536
	global_load_dwordx4 v[144:147], v[92:93], off offset:1536
	global_load_dwordx4 v[148:151], v[94:95], off offset:1536
	s_waitcnt lgkmcnt(1)
	v_mfma_f32_32x32x16_bf16 v[48:63], v[160:163], v[152:155], v[48:63]
	v_mfma_f32_32x32x16_bf16 v[32:47], v[160:163], v[156:159], v[32:47]
	s_waitcnt lgkmcnt(0)
	v_mfma_f32_32x32x16_bf16 v[16:31], v[164:167], v[152:155], v[16:31]
	ds_read_b128 v[152:155], v102 offset:18464
	ds_read_b128 v[160:163], v102 offset:23072
	ds_read_b128 v[168:171], v101 offset:32
	ds_read_b128 v[172:175], v101 offset:4640
	v_mfma_f32_32x32x16_bf16 v[0:15], v[164:167], v[156:159], v[0:15]
	s_waitcnt lgkmcnt(1)
	v_mfma_f32_32x32x16_bf16 v[48:63], v[168:171], v[152:155], v[48:63]
	v_mfma_f32_32x32x16_bf16 v[32:47], v[168:171], v[160:163], v[32:47]
	s_waitcnt lgkmcnt(0)
	v_mfma_f32_32x32x16_bf16 v[16:31], v[172:175], v[152:155], v[16:31]
	ds_read_b128 v[152:155], v102 offset:18496
	ds_read_b128 v[156:159], v102 offset:23104
	ds_read_b128 v[164:167], v101 offset:64
	ds_read_b128 v[168:171], v101 offset:4672
	s_waitcnt vmcnt(15)
	ds_write_b128 v100, v[104:107] offset:36864
	s_waitcnt vmcnt(13)
	ds_write_b128 v100, v[112:115] offset:41472
	s_waitcnt vmcnt(11)
	ds_write_b128 v100, v[120:123] offset:46080
	s_waitcnt vmcnt(9)
	ds_write_b128 v100, v[128:131] offset:50688
	v_mfma_f32_32x32x16_bf16 v[0:15], v[172:175], v[160:163], v[0:15]
	ds_read_b128 v[104:107], v102 offset:18528
	ds_read_b128 v[112:115], v102 offset:23136
	ds_read_b128 v[120:123], v101 offset:96
	ds_read_b128 v[128:131], v101 offset:4704
	s_waitcnt lgkmcnt(9)
	v_mfma_f32_32x32x16_bf16 v[48:63], v[164:167], v[152:155], v[48:63]
	ds_write_b128 v100, v[108:111] offset:55296
	ds_write_b128 v100, v[116:119] offset:59904
	ds_write_b128 v100, v[124:127] offset:64512
	s_waitcnt vmcnt(8)
	ds_write_b128 v103, v[132:135] offset:13824
	v_mfma_f32_32x32x16_bf16 v[32:47], v[164:167], v[156:159], v[32:47]
	s_waitcnt lgkmcnt(12)
	v_mfma_f32_32x32x16_bf16 v[16:31], v[168:171], v[152:155], v[16:31]
	v_mfma_f32_32x32x16_bf16 v[0:15], v[168:171], v[156:159], v[0:15]
	s_waitcnt lgkmcnt(0)
	s_barrier
; template <bool SWAP>
; DI void gemm_tile(const bf16_t* __restrict__ A, int lda, const bf16_t* __restrict__ Bt, int ldb, int K, f32x16 (&acc)[2][2], bf16_t* As, bf16_t* Bs_unused) {
;     ...
;   auto step = [&](int buf, u32x4 (&ra)[4], u32x4 (&rb)[4], bool do_write, bool do_load, int tload) __attribute__((always_inline)) {
;     const bf16_t* pa = As + buf * 2 * GT_IMG + pao; const bf16_t* pb = As + buf * 2 * GT_IMG + pbo;
;     bf16_t* Ad = As + (buf ^ 1) * 2 * GT_IMG; bf16_t* Bd = Ad + GT_IMG;
;     bf16x8 F0[4], F1[4];
;     frag_read(F0, pa, pb, 0);
;     __builtin_amdgcn_sched_barrier(0);
;     frag_read(F1, pa, pb, 16);
;     mfma4(F0);
;     __builtin_amdgcn_sched_barrier(0);
;     frag_read(F0, pa, pb, 32);
;     mfma4(F1);
;     if (do_write) {
; #pragma unroll
;       for (int i = 0; i < 4; ++i) *(u32x4*)(Ad + (lr + 32 * i) * 72 + lc) = ra[i];
;     }
;     __builtin_amdgcn_sched_barrier(0);
;     frag_read(F1, pa, pb, 48);
;     mfma4(F0);
;     if (do_write) {
; #pragma unroll
;       for (int i = 0; i < 4; ++i) *(u32x4*)(Bd + (lr + 32 * i) * 72 + lc) = rb[i];
;     }
;     __builtin_amdgcn_sched_barrier(0);
;     mfma4(F1);
;     if (do_load) load_stage(ra, rb, tload);
;     __builtin_amdgcn_sched_barrier(0);
;   };
;   const int nk = K >> 6;
;   load_stage(ra0, rb0, 0); load_stage(ra1, rb1, 1);
;   __syncthreads();
;   write_stage(ra0, rb0, 0);
;   load_stage(ra0, rb0, 2);
;   __syncthreads();
;   for (int kt = 0; kt < nk; kt += 2) {
;     step(0, ra1, rb1, true, kt + 3 < nk, kt + 3);
;     __syncthreads();
;     step(1, ra0, rb0, kt + 2 < nk, kt + 4 < nk, kt + 4);
;     __syncthreads();
	ds_read_b128 v[152:155], v102 offset:55296
	ds_read_b128 v[156:159], v102 offset:59904
	ds_read_b128 v[160:163], v101 offset:36864
	ds_read_b128 v[164:167], v101 offset:41472
	v_mfma_f32_32x32x16_bf16 v[48:63], v[120:123], v[104:107], v[48:63]
	v_mfma_f32_32x32x16_bf16 v[32:47], v[120:123], v[112:115], v[32:47]
	v_mfma_f32_32x32x16_bf16 v[16:31], v[128:131], v[104:107], v[16:31]
	v_mfma_f32_32x32x16_bf16 v[0:15], v[128:131], v[112:115], v[0:15]
	global_load_dwordx4 v[104:107], v[80:81], off offset:1664
	global_load_dwordx4 v[108:111], v[82:83], off offset:1664
	global_load_dwordx4 v[112:115], v[84:85], off offset:1664
	global_load_dwordx4 v[116:119], v[86:87], off offset:1664
	global_load_dwordx4 v[120:123], v[88:89], off offset:1664
	global_load_dwordx4 v[124:127], v[90:91], off offset:1664
	global_load_dwordx4 v[128:131], v[92:93], off offset:1664
	global_load_dwordx4 v[132:135], v[94:95], off offset:1664
	s_waitcnt lgkmcnt(1)
	v_mfma_f32_32x32x16_bf16 v[48:63], v[160:163], v[152:155], v[48:63]
	v_mfma_f32_32x32x16_bf16 v[32:47], v[160:163], v[156:159], v[32:47]
	s_waitcnt lgkmcnt(0)
	v_mfma_f32_32x32x16_bf16 v[16:31], v[164:167], v[152:155], v[16:31]
	ds_read_b128 v[152:155], v102 offset:55328
	ds_read_b128 v[160:163], v102 offset:59936
	ds_read_b128 v[168:171], v101 offset:36896
	ds_read_b128 v[172:175], v101 offset:41504
	v_mfma_f32_32x32x16_bf16 v[0:15], v[164:167], v[156:159], v[0:15]
	s_waitcnt lgkmcnt(1)
	v_mfma_f32_32x32x16_bf16 v[48:63], v[168:171], v[152:155], v[48:63]
	v_mfma_f32_32x32x16_bf16 v[32:47], v[168:171], v[160:163], v[32:47]
	s_waitcnt lgkmcnt(0)
	v_mfma_f32_32x32x16_bf16 v[16:31], v[172:175], v[152:155], v[16:31]
	ds_read_b128 v[152:155], v102 offset:55360
	ds_read_b128 v[156:159], v102 offset:59968
	ds_read_b128 v[164:167], v101 offset:36928
	ds_read_b128 v[168:171], v101 offset:41536
	s_waitcnt vmcnt(15)
	ds_write_b128 v100, v[64:67]
	s_waitcnt vmcnt(13)
	ds_write_b128 v100, v[72:75] offset:4608
	s_waitcnt vmcnt(11)
	ds_write_b128 v100, v[136:139] offset:9216
	s_waitcnt vmcnt(9)
	ds_write_b128 v100, v[144:147] offset:13824
	v_mfma_f32_32x32x16_bf16 v[0:15], v[172:175], v[160:163], v[0:15]
	ds_read_b128 v[64:67], v102 offset:55392
	ds_read_b128 v[72:75], v102 offset:60000
	ds_read_b128 v[136:139], v101 offset:36960
	ds_read_b128 v[144:147], v101 offset:41568
	s_waitcnt lgkmcnt(9)
	v_mfma_f32_32x32x16_bf16 v[48:63], v[164:167], v[152:155], v[48:63]
	ds_write_b128 v100, v[68:71] offset:18432
	ds_write_b128 v100, v[76:79] offset:23040
	ds_write_b128 v100, v[140:143] offset:27648
	s_waitcnt vmcnt(8)
	ds_write_b128 v100, v[148:151] offset:32256
	v_mfma_f32_32x32x16_bf16 v[32:47], v[164:167], v[156:159], v[32:47]
	s_waitcnt lgkmcnt(12)
	v_mfma_f32_32x32x16_bf16 v[16:31], v[168:171], v[152:155], v[16:31]
	v_mfma_f32_32x32x16_bf16 v[0:15], v[168:171], v[156:159], v[0:15]
	s_waitcnt lgkmcnt(0)
	s_barrier
	ds_read_b128 v[152:155], v102 offset:18432
	ds_read_b128 v[156:159], v102 offset:23040
	ds_read_b128 v[160:163], v101
	ds_read_b128 v[164:167], v101 offset:4608
	v_mfma_f32_32x32x16_bf16 v[48:63], v[136:139], v[64:67], v[48:63]
	v_mfma_f32_32x32x16_bf16 v[32:47], v[136:139], v[72:75], v[32:47]
	v_mfma_f32_32x32x16_bf16 v[16:31], v[144:147], v[64:67], v[16:31]
	v_mfma_f32_32x32x16_bf16 v[0:15], v[144:147], v[72:75], v[0:15]
	global_load_dwordx4 v[64:67], v[80:81], off offset:1792
	global_load_dwordx4 v[68:71], v[82:83], off offset:1792
	global_load_dwordx4 v[72:75], v[84:85], off offset:1792
	global_load_dwordx4 v[76:79], v[86:87], off offset:1792
	global_load_dwordx4 v[136:139], v[88:89], off offset:1792
	global_load_dwordx4 v[140:143], v[90:91], off offset:1792
	global_load_dwordx4 v[144:147], v[92:93], off offset:1792
	global_load_dwordx4 v[148:151], v[94:95], off offset:1792
	s_waitcnt lgkmcnt(1)
	v_mfma_f32_32x32x16_bf16 v[48:63], v[160:163], v[152:155], v[48:63]
	v_mfma_f32_32x32x16_bf16 v[32:47], v[160:163], v[156:159], v[32:47]
	s_waitcnt lgkmcnt(0)
	v_mfma_f32_32x32x16_bf16 v[16:31], v[164:167], v[152:155], v[16:31]
	ds_read_b128 v[152:155], v102 offset:18464
	ds_read_b128 v[160:163], v102 offset:23072
	ds_read_b128 v[168:171], v101 offset:32
	ds_read_b128 v[172:175], v101 offset:4640
	v_mfma_f32_32x32x16_bf16 v[0:15], v[164:167], v[156:159], v[0:15]
	s_waitcnt lgkmcnt(1)
	v_mfma_f32_32x32x16_bf16 v[48:63], v[168:171], v[152:155], v[48:63]
	v_mfma_f32_32x32x16_bf16 v[32:47], v[168:171], v[160:163], v[32:47]
	s_waitcnt lgkmcnt(0)
	v_mfma_f32_32x32x16_bf16 v[16:31], v[172:175], v[152:155], v[16:31]
	ds_read_b128 v[152:155], v102 offset:18496
	ds_read_b128 v[156:159], v102 offset:23104
	ds_read_b128 v[164:167], v101 offset:64
	ds_read_b128 v[168:171], v101 offset:4672
	s_waitcnt vmcnt(15)
	ds_write_b128 v100, v[104:107] offset:36864
	s_waitcnt vmcnt(13)
	ds_write_b128 v100, v[112:115] offset:41472
	s_waitcnt vmcnt(11)
	ds_write_b128 v100, v[120:123] offset:46080
	s_waitcnt vmcnt(9)
	ds_write_b128 v100, v[128:131] offset:50688
	v_mfma_f32_32x32x16_bf16 v[0:15], v[172:175], v[160:163], v[0:15]
	ds_read_b128 v[104:107], v102 offset:18528
	ds_read_b128 v[112:115], v102 offset:23136
	ds_read_b128 v[120:123], v101 offset:96
	ds_read_b128 v[128:131], v101 offset:4704
	s_waitcnt lgkmcnt(9)
	v_mfma_f32_32x32x16_bf16 v[48:63], v[164:167], v[152:155], v[48:63]
	ds_write_b128 v100, v[108:111] offset:55296
	ds_write_b128 v100, v[116:119] offset:59904
	ds_write_b128 v100, v[124:127] offset:64512
	s_waitcnt vmcnt(8)
	ds_write_b128 v103, v[132:135] offset:13824
	v_mfma_f32_32x32x16_bf16 v[32:47], v[164:167], v[156:159], v[32:47]
	s_waitcnt lgkmcnt(12)
	v_mfma_f32_32x32x16_bf16 v[16:31], v[168:171], v[152:155], v[16:31]
	v_mfma_f32_32x32x16_bf16 v[0:15], v[168:171], v[156:159], v[0:15]
	s_waitcnt lgkmcnt(5)
	v_mfma_f32_32x32x16_bf16 v[48:63], v[120:123], v[104:107], v[48:63]
	v_mfma_f32_32x32x16_bf16 v[32:47], v[120:123], v[112:115], v[32:47]
	s_waitcnt lgkmcnt(4)
	v_mfma_f32_32x32x16_bf16 v[16:31], v[128:131], v[104:107], v[16:31]
	v_mfma_f32_32x32x16_bf16 v[0:15], v[128:131], v[112:115], v[0:15]
	global_load_dwordx4 v[104:107], v[80:81], off offset:1920
	s_nop 0
	global_load_dwordx4 v[80:83], v[82:83], off offset:1920
	s_nop 0
	global_load_dwordx4 v[108:111], v[84:85], off offset:1920
	s_nop 0
	global_load_dwordx4 v[84:87], v[86:87], off offset:1920
	s_nop 0
	global_load_dwordx4 v[112:115], v[88:89], off offset:1920
	s_nop 0
	global_load_dwordx4 v[88:91], v[90:91], off offset:1920
	s_nop 0
	global_load_dwordx4 v[116:119], v[92:93], off offset:1920
	s_nop 0
	global_load_dwordx4 v[92:95], v[94:95], off offset:1920
	s_waitcnt lgkmcnt(0)
	s_barrier
; template <bool SWAP>
; DI void gemm_tile(const bf16_t* __restrict__ A, int lda, const bf16_t* __restrict__ Bt, int ldb, int K, f32x16 (&acc)[2][2], bf16_t* As, bf16_t* Bs_unused) {
;     ...
;   auto step = [&](int buf, u32x4 (&ra)[4], u32x4 (&rb)[4], bool do_write, bool do_load, int tload) __attribute__((always_inline)) {
;     const bf16_t* pa = As + buf * 2 * GT_IMG + pao; const bf16_t* pb = As + buf * 2 * GT_IMG + pbo;
;     bf16_t* Ad = As + (buf ^ 1) * 2 * GT_IMG; bf16_t* Bd = Ad + GT_IMG;
;     bf16x8 F0[4], F1[4];
;     frag_read(F0, pa, pb, 0);
;     __builtin_amdgcn_sched_barrier(0);
;     frag_read(F1, pa, pb, 16);
;     mfma4(F0);
;     __builtin_amdgcn_sched_barrier(0);
;     frag_read(F0, pa, pb, 32);
;     mfma4(F1);
;     if (do_write) {
; #pragma unroll
;       for (int i = 0; i < 4; ++i) *(u32x4*)(Ad + (lr + 32 * i) * 72 + lc) = ra[i];
;     }
;     __builtin_amdgcn_sched_barrier(0);
;     frag_read(F1, pa, pb, 48);
;     mfma4(F0);
;     if (do_write) {
; #pragma unroll
;       for (int i = 0; i < 4; ++i) *(u32x4*)(Bd + (lr + 32 * i) * 72 + lc) = rb[i];
;     }
;     __builtin_amdgcn_sched_barrier(0);
;     mfma4(F1);
;     if (do_load) load_stage(ra, rb, tload);
;     __builtin_amdgcn_sched_barrier(0);
;   };
	ds_read_b128 v[120:123], v102 offset:55296
	ds_read_b128 v[124:127], v102 offset:59904
	ds_read_b128 v[128:131], v101 offset:36864
	ds_read_b128 v[132:135], v101 offset:41472
	s_waitcnt lgkmcnt(1)
	v_mfma_f32_32x32x16_bf16 v[48:63], v[128:131], v[120:123], v[48:63]
	v_mfma_f32_32x32x16_bf16 v[32:47], v[128:131], v[124:127], v[32:47]
	s_waitcnt lgkmcnt(0)
	v_mfma_f32_32x32x16_bf16 v[16:31], v[132:135], v[120:123], v[16:31]
	ds_read_b128 v[120:123], v102 offset:55328
	ds_read_b128 v[128:131], v102 offset:59936
	ds_read_b128 v[152:155], v101 offset:36896
	ds_read_b128 v[156:159], v101 offset:41504
	v_mfma_f32_32x32x16_bf16 v[0:15], v[132:135], v[124:127], v[0:15]
	s_waitcnt lgkmcnt(1)
	v_mfma_f32_32x32x16_bf16 v[48:63], v[152:155], v[120:123], v[48:63]
	v_mfma_f32_32x32x16_bf16 v[32:47], v[152:155], v[128:131], v[32:47]
	s_waitcnt lgkmcnt(0)
	v_mfma_f32_32x32x16_bf16 v[16:31], v[156:159], v[120:123], v[16:31]
	ds_read_b128 v[120:123], v102 offset:55360
	ds_read_b128 v[124:127], v102 offset:59968
	ds_read_b128 v[132:135], v101 offset:36928
	ds_read_b128 v[152:155], v101 offset:41536
	s_waitcnt vmcnt(15)
	ds_write_b128 v100, v[64:67]
	s_waitcnt vmcnt(13)
	ds_write_b128 v100, v[72:75] offset:4608
	s_waitcnt vmcnt(11)
	ds_write_b128 v100, v[136:139] offset:9216
	s_waitcnt vmcnt(9)
	ds_write_b128 v100, v[144:147] offset:13824
	v_mfma_f32_32x32x16_bf16 v[0:15], v[156:159], v[128:131], v[0:15]
	s_waitcnt lgkmcnt(5)
	v_mfma_f32_32x32x16_bf16 v[48:63], v[132:135], v[120:123], v[48:63]
	s_waitcnt lgkmcnt(4)
	v_mfma_f32_32x32x16_bf16 v[16:31], v[152:155], v[120:123], v[16:31]
	ds_read_b128 v[64:67], v102 offset:55392
	ds_read_b128 v[72:75], v102 offset:60000
	ds_read_b128 v[120:123], v101 offset:36960
	ds_read_b128 v[128:131], v101 offset:41568
	ds_write_b128 v100, v[68:71] offset:18432
	ds_write_b128 v100, v[76:79] offset:23040
	ds_write_b128 v100, v[140:143] offset:27648
	s_waitcnt vmcnt(8)
	ds_write_b128 v100, v[148:151] offset:32256
	v_mfma_f32_32x32x16_bf16 v[32:47], v[132:135], v[124:127], v[32:47]
	v_mfma_f32_32x32x16_bf16 v[0:15], v[152:155], v[124:127], v[0:15]
	s_waitcnt lgkmcnt(5)
	v_mfma_f32_32x32x16_bf16 v[48:63], v[120:123], v[64:67], v[48:63]
	v_mfma_f32_32x32x16_bf16 v[32:47], v[120:123], v[72:75], v[32:47]
	s_waitcnt lgkmcnt(4)
	v_mfma_f32_32x32x16_bf16 v[16:31], v[128:131], v[64:67], v[16:31]
	v_mfma_f32_32x32x16_bf16 v[0:15], v[128:131], v[72:75], v[0:15]
	s_waitcnt lgkmcnt(0)
	s_barrier
	ds_read_b128 v[64:67], v102 offset:18432
	ds_read_b128 v[68:71], v102 offset:23040
	ds_read_b128 v[72:75], v101
	ds_read_b128 v[76:79], v101 offset:4608
	s_waitcnt lgkmcnt(1)
	v_mfma_f32_32x32x16_bf16 v[48:63], v[72:75], v[64:67], v[48:63]
	v_mfma_f32_32x32x16_bf16 v[32:47], v[72:75], v[68:71], v[32:47]
	s_waitcnt lgkmcnt(0)
	v_mfma_f32_32x32x16_bf16 v[16:31], v[76:79], v[64:67], v[16:31]
	ds_read_b128 v[64:67], v102 offset:18464
	ds_read_b128 v[72:75], v102 offset:23072
	ds_read_b128 v[120:123], v101 offset:32
	ds_read_b128 v[124:127], v101 offset:4640
	v_mfma_f32_32x32x16_bf16 v[0:15], v[76:79], v[68:71], v[0:15]
	s_waitcnt lgkmcnt(1)
	v_mfma_f32_32x32x16_bf16 v[48:63], v[120:123], v[64:67], v[48:63]
	v_mfma_f32_32x32x16_bf16 v[32:47], v[120:123], v[72:75], v[32:47]
	s_waitcnt lgkmcnt(0)
	v_mfma_f32_32x32x16_bf16 v[16:31], v[124:127], v[64:67], v[16:31]
	ds_read_b128 v[64:67], v102 offset:18496
	ds_read_b128 v[68:71], v102 offset:23104
	ds_read_b128 v[76:79], v101 offset:64
	ds_read_b128 v[120:123], v101 offset:4672
	s_waitcnt vmcnt(7)
	ds_write_b128 v100, v[104:107] offset:36864
	s_waitcnt vmcnt(5)
	ds_write_b128 v100, v[108:111] offset:41472
	s_waitcnt vmcnt(3)
	ds_write_b128 v100, v[112:115] offset:46080
	s_waitcnt vmcnt(1)
	ds_write_b128 v100, v[116:119] offset:50688
	v_mfma_f32_32x32x16_bf16 v[0:15], v[124:127], v[72:75], v[0:15]
	s_waitcnt lgkmcnt(5)
	v_mfma_f32_32x32x16_bf16 v[48:63], v[76:79], v[64:67], v[48:63]
	v_mfma_f32_32x32x16_bf16 v[32:47], v[76:79], v[68:71], v[32:47]
	s_waitcnt lgkmcnt(4)
	v_mfma_f32_32x32x16_bf16 v[16:31], v[120:123], v[64:67], v[16:31]
	ds_read_b128 v[64:67], v102 offset:18528
	ds_read_b128 v[72:75], v102 offset:23136
	ds_read_b128 v[76:79], v101 offset:96
	ds_read_b128 v[104:107], v101 offset:4704
	ds_write_b128 v100, v[80:83] offset:55296
	ds_write_b128 v100, v[84:87] offset:59904
	ds_write_b128 v100, v[88:91] offset:64512
	s_waitcnt vmcnt(0)
	ds_write_b128 v103, v[92:95] offset:13824
	v_mfma_f32_32x32x16_bf16 v[0:15], v[120:123], v[68:71], v[0:15]
	s_waitcnt lgkmcnt(5)
	v_mfma_f32_32x32x16_bf16 v[48:63], v[76:79], v[64:67], v[48:63]
	v_mfma_f32_32x32x16_bf16 v[32:47], v[76:79], v[72:75], v[32:47]
	s_waitcnt lgkmcnt(4)
	v_mfma_f32_32x32x16_bf16 v[16:31], v[104:107], v[64:67], v[16:31]
	v_mfma_f32_32x32x16_bf16 v[0:15], v[104:107], v[72:75], v[0:15]
	s_waitcnt lgkmcnt(0)
	s_barrier
; DI bf16_t f2bf(float x) { return (bf16_t)(pk_bf16(x, 0.f) & 0xffffu); }
; DI int crow(int r, int h) { return (r & 3) + 8 * (r >> 2) + 4 * h; }
; template <bool SWAP>
; DI void gemm_tile(const bf16_t* __restrict__ A, int lda, const bf16_t* __restrict__ Bt, int ldb, int K, f32x16 (&acc)[2][2], bf16_t* As, bf16_t* Bs_unused) {
;     ...
;   auto step = [&](int buf, u32x4 (&ra)[4], u32x4 (&rb)[4], bool do_write, bool do_load, int tload) __attribute__((always_inline)) {
;     const bf16_t* pa = As + buf * 2 * GT_IMG + pao; const bf16_t* pb = As + buf * 2 * GT_IMG + pbo;
;     bf16_t* Ad = As + (buf ^ 1) * 2 * GT_IMG; bf16_t* Bd = Ad + GT_IMG;
;     bf16x8 F0[4], F1[4];
;     frag_read(F0, pa, pb, 0);
;     __builtin_amdgcn_sched_barrier(0);
;     frag_read(F1, pa, pb, 16);
;     mfma4(F0);
;     __builtin_amdgcn_sched_barrier(0);
;     frag_read(F0, pa, pb, 32);
;     mfma4(F1);
;     if (do_write) {
; #pragma unroll
;       for (int i = 0; i < 4; ++i) *(u32x4*)(Ad + (lr + 32 * i) * 72 + lc) = ra[i];
;     }
;     __builtin_amdgcn_sched_barrier(0);
;     frag_read(F1, pa, pb, 48);
;     mfma4(F0);
;     if (do_write) {
; #pragma unroll
;       for (int i = 0; i < 4; ++i) *(u32x4*)(Bd + (lr + 32 * i) * 72 + lc) = rb[i];
;     }
;     __builtin_amdgcn_sched_barrier(0);
;     mfma4(F1);
;     if (do_load) load_stage(ra, rb, tload);
;     __builtin_amdgcn_sched_barrier(0);
;   };
; DI void phase_up(const Params& p, int g, char* smem, int bid, int nb) {
;     ...
; #pragma unroll
;     for (int mi = 0; mi < 2; ++mi)
; #pragma unroll
;       for (int ni = 0; ni < 2; ++ni)
; #pragma unroll
;         for (int r = 0; r < 16; ++r) {
;           const float v = fmaxf(acc[mi][ni][r], 0.f);
;           (U + (size_t)mt * 128 * 4096)[(wm * 64 + mi * 32 + crow(r, h)) * 4096 + nt * 128 + wn * 64 + ni * 32 + l31] = f2bf(v * v);
;         }
	ds_read_b128 v[64:67], v102 offset:55296
	ds_read_b128 v[68:71], v102 offset:59904
	ds_read_b128 v[72:75], v101 offset:36864
	ds_read_b128 v[76:79], v101 offset:41472
	s_waitcnt lgkmcnt(1)
	v_mfma_f32_32x32x16_bf16 v[48:63], v[72:75], v[64:67], v[48:63]
	v_mfma_f32_32x32x16_bf16 v[32:47], v[72:75], v[68:71], v[32:47]
	s_waitcnt lgkmcnt(0)
	v_mfma_f32_32x32x16_bf16 v[16:31], v[76:79], v[64:67], v[16:31]
	ds_read_b128 v[64:67], v102 offset:55328
	ds_read_b128 v[72:75], v102 offset:59936
	ds_read_b128 v[80:83], v101 offset:36896
	ds_read_b128 v[84:87], v101 offset:41504
	v_mfma_f32_32x32x16_bf16 v[0:15], v[76:79], v[68:71], v[0:15]
	s_waitcnt lgkmcnt(1)
	v_mfma_f32_32x32x16_bf16 v[48:63], v[80:83], v[64:67], v[48:63]
	v_mfma_f32_32x32x16_bf16 v[32:47], v[80:83], v[72:75], v[32:47]
	s_waitcnt lgkmcnt(0)
	v_mfma_f32_32x32x16_bf16 v[16:31], v[84:87], v[64:67], v[16:31]
	v_mfma_f32_32x32x16_bf16 v[0:15], v[84:87], v[72:75], v[0:15]
	ds_read_b128 v[64:67], v101 offset:41536
	ds_read_b128 v[68:71], v102 offset:59968
	ds_read_b128 v[72:75], v102 offset:55360
	ds_read_b128 v[76:79], v101 offset:36928
	s_waitcnt lgkmcnt(0)
	v_mfma_f32_32x32x16_bf16 v[48:63], v[76:79], v[72:75], v[48:63]
	v_mfma_f32_32x32x16_bf16 v[32:47], v[76:79], v[68:71], v[32:47]
	v_mfma_f32_32x32x16_bf16 v[16:31], v[64:67], v[72:75], v[16:31]
	v_mfma_f32_32x32x16_bf16 v[0:15], v[64:67], v[68:71], v[0:15]
	ds_read_b128 v[64:67], v101 offset:41568
	ds_read_b128 v[68:71], v102 offset:60000
	ds_read_b128 v[72:75], v102 offset:55392
	ds_read_b128 v[76:79], v101 offset:36960
	s_waitcnt lgkmcnt(0)
	v_mfma_f32_32x32x16_bf16 v[48:63], v[76:79], v[72:75], v[48:63]
	v_mfma_f32_32x32x16_bf16 v[32:47], v[76:79], v[68:71], v[32:47]
	v_mfma_f32_32x32x16_bf16 v[16:31], v[64:67], v[72:75], v[16:31]
	v_mfma_f32_32x32x16_bf16 v[0:15], v[64:67], v[68:71], v[0:15]
	v_mov_b32_e32 v64, v96
	s_lshl_b64 s[6:7], s[6:7], 20
	s_barrier
	v_mov_b32_e32 v65, v97
	s_add_u32 s6, s94, s6
	v_mov_b32_e32 v66, v98
	v_mov_b32_e32 v67, v99
	s_addc_u32 s7, s95, s7
	v_lshlrev_b32_e32 v68, 18, v64
	s_lshl_b32 s0, s0, 7
	v_lshlrev_b32_e32 v64, 6, v65
	v_max_f32_e32 v48, v48, v48
	v_add3_u32 v64, v64, s0, v67
	v_lshl_add_u32 v65, v66, 14, v68
	v_max_f32_e32 v48, 0, v48
	v_add_u32_e32 v66, v65, v64
	v_mul_f32_e32 v48, v48, v48
	v_ashrrev_i32_e32 v67, 31, v66
	v_cvt_pk_bf16_f32 v48, v48, s0
	v_lshl_add_u64 v[66:67], v[66:67], 1, s[6:7]
	global_store_short v[66:67], v48, off
	v_max_f32_e32 v48, v49, v49
	v_max_f32_e32 v48, 0, v48
	v_mul_f32_e32 v48, v48, v48
	v_or_b32_e32 v67, 0x1000, v65
	v_cvt_pk_bf16_f32 v66, v48, s0
	v_add_u32_e32 v48, v67, v64
	v_ashrrev_i32_e32 v49, 31, v48
	v_lshl_add_u64 v[48:49], v[48:49], 1, s[6:7]
	global_store_short v[48:49], v66, off
	v_max_f32_e32 v48, v50, v50
	v_max_f32_e32 v48, 0, v48
	v_mul_f32_e32 v48, v48, v48
	v_or_b32_e32 v66, 0x2000, v65
	v_cvt_pk_bf16_f32 v50, v48, s0
	v_add_u32_e32 v48, v66, v64
	v_ashrrev_i32_e32 v49, 31, v48
	v_lshl_add_u64 v[48:49], v[48:49], 1, s[6:7]
	global_store_short v[48:49], v50, off
	v_max_f32_e32 v48, v51, v51
	v_max_f32_e32 v48, 0, v48
	v_mul_f32_e32 v48, v48, v48
	v_or_b32_e32 v51, 0x3000, v65
	v_cvt_pk_bf16_f32 v50, v48, s0
	v_add_u32_e32 v48, v51, v64
	v_ashrrev_i32_e32 v49, 31, v48
	v_lshl_add_u64 v[48:49], v[48:49], 1, s[6:7]
	global_store_short v[48:49], v50, off
	v_max_f32_e32 v48, v52, v52
	v_max_f32_e32 v48, 0, v48
	v_mul_f32_e32 v48, v48, v48
	v_add_u32_e32 v52, 0x8000, v65
	v_cvt_pk_bf16_f32 v50, v48, s0
	v_add_u32_e32 v48, v52, v64
	v_ashrrev_i32_e32 v49, 31, v48
	v_lshl_add_u64 v[48:49], v[48:49], 1, s[6:7]
	global_store_short v[48:49], v50, off
	v_max_f32_e32 v48, v53, v53
	v_max_f32_e32 v48, 0, v48
	v_mul_f32_e32 v48, v48, v48
	v_add_u32_e32 v53, 0x9000, v65
	v_cvt_pk_bf16_f32 v50, v48, s0
	v_add_u32_e32 v48, v53, v64
	v_ashrrev_i32_e32 v49, 31, v48
	v_lshl_add_u64 v[48:49], v[48:49], 1, s[6:7]
	global_store_short v[48:49], v50, off
	v_max_f32_e32 v48, v54, v54
	v_max_f32_e32 v48, 0, v48
	v_mul_f32_e32 v48, v48, v48
	v_add_u32_e32 v54, 0xa000, v65
	v_cvt_pk_bf16_f32 v50, v48, s0
	v_add_u32_e32 v48, v54, v64
	v_ashrrev_i32_e32 v49, 31, v48
	v_lshl_add_u64 v[48:49], v[48:49], 1, s[6:7]
	global_store_short v[48:49], v50, off
	v_max_f32_e32 v48, v55, v55
	v_max_f32_e32 v48, 0, v48
	v_mul_f32_e32 v48, v48, v48
	v_add_u32_e32 v55, 0xb000, v65
	v_cvt_pk_bf16_f32 v50, v48, s0
	v_add_u32_e32 v48, v55, v64
	v_ashrrev_i32_e32 v49, 31, v48
	v_lshl_add_u64 v[48:49], v[48:49], 1, s[6:7]
	global_store_short v[48:49], v50, off
	v_max_f32_e32 v48, v56, v56
	v_max_f32_e32 v48, 0, v48
	v_mul_f32_e32 v48, v48, v48
	v_add_u32_e32 v56, 0x10000, v65
	v_cvt_pk_bf16_f32 v50, v48, s0
	v_add_u32_e32 v48, v56, v64
	v_ashrrev_i32_e32 v49, 31, v48
	v_lshl_add_u64 v[48:49], v[48:49], 1, s[6:7]
	global_store_short v[48:49], v50, off
	v_max_f32_e32 v48, v57, v57
	v_max_f32_e32 v48, 0, v48
	v_mul_f32_e32 v48, v48, v48
	v_add_u32_e32 v57, 0x11000, v65
	v_cvt_pk_bf16_f32 v50, v48, s0
	v_add_u32_e32 v48, v57, v64
	v_ashrrev_i32_e32 v49, 31, v48
	v_lshl_add_u64 v[48:49], v[48:49], 1, s[6:7]
	global_store_short v[48:49], v50, off
	v_max_f32_e32 v48, v58, v58
	v_max_f32_e32 v48, 0, v48
	v_mul_f32_e32 v48, v48, v48
	v_add_u32_e32 v58, 0x12000, v65
	v_cvt_pk_bf16_f32 v50, v48, s0
	v_add_u32_e32 v48, v58, v64
	v_ashrrev_i32_e32 v49, 31, v48
	v_lshl_add_u64 v[48:49], v[48:49], 1, s[6:7]
	global_store_short v[48:49], v50, off
	v_max_f32_e32 v48, v59, v59
	v_max_f32_e32 v48, 0, v48
	v_mul_f32_e32 v48, v48, v48
	v_add_u32_e32 v59, 0x13000, v65
	v_cvt_pk_bf16_f32 v50, v48, s0
	v_add_u32_e32 v48, v59, v64
	v_ashrrev_i32_e32 v49, 31, v48
	v_lshl_add_u64 v[48:49], v[48:49], 1, s[6:7]
; DI bf16_t f2bf(float x) { return (bf16_t)(pk_bf16(x, 0.f) & 0xffffu); }
; DI int crow(int r, int h) { return (r & 3) + 8 * (r >> 2) + 4 * h; }
; DI void phase_up(const Params& p, int g, char* smem, int bid, int nb) {
;     ...
; #pragma unroll
;     for (int mi = 0; mi < 2; ++mi)
; #pragma unroll
;       for (int ni = 0; ni < 2; ++ni)
; #pragma unroll
;         for (int r = 0; r < 16; ++r) {
;           const float v = fmaxf(acc[mi][ni][r], 0.f);
;           (U + (size_t)mt * 128 * 4096)[(wm * 64 + mi * 32 + crow(r, h)) * 4096 + nt * 128 + wn * 64 + ni * 32 + l31] = f2bf(v * v);
;         }
	global_store_short v[48:49], v50, off
	v_max_f32_e32 v48, v60, v60
	v_max_f32_e32 v48, 0, v48
	v_mul_f32_e32 v48, v48, v48
	v_add_u32_e32 v60, 0x18000, v65
	v_cvt_pk_bf16_f32 v50, v48, s0
	v_add_u32_e32 v48, v60, v64
	v_ashrrev_i32_e32 v49, 31, v48
	v_lshl_add_u64 v[48:49], v[48:49], 1, s[6:7]
	global_store_short v[48:49], v50, off
	v_max_f32_e32 v48, v61, v61
	v_max_f32_e32 v48, 0, v48
	v_mul_f32_e32 v48, v48, v48
	v_add_u32_e32 v61, 0x19000, v65
	v_cvt_pk_bf16_f32 v50, v48, s0
	v_add_u32_e32 v48, v61, v64
	v_ashrrev_i32_e32 v49, 31, v48
	v_lshl_add_u64 v[48:49], v[48:49], 1, s[6:7]
	global_store_short v[48:49], v50, off
	v_max_f32_e32 v48, v62, v62
	v_max_f32_e32 v48, 0, v48
	v_mul_f32_e32 v48, v48, v48
	v_add_u32_e32 v62, 0x1a000, v65
	v_cvt_pk_bf16_f32 v50, v48, s0
	v_add_u32_e32 v48, v62, v64
	v_ashrrev_i32_e32 v49, 31, v48
	v_lshl_add_u64 v[48:49], v[48:49], 1, s[6:7]
	global_store_short v[48:49], v50, off
	v_max_f32_e32 v48, v63, v63
	v_max_f32_e32 v48, 0, v48
	v_mul_f32_e32 v48, v48, v48
	v_add_u32_e32 v63, 0x1b000, v65
	v_cvt_pk_bf16_f32 v50, v48, s0
	v_add_u32_e32 v48, v63, v64
	v_ashrrev_i32_e32 v49, 31, v48
	v_lshl_add_u64 v[48:49], v[48:49], 1, s[6:7]
	global_store_short v[48:49], v50, off
	v_add_u32_e32 v50, 32, v64
	v_max_f32_e32 v32, v32, v32
	v_max_f32_e32 v32, 0, v32
	v_add_u32_e32 v48, v50, v65
	v_mul_f32_e32 v32, v32, v32
	v_ashrrev_i32_e32 v49, 31, v48
	v_cvt_pk_bf16_f32 v32, v32, s0
	v_lshl_add_u64 v[48:49], v[48:49], 1, s[6:7]
	global_store_short v[48:49], v32, off
	v_max_f32_e32 v32, v33, v33
	v_max_f32_e32 v32, 0, v32
	v_mul_f32_e32 v32, v32, v32
	v_cvt_pk_bf16_f32 v48, v32, s0
	v_add_u32_e32 v32, v67, v50
	v_ashrrev_i32_e32 v33, 31, v32
	v_lshl_add_u64 v[32:33], v[32:33], 1, s[6:7]
	global_store_short v[32:33], v48, off
	v_max_f32_e32 v32, v34, v34
	v_max_f32_e32 v32, 0, v32
	v_mul_f32_e32 v32, v32, v32
	v_cvt_pk_bf16_f32 v34, v32, s0
	v_add_u32_e32 v32, v66, v50
	v_ashrrev_i32_e32 v33, 31, v32
	v_lshl_add_u64 v[32:33], v[32:33], 1, s[6:7]
	global_store_short v[32:33], v34, off
	v_max_f32_e32 v32, v35, v35
	v_max_f32_e32 v32, 0, v32
	v_mul_f32_e32 v32, v32, v32
	v_cvt_pk_bf16_f32 v34, v32, s0
	v_add_u32_e32 v32, v51, v50
	v_ashrrev_i32_e32 v33, 31, v32
	v_lshl_add_u64 v[32:33], v[32:33], 1, s[6:7]
	global_store_short v[32:33], v34, off
	v_max_f32_e32 v32, v36, v36
	v_max_f32_e32 v32, 0, v32
	v_mul_f32_e32 v32, v32, v32
	v_cvt_pk_bf16_f32 v34, v32, s0
	v_add_u32_e32 v32, v52, v50
	v_ashrrev_i32_e32 v33, 31, v32
	v_lshl_add_u64 v[32:33], v[32:33], 1, s[6:7]
	global_store_short v[32:33], v34, off
	v_max_f32_e32 v32, v37, v37
	v_max_f32_e32 v32, 0, v32
	v_mul_f32_e32 v32, v32, v32
	v_cvt_pk_bf16_f32 v34, v32, s0
	v_add_u32_e32 v32, v53, v50
	v_ashrrev_i32_e32 v33, 31, v32
	v_lshl_add_u64 v[32:33], v[32:33], 1, s[6:7]
	global_store_short v[32:33], v34, off
	v_max_f32_e32 v32, v38, v38
	v_max_f32_e32 v32, 0, v32
	v_mul_f32_e32 v32, v32, v32
	v_cvt_pk_bf16_f32 v34, v32, s0
	v_add_u32_e32 v32, v54, v50
	v_ashrrev_i32_e32 v33, 31, v32
	v_lshl_add_u64 v[32:33], v[32:33], 1, s[6:7]
	global_store_short v[32:33], v34, off
	v_max_f32_e32 v32, v39, v39
	v_max_f32_e32 v32, 0, v32
	v_mul_f32_e32 v32, v32, v32
	v_cvt_pk_bf16_f32 v34, v32, s0
	v_add_u32_e32 v32, v55, v50
	v_ashrrev_i32_e32 v33, 31, v32
	v_lshl_add_u64 v[32:33], v[32:33], 1, s[6:7]
	global_store_short v[32:33], v34, off
	v_max_f32_e32 v32, v40, v40
	v_max_f32_e32 v32, 0, v32
	v_mul_f32_e32 v32, v32, v32
	v_cvt_pk_bf16_f32 v34, v32, s0
	v_add_u32_e32 v32, v56, v50
	v_ashrrev_i32_e32 v33, 31, v32
	v_lshl_add_u64 v[32:33], v[32:33], 1, s[6:7]
	global_store_short v[32:33], v34, off
	v_max_f32_e32 v32, v41, v41
	v_max_f32_e32 v32, 0, v32
	v_mul_f32_e32 v32, v32, v32
	v_cvt_pk_bf16_f32 v34, v32, s0
	v_add_u32_e32 v32, v57, v50
	v_ashrrev_i32_e32 v33, 31, v32
	v_lshl_add_u64 v[32:33], v[32:33], 1, s[6:7]
	global_store_short v[32:33], v34, off
	v_max_f32_e32 v32, v42, v42
	v_max_f32_e32 v32, 0, v32
	v_mul_f32_e32 v32, v32, v32
	v_cvt_pk_bf16_f32 v34, v32, s0
	v_add_u32_e32 v32, v58, v50
	v_ashrrev_i32_e32 v33, 31, v32
	v_lshl_add_u64 v[32:33], v[32:33], 1, s[6:7]
	global_store_short v[32:33], v34, off
	v_max_f32_e32 v32, v43, v43
	v_max_f32_e32 v32, 0, v32
	v_mul_f32_e32 v32, v32, v32
	v_cvt_pk_bf16_f32 v34, v32, s0
	v_add_u32_e32 v32, v59, v50
	v_ashrrev_i32_e32 v33, 31, v32
	v_lshl_add_u64 v[32:33], v[32:33], 1, s[6:7]
	global_store_short v[32:33], v34, off
	v_max_f32_e32 v32, v44, v44
	v_max_f32_e32 v32, 0, v32
	v_mul_f32_e32 v32, v32, v32
	v_cvt_pk_bf16_f32 v34, v32, s0
	v_add_u32_e32 v32, v60, v50
	v_ashrrev_i32_e32 v33, 31, v32
	v_lshl_add_u64 v[32:33], v[32:33], 1, s[6:7]
	global_store_short v[32:33], v34, off
	v_max_f32_e32 v32, v45, v45
	v_max_f32_e32 v32, 0, v32
	v_mul_f32_e32 v32, v32, v32
	v_cvt_pk_bf16_f32 v34, v32, s0
	v_add_u32_e32 v32, v61, v50
	v_ashrrev_i32_e32 v33, 31, v32
	v_lshl_add_u64 v[32:33], v[32:33], 1, s[6:7]
	global_store_short v[32:33], v34, off
	v_max_f32_e32 v32, v46, v46
	v_max_f32_e32 v32, 0, v32
	v_mul_f32_e32 v32, v32, v32
	v_cvt_pk_bf16_f32 v34, v32, s0
	v_add_u32_e32 v32, v62, v50
	v_ashrrev_i32_e32 v33, 31, v32
	v_lshl_add_u64 v[32:33], v[32:33], 1, s[6:7]
	global_store_short v[32:33], v34, off
	v_max_f32_e32 v32, v47, v47
	v_max_f32_e32 v32, 0, v32
	v_mul_f32_e32 v32, v32, v32
	v_cvt_pk_bf16_f32 v34, v32, s0
	v_add_u32_e32 v32, v63, v50
	v_ashrrev_i32_e32 v33, 31, v32
	v_lshl_add_u64 v[32:33], v[32:33], 1, s[6:7]
	global_store_short v[32:33], v34, off
	v_max_f32_e32 v16, v16, v16
	v_add_u32_e32 v34, 0x20000, v65
	v_max_f32_e32 v16, 0, v16
	v_add_u32_e32 v32, v34, v64
	v_mul_f32_e32 v16, v16, v16
	v_ashrrev_i32_e32 v33, 31, v32
; DI bf16_t f2bf(float x) { return (bf16_t)(pk_bf16(x, 0.f) & 0xffffu); }
; DI int crow(int r, int h) { return (r & 3) + 8 * (r >> 2) + 4 * h; }
; DI void phase_up(const Params& p, int g, char* smem, int bid, int nb) {
;     ...
; #pragma unroll
;     for (int mi = 0; mi < 2; ++mi)
; #pragma unroll
;       for (int ni = 0; ni < 2; ++ni)
; #pragma unroll
;         for (int r = 0; r < 16; ++r) {
;           const float v = fmaxf(acc[mi][ni][r], 0.f);
;           (U + (size_t)mt * 128 * 4096)[(wm * 64 + mi * 32 + crow(r, h)) * 4096 + nt * 128 + wn * 64 + ni * 32 + l31] = f2bf(v * v);
;         }
	v_cvt_pk_bf16_f32 v16, v16, s0
	v_lshl_add_u64 v[32:33], v[32:33], 1, s[6:7]
	global_store_short v[32:33], v16, off
	v_max_f32_e32 v16, v17, v17
	v_max_f32_e32 v16, 0, v16
	v_mul_f32_e32 v16, v16, v16
	v_add_u32_e32 v33, 0x21000, v65
	v_cvt_pk_bf16_f32 v32, v16, s0
	v_add_u32_e32 v16, v33, v64
	v_ashrrev_i32_e32 v17, 31, v16
	v_lshl_add_u64 v[16:17], v[16:17], 1, s[6:7]
	global_store_short v[16:17], v32, off
	v_max_f32_e32 v16, v18, v18
	v_max_f32_e32 v16, 0, v16
	v_mul_f32_e32 v16, v16, v16
	v_add_u32_e32 v32, 0x22000, v65
	v_cvt_pk_bf16_f32 v18, v16, s0
	v_add_u32_e32 v16, v32, v64
	v_ashrrev_i32_e32 v17, 31, v16
	v_lshl_add_u64 v[16:17], v[16:17], 1, s[6:7]
	global_store_short v[16:17], v18, off
	v_max_f32_e32 v16, v19, v19
	v_max_f32_e32 v16, 0, v16
	v_mul_f32_e32 v16, v16, v16
	v_add_u32_e32 v19, 0x23000, v65
	v_cvt_pk_bf16_f32 v18, v16, s0
	v_add_u32_e32 v16, v19, v64
	v_ashrrev_i32_e32 v17, 31, v16
	v_lshl_add_u64 v[16:17], v[16:17], 1, s[6:7]
	global_store_short v[16:17], v18, off
	v_max_f32_e32 v16, v20, v20
	v_max_f32_e32 v16, 0, v16
	v_mul_f32_e32 v16, v16, v16
	v_add_u32_e32 v20, 0x28000, v65
	v_cvt_pk_bf16_f32 v18, v16, s0
	v_add_u32_e32 v16, v20, v64
	v_ashrrev_i32_e32 v17, 31, v16
	v_lshl_add_u64 v[16:17], v[16:17], 1, s[6:7]
	global_store_short v[16:17], v18, off
	v_max_f32_e32 v16, v21, v21
	v_max_f32_e32 v16, 0, v16
	v_mul_f32_e32 v16, v16, v16
	v_add_u32_e32 v21, 0x29000, v65
	v_cvt_pk_bf16_f32 v18, v16, s0
	v_add_u32_e32 v16, v21, v64
	v_ashrrev_i32_e32 v17, 31, v16
	v_lshl_add_u64 v[16:17], v[16:17], 1, s[6:7]
	global_store_short v[16:17], v18, off
	v_max_f32_e32 v16, v22, v22
	v_max_f32_e32 v16, 0, v16
	v_mul_f32_e32 v16, v16, v16
	v_add_u32_e32 v22, 0x2a000, v65
	v_cvt_pk_bf16_f32 v18, v16, s0
	v_add_u32_e32 v16, v22, v64
	v_ashrrev_i32_e32 v17, 31, v16
	v_lshl_add_u64 v[16:17], v[16:17], 1, s[6:7]
	global_store_short v[16:17], v18, off
	v_max_f32_e32 v16, v23, v23
	v_max_f32_e32 v16, 0, v16
	v_mul_f32_e32 v16, v16, v16
	v_add_u32_e32 v23, 0x2b000, v65
	v_cvt_pk_bf16_f32 v18, v16, s0
	v_add_u32_e32 v16, v23, v64
	v_ashrrev_i32_e32 v17, 31, v16
	v_lshl_add_u64 v[16:17], v[16:17], 1, s[6:7]
	global_store_short v[16:17], v18, off
	v_max_f32_e32 v16, v24, v24
	v_max_f32_e32 v16, 0, v16
	v_mul_f32_e32 v16, v16, v16
	v_add_u32_e32 v24, 0x30000, v65
	v_cvt_pk_bf16_f32 v18, v16, s0
	v_add_u32_e32 v16, v24, v64
	v_ashrrev_i32_e32 v17, 31, v16
	v_lshl_add_u64 v[16:17], v[16:17], 1, s[6:7]
	global_store_short v[16:17], v18, off
	v_max_f32_e32 v16, v25, v25
	v_max_f32_e32 v16, 0, v16
	v_mul_f32_e32 v16, v16, v16
	v_add_u32_e32 v25, 0x31000, v65
	v_cvt_pk_bf16_f32 v18, v16, s0
	v_add_u32_e32 v16, v25, v64
	v_ashrrev_i32_e32 v17, 31, v16
	v_lshl_add_u64 v[16:17], v[16:17], 1, s[6:7]
	global_store_short v[16:17], v18, off
	v_max_f32_e32 v16, v26, v26
	v_max_f32_e32 v16, 0, v16
	v_mul_f32_e32 v16, v16, v16
	v_add_u32_e32 v26, 0x32000, v65
	v_cvt_pk_bf16_f32 v18, v16, s0
	v_add_u32_e32 v16, v26, v64
	v_ashrrev_i32_e32 v17, 31, v16
	v_lshl_add_u64 v[16:17], v[16:17], 1, s[6:7]
	global_store_short v[16:17], v18, off
	v_max_f32_e32 v16, v27, v27
	v_max_f32_e32 v16, 0, v16
	v_mul_f32_e32 v16, v16, v16
	v_add_u32_e32 v27, 0x33000, v65
	v_cvt_pk_bf16_f32 v18, v16, s0
	v_add_u32_e32 v16, v27, v64
	v_ashrrev_i32_e32 v17, 31, v16
	v_lshl_add_u64 v[16:17], v[16:17], 1, s[6:7]
	global_store_short v[16:17], v18, off
	v_max_f32_e32 v16, v28, v28
	v_max_f32_e32 v16, 0, v16
	v_mul_f32_e32 v16, v16, v16
	v_add_u32_e32 v28, 0x38000, v65
	v_cvt_pk_bf16_f32 v18, v16, s0
	v_add_u32_e32 v16, v28, v64
	v_ashrrev_i32_e32 v17, 31, v16
	v_lshl_add_u64 v[16:17], v[16:17], 1, s[6:7]
	global_store_short v[16:17], v18, off
	v_max_f32_e32 v16, v29, v29
	v_max_f32_e32 v16, 0, v16
	v_mul_f32_e32 v16, v16, v16
	v_add_u32_e32 v29, 0x39000, v65
	v_cvt_pk_bf16_f32 v18, v16, s0
	v_add_u32_e32 v16, v29, v64
	v_ashrrev_i32_e32 v17, 31, v16
	v_lshl_add_u64 v[16:17], v[16:17], 1, s[6:7]
	global_store_short v[16:17], v18, off
	v_max_f32_e32 v16, v30, v30
	v_max_f32_e32 v16, 0, v16
	v_mul_f32_e32 v16, v16, v16
	v_add_u32_e32 v30, 0x3a000, v65
	v_cvt_pk_bf16_f32 v18, v16, s0
	v_add_u32_e32 v16, v30, v64
	v_ashrrev_i32_e32 v17, 31, v16
	v_lshl_add_u64 v[16:17], v[16:17], 1, s[6:7]
	global_store_short v[16:17], v18, off
; DI bf16_t f2bf(float x) { return (bf16_t)(pk_bf16(x, 0.f) & 0xffffu); }
; DI int crow(int r, int h) { return (r & 3) + 8 * (r >> 2) + 4 * h; }
;   DI bool next(int& mt, int& nt) {
;     if (j >= total) return false;
;     if (simple) { mt = j & 127; nt = j >> 7; }
;     else { const int half = j / (8 * NT), jj = j - half * 8 * NT; mt = xcd * 16 + half * 8 + (jj & 7); nt = jj >> 3; }
;     j += step; return true;
;   }
; DI void phase_up(const Params& p, int g, char* smem, int bid, int nb) {
;     ...
; #pragma unroll
;     for (int mi = 0; mi < 2; ++mi)
; #pragma unroll
;       for (int ni = 0; ni < 2; ++ni)
; #pragma unroll
;         for (int r = 0; r < 16; ++r) {
;           const float v = fmaxf(acc[mi][ni][r], 0.f);
;           (U + (size_t)mt * 128 * 4096)[(wm * 64 + mi * 32 + crow(r, h)) * 4096 + nt * 128 + wn * 64 + ni * 32 + l31] = f2bf(v * v);
;         }
	v_max_f32_e32 v16, v31, v31
	v_max_f32_e32 v16, 0, v16
	v_mul_f32_e32 v16, v16, v16
	v_add_u32_e32 v31, 0x3b000, v65
	v_cvt_pk_bf16_f32 v18, v16, s0
	v_add_u32_e32 v16, v31, v64
	v_ashrrev_i32_e32 v17, 31, v16
	v_lshl_add_u64 v[16:17], v[16:17], 1, s[6:7]
	v_max_f32_e32 v0, v0, v0
	global_store_short v[16:17], v18, off
	v_max_f32_e32 v0, 0, v0
	v_add_u32_e32 v16, v34, v50
	v_mul_f32_e32 v0, v0, v0
	v_ashrrev_i32_e32 v17, 31, v16
	v_cvt_pk_bf16_f32 v0, v0, s0
	v_lshl_add_u64 v[16:17], v[16:17], 1, s[6:7]
	global_store_short v[16:17], v0, off
	v_max_f32_e32 v0, v1, v1
	v_max_f32_e32 v0, 0, v0
	v_mul_f32_e32 v0, v0, v0
	v_cvt_pk_bf16_f32 v16, v0, s0
	v_add_u32_e32 v0, v33, v50
	v_ashrrev_i32_e32 v1, 31, v0
	v_lshl_add_u64 v[0:1], v[0:1], 1, s[6:7]
	global_store_short v[0:1], v16, off
	v_max_f32_e32 v0, v2, v2
	v_max_f32_e32 v0, 0, v0
	v_mul_f32_e32 v0, v0, v0
	v_cvt_pk_bf16_f32 v2, v0, s0
	v_add_u32_e32 v0, v32, v50
	v_ashrrev_i32_e32 v1, 31, v0
	v_lshl_add_u64 v[0:1], v[0:1], 1, s[6:7]
	global_store_short v[0:1], v2, off
	v_max_f32_e32 v0, v3, v3
	v_max_f32_e32 v0, 0, v0
	v_mul_f32_e32 v0, v0, v0
	v_cvt_pk_bf16_f32 v2, v0, s0
	v_add_u32_e32 v0, v19, v50
	v_ashrrev_i32_e32 v1, 31, v0
	v_lshl_add_u64 v[0:1], v[0:1], 1, s[6:7]
	global_store_short v[0:1], v2, off
	v_max_f32_e32 v0, v4, v4
	v_max_f32_e32 v0, 0, v0
	v_mul_f32_e32 v0, v0, v0
	v_cvt_pk_bf16_f32 v2, v0, s0
	v_add_u32_e32 v0, v20, v50
	v_ashrrev_i32_e32 v1, 31, v0
	v_lshl_add_u64 v[0:1], v[0:1], 1, s[6:7]
	global_store_short v[0:1], v2, off
	v_max_f32_e32 v0, v5, v5
	v_max_f32_e32 v0, 0, v0
	v_mul_f32_e32 v0, v0, v0
	v_cvt_pk_bf16_f32 v2, v0, s0
	v_add_u32_e32 v0, v21, v50
	v_ashrrev_i32_e32 v1, 31, v0
	v_lshl_add_u64 v[0:1], v[0:1], 1, s[6:7]
	global_store_short v[0:1], v2, off
	v_max_f32_e32 v0, v6, v6
	v_max_f32_e32 v0, 0, v0
	v_mul_f32_e32 v0, v0, v0
	v_cvt_pk_bf16_f32 v2, v0, s0
	v_add_u32_e32 v0, v22, v50
	v_ashrrev_i32_e32 v1, 31, v0
	v_lshl_add_u64 v[0:1], v[0:1], 1, s[6:7]
	global_store_short v[0:1], v2, off
	v_max_f32_e32 v0, v7, v7
	v_max_f32_e32 v0, 0, v0
	v_mul_f32_e32 v0, v0, v0
	v_cvt_pk_bf16_f32 v2, v0, s0
	v_add_u32_e32 v0, v23, v50
	v_ashrrev_i32_e32 v1, 31, v0
	v_lshl_add_u64 v[0:1], v[0:1], 1, s[6:7]
	global_store_short v[0:1], v2, off
	v_max_f32_e32 v0, v8, v8
	v_max_f32_e32 v0, 0, v0
	v_mul_f32_e32 v0, v0, v0
	v_cvt_pk_bf16_f32 v2, v0, s0
	v_add_u32_e32 v0, v24, v50
	v_ashrrev_i32_e32 v1, 31, v0
	v_lshl_add_u64 v[0:1], v[0:1], 1, s[6:7]
	global_store_short v[0:1], v2, off
	v_max_f32_e32 v0, v9, v9
	v_max_f32_e32 v0, 0, v0
	v_mul_f32_e32 v0, v0, v0
	v_cvt_pk_bf16_f32 v2, v0, s0
	v_add_u32_e32 v0, v25, v50
	v_ashrrev_i32_e32 v1, 31, v0
	v_lshl_add_u64 v[0:1], v[0:1], 1, s[6:7]
	global_store_short v[0:1], v2, off
	v_max_f32_e32 v0, v10, v10
	v_max_f32_e32 v0, 0, v0
	v_mul_f32_e32 v0, v0, v0
	v_cvt_pk_bf16_f32 v2, v0, s0
	v_add_u32_e32 v0, v26, v50
	v_ashrrev_i32_e32 v1, 31, v0
	v_lshl_add_u64 v[0:1], v[0:1], 1, s[6:7]
	global_store_short v[0:1], v2, off
	v_max_f32_e32 v0, v11, v11
	v_max_f32_e32 v0, 0, v0
	v_mul_f32_e32 v0, v0, v0
	v_cvt_pk_bf16_f32 v2, v0, s0
	v_add_u32_e32 v0, v27, v50
	v_ashrrev_i32_e32 v1, 31, v0
	v_lshl_add_u64 v[0:1], v[0:1], 1, s[6:7]
	global_store_short v[0:1], v2, off
	v_max_f32_e32 v0, v12, v12
	v_max_f32_e32 v0, 0, v0
	v_mul_f32_e32 v0, v0, v0
	v_cvt_pk_bf16_f32 v2, v0, s0
	v_add_u32_e32 v0, v28, v50
	v_ashrrev_i32_e32 v1, 31, v0
	v_lshl_add_u64 v[0:1], v[0:1], 1, s[6:7]
	global_store_short v[0:1], v2, off
	v_max_f32_e32 v0, v13, v13
	v_max_f32_e32 v0, 0, v0
	v_mul_f32_e32 v0, v0, v0
	v_cvt_pk_bf16_f32 v2, v0, s0
	v_add_u32_e32 v0, v29, v50
	v_ashrrev_i32_e32 v1, 31, v0
	v_lshl_add_u64 v[0:1], v[0:1], 1, s[6:7]
	global_store_short v[0:1], v2, off
	v_max_f32_e32 v0, v14, v14
	v_max_f32_e32 v0, 0, v0
	v_mul_f32_e32 v0, v0, v0
	v_cvt_pk_bf16_f32 v2, v0, s0
	v_add_u32_e32 v0, v30, v50
	v_ashrrev_i32_e32 v1, 31, v0
	v_lshl_add_u64 v[0:1], v[0:1], 1, s[6:7]
	global_store_short v[0:1], v2, off
	v_max_f32_e32 v0, v15, v15
	v_max_f32_e32 v0, 0, v0
	v_mul_f32_e32 v0, v0, v0
	v_cvt_pk_bf16_f32 v2, v0, s0
	v_add_u32_e32 v0, v31, v50
	v_ashrrev_i32_e32 v1, 31, v0
	s_add_i32 s11, s11, s12
	v_lshl_add_u64 v[0:1], v[0:1], 1, s[6:7]
	s_cmp_ge_i32 s11, s13
	global_store_short v[0:1], v2, off
	s_cbranch_scc1 .LBB0_198

; template <bool SWAP>
; DI void gemm_tile(const bf16_t* __restrict__ A, int lda, const bf16_t* __restrict__ Bt, int ldb, int K, f32x16 (&acc)[2][2], bf16_t* As, bf16_t* Bs_unused) {
;     ...
;   const int tid = TID(), lane = tid & 63, wave = tid >> 6, wm = wave >> 1, wn = wave & 1;
;   const int lr = tid >> 3, lc = (tid & 7) * 8;
;   const bf16_t* ga = A + (size_t)lr * lda + lc;
;   const bf16_t* gb = Bt + (size_t)lr * ldb + lc;
;   u32x4 ra0[4], rb0[4], ra1[4], rb1[4];
;   auto load_stage = [&](u32x4 (&ra)[4], u32x4 (&rb)[4], int t) __attribute__((always_inline)) {
; #pragma unroll
;     for (int i = 0; i < 4; ++i) { ra[i] = *(const u32x4*)(ga + (size_t)(32 * i) * lda + t * 64); rb[i] = *(const u32x4*)(gb + (size_t)(32 * i) * ldb + t * 64); }
;   };
;   auto write_stage = [&](const u32x4 (&ra)[4], const u32x4 (&rb)[4], int buf) __attribute__((always_inline)) {
;     bf16_t* Ad = As + buf * 2 * GT_IMG; bf16_t* Bd = Ad + GT_IMG;
; #pragma unroll
;     for (int i = 0; i < 4; ++i) { *(u32x4*)(Ad + (lr + 32 * i) * 72 + lc) = ra[i]; *(u32x4*)(Bd + (lr + 32 * i) * 72 + lc) = rb[i]; }
;   };
;   const int fr = lane & 31, fk = (lane >> 5) * 8;
;   const int pao = (wm * 64 + fr) * 72 + fk, pbo = GT_IMG + (wn * 64 + fr) * 72 + fk;
;   auto frag_read = [&](bf16x8 (&f)[4], const bf16_t* pa, const bf16_t* pb, int so) __attribute__((always_inline)) {
;     f[0] = *(const bf16x8*)(pa + so); f[1] = *(const bf16x8*)(pb + so); f[2] = *(const bf16x8*)(pb + 32 * 72 + so); f[3] = *(const bf16x8*)(pa + 32 * 72 + so);
;   };
;   auto mfma4 = [&](const bf16x8 (&f)[4]) __attribute__((always_inline)) {
;     if (SWAP) {
;       acc[0][0] = MFMA32(f[1], f[0], acc[0][0]); acc[0][1] = MFMA32(f[2], f[0], acc[0][1]);
;       acc[1][0] = MFMA32(f[1], f[3], acc[1][0]); acc[1][1] = MFMA32(f[2], f[3], acc[1][1]);
;     } else {
;       acc[0][0] = MFMA32(f[0], f[1], acc[0][0]); acc[0][1] = MFMA32(f[0], f[2], acc[0][1]);
;       acc[1][0] = MFMA32(f[3], f[1], acc[1][0]); acc[1][1] = MFMA32(f[3], f[2], acc[1][1]);
;     }
;   };
;   auto step = [&](int buf, u32x4 (&ra)[4], u32x4 (&rb)[4], bool do_write, bool do_load, int tload) __attribute__((always_inline)) {
;     const bf16_t* pa = As + buf * 2 * GT_IMG + pao; const bf16_t* pb = As + buf * 2 * GT_IMG + pbo;
;     bf16_t* Ad = As + (buf ^ 1) * 2 * GT_IMG; bf16_t* Bd = Ad + GT_IMG;
;     bf16x8 F0[4], F1[4];
;     frag_read(F0, pa, pb, 0);
.LBB0_211:
	s_ashr_i32 s7, s6, 31
	s_add_i32 s11, s11, s12
	s_lshl_b64 s[8:9], s[6:7], 18
	v_mov_b32_e32 v34, v195
	s_add_u32 s8, s4, s8
	s_addc_u32 s9, s5, s9
	v_ashrrev_i32_e32 v32, 3, v34
	s_ashr_i32 s1, s0, 31
	v_ashrrev_i32_e32 v33, 31, v32
	s_lshl_b64 s[14:15], s[0:1], 18
	v_readlane_b32 s1, v235, 59
	v_lshlrev_b64 v[0:1], 11, v[32:33]
	s_waitcnt lgkmcnt(0)
	v_lshlrev_b32_e32 v4, 4, v34
	s_add_u32 s14, s1, s14
	v_readlane_b32 s1, v235, 60
	v_lshl_add_u64 v[2:3], s[8:9], 0, v[0:1]
	v_and_b32_e32 v192, 0x70, v4
	s_addc_u32 s15, s1, s15
	v_lshl_add_u64 v[80:81], v[2:3], 0, v[192:193]
	s_mov_b32 s1, 0x10000
	v_lshl_add_u64 v[0:1], s[14:15], 0, v[0:1]
	v_add_co_u32_e32 v84, vcc, s1, v80
	v_lshl_add_u64 v[82:83], v[0:1], 0, v[192:193]
	s_nop 0
	v_addc_co_u32_e32 v85, vcc, 0, v81, vcc
	v_add_co_u32_e32 v86, vcc, s1, v82
	s_mov_b32 s1, 0x20000
	s_nop 0
	v_addc_co_u32_e32 v87, vcc, 0, v83, vcc
	global_load_dwordx4 v[0:3], v[80:81], off
	global_load_dwordx4 v[4:7], v[82:83], off
	v_add_co_u32_e32 v88, vcc, s1, v80
	global_load_dwordx4 v[8:11], v[84:85], off
	global_load_dwordx4 v[12:15], v[86:87], off
	v_addc_co_u32_e32 v89, vcc, 0, v81, vcc
	v_add_co_u32_e32 v90, vcc, s1, v82
	s_mov_b32 s1, 0x30000
	s_nop 0
	v_addc_co_u32_e32 v91, vcc, 0, v83, vcc
	global_load_dwordx4 v[16:19], v[88:89], off
	global_load_dwordx4 v[20:23], v[90:91], off
	v_add_co_u32_e32 v92, vcc, s1, v80
	v_mul_lo_u32 v32, v32, s71
	s_nop 0
	v_addc_co_u32_e32 v93, vcc, 0, v81, vcc
	global_load_dwordx4 v[24:27], v[92:93], off
	v_add_co_u32_e32 v94, vcc, s1, v82
	v_add3_u32 v100, 32, v32, v192
	s_nop 0
	v_addc_co_u32_e32 v95, vcc, 0, v83, vcc
	global_load_dwordx4 v[28:31], v[94:95], off
	global_load_dwordx4 v[104:107], v[80:81], off offset:128
	global_load_dwordx4 v[108:111], v[82:83], off offset:128
	global_load_dwordx4 v[112:115], v[84:85], off offset:128
	global_load_dwordx4 v[116:119], v[86:87], off offset:128
	global_load_dwordx4 v[120:123], v[88:89], off offset:128
	global_load_dwordx4 v[124:127], v[90:91], off offset:128
	global_load_dwordx4 v[128:131], v[92:93], off offset:128
	global_load_dwordx4 v[132:135], v[94:95], off offset:128
	s_waitcnt vmcnt(63) expcnt(7) lgkmcnt(15)
	s_barrier
	v_add_u32_e32 v103, 0xd800, v100
	s_waitcnt vmcnt(15)
	ds_write_b128 v100, v[0:3]
	s_waitcnt vmcnt(14)
	ds_write_b128 v100, v[4:7] offset:18432
	s_waitcnt vmcnt(13)
	ds_write_b128 v100, v[8:11] offset:4608
	s_waitcnt vmcnt(12)
	ds_write_b128 v100, v[12:15] offset:23040
	s_waitcnt vmcnt(11)
	ds_write_b128 v100, v[16:19] offset:9216
	s_waitcnt vmcnt(10)
	ds_write_b128 v100, v[20:23] offset:27648
	s_waitcnt vmcnt(9)
	ds_write_b128 v100, v[24:27] offset:13824
	s_waitcnt vmcnt(8)
	ds_write_b128 v100, v[28:31] offset:32256
	global_load_dwordx4 v[136:139], v[80:81], off offset:256
	global_load_dwordx4 v[64:67], v[82:83], off offset:256
	global_load_dwordx4 v[140:143], v[84:85], off offset:256
	global_load_dwordx4 v[68:71], v[86:87], off offset:256
	global_load_dwordx4 v[144:147], v[88:89], off offset:256
	global_load_dwordx4 v[72:75], v[90:91], off offset:256
	global_load_dwordx4 v[148:151], v[92:93], off offset:256
	global_load_dwordx4 v[76:79], v[94:95], off offset:256
	v_lshrrev_b32_e32 v0, 2, v34
	v_lshrrev_b32_e32 v2, 1, v34
	v_and_b32_e32 v3, 31, v34
	v_and_b32_e32 v1, 0x5f, v34
	v_and_b32_e32 v0, 8, v0
	v_and_or_b32 v2, v2, s80, v3
	v_mad_u64_u32 v[2:3], s[8:9], v2, s72, v[0:1]
	v_lshl_add_u32 v101, v2, 1, 32
	v_mad_u32_u24 v0, v1, s72, v0
	s_waitcnt lgkmcnt(0)
	s_barrier
	v_lshl_add_u32 v102, v0, 1, 32
	ds_read_b128 v[0:3], v101
	ds_read_b128 v[4:7], v102 offset:18432
	ds_read_b128 v[8:11], v102 offset:23040
	ds_read_b128 v[12:15], v101 offset:4608
	ds_read_b128 v[152:155], v102 offset:18464
	ds_read_b128 v[156:159], v102 offset:23072
	ds_read_b128 v[160:163], v101 offset:32
	ds_read_b128 v[164:167], v101 offset:4640
	s_waitcnt lgkmcnt(6)
	v_mfma_f32_32x32x16_bf16 v[48:63], v[0:3], v[4:7], 0
	s_waitcnt lgkmcnt(5)
	v_mfma_f32_32x32x16_bf16 v[16:31], v[0:3], v[8:11], 0
	s_waitcnt lgkmcnt(4)
	v_mfma_f32_32x32x16_bf16 v[32:47], v[12:15], v[4:7], 0
	v_mfma_f32_32x32x16_bf16 v[0:15], v[12:15], v[8:11], 0
	s_waitcnt lgkmcnt(1)
	v_mfma_f32_32x32x16_bf16 v[48:63], v[160:163], v[152:155], v[48:63]
	v_mfma_f32_32x32x16_bf16 v[16:31], v[160:163], v[156:159], v[16:31]
	s_waitcnt lgkmcnt(0)
	v_mfma_f32_32x32x16_bf16 v[32:47], v[164:167], v[152:155], v[32:47]
	ds_read_b128 v[152:155], v102 offset:18496
	ds_read_b128 v[160:163], v102 offset:23104
	ds_read_b128 v[168:171], v101 offset:64
	ds_read_b128 v[172:175], v101 offset:4672
	s_waitcnt vmcnt(15)
	ds_write_b128 v100, v[104:107] offset:36864
	s_waitcnt vmcnt(13)
	ds_write_b128 v100, v[112:115] offset:41472
	s_waitcnt vmcnt(11)
	ds_write_b128 v100, v[120:123] offset:46080
	s_waitcnt vmcnt(9)
	ds_write_b128 v100, v[128:131] offset:50688
	v_mfma_f32_32x32x16_bf16 v[0:15], v[164:167], v[156:159], v[0:15]
	ds_read_b128 v[104:107], v102 offset:18528
	ds_read_b128 v[112:115], v102 offset:23136
	ds_read_b128 v[120:123], v101 offset:96
	ds_read_b128 v[128:131], v101 offset:4704
	s_waitcnt lgkmcnt(9)
	v_mfma_f32_32x32x16_bf16 v[48:63], v[168:171], v[152:155], v[48:63]
	ds_write_b128 v100, v[108:111] offset:55296
	ds_write_b128 v100, v[116:119] offset:59904
	ds_write_b128 v100, v[124:127] offset:64512
	s_waitcnt vmcnt(8)
	ds_write_b128 v103, v[132:135] offset:13824
	v_mfma_f32_32x32x16_bf16 v[16:31], v[168:171], v[160:163], v[16:31]
	s_waitcnt lgkmcnt(12)
	v_mfma_f32_32x32x16_bf16 v[32:47], v[172:175], v[152:155], v[32:47]
	v_mfma_f32_32x32x16_bf16 v[0:15], v[172:175], v[160:163], v[0:15]
	s_waitcnt lgkmcnt(0)
	s_barrier
; template <bool SWAP>
; DI void gemm_tile(const bf16_t* __restrict__ A, int lda, const bf16_t* __restrict__ Bt, int ldb, int K, f32x16 (&acc)[2][2], bf16_t* As, bf16_t* Bs_unused) {
;     ...
;   auto step = [&](int buf, u32x4 (&ra)[4], u32x4 (&rb)[4], bool do_write, bool do_load, int tload) __attribute__((always_inline)) {
;     const bf16_t* pa = As + buf * 2 * GT_IMG + pao; const bf16_t* pb = As + buf * 2 * GT_IMG + pbo;
;     bf16_t* Ad = As + (buf ^ 1) * 2 * GT_IMG; bf16_t* Bd = Ad + GT_IMG;
;     bf16x8 F0[4], F1[4];
;     frag_read(F0, pa, pb, 0);
;     __builtin_amdgcn_sched_barrier(0);
;     frag_read(F1, pa, pb, 16);
;     mfma4(F0);
;     __builtin_amdgcn_sched_barrier(0);
;     frag_read(F0, pa, pb, 32);
;     mfma4(F1);
;     if (do_write) {
; #pragma unroll
;       for (int i = 0; i < 4; ++i) *(u32x4*)(Ad + (lr + 32 * i) * 72 + lc) = ra[i];
;     }
;     __builtin_amdgcn_sched_barrier(0);
;     frag_read(F1, pa, pb, 48);
;     mfma4(F0);
;     if (do_write) {
; #pragma unroll
;       for (int i = 0; i < 4; ++i) *(u32x4*)(Bd + (lr + 32 * i) * 72 + lc) = rb[i];
;     }
;     __builtin_amdgcn_sched_barrier(0);
;     mfma4(F1);
;     if (do_load) load_stage(ra, rb, tload);
;     __builtin_amdgcn_sched_barrier(0);
;   };
;   const int nk = K >> 6;
;   load_stage(ra0, rb0, 0); load_stage(ra1, rb1, 1);
;   __syncthreads();
;   write_stage(ra0, rb0, 0);
;   load_stage(ra0, rb0, 2);
;   __syncthreads();
;   for (int kt = 0; kt < nk; kt += 2) {
;     step(0, ra1, rb1, true, kt + 3 < nk, kt + 3);
;     __syncthreads();
;     step(1, ra0, rb0, kt + 2 < nk, kt + 4 < nk, kt + 4);
;     __syncthreads();
	ds_read_b128 v[152:155], v102 offset:55296
	ds_read_b128 v[156:159], v102 offset:59904
	ds_read_b128 v[160:163], v101 offset:36864
	ds_read_b128 v[164:167], v101 offset:41472
	v_mfma_f32_32x32x16_bf16 v[48:63], v[120:123], v[104:107], v[48:63]
	v_mfma_f32_32x32x16_bf16 v[16:31], v[120:123], v[112:115], v[16:31]
	v_mfma_f32_32x32x16_bf16 v[32:47], v[128:131], v[104:107], v[32:47]
	v_mfma_f32_32x32x16_bf16 v[0:15], v[128:131], v[112:115], v[0:15]
	global_load_dwordx4 v[104:107], v[80:81], off offset:384
	global_load_dwordx4 v[108:111], v[82:83], off offset:384
	global_load_dwordx4 v[112:115], v[84:85], off offset:384
	global_load_dwordx4 v[116:119], v[86:87], off offset:384
	global_load_dwordx4 v[120:123], v[88:89], off offset:384
	global_load_dwordx4 v[124:127], v[90:91], off offset:384
	global_load_dwordx4 v[128:131], v[92:93], off offset:384
	global_load_dwordx4 v[132:135], v[94:95], off offset:384
	s_waitcnt lgkmcnt(1)
	v_mfma_f32_32x32x16_bf16 v[48:63], v[160:163], v[152:155], v[48:63]
	v_mfma_f32_32x32x16_bf16 v[16:31], v[160:163], v[156:159], v[16:31]
	s_waitcnt lgkmcnt(0)
	v_mfma_f32_32x32x16_bf16 v[32:47], v[164:167], v[152:155], v[32:47]
	ds_read_b128 v[152:155], v102 offset:55328
	ds_read_b128 v[160:163], v102 offset:59936
	ds_read_b128 v[168:171], v101 offset:36896
	ds_read_b128 v[172:175], v101 offset:41504
	v_mfma_f32_32x32x16_bf16 v[0:15], v[164:167], v[156:159], v[0:15]
	s_waitcnt lgkmcnt(1)
	v_mfma_f32_32x32x16_bf16 v[48:63], v[168:171], v[152:155], v[48:63]
	v_mfma_f32_32x32x16_bf16 v[16:31], v[168:171], v[160:163], v[16:31]
	s_waitcnt lgkmcnt(0)
	v_mfma_f32_32x32x16_bf16 v[32:47], v[172:175], v[152:155], v[32:47]
	ds_read_b128 v[152:155], v102 offset:55360
	ds_read_b128 v[156:159], v102 offset:59968
	ds_read_b128 v[164:167], v101 offset:36928
	ds_read_b128 v[168:171], v101 offset:41536
	s_waitcnt vmcnt(15)
	ds_write_b128 v100, v[136:139]
	s_waitcnt vmcnt(13)
	ds_write_b128 v100, v[140:143] offset:4608
	s_waitcnt vmcnt(11)
	ds_write_b128 v100, v[144:147] offset:9216
	s_waitcnt vmcnt(9)
	ds_write_b128 v100, v[148:151] offset:13824
	v_mfma_f32_32x32x16_bf16 v[0:15], v[172:175], v[160:163], v[0:15]
	ds_read_b128 v[136:139], v102 offset:55392
	ds_read_b128 v[140:143], v102 offset:60000
	ds_read_b128 v[144:147], v101 offset:36960
	ds_read_b128 v[148:151], v101 offset:41568
	s_waitcnt lgkmcnt(9)
	v_mfma_f32_32x32x16_bf16 v[48:63], v[164:167], v[152:155], v[48:63]
	ds_write_b128 v100, v[64:67] offset:18432
	ds_write_b128 v100, v[68:71] offset:23040
	ds_write_b128 v100, v[72:75] offset:27648
	s_waitcnt vmcnt(8)
	ds_write_b128 v100, v[76:79] offset:32256
	v_mfma_f32_32x32x16_bf16 v[16:31], v[164:167], v[156:159], v[16:31]
	s_waitcnt lgkmcnt(12)
	v_mfma_f32_32x32x16_bf16 v[32:47], v[168:171], v[152:155], v[32:47]
	v_mfma_f32_32x32x16_bf16 v[0:15], v[168:171], v[156:159], v[0:15]
	s_waitcnt lgkmcnt(0)
	s_barrier
	ds_read_b128 v[152:155], v102 offset:18432
	ds_read_b128 v[156:159], v102 offset:23040
	ds_read_b128 v[160:163], v101
	ds_read_b128 v[164:167], v101 offset:4608
	v_mfma_f32_32x32x16_bf16 v[48:63], v[144:147], v[136:139], v[48:63]
	v_mfma_f32_32x32x16_bf16 v[16:31], v[144:147], v[140:143], v[16:31]
	v_mfma_f32_32x32x16_bf16 v[32:47], v[148:151], v[136:139], v[32:47]
	v_mfma_f32_32x32x16_bf16 v[0:15], v[148:151], v[140:143], v[0:15]
	global_load_dwordx4 v[64:67], v[80:81], off offset:512
	global_load_dwordx4 v[68:71], v[82:83], off offset:512
	global_load_dwordx4 v[72:75], v[84:85], off offset:512
	global_load_dwordx4 v[76:79], v[86:87], off offset:512
	global_load_dwordx4 v[136:139], v[88:89], off offset:512
	global_load_dwordx4 v[140:143], v[90:91], off offset:512
	global_load_dwordx4 v[144:147], v[92:93], off offset:512
	global_load_dwordx4 v[148:151], v[94:95], off offset:512
	s_waitcnt lgkmcnt(1)
	v_mfma_f32_32x32x16_bf16 v[48:63], v[160:163], v[152:155], v[48:63]
	v_mfma_f32_32x32x16_bf16 v[16:31], v[160:163], v[156:159], v[16:31]
	s_waitcnt lgkmcnt(0)
	v_mfma_f32_32x32x16_bf16 v[32:47], v[164:167], v[152:155], v[32:47]
	ds_read_b128 v[152:155], v102 offset:18464
	ds_read_b128 v[160:163], v102 offset:23072
	ds_read_b128 v[168:171], v101 offset:32
	ds_read_b128 v[172:175], v101 offset:4640
	v_mfma_f32_32x32x16_bf16 v[0:15], v[164:167], v[156:159], v[0:15]
	s_waitcnt lgkmcnt(1)
	v_mfma_f32_32x32x16_bf16 v[48:63], v[168:171], v[152:155], v[48:63]
	v_mfma_f32_32x32x16_bf16 v[16:31], v[168:171], v[160:163], v[16:31]
	s_waitcnt lgkmcnt(0)
	v_mfma_f32_32x32x16_bf16 v[32:47], v[172:175], v[152:155], v[32:47]
	ds_read_b128 v[152:155], v102 offset:18496
	ds_read_b128 v[156:159], v102 offset:23104
	ds_read_b128 v[164:167], v101 offset:64
	ds_read_b128 v[168:171], v101 offset:4672
	s_waitcnt vmcnt(15)
	ds_write_b128 v100, v[104:107] offset:36864
	s_waitcnt vmcnt(13)
	ds_write_b128 v100, v[112:115] offset:41472
	s_waitcnt vmcnt(11)
	ds_write_b128 v100, v[120:123] offset:46080
	s_waitcnt vmcnt(9)
	ds_write_b128 v100, v[128:131] offset:50688
	v_mfma_f32_32x32x16_bf16 v[0:15], v[172:175], v[160:163], v[0:15]
	ds_read_b128 v[104:107], v102 offset:18528
	ds_read_b128 v[112:115], v102 offset:23136
	ds_read_b128 v[120:123], v101 offset:96
	ds_read_b128 v[128:131], v101 offset:4704
	s_waitcnt lgkmcnt(9)
	v_mfma_f32_32x32x16_bf16 v[48:63], v[164:167], v[152:155], v[48:63]
	ds_write_b128 v100, v[108:111] offset:55296
	ds_write_b128 v100, v[116:119] offset:59904
	ds_write_b128 v100, v[124:127] offset:64512
	s_waitcnt vmcnt(8)
	ds_write_b128 v103, v[132:135] offset:13824
	v_mfma_f32_32x32x16_bf16 v[16:31], v[164:167], v[156:159], v[16:31]
	s_waitcnt lgkmcnt(12)
	v_mfma_f32_32x32x16_bf16 v[32:47], v[168:171], v[152:155], v[32:47]
	v_mfma_f32_32x32x16_bf16 v[0:15], v[168:171], v[156:159], v[0:15]
	s_waitcnt lgkmcnt(0)
	s_barrier
; template <bool SWAP>
; DI void gemm_tile(const bf16_t* __restrict__ A, int lda, const bf16_t* __restrict__ Bt, int ldb, int K, f32x16 (&acc)[2][2], bf16_t* As, bf16_t* Bs_unused) {
;     ...
;   auto step = [&](int buf, u32x4 (&ra)[4], u32x4 (&rb)[4], bool do_write, bool do_load, int tload) __attribute__((always_inline)) {
;     const bf16_t* pa = As + buf * 2 * GT_IMG + pao; const bf16_t* pb = As + buf * 2 * GT_IMG + pbo;
;     bf16_t* Ad = As + (buf ^ 1) * 2 * GT_IMG; bf16_t* Bd = Ad + GT_IMG;
;     bf16x8 F0[4], F1[4];
;     frag_read(F0, pa, pb, 0);
;     __builtin_amdgcn_sched_barrier(0);
;     frag_read(F1, pa, pb, 16);
;     mfma4(F0);
;     __builtin_amdgcn_sched_barrier(0);
;     frag_read(F0, pa, pb, 32);
;     mfma4(F1);
;     if (do_write) {
; #pragma unroll
;       for (int i = 0; i < 4; ++i) *(u32x4*)(Ad + (lr + 32 * i) * 72 + lc) = ra[i];
;     }
;     __builtin_amdgcn_sched_barrier(0);
;     frag_read(F1, pa, pb, 48);
;     mfma4(F0);
;     if (do_write) {
; #pragma unroll
;       for (int i = 0; i < 4; ++i) *(u32x4*)(Bd + (lr + 32 * i) * 72 + lc) = rb[i];
;     }
;     __builtin_amdgcn_sched_barrier(0);
;     mfma4(F1);
;     if (do_load) load_stage(ra, rb, tload);
;     __builtin_amdgcn_sched_barrier(0);
;   };
;   const int nk = K >> 6;
;   load_stage(ra0, rb0, 0); load_stage(ra1, rb1, 1);
;   __syncthreads();
;   write_stage(ra0, rb0, 0);
;   load_stage(ra0, rb0, 2);
;   __syncthreads();
;   for (int kt = 0; kt < nk; kt += 2) {
;     step(0, ra1, rb1, true, kt + 3 < nk, kt + 3);
;     __syncthreads();
;     step(1, ra0, rb0, kt + 2 < nk, kt + 4 < nk, kt + 4);
;     __syncthreads();
	ds_read_b128 v[152:155], v102 offset:55296
	ds_read_b128 v[156:159], v102 offset:59904
	ds_read_b128 v[160:163], v101 offset:36864
	ds_read_b128 v[164:167], v101 offset:41472
	v_mfma_f32_32x32x16_bf16 v[48:63], v[120:123], v[104:107], v[48:63]
	v_mfma_f32_32x32x16_bf16 v[16:31], v[120:123], v[112:115], v[16:31]
	v_mfma_f32_32x32x16_bf16 v[32:47], v[128:131], v[104:107], v[32:47]
	v_mfma_f32_32x32x16_bf16 v[0:15], v[128:131], v[112:115], v[0:15]
	global_load_dwordx4 v[104:107], v[80:81], off offset:640
	global_load_dwordx4 v[108:111], v[82:83], off offset:640
	global_load_dwordx4 v[112:115], v[84:85], off offset:640
	global_load_dwordx4 v[116:119], v[86:87], off offset:640
	global_load_dwordx4 v[120:123], v[88:89], off offset:640
	global_load_dwordx4 v[124:127], v[90:91], off offset:640
	global_load_dwordx4 v[128:131], v[92:93], off offset:640
	global_load_dwordx4 v[132:135], v[94:95], off offset:640
	s_waitcnt lgkmcnt(1)
	v_mfma_f32_32x32x16_bf16 v[48:63], v[160:163], v[152:155], v[48:63]
	v_mfma_f32_32x32x16_bf16 v[16:31], v[160:163], v[156:159], v[16:31]
	s_waitcnt lgkmcnt(0)
	v_mfma_f32_32x32x16_bf16 v[32:47], v[164:167], v[152:155], v[32:47]
	ds_read_b128 v[152:155], v102 offset:55328
	ds_read_b128 v[160:163], v102 offset:59936
	ds_read_b128 v[168:171], v101 offset:36896
	ds_read_b128 v[172:175], v101 offset:41504
	v_mfma_f32_32x32x16_bf16 v[0:15], v[164:167], v[156:159], v[0:15]
	s_waitcnt lgkmcnt(1)
	v_mfma_f32_32x32x16_bf16 v[48:63], v[168:171], v[152:155], v[48:63]
	v_mfma_f32_32x32x16_bf16 v[16:31], v[168:171], v[160:163], v[16:31]
	s_waitcnt lgkmcnt(0)
	v_mfma_f32_32x32x16_bf16 v[32:47], v[172:175], v[152:155], v[32:47]
	ds_read_b128 v[152:155], v102 offset:55360
	ds_read_b128 v[156:159], v102 offset:59968
	ds_read_b128 v[164:167], v101 offset:36928
	ds_read_b128 v[168:171], v101 offset:41536
	s_waitcnt vmcnt(15)
	ds_write_b128 v100, v[64:67]
	s_waitcnt vmcnt(13)
	ds_write_b128 v100, v[72:75] offset:4608
	s_waitcnt vmcnt(11)
	ds_write_b128 v100, v[136:139] offset:9216
	s_waitcnt vmcnt(9)
	ds_write_b128 v100, v[144:147] offset:13824
	v_mfma_f32_32x32x16_bf16 v[0:15], v[172:175], v[160:163], v[0:15]
	ds_read_b128 v[64:67], v102 offset:55392
	ds_read_b128 v[72:75], v102 offset:60000
	ds_read_b128 v[136:139], v101 offset:36960
	ds_read_b128 v[144:147], v101 offset:41568
	s_waitcnt lgkmcnt(9)
	v_mfma_f32_32x32x16_bf16 v[48:63], v[164:167], v[152:155], v[48:63]
	ds_write_b128 v100, v[68:71] offset:18432
	ds_write_b128 v100, v[76:79] offset:23040
	ds_write_b128 v100, v[140:143] offset:27648
	s_waitcnt vmcnt(8)
	ds_write_b128 v100, v[148:151] offset:32256
	v_mfma_f32_32x32x16_bf16 v[16:31], v[164:167], v[156:159], v[16:31]
	s_waitcnt lgkmcnt(12)
	v_mfma_f32_32x32x16_bf16 v[32:47], v[168:171], v[152:155], v[32:47]
	v_mfma_f32_32x32x16_bf16 v[0:15], v[168:171], v[156:159], v[0:15]
	s_waitcnt lgkmcnt(0)
	s_barrier
	ds_read_b128 v[152:155], v102 offset:18432
	ds_read_b128 v[156:159], v102 offset:23040
	ds_read_b128 v[160:163], v101
	ds_read_b128 v[164:167], v101 offset:4608
	v_mfma_f32_32x32x16_bf16 v[48:63], v[136:139], v[64:67], v[48:63]
	v_mfma_f32_32x32x16_bf16 v[16:31], v[136:139], v[72:75], v[16:31]
	v_mfma_f32_32x32x16_bf16 v[32:47], v[144:147], v[64:67], v[32:47]
	v_mfma_f32_32x32x16_bf16 v[0:15], v[144:147], v[72:75], v[0:15]
	global_load_dwordx4 v[64:67], v[80:81], off offset:768
	global_load_dwordx4 v[68:71], v[82:83], off offset:768
	global_load_dwordx4 v[72:75], v[84:85], off offset:768
	global_load_dwordx4 v[76:79], v[86:87], off offset:768
	global_load_dwordx4 v[136:139], v[88:89], off offset:768
	global_load_dwordx4 v[140:143], v[90:91], off offset:768
	global_load_dwordx4 v[144:147], v[92:93], off offset:768
	global_load_dwordx4 v[148:151], v[94:95], off offset:768
	s_waitcnt lgkmcnt(1)
	v_mfma_f32_32x32x16_bf16 v[48:63], v[160:163], v[152:155], v[48:63]
	v_mfma_f32_32x32x16_bf16 v[16:31], v[160:163], v[156:159], v[16:31]
	s_waitcnt lgkmcnt(0)
	v_mfma_f32_32x32x16_bf16 v[32:47], v[164:167], v[152:155], v[32:47]
	ds_read_b128 v[152:155], v102 offset:18464
	ds_read_b128 v[160:163], v102 offset:23072
	ds_read_b128 v[168:171], v101 offset:32
	ds_read_b128 v[172:175], v101 offset:4640
	v_mfma_f32_32x32x16_bf16 v[0:15], v[164:167], v[156:159], v[0:15]
	s_waitcnt lgkmcnt(1)
	v_mfma_f32_32x32x16_bf16 v[48:63], v[168:171], v[152:155], v[48:63]
	v_mfma_f32_32x32x16_bf16 v[16:31], v[168:171], v[160:163], v[16:31]
	s_waitcnt lgkmcnt(0)
	v_mfma_f32_32x32x16_bf16 v[32:47], v[172:175], v[152:155], v[32:47]
	ds_read_b128 v[152:155], v102 offset:18496
	ds_read_b128 v[156:159], v102 offset:23104
	ds_read_b128 v[164:167], v101 offset:64
	ds_read_b128 v[168:171], v101 offset:4672
	s_waitcnt vmcnt(15)
	ds_write_b128 v100, v[104:107] offset:36864
	s_waitcnt vmcnt(13)
	ds_write_b128 v100, v[112:115] offset:41472
	s_waitcnt vmcnt(11)
	ds_write_b128 v100, v[120:123] offset:46080
	s_waitcnt vmcnt(9)
	ds_write_b128 v100, v[128:131] offset:50688
	v_mfma_f32_32x32x16_bf16 v[0:15], v[172:175], v[160:163], v[0:15]
	ds_read_b128 v[104:107], v102 offset:18528
	ds_read_b128 v[112:115], v102 offset:23136
	ds_read_b128 v[120:123], v101 offset:96
	ds_read_b128 v[128:131], v101 offset:4704
	s_waitcnt lgkmcnt(9)
	v_mfma_f32_32x32x16_bf16 v[48:63], v[164:167], v[152:155], v[48:63]
	ds_write_b128 v100, v[108:111] offset:55296
	ds_write_b128 v100, v[116:119] offset:59904
	ds_write_b128 v100, v[124:127] offset:64512
	s_waitcnt vmcnt(8)
	ds_write_b128 v103, v[132:135] offset:13824
	v_mfma_f32_32x32x16_bf16 v[16:31], v[164:167], v[156:159], v[16:31]
	s_waitcnt lgkmcnt(12)
	v_mfma_f32_32x32x16_bf16 v[32:47], v[168:171], v[152:155], v[32:47]
	v_mfma_f32_32x32x16_bf16 v[0:15], v[168:171], v[156:159], v[0:15]
	s_waitcnt lgkmcnt(0)
	s_barrier
; template <bool SWAP>
; DI void gemm_tile(const bf16_t* __restrict__ A, int lda, const bf16_t* __restrict__ Bt, int ldb, int K, f32x16 (&acc)[2][2], bf16_t* As, bf16_t* Bs_unused) {
;     ...
;   auto step = [&](int buf, u32x4 (&ra)[4], u32x4 (&rb)[4], bool do_write, bool do_load, int tload) __attribute__((always_inline)) {
;     const bf16_t* pa = As + buf * 2 * GT_IMG + pao; const bf16_t* pb = As + buf * 2 * GT_IMG + pbo;
;     bf16_t* Ad = As + (buf ^ 1) * 2 * GT_IMG; bf16_t* Bd = Ad + GT_IMG;
;     bf16x8 F0[4], F1[4];
;     frag_read(F0, pa, pb, 0);
;     __builtin_amdgcn_sched_barrier(0);
;     frag_read(F1, pa, pb, 16);
;     mfma4(F0);
;     __builtin_amdgcn_sched_barrier(0);
;     frag_read(F0, pa, pb, 32);
;     mfma4(F1);
;     if (do_write) {
; #pragma unroll
;       for (int i = 0; i < 4; ++i) *(u32x4*)(Ad + (lr + 32 * i) * 72 + lc) = ra[i];
;     }
;     __builtin_amdgcn_sched_barrier(0);
;     frag_read(F1, pa, pb, 48);
;     mfma4(F0);
;     if (do_write) {
; #pragma unroll
;       for (int i = 0; i < 4; ++i) *(u32x4*)(Bd + (lr + 32 * i) * 72 + lc) = rb[i];
;     }
;     __builtin_amdgcn_sched_barrier(0);
;     mfma4(F1);
;     if (do_load) load_stage(ra, rb, tload);
;     __builtin_amdgcn_sched_barrier(0);
;   };
;   const int nk = K >> 6;
;   load_stage(ra0, rb0, 0); load_stage(ra1, rb1, 1);
;   __syncthreads();
;   write_stage(ra0, rb0, 0);
;   load_stage(ra0, rb0, 2);
;   __syncthreads();
;   for (int kt = 0; kt < nk; kt += 2) {
;     step(0, ra1, rb1, true, kt + 3 < nk, kt + 3);
;     __syncthreads();
;     step(1, ra0, rb0, kt + 2 < nk, kt + 4 < nk, kt + 4);
;     __syncthreads();
	ds_read_b128 v[152:155], v102 offset:55296
	ds_read_b128 v[156:159], v102 offset:59904
	ds_read_b128 v[160:163], v101 offset:36864
	ds_read_b128 v[164:167], v101 offset:41472
	v_mfma_f32_32x32x16_bf16 v[48:63], v[120:123], v[104:107], v[48:63]
	v_mfma_f32_32x32x16_bf16 v[16:31], v[120:123], v[112:115], v[16:31]
	v_mfma_f32_32x32x16_bf16 v[32:47], v[128:131], v[104:107], v[32:47]
	v_mfma_f32_32x32x16_bf16 v[0:15], v[128:131], v[112:115], v[0:15]
	global_load_dwordx4 v[104:107], v[80:81], off offset:896
	global_load_dwordx4 v[108:111], v[82:83], off offset:896
	global_load_dwordx4 v[112:115], v[84:85], off offset:896
	global_load_dwordx4 v[116:119], v[86:87], off offset:896
	global_load_dwordx4 v[120:123], v[88:89], off offset:896
	global_load_dwordx4 v[124:127], v[90:91], off offset:896
	global_load_dwordx4 v[128:131], v[92:93], off offset:896
	global_load_dwordx4 v[132:135], v[94:95], off offset:896
	s_waitcnt lgkmcnt(1)
	v_mfma_f32_32x32x16_bf16 v[48:63], v[160:163], v[152:155], v[48:63]
	v_mfma_f32_32x32x16_bf16 v[16:31], v[160:163], v[156:159], v[16:31]
	s_waitcnt lgkmcnt(0)
	v_mfma_f32_32x32x16_bf16 v[32:47], v[164:167], v[152:155], v[32:47]
	ds_read_b128 v[152:155], v102 offset:55328
	ds_read_b128 v[160:163], v102 offset:59936
	ds_read_b128 v[168:171], v101 offset:36896
	ds_read_b128 v[172:175], v101 offset:41504
	v_mfma_f32_32x32x16_bf16 v[0:15], v[164:167], v[156:159], v[0:15]
	s_waitcnt lgkmcnt(1)
	v_mfma_f32_32x32x16_bf16 v[48:63], v[168:171], v[152:155], v[48:63]
	v_mfma_f32_32x32x16_bf16 v[16:31], v[168:171], v[160:163], v[16:31]
	s_waitcnt lgkmcnt(0)
	v_mfma_f32_32x32x16_bf16 v[32:47], v[172:175], v[152:155], v[32:47]
	ds_read_b128 v[152:155], v102 offset:55360
	ds_read_b128 v[156:159], v102 offset:59968
	ds_read_b128 v[164:167], v101 offset:36928
	ds_read_b128 v[168:171], v101 offset:41536
	s_waitcnt vmcnt(15)
	ds_write_b128 v100, v[64:67]
	s_waitcnt vmcnt(13)
	ds_write_b128 v100, v[72:75] offset:4608
	s_waitcnt vmcnt(11)
	ds_write_b128 v100, v[136:139] offset:9216
	s_waitcnt vmcnt(9)
	ds_write_b128 v100, v[144:147] offset:13824
	v_mfma_f32_32x32x16_bf16 v[0:15], v[172:175], v[160:163], v[0:15]
	ds_read_b128 v[64:67], v102 offset:55392
	ds_read_b128 v[72:75], v102 offset:60000
	ds_read_b128 v[136:139], v101 offset:36960
	ds_read_b128 v[144:147], v101 offset:41568
	s_waitcnt lgkmcnt(9)
	v_mfma_f32_32x32x16_bf16 v[48:63], v[164:167], v[152:155], v[48:63]
	ds_write_b128 v100, v[68:71] offset:18432
	ds_write_b128 v100, v[76:79] offset:23040
	ds_write_b128 v100, v[140:143] offset:27648
	s_waitcnt vmcnt(8)
	ds_write_b128 v100, v[148:151] offset:32256
	v_mfma_f32_32x32x16_bf16 v[16:31], v[164:167], v[156:159], v[16:31]
	s_waitcnt lgkmcnt(12)
	v_mfma_f32_32x32x16_bf16 v[32:47], v[168:171], v[152:155], v[32:47]
	v_mfma_f32_32x32x16_bf16 v[0:15], v[168:171], v[156:159], v[0:15]
	s_waitcnt lgkmcnt(0)
	s_barrier
	ds_read_b128 v[152:155], v102 offset:18432
	ds_read_b128 v[156:159], v102 offset:23040
	ds_read_b128 v[160:163], v101
	ds_read_b128 v[164:167], v101 offset:4608
	v_mfma_f32_32x32x16_bf16 v[48:63], v[136:139], v[64:67], v[48:63]
	v_mfma_f32_32x32x16_bf16 v[16:31], v[136:139], v[72:75], v[16:31]
	v_mfma_f32_32x32x16_bf16 v[32:47], v[144:147], v[64:67], v[32:47]
	v_mfma_f32_32x32x16_bf16 v[0:15], v[144:147], v[72:75], v[0:15]
	global_load_dwordx4 v[64:67], v[80:81], off offset:1024
	global_load_dwordx4 v[68:71], v[82:83], off offset:1024
	global_load_dwordx4 v[72:75], v[84:85], off offset:1024
	global_load_dwordx4 v[76:79], v[86:87], off offset:1024
	global_load_dwordx4 v[136:139], v[88:89], off offset:1024
	global_load_dwordx4 v[140:143], v[90:91], off offset:1024
	global_load_dwordx4 v[144:147], v[92:93], off offset:1024
	global_load_dwordx4 v[148:151], v[94:95], off offset:1024
	s_waitcnt lgkmcnt(1)
	v_mfma_f32_32x32x16_bf16 v[48:63], v[160:163], v[152:155], v[48:63]
	v_mfma_f32_32x32x16_bf16 v[16:31], v[160:163], v[156:159], v[16:31]
	s_waitcnt lgkmcnt(0)
	v_mfma_f32_32x32x16_bf16 v[32:47], v[164:167], v[152:155], v[32:47]
	ds_read_b128 v[152:155], v102 offset:18464
	ds_read_b128 v[160:163], v102 offset:23072
	ds_read_b128 v[168:171], v101 offset:32
	ds_read_b128 v[172:175], v101 offset:4640
	v_mfma_f32_32x32x16_bf16 v[0:15], v[164:167], v[156:159], v[0:15]
	s_waitcnt lgkmcnt(1)
	v_mfma_f32_32x32x16_bf16 v[48:63], v[168:171], v[152:155], v[48:63]
	v_mfma_f32_32x32x16_bf16 v[16:31], v[168:171], v[160:163], v[16:31]
	s_waitcnt lgkmcnt(0)
	v_mfma_f32_32x32x16_bf16 v[32:47], v[172:175], v[152:155], v[32:47]
	ds_read_b128 v[152:155], v102 offset:18496
	ds_read_b128 v[156:159], v102 offset:23104
	ds_read_b128 v[164:167], v101 offset:64
	ds_read_b128 v[168:171], v101 offset:4672
	s_waitcnt vmcnt(15)
	ds_write_b128 v100, v[104:107] offset:36864
	s_waitcnt vmcnt(13)
	ds_write_b128 v100, v[112:115] offset:41472
	s_waitcnt vmcnt(11)
	ds_write_b128 v100, v[120:123] offset:46080
	s_waitcnt vmcnt(9)
	ds_write_b128 v100, v[128:131] offset:50688
	v_mfma_f32_32x32x16_bf16 v[0:15], v[172:175], v[160:163], v[0:15]
	ds_read_b128 v[104:107], v102 offset:18528
	ds_read_b128 v[112:115], v102 offset:23136
	ds_read_b128 v[120:123], v101 offset:96
	ds_read_b128 v[128:131], v101 offset:4704
	s_waitcnt lgkmcnt(9)
	v_mfma_f32_32x32x16_bf16 v[48:63], v[164:167], v[152:155], v[48:63]
	ds_write_b128 v100, v[108:111] offset:55296
	ds_write_b128 v100, v[116:119] offset:59904
	ds_write_b128 v100, v[124:127] offset:64512
	s_waitcnt vmcnt(8)
	ds_write_b128 v103, v[132:135] offset:13824
	v_mfma_f32_32x32x16_bf16 v[16:31], v[164:167], v[156:159], v[16:31]
	s_waitcnt lgkmcnt(12)
	v_mfma_f32_32x32x16_bf16 v[32:47], v[168:171], v[152:155], v[32:47]
	v_mfma_f32_32x32x16_bf16 v[0:15], v[168:171], v[156:159], v[0:15]
	s_waitcnt lgkmcnt(0)
	s_barrier
; template <bool SWAP>
; DI void gemm_tile(const bf16_t* __restrict__ A, int lda, const bf16_t* __restrict__ Bt, int ldb, int K, f32x16 (&acc)[2][2], bf16_t* As, bf16_t* Bs_unused) {
;     ...
;   auto step = [&](int buf, u32x4 (&ra)[4], u32x4 (&rb)[4], bool do_write, bool do_load, int tload) __attribute__((always_inline)) {
;     const bf16_t* pa = As + buf * 2 * GT_IMG + pao; const bf16_t* pb = As + buf * 2 * GT_IMG + pbo;
;     bf16_t* Ad = As + (buf ^ 1) * 2 * GT_IMG; bf16_t* Bd = Ad + GT_IMG;
;     bf16x8 F0[4], F1[4];
;     frag_read(F0, pa, pb, 0);
;     __builtin_amdgcn_sched_barrier(0);
;     frag_read(F1, pa, pb, 16);
;     mfma4(F0);
;     __builtin_amdgcn_sched_barrier(0);
;     frag_read(F0, pa, pb, 32);
;     mfma4(F1);
;     if (do_write) {
; #pragma unroll
;       for (int i = 0; i < 4; ++i) *(u32x4*)(Ad + (lr + 32 * i) * 72 + lc) = ra[i];
;     }
;     __builtin_amdgcn_sched_barrier(0);
;     frag_read(F1, pa, pb, 48);
;     mfma4(F0);
;     if (do_write) {
; #pragma unroll
;       for (int i = 0; i < 4; ++i) *(u32x4*)(Bd + (lr + 32 * i) * 72 + lc) = rb[i];
;     }
;     __builtin_amdgcn_sched_barrier(0);
;     mfma4(F1);
;     if (do_load) load_stage(ra, rb, tload);
;     __builtin_amdgcn_sched_barrier(0);
;   };
;   const int nk = K >> 6;
;   load_stage(ra0, rb0, 0); load_stage(ra1, rb1, 1);
;   __syncthreads();
;   write_stage(ra0, rb0, 0);
;   load_stage(ra0, rb0, 2);
;   __syncthreads();
;   for (int kt = 0; kt < nk; kt += 2) {
;     step(0, ra1, rb1, true, kt + 3 < nk, kt + 3);
;     __syncthreads();
;     step(1, ra0, rb0, kt + 2 < nk, kt + 4 < nk, kt + 4);
;     __syncthreads();
	ds_read_b128 v[152:155], v102 offset:55296
	ds_read_b128 v[156:159], v102 offset:59904
	ds_read_b128 v[160:163], v101 offset:36864
	ds_read_b128 v[164:167], v101 offset:41472
	v_mfma_f32_32x32x16_bf16 v[48:63], v[120:123], v[104:107], v[48:63]
	v_mfma_f32_32x32x16_bf16 v[16:31], v[120:123], v[112:115], v[16:31]
	v_mfma_f32_32x32x16_bf16 v[32:47], v[128:131], v[104:107], v[32:47]
	v_mfma_f32_32x32x16_bf16 v[0:15], v[128:131], v[112:115], v[0:15]
	global_load_dwordx4 v[104:107], v[80:81], off offset:1152
	global_load_dwordx4 v[108:111], v[82:83], off offset:1152
	global_load_dwordx4 v[112:115], v[84:85], off offset:1152
	global_load_dwordx4 v[116:119], v[86:87], off offset:1152
	global_load_dwordx4 v[120:123], v[88:89], off offset:1152
	global_load_dwordx4 v[124:127], v[90:91], off offset:1152
	global_load_dwordx4 v[128:131], v[92:93], off offset:1152
	global_load_dwordx4 v[132:135], v[94:95], off offset:1152
	s_waitcnt lgkmcnt(1)
	v_mfma_f32_32x32x16_bf16 v[48:63], v[160:163], v[152:155], v[48:63]
	v_mfma_f32_32x32x16_bf16 v[16:31], v[160:163], v[156:159], v[16:31]
	s_waitcnt lgkmcnt(0)
	v_mfma_f32_32x32x16_bf16 v[32:47], v[164:167], v[152:155], v[32:47]
	ds_read_b128 v[152:155], v102 offset:55328
	ds_read_b128 v[160:163], v102 offset:59936
	ds_read_b128 v[168:171], v101 offset:36896
	ds_read_b128 v[172:175], v101 offset:41504
	v_mfma_f32_32x32x16_bf16 v[0:15], v[164:167], v[156:159], v[0:15]
	s_waitcnt lgkmcnt(1)
	v_mfma_f32_32x32x16_bf16 v[48:63], v[168:171], v[152:155], v[48:63]
	v_mfma_f32_32x32x16_bf16 v[16:31], v[168:171], v[160:163], v[16:31]
	s_waitcnt lgkmcnt(0)
	v_mfma_f32_32x32x16_bf16 v[32:47], v[172:175], v[152:155], v[32:47]
	ds_read_b128 v[152:155], v102 offset:55360
	ds_read_b128 v[156:159], v102 offset:59968
	ds_read_b128 v[164:167], v101 offset:36928
	ds_read_b128 v[168:171], v101 offset:41536
	s_waitcnt vmcnt(15)
	ds_write_b128 v100, v[64:67]
	s_waitcnt vmcnt(13)
	ds_write_b128 v100, v[72:75] offset:4608
	s_waitcnt vmcnt(11)
	ds_write_b128 v100, v[136:139] offset:9216
	s_waitcnt vmcnt(9)
	ds_write_b128 v100, v[144:147] offset:13824
	v_mfma_f32_32x32x16_bf16 v[0:15], v[172:175], v[160:163], v[0:15]
	ds_read_b128 v[64:67], v102 offset:55392
	ds_read_b128 v[72:75], v102 offset:60000
	ds_read_b128 v[136:139], v101 offset:36960
	ds_read_b128 v[144:147], v101 offset:41568
	s_waitcnt lgkmcnt(9)
	v_mfma_f32_32x32x16_bf16 v[48:63], v[164:167], v[152:155], v[48:63]
	ds_write_b128 v100, v[68:71] offset:18432
	ds_write_b128 v100, v[76:79] offset:23040
	ds_write_b128 v100, v[140:143] offset:27648
	s_waitcnt vmcnt(8)
	ds_write_b128 v100, v[148:151] offset:32256
	v_mfma_f32_32x32x16_bf16 v[16:31], v[164:167], v[156:159], v[16:31]
	s_waitcnt lgkmcnt(12)
	v_mfma_f32_32x32x16_bf16 v[32:47], v[168:171], v[152:155], v[32:47]
	v_mfma_f32_32x32x16_bf16 v[0:15], v[168:171], v[156:159], v[0:15]
	s_waitcnt lgkmcnt(0)
	s_barrier
	ds_read_b128 v[152:155], v102 offset:18432
	ds_read_b128 v[156:159], v102 offset:23040
	ds_read_b128 v[160:163], v101
	ds_read_b128 v[164:167], v101 offset:4608
	v_mfma_f32_32x32x16_bf16 v[48:63], v[136:139], v[64:67], v[48:63]
	v_mfma_f32_32x32x16_bf16 v[16:31], v[136:139], v[72:75], v[16:31]
	v_mfma_f32_32x32x16_bf16 v[32:47], v[144:147], v[64:67], v[32:47]
	v_mfma_f32_32x32x16_bf16 v[0:15], v[144:147], v[72:75], v[0:15]
	global_load_dwordx4 v[64:67], v[80:81], off offset:1280
	global_load_dwordx4 v[68:71], v[82:83], off offset:1280
	global_load_dwordx4 v[72:75], v[84:85], off offset:1280
	global_load_dwordx4 v[76:79], v[86:87], off offset:1280
	global_load_dwordx4 v[136:139], v[88:89], off offset:1280
	global_load_dwordx4 v[140:143], v[90:91], off offset:1280
	global_load_dwordx4 v[144:147], v[92:93], off offset:1280
	global_load_dwordx4 v[148:151], v[94:95], off offset:1280
	s_waitcnt lgkmcnt(1)
	v_mfma_f32_32x32x16_bf16 v[48:63], v[160:163], v[152:155], v[48:63]
	v_mfma_f32_32x32x16_bf16 v[16:31], v[160:163], v[156:159], v[16:31]
	s_waitcnt lgkmcnt(0)
	v_mfma_f32_32x32x16_bf16 v[32:47], v[164:167], v[152:155], v[32:47]
	ds_read_b128 v[152:155], v102 offset:18464
	ds_read_b128 v[160:163], v102 offset:23072
	ds_read_b128 v[168:171], v101 offset:32
	ds_read_b128 v[172:175], v101 offset:4640
	v_mfma_f32_32x32x16_bf16 v[0:15], v[164:167], v[156:159], v[0:15]
	s_waitcnt lgkmcnt(1)
	v_mfma_f32_32x32x16_bf16 v[48:63], v[168:171], v[152:155], v[48:63]
	v_mfma_f32_32x32x16_bf16 v[16:31], v[168:171], v[160:163], v[16:31]
	s_waitcnt lgkmcnt(0)
	v_mfma_f32_32x32x16_bf16 v[32:47], v[172:175], v[152:155], v[32:47]
	ds_read_b128 v[152:155], v102 offset:18496
	ds_read_b128 v[156:159], v102 offset:23104
	ds_read_b128 v[164:167], v101 offset:64
	ds_read_b128 v[168:171], v101 offset:4672
	s_waitcnt vmcnt(15)
	ds_write_b128 v100, v[104:107] offset:36864
	s_waitcnt vmcnt(13)
	ds_write_b128 v100, v[112:115] offset:41472
	s_waitcnt vmcnt(11)
	ds_write_b128 v100, v[120:123] offset:46080
	s_waitcnt vmcnt(9)
	ds_write_b128 v100, v[128:131] offset:50688
	v_mfma_f32_32x32x16_bf16 v[0:15], v[172:175], v[160:163], v[0:15]
	ds_read_b128 v[104:107], v102 offset:18528
	ds_read_b128 v[112:115], v102 offset:23136
	ds_read_b128 v[120:123], v101 offset:96
	ds_read_b128 v[128:131], v101 offset:4704
	s_waitcnt lgkmcnt(9)
	v_mfma_f32_32x32x16_bf16 v[48:63], v[164:167], v[152:155], v[48:63]
	ds_write_b128 v100, v[108:111] offset:55296
	ds_write_b128 v100, v[116:119] offset:59904
	ds_write_b128 v100, v[124:127] offset:64512
	s_waitcnt vmcnt(8)
	ds_write_b128 v103, v[132:135] offset:13824
	v_mfma_f32_32x32x16_bf16 v[16:31], v[164:167], v[156:159], v[16:31]
	s_waitcnt lgkmcnt(12)
	v_mfma_f32_32x32x16_bf16 v[32:47], v[168:171], v[152:155], v[32:47]
	v_mfma_f32_32x32x16_bf16 v[0:15], v[168:171], v[156:159], v[0:15]
	s_waitcnt lgkmcnt(0)
	s_barrier
; template <bool SWAP>
; DI void gemm_tile(const bf16_t* __restrict__ A, int lda, const bf16_t* __restrict__ Bt, int ldb, int K, f32x16 (&acc)[2][2], bf16_t* As, bf16_t* Bs_unused) {
;     ...
;   auto step = [&](int buf, u32x4 (&ra)[4], u32x4 (&rb)[4], bool do_write, bool do_load, int tload) __attribute__((always_inline)) {
;     const bf16_t* pa = As + buf * 2 * GT_IMG + pao; const bf16_t* pb = As + buf * 2 * GT_IMG + pbo;
;     bf16_t* Ad = As + (buf ^ 1) * 2 * GT_IMG; bf16_t* Bd = Ad + GT_IMG;
;     bf16x8 F0[4], F1[4];
;     frag_read(F0, pa, pb, 0);
;     __builtin_amdgcn_sched_barrier(0);
;     frag_read(F1, pa, pb, 16);
;     mfma4(F0);
;     __builtin_amdgcn_sched_barrier(0);
;     frag_read(F0, pa, pb, 32);
;     mfma4(F1);
;     if (do_write) {
; #pragma unroll
;       for (int i = 0; i < 4; ++i) *(u32x4*)(Ad + (lr + 32 * i) * 72 + lc) = ra[i];
;     }
;     __builtin_amdgcn_sched_barrier(0);
;     frag_read(F1, pa, pb, 48);
;     mfma4(F0);
;     if (do_write) {
; #pragma unroll
;       for (int i = 0; i < 4; ++i) *(u32x4*)(Bd + (lr + 32 * i) * 72 + lc) = rb[i];
;     }
;     __builtin_amdgcn_sched_barrier(0);
;     mfma4(F1);
;     if (do_load) load_stage(ra, rb, tload);
;     __builtin_amdgcn_sched_barrier(0);
;   };
;   const int nk = K >> 6;
;   load_stage(ra0, rb0, 0); load_stage(ra1, rb1, 1);
;   __syncthreads();
;   write_stage(ra0, rb0, 0);
;   load_stage(ra0, rb0, 2);
;   __syncthreads();
;   for (int kt = 0; kt < nk; kt += 2) {
;     step(0, ra1, rb1, true, kt + 3 < nk, kt + 3);
;     __syncthreads();
;     step(1, ra0, rb0, kt + 2 < nk, kt + 4 < nk, kt + 4);
;     __syncthreads();
	ds_read_b128 v[152:155], v102 offset:55296
	ds_read_b128 v[156:159], v102 offset:59904
	ds_read_b128 v[160:163], v101 offset:36864
	ds_read_b128 v[164:167], v101 offset:41472
	v_mfma_f32_32x32x16_bf16 v[48:63], v[120:123], v[104:107], v[48:63]
	v_mfma_f32_32x32x16_bf16 v[16:31], v[120:123], v[112:115], v[16:31]
	v_mfma_f32_32x32x16_bf16 v[32:47], v[128:131], v[104:107], v[32:47]
	v_mfma_f32_32x32x16_bf16 v[0:15], v[128:131], v[112:115], v[0:15]
	global_load_dwordx4 v[104:107], v[80:81], off offset:1408
	global_load_dwordx4 v[108:111], v[82:83], off offset:1408
	global_load_dwordx4 v[112:115], v[84:85], off offset:1408
	global_load_dwordx4 v[116:119], v[86:87], off offset:1408
	global_load_dwordx4 v[120:123], v[88:89], off offset:1408
	global_load_dwordx4 v[124:127], v[90:91], off offset:1408
	global_load_dwordx4 v[128:131], v[92:93], off offset:1408
	global_load_dwordx4 v[132:135], v[94:95], off offset:1408
	s_waitcnt lgkmcnt(1)
	v_mfma_f32_32x32x16_bf16 v[48:63], v[160:163], v[152:155], v[48:63]
	v_mfma_f32_32x32x16_bf16 v[16:31], v[160:163], v[156:159], v[16:31]
	s_waitcnt lgkmcnt(0)
	v_mfma_f32_32x32x16_bf16 v[32:47], v[164:167], v[152:155], v[32:47]
	ds_read_b128 v[152:155], v102 offset:55328
	ds_read_b128 v[160:163], v102 offset:59936
	ds_read_b128 v[168:171], v101 offset:36896
	ds_read_b128 v[172:175], v101 offset:41504
	v_mfma_f32_32x32x16_bf16 v[0:15], v[164:167], v[156:159], v[0:15]
	s_waitcnt lgkmcnt(1)
	v_mfma_f32_32x32x16_bf16 v[48:63], v[168:171], v[152:155], v[48:63]
	v_mfma_f32_32x32x16_bf16 v[16:31], v[168:171], v[160:163], v[16:31]
	s_waitcnt lgkmcnt(0)
	v_mfma_f32_32x32x16_bf16 v[32:47], v[172:175], v[152:155], v[32:47]
	ds_read_b128 v[152:155], v102 offset:55360
	ds_read_b128 v[156:159], v102 offset:59968
	ds_read_b128 v[164:167], v101 offset:36928
	ds_read_b128 v[168:171], v101 offset:41536
	s_waitcnt vmcnt(15)
	ds_write_b128 v100, v[64:67]
	s_waitcnt vmcnt(13)
	ds_write_b128 v100, v[72:75] offset:4608
	s_waitcnt vmcnt(11)
	ds_write_b128 v100, v[136:139] offset:9216
	s_waitcnt vmcnt(9)
	ds_write_b128 v100, v[144:147] offset:13824
	v_mfma_f32_32x32x16_bf16 v[0:15], v[172:175], v[160:163], v[0:15]
	ds_read_b128 v[64:67], v102 offset:55392
	ds_read_b128 v[72:75], v102 offset:60000
	ds_read_b128 v[136:139], v101 offset:36960
	ds_read_b128 v[144:147], v101 offset:41568
	s_waitcnt lgkmcnt(9)
	v_mfma_f32_32x32x16_bf16 v[48:63], v[164:167], v[152:155], v[48:63]
	ds_write_b128 v100, v[68:71] offset:18432
	ds_write_b128 v100, v[76:79] offset:23040
	ds_write_b128 v100, v[140:143] offset:27648
	s_waitcnt vmcnt(8)
	ds_write_b128 v100, v[148:151] offset:32256
	v_mfma_f32_32x32x16_bf16 v[16:31], v[164:167], v[156:159], v[16:31]
	s_waitcnt lgkmcnt(12)
	v_mfma_f32_32x32x16_bf16 v[32:47], v[168:171], v[152:155], v[32:47]
	v_mfma_f32_32x32x16_bf16 v[0:15], v[168:171], v[156:159], v[0:15]
	s_waitcnt lgkmcnt(0)
	s_barrier
	ds_read_b128 v[152:155], v102 offset:18432
	ds_read_b128 v[156:159], v102 offset:23040
	ds_read_b128 v[160:163], v101
	ds_read_b128 v[164:167], v101 offset:4608
	v_mfma_f32_32x32x16_bf16 v[48:63], v[136:139], v[64:67], v[48:63]
	v_mfma_f32_32x32x16_bf16 v[16:31], v[136:139], v[72:75], v[16:31]
	v_mfma_f32_32x32x16_bf16 v[32:47], v[144:147], v[64:67], v[32:47]
	v_mfma_f32_32x32x16_bf16 v[0:15], v[144:147], v[72:75], v[0:15]
	global_load_dwordx4 v[64:67], v[80:81], off offset:1536
	global_load_dwordx4 v[68:71], v[82:83], off offset:1536
	global_load_dwordx4 v[72:75], v[84:85], off offset:1536
	global_load_dwordx4 v[76:79], v[86:87], off offset:1536
	global_load_dwordx4 v[136:139], v[88:89], off offset:1536
	global_load_dwordx4 v[140:143], v[90:91], off offset:1536
	global_load_dwordx4 v[144:147], v[92:93], off offset:1536
	global_load_dwordx4 v[148:151], v[94:95], off offset:1536
	s_waitcnt lgkmcnt(1)
	v_mfma_f32_32x32x16_bf16 v[48:63], v[160:163], v[152:155], v[48:63]
	v_mfma_f32_32x32x16_bf16 v[16:31], v[160:163], v[156:159], v[16:31]
	s_waitcnt lgkmcnt(0)
	v_mfma_f32_32x32x16_bf16 v[32:47], v[164:167], v[152:155], v[32:47]
	ds_read_b128 v[152:155], v102 offset:18464
	ds_read_b128 v[160:163], v102 offset:23072
	ds_read_b128 v[168:171], v101 offset:32
	ds_read_b128 v[172:175], v101 offset:4640
	v_mfma_f32_32x32x16_bf16 v[0:15], v[164:167], v[156:159], v[0:15]
	s_waitcnt lgkmcnt(1)
	v_mfma_f32_32x32x16_bf16 v[48:63], v[168:171], v[152:155], v[48:63]
	v_mfma_f32_32x32x16_bf16 v[16:31], v[168:171], v[160:163], v[16:31]
	s_waitcnt lgkmcnt(0)
	v_mfma_f32_32x32x16_bf16 v[32:47], v[172:175], v[152:155], v[32:47]
	ds_read_b128 v[152:155], v102 offset:18496
	ds_read_b128 v[156:159], v102 offset:23104
	ds_read_b128 v[164:167], v101 offset:64
	ds_read_b128 v[168:171], v101 offset:4672
	s_waitcnt vmcnt(15)
	ds_write_b128 v100, v[104:107] offset:36864
	s_waitcnt vmcnt(13)
	ds_write_b128 v100, v[112:115] offset:41472
	s_waitcnt vmcnt(11)
	ds_write_b128 v100, v[120:123] offset:46080
	s_waitcnt vmcnt(9)
	ds_write_b128 v100, v[128:131] offset:50688
	v_mfma_f32_32x32x16_bf16 v[0:15], v[172:175], v[160:163], v[0:15]
	ds_read_b128 v[104:107], v102 offset:18528
	ds_read_b128 v[112:115], v102 offset:23136
	ds_read_b128 v[120:123], v101 offset:96
	ds_read_b128 v[128:131], v101 offset:4704
	s_waitcnt lgkmcnt(9)
	v_mfma_f32_32x32x16_bf16 v[48:63], v[164:167], v[152:155], v[48:63]
	ds_write_b128 v100, v[108:111] offset:55296
	ds_write_b128 v100, v[116:119] offset:59904
	ds_write_b128 v100, v[124:127] offset:64512
	s_waitcnt vmcnt(8)
	ds_write_b128 v103, v[132:135] offset:13824
	v_mfma_f32_32x32x16_bf16 v[16:31], v[164:167], v[156:159], v[16:31]
	s_waitcnt lgkmcnt(12)
	v_mfma_f32_32x32x16_bf16 v[32:47], v[168:171], v[152:155], v[32:47]
	v_mfma_f32_32x32x16_bf16 v[0:15], v[168:171], v[156:159], v[0:15]
	s_waitcnt lgkmcnt(0)
	s_barrier
; template <bool SWAP>
; DI void gemm_tile(const bf16_t* __restrict__ A, int lda, const bf16_t* __restrict__ Bt, int ldb, int K, f32x16 (&acc)[2][2], bf16_t* As, bf16_t* Bs_unused) {
;     ...
;   auto step = [&](int buf, u32x4 (&ra)[4], u32x4 (&rb)[4], bool do_write, bool do_load, int tload) __attribute__((always_inline)) {
;     const bf16_t* pa = As + buf * 2 * GT_IMG + pao; const bf16_t* pb = As + buf * 2 * GT_IMG + pbo;
;     bf16_t* Ad = As + (buf ^ 1) * 2 * GT_IMG; bf16_t* Bd = Ad + GT_IMG;
;     bf16x8 F0[4], F1[4];
;     frag_read(F0, pa, pb, 0);
;     __builtin_amdgcn_sched_barrier(0);
;     frag_read(F1, pa, pb, 16);
;     mfma4(F0);
;     __builtin_amdgcn_sched_barrier(0);
;     frag_read(F0, pa, pb, 32);
;     mfma4(F1);
;     if (do_write) {
; #pragma unroll
;       for (int i = 0; i < 4; ++i) *(u32x4*)(Ad + (lr + 32 * i) * 72 + lc) = ra[i];
;     }
;     __builtin_amdgcn_sched_barrier(0);
;     frag_read(F1, pa, pb, 48);
;     mfma4(F0);
;     if (do_write) {
; #pragma unroll
;       for (int i = 0; i < 4; ++i) *(u32x4*)(Bd + (lr + 32 * i) * 72 + lc) = rb[i];
;     }
;     __builtin_amdgcn_sched_barrier(0);
;     mfma4(F1);
;     if (do_load) load_stage(ra, rb, tload);
;     __builtin_amdgcn_sched_barrier(0);
;   };
;   const int nk = K >> 6;
;   load_stage(ra0, rb0, 0); load_stage(ra1, rb1, 1);
;   __syncthreads();
;   write_stage(ra0, rb0, 0);
;   load_stage(ra0, rb0, 2);
;   __syncthreads();
;   for (int kt = 0; kt < nk; kt += 2) {
;     step(0, ra1, rb1, true, kt + 3 < nk, kt + 3);
;     __syncthreads();
;     step(1, ra0, rb0, kt + 2 < nk, kt + 4 < nk, kt + 4);
;     __syncthreads();
	ds_read_b128 v[152:155], v102 offset:55296
	ds_read_b128 v[156:159], v102 offset:59904
	ds_read_b128 v[160:163], v101 offset:36864
	ds_read_b128 v[164:167], v101 offset:41472
	v_mfma_f32_32x32x16_bf16 v[48:63], v[120:123], v[104:107], v[48:63]
	v_mfma_f32_32x32x16_bf16 v[16:31], v[120:123], v[112:115], v[16:31]
	v_mfma_f32_32x32x16_bf16 v[32:47], v[128:131], v[104:107], v[32:47]
	v_mfma_f32_32x32x16_bf16 v[0:15], v[128:131], v[112:115], v[0:15]
	global_load_dwordx4 v[104:107], v[80:81], off offset:1664
	global_load_dwordx4 v[108:111], v[82:83], off offset:1664
	global_load_dwordx4 v[112:115], v[84:85], off offset:1664
	global_load_dwordx4 v[116:119], v[86:87], off offset:1664
	global_load_dwordx4 v[120:123], v[88:89], off offset:1664
	global_load_dwordx4 v[124:127], v[90:91], off offset:1664
	global_load_dwordx4 v[128:131], v[92:93], off offset:1664
	global_load_dwordx4 v[132:135], v[94:95], off offset:1664
	s_waitcnt lgkmcnt(1)
	v_mfma_f32_32x32x16_bf16 v[48:63], v[160:163], v[152:155], v[48:63]
	v_mfma_f32_32x32x16_bf16 v[16:31], v[160:163], v[156:159], v[16:31]
	s_waitcnt lgkmcnt(0)
	v_mfma_f32_32x32x16_bf16 v[32:47], v[164:167], v[152:155], v[32:47]
	ds_read_b128 v[152:155], v102 offset:55328
	ds_read_b128 v[160:163], v102 offset:59936
	ds_read_b128 v[168:171], v101 offset:36896
	ds_read_b128 v[172:175], v101 offset:41504
	v_mfma_f32_32x32x16_bf16 v[0:15], v[164:167], v[156:159], v[0:15]
	s_waitcnt lgkmcnt(1)
	v_mfma_f32_32x32x16_bf16 v[48:63], v[168:171], v[152:155], v[48:63]
	v_mfma_f32_32x32x16_bf16 v[16:31], v[168:171], v[160:163], v[16:31]
	s_waitcnt lgkmcnt(0)
	v_mfma_f32_32x32x16_bf16 v[32:47], v[172:175], v[152:155], v[32:47]
	ds_read_b128 v[152:155], v102 offset:55360
	ds_read_b128 v[156:159], v102 offset:59968
	ds_read_b128 v[164:167], v101 offset:36928
	ds_read_b128 v[168:171], v101 offset:41536
	s_waitcnt vmcnt(15)
	ds_write_b128 v100, v[64:67]
	s_waitcnt vmcnt(13)
	ds_write_b128 v100, v[72:75] offset:4608
	s_waitcnt vmcnt(11)
	ds_write_b128 v100, v[136:139] offset:9216
	s_waitcnt vmcnt(9)
	ds_write_b128 v100, v[144:147] offset:13824
	v_mfma_f32_32x32x16_bf16 v[0:15], v[172:175], v[160:163], v[0:15]
	ds_read_b128 v[64:67], v102 offset:55392
	ds_read_b128 v[72:75], v102 offset:60000
	ds_read_b128 v[136:139], v101 offset:36960
	ds_read_b128 v[144:147], v101 offset:41568
	s_waitcnt lgkmcnt(9)
	v_mfma_f32_32x32x16_bf16 v[48:63], v[164:167], v[152:155], v[48:63]
	ds_write_b128 v100, v[68:71] offset:18432
	ds_write_b128 v100, v[76:79] offset:23040
	ds_write_b128 v100, v[140:143] offset:27648
	s_waitcnt vmcnt(8)
	ds_write_b128 v100, v[148:151] offset:32256
	v_mfma_f32_32x32x16_bf16 v[16:31], v[164:167], v[156:159], v[16:31]
	s_waitcnt lgkmcnt(12)
	v_mfma_f32_32x32x16_bf16 v[32:47], v[168:171], v[152:155], v[32:47]
	v_mfma_f32_32x32x16_bf16 v[0:15], v[168:171], v[156:159], v[0:15]
	s_waitcnt lgkmcnt(0)
	s_barrier
	ds_read_b128 v[152:155], v102 offset:18432
	ds_read_b128 v[156:159], v102 offset:23040
	ds_read_b128 v[160:163], v101
	ds_read_b128 v[164:167], v101 offset:4608
	v_mfma_f32_32x32x16_bf16 v[48:63], v[136:139], v[64:67], v[48:63]
	v_mfma_f32_32x32x16_bf16 v[16:31], v[136:139], v[72:75], v[16:31]
	v_mfma_f32_32x32x16_bf16 v[32:47], v[144:147], v[64:67], v[32:47]
	v_mfma_f32_32x32x16_bf16 v[0:15], v[144:147], v[72:75], v[0:15]
	global_load_dwordx4 v[64:67], v[80:81], off offset:1792
	global_load_dwordx4 v[68:71], v[82:83], off offset:1792
	global_load_dwordx4 v[72:75], v[84:85], off offset:1792
	global_load_dwordx4 v[76:79], v[86:87], off offset:1792
	global_load_dwordx4 v[136:139], v[88:89], off offset:1792
	global_load_dwordx4 v[140:143], v[90:91], off offset:1792
	global_load_dwordx4 v[144:147], v[92:93], off offset:1792
	global_load_dwordx4 v[148:151], v[94:95], off offset:1792
	s_waitcnt lgkmcnt(1)
	v_mfma_f32_32x32x16_bf16 v[48:63], v[160:163], v[152:155], v[48:63]
	v_mfma_f32_32x32x16_bf16 v[16:31], v[160:163], v[156:159], v[16:31]
	s_waitcnt lgkmcnt(0)
	v_mfma_f32_32x32x16_bf16 v[32:47], v[164:167], v[152:155], v[32:47]
	ds_read_b128 v[152:155], v102 offset:18464
	ds_read_b128 v[160:163], v102 offset:23072
	ds_read_b128 v[168:171], v101 offset:32
	ds_read_b128 v[172:175], v101 offset:4640
	v_mfma_f32_32x32x16_bf16 v[0:15], v[164:167], v[156:159], v[0:15]
	s_waitcnt lgkmcnt(1)
	v_mfma_f32_32x32x16_bf16 v[48:63], v[168:171], v[152:155], v[48:63]
	v_mfma_f32_32x32x16_bf16 v[16:31], v[168:171], v[160:163], v[16:31]
	s_waitcnt lgkmcnt(0)
	v_mfma_f32_32x32x16_bf16 v[32:47], v[172:175], v[152:155], v[32:47]
	ds_read_b128 v[152:155], v102 offset:18496
	ds_read_b128 v[156:159], v102 offset:23104
	ds_read_b128 v[164:167], v101 offset:64
	ds_read_b128 v[168:171], v101 offset:4672
	s_waitcnt vmcnt(15)
	ds_write_b128 v100, v[104:107] offset:36864
	s_waitcnt vmcnt(13)
	ds_write_b128 v100, v[112:115] offset:41472
	s_waitcnt vmcnt(11)
	ds_write_b128 v100, v[120:123] offset:46080
	s_waitcnt vmcnt(9)
	ds_write_b128 v100, v[128:131] offset:50688
	v_mfma_f32_32x32x16_bf16 v[0:15], v[172:175], v[160:163], v[0:15]
	ds_read_b128 v[104:107], v102 offset:18528
	ds_read_b128 v[112:115], v102 offset:23136
	ds_read_b128 v[120:123], v101 offset:96
	ds_read_b128 v[128:131], v101 offset:4704
	s_waitcnt lgkmcnt(9)
	v_mfma_f32_32x32x16_bf16 v[48:63], v[164:167], v[152:155], v[48:63]
	ds_write_b128 v100, v[108:111] offset:55296
	ds_write_b128 v100, v[116:119] offset:59904
	ds_write_b128 v100, v[124:127] offset:64512
	s_waitcnt vmcnt(8)
	ds_write_b128 v103, v[132:135] offset:13824
	v_mfma_f32_32x32x16_bf16 v[16:31], v[164:167], v[156:159], v[16:31]
	s_waitcnt lgkmcnt(12)
	v_mfma_f32_32x32x16_bf16 v[32:47], v[168:171], v[152:155], v[32:47]
	v_mfma_f32_32x32x16_bf16 v[0:15], v[168:171], v[156:159], v[0:15]
	s_waitcnt lgkmcnt(5)
	v_mfma_f32_32x32x16_bf16 v[48:63], v[120:123], v[104:107], v[48:63]
	v_mfma_f32_32x32x16_bf16 v[16:31], v[120:123], v[112:115], v[16:31]
	s_waitcnt lgkmcnt(4)
	v_mfma_f32_32x32x16_bf16 v[32:47], v[128:131], v[104:107], v[32:47]
	v_mfma_f32_32x32x16_bf16 v[0:15], v[128:131], v[112:115], v[0:15]
	global_load_dwordx4 v[104:107], v[80:81], off offset:1920
	s_nop 0
	global_load_dwordx4 v[80:83], v[82:83], off offset:1920
	s_nop 0
	global_load_dwordx4 v[108:111], v[84:85], off offset:1920
	s_nop 0
	global_load_dwordx4 v[84:87], v[86:87], off offset:1920
	s_nop 0
	global_load_dwordx4 v[112:115], v[88:89], off offset:1920
	s_nop 0
	global_load_dwordx4 v[88:91], v[90:91], off offset:1920
	s_nop 0
	global_load_dwordx4 v[116:119], v[92:93], off offset:1920
	s_nop 0
	global_load_dwordx4 v[92:95], v[94:95], off offset:1920
	s_waitcnt lgkmcnt(0)
	s_barrier
; template <bool SWAP>
; DI void gemm_tile(const bf16_t* __restrict__ A, int lda, const bf16_t* __restrict__ Bt, int ldb, int K, f32x16 (&acc)[2][2], bf16_t* As, bf16_t* Bs_unused) {
;     ...
;   auto step = [&](int buf, u32x4 (&ra)[4], u32x4 (&rb)[4], bool do_write, bool do_load, int tload) __attribute__((always_inline)) {
;     const bf16_t* pa = As + buf * 2 * GT_IMG + pao; const bf16_t* pb = As + buf * 2 * GT_IMG + pbo;
;     bf16_t* Ad = As + (buf ^ 1) * 2 * GT_IMG; bf16_t* Bd = Ad + GT_IMG;
;     bf16x8 F0[4], F1[4];
;     frag_read(F0, pa, pb, 0);
;     __builtin_amdgcn_sched_barrier(0);
;     frag_read(F1, pa, pb, 16);
;     mfma4(F0);
;     __builtin_amdgcn_sched_barrier(0);
;     frag_read(F0, pa, pb, 32);
;     mfma4(F1);
;     if (do_write) {
; #pragma unroll
;       for (int i = 0; i < 4; ++i) *(u32x4*)(Ad + (lr + 32 * i) * 72 + lc) = ra[i];
;     }
;     __builtin_amdgcn_sched_barrier(0);
;     frag_read(F1, pa, pb, 48);
;     mfma4(F0);
;     if (do_write) {
; #pragma unroll
;       for (int i = 0; i < 4; ++i) *(u32x4*)(Bd + (lr + 32 * i) * 72 + lc) = rb[i];
;     }
;     __builtin_amdgcn_sched_barrier(0);
;     mfma4(F1);
;     if (do_load) load_stage(ra, rb, tload);
;     __builtin_amdgcn_sched_barrier(0);
;   };
	ds_read_b128 v[120:123], v102 offset:55296
	ds_read_b128 v[124:127], v102 offset:59904
	ds_read_b128 v[128:131], v101 offset:36864
	ds_read_b128 v[132:135], v101 offset:41472
	s_waitcnt lgkmcnt(1)
	v_mfma_f32_32x32x16_bf16 v[48:63], v[128:131], v[120:123], v[48:63]
	v_mfma_f32_32x32x16_bf16 v[16:31], v[128:131], v[124:127], v[16:31]
	s_waitcnt lgkmcnt(0)
	v_mfma_f32_32x32x16_bf16 v[32:47], v[132:135], v[120:123], v[32:47]
	ds_read_b128 v[120:123], v102 offset:55328
	ds_read_b128 v[128:131], v102 offset:59936
	ds_read_b128 v[152:155], v101 offset:36896
	ds_read_b128 v[156:159], v101 offset:41504
	v_mfma_f32_32x32x16_bf16 v[0:15], v[132:135], v[124:127], v[0:15]
	s_waitcnt lgkmcnt(1)
	v_mfma_f32_32x32x16_bf16 v[48:63], v[152:155], v[120:123], v[48:63]
	v_mfma_f32_32x32x16_bf16 v[16:31], v[152:155], v[128:131], v[16:31]
	s_waitcnt lgkmcnt(0)
	v_mfma_f32_32x32x16_bf16 v[32:47], v[156:159], v[120:123], v[32:47]
	ds_read_b128 v[120:123], v102 offset:55360
	ds_read_b128 v[124:127], v102 offset:59968
	ds_read_b128 v[132:135], v101 offset:36928
	ds_read_b128 v[152:155], v101 offset:41536
	s_waitcnt vmcnt(15)
	ds_write_b128 v100, v[64:67]
	s_waitcnt vmcnt(13)
	ds_write_b128 v100, v[72:75] offset:4608
	s_waitcnt vmcnt(11)
	ds_write_b128 v100, v[136:139] offset:9216
	s_waitcnt vmcnt(9)
	ds_write_b128 v100, v[144:147] offset:13824
	v_mfma_f32_32x32x16_bf16 v[0:15], v[156:159], v[128:131], v[0:15]
	s_waitcnt lgkmcnt(5)
	v_mfma_f32_32x32x16_bf16 v[48:63], v[132:135], v[120:123], v[48:63]
	s_waitcnt lgkmcnt(4)
	v_mfma_f32_32x32x16_bf16 v[32:47], v[152:155], v[120:123], v[32:47]
	ds_read_b128 v[64:67], v102 offset:55392
	ds_read_b128 v[72:75], v102 offset:60000
	ds_read_b128 v[120:123], v101 offset:36960
	ds_read_b128 v[128:131], v101 offset:41568
	ds_write_b128 v100, v[68:71] offset:18432
	ds_write_b128 v100, v[76:79] offset:23040
	ds_write_b128 v100, v[140:143] offset:27648
	s_waitcnt vmcnt(8)
	ds_write_b128 v100, v[148:151] offset:32256
	v_mfma_f32_32x32x16_bf16 v[16:31], v[132:135], v[124:127], v[16:31]
	v_mfma_f32_32x32x16_bf16 v[0:15], v[152:155], v[124:127], v[0:15]
	s_waitcnt lgkmcnt(5)
	v_mfma_f32_32x32x16_bf16 v[48:63], v[120:123], v[64:67], v[48:63]
	v_mfma_f32_32x32x16_bf16 v[16:31], v[120:123], v[72:75], v[16:31]
	s_waitcnt lgkmcnt(4)
	v_mfma_f32_32x32x16_bf16 v[32:47], v[128:131], v[64:67], v[32:47]
	v_mfma_f32_32x32x16_bf16 v[0:15], v[128:131], v[72:75], v[0:15]
	s_waitcnt lgkmcnt(0)
	s_barrier
	ds_read_b128 v[64:67], v102 offset:18432
	ds_read_b128 v[68:71], v102 offset:23040
	ds_read_b128 v[72:75], v101
	ds_read_b128 v[76:79], v101 offset:4608
	s_waitcnt lgkmcnt(1)
	v_mfma_f32_32x32x16_bf16 v[48:63], v[72:75], v[64:67], v[48:63]
	v_mfma_f32_32x32x16_bf16 v[16:31], v[72:75], v[68:71], v[16:31]
	s_waitcnt lgkmcnt(0)
	v_mfma_f32_32x32x16_bf16 v[32:47], v[76:79], v[64:67], v[32:47]
	ds_read_b128 v[64:67], v102 offset:18464
	ds_read_b128 v[72:75], v102 offset:23072
	ds_read_b128 v[120:123], v101 offset:32
	ds_read_b128 v[124:127], v101 offset:4640
	v_mfma_f32_32x32x16_bf16 v[0:15], v[76:79], v[68:71], v[0:15]
	s_waitcnt lgkmcnt(1)
	v_mfma_f32_32x32x16_bf16 v[48:63], v[120:123], v[64:67], v[48:63]
	v_mfma_f32_32x32x16_bf16 v[16:31], v[120:123], v[72:75], v[16:31]
	s_waitcnt lgkmcnt(0)
	v_mfma_f32_32x32x16_bf16 v[32:47], v[124:127], v[64:67], v[32:47]
	ds_read_b128 v[64:67], v102 offset:18496
	ds_read_b128 v[68:71], v102 offset:23104
	ds_read_b128 v[76:79], v101 offset:64
	ds_read_b128 v[120:123], v101 offset:4672
	s_waitcnt vmcnt(7)
	ds_write_b128 v100, v[104:107] offset:36864
	s_waitcnt vmcnt(5)
	ds_write_b128 v100, v[108:111] offset:41472
	s_waitcnt vmcnt(3)
	ds_write_b128 v100, v[112:115] offset:46080
	s_waitcnt vmcnt(1)
	ds_write_b128 v100, v[116:119] offset:50688
	v_mfma_f32_32x32x16_bf16 v[0:15], v[124:127], v[72:75], v[0:15]
	s_waitcnt lgkmcnt(5)
	v_mfma_f32_32x32x16_bf16 v[48:63], v[76:79], v[64:67], v[48:63]
	v_mfma_f32_32x32x16_bf16 v[16:31], v[76:79], v[68:71], v[16:31]
	s_waitcnt lgkmcnt(4)
	v_mfma_f32_32x32x16_bf16 v[32:47], v[120:123], v[64:67], v[32:47]
	ds_read_b128 v[64:67], v102 offset:18528
	ds_read_b128 v[72:75], v102 offset:23136
	ds_read_b128 v[76:79], v101 offset:96
	ds_read_b128 v[104:107], v101 offset:4704
	ds_write_b128 v100, v[80:83] offset:55296
	ds_write_b128 v100, v[84:87] offset:59904
	ds_write_b128 v100, v[88:91] offset:64512
	s_waitcnt vmcnt(0)
	ds_write_b128 v103, v[92:95] offset:13824
	v_mfma_f32_32x32x16_bf16 v[0:15], v[120:123], v[68:71], v[0:15]
	s_waitcnt lgkmcnt(5)
	v_mfma_f32_32x32x16_bf16 v[48:63], v[76:79], v[64:67], v[48:63]
	v_mfma_f32_32x32x16_bf16 v[16:31], v[76:79], v[72:75], v[16:31]
	s_waitcnt lgkmcnt(4)
	v_mfma_f32_32x32x16_bf16 v[32:47], v[104:107], v[64:67], v[32:47]
	v_mfma_f32_32x32x16_bf16 v[0:15], v[104:107], v[72:75], v[0:15]
	s_waitcnt lgkmcnt(0)
	s_barrier
; #define OPAQUE(x) asm volatile("" : "+v"(x))
; DI int crow(int r, int h) { return (r & 3) + 8 * (r >> 2) + 4 * h; }
; template <bool SWAP>
; DI void gemm_tile(const bf16_t* __restrict__ A, int lda, const bf16_t* __restrict__ Bt, int ldb, int K, f32x16 (&acc)[2][2], bf16_t* As, bf16_t* Bs_unused) {
;     ...
;   auto step = [&](int buf, u32x4 (&ra)[4], u32x4 (&rb)[4], bool do_write, bool do_load, int tload) __attribute__((always_inline)) {
;     const bf16_t* pa = As + buf * 2 * GT_IMG + pao; const bf16_t* pb = As + buf * 2 * GT_IMG + pbo;
;     bf16_t* Ad = As + (buf ^ 1) * 2 * GT_IMG; bf16_t* Bd = Ad + GT_IMG;
;     bf16x8 F0[4], F1[4];
;     frag_read(F0, pa, pb, 0);
;     __builtin_amdgcn_sched_barrier(0);
;     frag_read(F1, pa, pb, 16);
;     mfma4(F0);
;     __builtin_amdgcn_sched_barrier(0);
;     frag_read(F0, pa, pb, 32);
;     mfma4(F1);
;     if (do_write) {
; #pragma unroll
;       for (int i = 0; i < 4; ++i) *(u32x4*)(Ad + (lr + 32 * i) * 72 + lc) = ra[i];
;     }
;     __builtin_amdgcn_sched_barrier(0);
;     frag_read(F1, pa, pb, 48);
;     mfma4(F0);
;     if (do_write) {
; #pragma unroll
;       for (int i = 0; i < 4; ++i) *(u32x4*)(Bd + (lr + 32 * i) * 72 + lc) = rb[i];
;     }
;     __builtin_amdgcn_sched_barrier(0);
;     mfma4(F1);
;     if (do_load) load_stage(ra, rb, tload);
;     __builtin_amdgcn_sched_barrier(0);
;   };
; DI void phase_outproj(const Params& p, int g, char* smem, int bid, int nb) {
;     ...
;     int wm = wm_, wn = wn_, h = h_, l31 = l31_; OPAQUE(wm); OPAQUE(wn); OPAQUE(h); OPAQUE(l31);
;     const int b = row_batch(gi, mt * 128);
;     const float* xt = gi.x + (size_t)mt * 128 * 1024; float* ot = gi.out + (size_t)mt * 128 * 1024;
; #pragma unroll
;     for (int ni = 0; ni < 2; ++ni) {
;       const int col = nt * 128 + wn * 64 + ni * 32 + l31;
;       const float gt = mod[b * 6144 + 2048 + col];
; #pragma unroll
;       for (int mi = 0; mi < 2; ++mi) {
;         float xv[16];
; #pragma unroll
;         for (int r = 0; r < 16; ++r) xv[r] = __builtin_nontemporal_load(&xt[(wm * 64 + mi * 32 + crow(r, h)) * 1024 + col]);
	ds_read_b128 v[64:67], v102 offset:55296
	ds_read_b128 v[68:71], v102 offset:59904
	ds_read_b128 v[72:75], v101 offset:36864
	ds_read_b128 v[76:79], v101 offset:41472
	s_waitcnt lgkmcnt(1)
	v_mfma_f32_32x32x16_bf16 v[48:63], v[72:75], v[64:67], v[48:63]
	v_mfma_f32_32x32x16_bf16 v[16:31], v[72:75], v[68:71], v[16:31]
	s_waitcnt lgkmcnt(0)
	v_mfma_f32_32x32x16_bf16 v[32:47], v[76:79], v[64:67], v[32:47]
	ds_read_b128 v[64:67], v102 offset:55328
	ds_read_b128 v[72:75], v102 offset:59936
	ds_read_b128 v[80:83], v101 offset:36896
	ds_read_b128 v[84:87], v101 offset:41504
	v_mfma_f32_32x32x16_bf16 v[0:15], v[76:79], v[68:71], v[0:15]
	s_waitcnt lgkmcnt(1)
	v_mfma_f32_32x32x16_bf16 v[48:63], v[80:83], v[64:67], v[48:63]
	v_mfma_f32_32x32x16_bf16 v[16:31], v[80:83], v[72:75], v[16:31]
	s_waitcnt lgkmcnt(0)
	v_mfma_f32_32x32x16_bf16 v[32:47], v[84:87], v[64:67], v[32:47]
	v_mfma_f32_32x32x16_bf16 v[0:15], v[84:87], v[72:75], v[0:15]
	ds_read_b128 v[64:67], v101 offset:41536
	ds_read_b128 v[68:71], v102 offset:59968
	ds_read_b128 v[72:75], v102 offset:55360
	ds_read_b128 v[76:79], v101 offset:36928
	s_waitcnt lgkmcnt(0)
	v_mfma_f32_32x32x16_bf16 v[48:63], v[76:79], v[72:75], v[48:63]
	v_mfma_f32_32x32x16_bf16 v[16:31], v[76:79], v[68:71], v[16:31]
	v_mfma_f32_32x32x16_bf16 v[32:47], v[64:67], v[72:75], v[32:47]
	v_mfma_f32_32x32x16_bf16 v[0:15], v[64:67], v[68:71], v[0:15]
	ds_read_b128 v[64:67], v101 offset:41568
	ds_read_b128 v[68:71], v102 offset:60000
	ds_read_b128 v[72:75], v102 offset:55392
	ds_read_b128 v[76:79], v101 offset:36960
	s_waitcnt lgkmcnt(0)
	v_mfma_f32_32x32x16_bf16 v[48:63], v[76:79], v[72:75], v[48:63]
	v_mfma_f32_32x32x16_bf16 v[16:31], v[76:79], v[68:71], v[16:31]
	v_mfma_f32_32x32x16_bf16 v[32:47], v[64:67], v[72:75], v[32:47]
	v_mfma_f32_32x32x16_bf16 v[0:15], v[64:67], v[68:71], v[0:15]
	s_lshr_b32 s1, s6, 4
	v_readlane_b32 s8, v231, 25
	s_add_i32 s1, s8, s1
	s_lshl_b64 s[6:7], s[6:7], 19
	v_readlane_b32 s8, v231, 47
	s_add_u32 s8, s8, s6
	v_readlane_b32 s9, v231, 48
	v_mov_b32_e32 v65, v96
	v_mov_b32_e32 v64, v97
	s_addc_u32 s9, s9, s7
	v_readlane_b32 s14, v231, 23
	s_barrier
	s_add_u32 s6, s14, s6
	v_readlane_b32 s14, v231, 24
	v_mov_b32_e32 v68, v98
	v_mov_b32_e32 v66, v99
	s_addc_u32 s7, s14, s7
	s_lshl_b32 s0, s0, 7
	v_lshlrev_b32_e32 v64, 6, v64
	v_lshlrev_b32_e32 v65, 16, v65
	v_add3_u32 v64, v64, s0, v66
	s_mul_i32 s0, s1, 0x1800
	s_add_i32 s14, s0, 0x800
	s_and_b64 s[0:1], s[22:23], exec
	s_cselect_b32 s0, 0x800, s14
	v_add_u32_e32 v66, s0, v64
	v_ashrrev_i32_e32 v67, 31, v66
	v_lshl_add_u64 v[66:67], v[66:67], 2, s[92:93]
	v_lshl_add_u32 v65, v68, 12, v65
	global_load_dword v74, v[66:67], off
	v_add_u32_e32 v66, v65, v64
	v_ashrrev_i32_e32 v67, 31, v66
	v_lshlrev_b64 v[82:83], 2, v[66:67]
	v_lshl_add_u64 v[66:67], s[8:9], 0, v[82:83]
	global_load_dword v120, v[66:67], off nt
	v_or_b32_e32 v66, 0x400, v65
	v_add_u32_e32 v68, v66, v64
	v_ashrrev_i32_e32 v69, 31, v68
	v_lshlrev_b64 v[84:85], 2, v[68:69]
	v_lshl_add_u64 v[68:69], s[8:9], 0, v[84:85]
	v_or_b32_e32 v67, 0x800, v65
	global_load_dword v121, v[68:69], off nt
	v_add_u32_e32 v68, v67, v64
	v_ashrrev_i32_e32 v69, 31, v68
	v_lshlrev_b64 v[86:87], 2, v[68:69]
	v_lshl_add_u64 v[68:69], s[8:9], 0, v[86:87]
	global_load_dword v122, v[68:69], off nt
	v_or_b32_e32 v68, 0xc00, v65
	v_add_u32_e32 v70, v68, v64
	v_ashrrev_i32_e32 v71, 31, v70
	v_lshlrev_b64 v[88:89], 2, v[70:71]
	v_lshl_add_u64 v[70:71], s[8:9], 0, v[88:89]
	v_add_u32_e32 v69, 0x2000, v65
	global_load_dword v123, v[70:71], off nt
	v_add_u32_e32 v70, v69, v64
	v_ashrrev_i32_e32 v71, 31, v70
	v_lshlrev_b64 v[90:91], 2, v[70:71]
	v_lshl_add_u64 v[70:71], s[8:9], 0, v[90:91]
	global_load_dword v124, v[70:71], off nt
	v_add_u32_e32 v70, 0x2400, v65
	v_add_u32_e32 v72, v70, v64
	v_ashrrev_i32_e32 v73, 31, v72
	v_lshlrev_b64 v[92:93], 2, v[72:73]
	v_lshl_add_u64 v[72:73], s[8:9], 0, v[92:93]
	v_add_u32_e32 v71, 0x2800, v65
	global_load_dword v125, v[72:73], off nt
	v_add_u32_e32 v72, v71, v64
	v_ashrrev_i32_e32 v73, 31, v72
	v_lshlrev_b64 v[94:95], 2, v[72:73]
	v_lshl_add_u64 v[72:73], s[8:9], 0, v[94:95]
	global_load_dword v126, v[72:73], off nt
	v_add_u32_e32 v72, 0x2c00, v65
	v_add_u32_e32 v76, v72, v64
	v_ashrrev_i32_e32 v77, 31, v76
	v_lshlrev_b64 v[100:101], 2, v[76:77]
	v_lshl_add_u64 v[76:77], s[8:9], 0, v[100:101]
	v_add_u32_e32 v73, 0x4000, v65
	global_load_dword v127, v[76:77], off nt
	v_add_u32_e32 v76, v73, v64
	v_ashrrev_i32_e32 v77, 31, v76
	v_lshlrev_b64 v[102:103], 2, v[76:77]
	v_lshl_add_u64 v[76:77], s[8:9], 0, v[102:103]
	v_add_u32_e32 v75, 0x4400, v65
	global_load_dword v128, v[76:77], off nt
	v_add_u32_e32 v76, v75, v64
	v_ashrrev_i32_e32 v77, 31, v76
	v_lshlrev_b64 v[104:105], 2, v[76:77]
	v_lshl_add_u64 v[76:77], s[8:9], 0, v[104:105]
	global_load_dword v129, v[76:77], off nt
	v_add_u32_e32 v76, 0x4800, v65
	v_add_u32_e32 v78, v76, v64
	v_ashrrev_i32_e32 v79, 31, v78
	v_lshlrev_b64 v[106:107], 2, v[78:79]
	v_lshl_add_u64 v[78:79], s[8:9], 0, v[106:107]
	v_add_u32_e32 v77, 0x4c00, v65
	global_load_dword v130, v[78:79], off nt
	v_add_u32_e32 v78, v77, v64
	v_ashrrev_i32_e32 v79, 31, v78
	v_lshlrev_b64 v[108:109], 2, v[78:79]
	v_lshl_add_u64 v[78:79], s[8:9], 0, v[108:109]
	global_load_dword v131, v[78:79], off nt
	v_add_u32_e32 v78, 0x6000, v65
	v_add_u32_e32 v80, v78, v64
	v_ashrrev_i32_e32 v81, 31, v80
	v_lshlrev_b64 v[110:111], 2, v[80:81]
	v_lshl_add_u64 v[80:81], s[8:9], 0, v[110:111]
	v_add_u32_e32 v79, 0x6400, v65
	global_load_dword v132, v[80:81], off nt
	v_add_u32_e32 v80, v79, v64
	v_ashrrev_i32_e32 v81, 31, v80
	v_lshlrev_b64 v[112:113], 2, v[80:81]
	v_lshl_add_u64 v[80:81], s[8:9], 0, v[112:113]
	global_load_dword v133, v[80:81], off nt
	v_add_u32_e32 v80, 0x6800, v65
	v_add_u32_e32 v114, v80, v64
	v_ashrrev_i32_e32 v115, 31, v114
	v_lshlrev_b64 v[114:115], 2, v[114:115]
	v_lshl_add_u64 v[116:117], s[8:9], 0, v[114:115]
	v_add_u32_e32 v81, 0x6c00, v65
	global_load_dword v134, v[116:117], off nt
	v_add_u32_e32 v116, v81, v64
	v_ashrrev_i32_e32 v117, 31, v116
	v_lshlrev_b64 v[116:117], 2, v[116:117]
	v_lshl_add_u64 v[118:119], s[8:9], 0, v[116:117]
	global_load_dword v118, v[118:119], off nt
	s_waitcnt vmcnt(15)
; DI int crow(int r, int h) { return (r & 3) + 8 * (r >> 2) + 4 * h; }
; DI void phase_outproj(const Params& p, int g, char* smem, int bid, int nb) {
;     ...
;     for (int ni = 0; ni < 2; ++ni) {
;       const int col = nt * 128 + wn * 64 + ni * 32 + l31;
;       const float gt = mod[b * 6144 + 2048 + col];
; #pragma unroll
;       for (int mi = 0; mi < 2; ++mi) {
;         float xv[16];
; #pragma unroll
;         for (int r = 0; r < 16; ++r) xv[r] = __builtin_nontemporal_load(&xt[(wm * 64 + mi * 32 + crow(r, h)) * 1024 + col]);
; #pragma unroll
;         for (int r = 0; r < 16; ++r) ot[(wm * 64 + mi * 32 + crow(r, h)) * 1024 + col] = xv[r] + gt * acc[mi][ni][r];
;       }
	v_fmac_f32_e32 v120, v48, v74
	s_waitcnt vmcnt(14)
	v_fmac_f32_e32 v121, v49, v74
	v_lshl_add_u64 v[48:49], s[6:7], 0, v[84:85]
	global_store_dword v[48:49], v121, off
	s_waitcnt vmcnt(14)
	v_fmac_f32_e32 v122, v50, v74
	v_lshl_add_u64 v[48:49], s[6:7], 0, v[86:87]
	global_store_dword v[48:49], v122, off
	v_lshl_add_u64 v[48:49], s[6:7], 0, v[88:89]
	s_waitcnt vmcnt(14)
	v_fmac_f32_e32 v123, v51, v74
	global_store_dword v[48:49], v123, off
	v_lshl_add_u64 v[48:49], s[6:7], 0, v[90:91]
	v_lshl_add_u64 v[82:83], s[6:7], 0, v[82:83]
	global_store_dword v[82:83], v120, off
	s_waitcnt vmcnt(15)
	v_fmac_f32_e32 v124, v52, v74
	global_store_dword v[48:49], v124, off
	v_lshl_add_u64 v[48:49], s[6:7], 0, v[92:93]
	v_add_u32_e32 v120, 0xc000, v65
	v_add_u32_e32 v122, 0xc400, v65
	v_add_u32_e32 v124, 0xc800, v65
	s_cmp_ge_i32 s11, s13
	s_waitcnt vmcnt(15)
	v_fmac_f32_e32 v125, v53, v74
	global_store_dword v[48:49], v125, off
	v_lshl_add_u64 v[48:49], s[6:7], 0, v[94:95]
	s_waitcnt vmcnt(15)
	v_fmac_f32_e32 v126, v54, v74
	global_store_dword v[48:49], v126, off
	v_lshl_add_u64 v[48:49], s[6:7], 0, v[100:101]
	v_add_u32_e32 v126, 0xcc00, v65
	s_waitcnt vmcnt(15)
	v_fmac_f32_e32 v127, v55, v74
	global_store_dword v[48:49], v127, off
	v_lshl_add_u64 v[48:49], s[6:7], 0, v[102:103]
	s_waitcnt vmcnt(15)
	v_fmac_f32_e32 v128, v56, v74
	global_store_dword v[48:49], v128, off
	v_lshl_add_u64 v[48:49], s[6:7], 0, v[104:105]
	v_add_u32_e32 v128, 0xe000, v65
	s_waitcnt vmcnt(15)
	v_fmac_f32_e32 v129, v57, v74
	global_store_dword v[48:49], v129, off
	v_lshl_add_u64 v[48:49], s[6:7], 0, v[106:107]
	s_waitcnt vmcnt(15)
	v_fmac_f32_e32 v130, v58, v74
	global_store_dword v[48:49], v130, off
	v_lshl_add_u64 v[48:49], s[6:7], 0, v[108:109]
	v_add_u32_e32 v130, 0xe400, v65
	s_waitcnt vmcnt(15)
	v_fmac_f32_e32 v131, v59, v74
	global_store_dword v[48:49], v131, off
	v_lshl_add_u64 v[48:49], s[6:7], 0, v[110:111]
	s_waitcnt vmcnt(15)
	v_fmac_f32_e32 v132, v60, v74
	global_store_dword v[48:49], v132, off
	v_lshl_add_u64 v[48:49], s[6:7], 0, v[112:113]
	v_add_u32_e32 v132, 0xe800, v65
	s_waitcnt vmcnt(15)
	v_fmac_f32_e32 v133, v61, v74
	global_store_dword v[48:49], v133, off
	v_lshl_add_u64 v[48:49], s[6:7], 0, v[114:115]
	s_waitcnt vmcnt(15)
	v_fmac_f32_e32 v134, v62, v74
	global_store_dword v[48:49], v134, off
	v_lshl_add_u64 v[48:49], s[6:7], 0, v[116:117]
	v_add_u32_e32 v134, 0xec00, v65
	s_waitcnt vmcnt(15)
	v_fmac_f32_e32 v118, v63, v74
	global_store_dword v[48:49], v118, off
	v_add_u32_e32 v48, 0x8000, v65
	v_add_u32_e32 v50, v48, v64
	v_ashrrev_i32_e32 v51, 31, v50
	v_lshlrev_b64 v[56:57], 2, v[50:51]
	v_lshl_add_u64 v[50:51], s[8:9], 0, v[56:57]
	v_add_u32_e32 v49, 0x8400, v65
	global_load_dword v112, v[50:51], off nt
	v_add_u32_e32 v50, v49, v64
	v_ashrrev_i32_e32 v51, 31, v50
	v_lshlrev_b64 v[58:59], 2, v[50:51]
	v_lshl_add_u64 v[50:51], s[8:9], 0, v[58:59]
	global_load_dword v113, v[50:51], off nt
	v_add_u32_e32 v50, 0x8800, v65
	v_add_u32_e32 v52, v50, v64
	v_ashrrev_i32_e32 v53, 31, v52
	v_lshlrev_b64 v[60:61], 2, v[52:53]
	v_lshl_add_u64 v[52:53], s[8:9], 0, v[60:61]
	v_add_u32_e32 v51, 0x8c00, v65
	global_load_dword v114, v[52:53], off nt
	v_add_u32_e32 v52, v51, v64
	v_ashrrev_i32_e32 v53, 31, v52
	v_lshlrev_b64 v[62:63], 2, v[52:53]
	v_lshl_add_u64 v[52:53], s[8:9], 0, v[62:63]
	global_load_dword v115, v[52:53], off nt
	v_add_u32_e32 v52, 0xa000, v65
	v_add_u32_e32 v54, v52, v64
	v_ashrrev_i32_e32 v55, 31, v54
	v_lshlrev_b64 v[82:83], 2, v[54:55]
	v_lshl_add_u64 v[54:55], s[8:9], 0, v[82:83]
	v_add_u32_e32 v53, 0xa400, v65
	global_load_dword v116, v[54:55], off nt
	v_add_u32_e32 v54, v53, v64
	v_ashrrev_i32_e32 v55, 31, v54
	v_lshlrev_b64 v[84:85], 2, v[54:55]
	v_lshl_add_u64 v[54:55], s[8:9], 0, v[84:85]
	global_load_dword v55, v[54:55], off nt
	v_add_u32_e32 v54, 0xa800, v65
	v_add_u32_e32 v86, v54, v64
	v_ashrrev_i32_e32 v87, 31, v86
	v_lshlrev_b64 v[86:87], 2, v[86:87]
	v_lshl_add_u64 v[88:89], s[8:9], 0, v[86:87]
	v_add_u32_e32 v118, 0xac00, v65
	global_load_dword v117, v[88:89], off nt
	v_add_u32_e32 v88, v118, v64
	v_ashrrev_i32_e32 v89, 31, v88
	v_lshlrev_b64 v[88:89], 2, v[88:89]
	v_lshl_add_u64 v[90:91], s[8:9], 0, v[88:89]
	global_load_dword v119, v[90:91], off nt
	v_add_u32_e32 v90, v120, v64
	v_ashrrev_i32_e32 v91, 31, v90
	v_lshlrev_b64 v[90:91], 2, v[90:91]
	v_lshl_add_u64 v[92:93], s[8:9], 0, v[90:91]
	global_load_dword v121, v[92:93], off nt
	v_add_u32_e32 v92, v122, v64
	v_ashrrev_i32_e32 v93, 31, v92
	v_lshlrev_b64 v[92:93], 2, v[92:93]
	v_lshl_add_u64 v[94:95], s[8:9], 0, v[92:93]
	global_load_dword v123, v[94:95], off nt
	v_add_u32_e32 v94, v124, v64
	v_ashrrev_i32_e32 v95, 31, v94
	v_lshlrev_b64 v[94:95], 2, v[94:95]
	v_lshl_add_u64 v[100:101], s[8:9], 0, v[94:95]
	global_load_dword v125, v[100:101], off nt
	v_add_u32_e32 v100, v126, v64
	v_ashrrev_i32_e32 v101, 31, v100
	v_lshlrev_b64 v[100:101], 2, v[100:101]
	v_lshl_add_u64 v[102:103], s[8:9], 0, v[100:101]
	global_load_dword v127, v[102:103], off nt
	v_add_u32_e32 v102, v128, v64
	v_ashrrev_i32_e32 v103, 31, v102
	v_lshlrev_b64 v[102:103], 2, v[102:103]
	v_lshl_add_u64 v[104:105], s[8:9], 0, v[102:103]
	global_load_dword v129, v[104:105], off nt
	v_add_u32_e32 v104, v130, v64
	v_ashrrev_i32_e32 v105, 31, v104
	v_lshlrev_b64 v[104:105], 2, v[104:105]
	v_lshl_add_u64 v[106:107], s[8:9], 0, v[104:105]
	global_load_dword v131, v[106:107], off nt
	v_add_u32_e32 v106, v132, v64
	v_ashrrev_i32_e32 v107, 31, v106
	v_lshlrev_b64 v[106:107], 2, v[106:107]
	v_lshl_add_u64 v[108:109], s[8:9], 0, v[106:107]
	global_load_dword v133, v[108:109], off nt
	v_add_u32_e32 v108, v134, v64
	v_ashrrev_i32_e32 v109, 31, v108
	v_lshlrev_b64 v[108:109], 2, v[108:109]
	v_lshl_add_u64 v[110:111], s[8:9], 0, v[108:109]
	global_load_dword v110, v[110:111], off nt
	s_waitcnt vmcnt(15)
; DI int crow(int r, int h) { return (r & 3) + 8 * (r >> 2) + 4 * h; }
; DI void phase_outproj(const Params& p, int g, char* smem, int bid, int nb) {
;     ...
; #pragma unroll
;     for (int ni = 0; ni < 2; ++ni) {
;       const int col = nt * 128 + wn * 64 + ni * 32 + l31;
;       const float gt = mod[b * 6144 + 2048 + col];
; #pragma unroll
;       for (int mi = 0; mi < 2; ++mi) {
;         float xv[16];
; #pragma unroll
;         for (int r = 0; r < 16; ++r) xv[r] = __builtin_nontemporal_load(&xt[(wm * 64 + mi * 32 + crow(r, h)) * 1024 + col]);
; #pragma unroll
;         for (int r = 0; r < 16; ++r) ot[(wm * 64 + mi * 32 + crow(r, h)) * 1024 + col] = xv[r] + gt * acc[mi][ni][r];
;       }
;     }
	v_fmac_f32_e32 v112, v32, v74
	v_lshl_add_u64 v[56:57], s[6:7], 0, v[56:57]
	global_store_dword v[56:57], v112, off
	s_waitcnt vmcnt(15)
	v_fmac_f32_e32 v113, v33, v74
	v_lshl_add_u64 v[32:33], s[6:7], 0, v[58:59]
	global_store_dword v[32:33], v113, off
	v_lshl_add_u64 v[32:33], s[6:7], 0, v[60:61]
	s_waitcnt vmcnt(15)
	v_fmac_f32_e32 v114, v34, v74
	global_store_dword v[32:33], v114, off
	v_lshl_add_u64 v[32:33], s[6:7], 0, v[62:63]
	s_waitcnt vmcnt(15)
	v_fmac_f32_e32 v115, v35, v74
	global_store_dword v[32:33], v115, off
	v_lshl_add_u64 v[32:33], s[6:7], 0, v[82:83]
	s_waitcnt vmcnt(15)
	v_fmac_f32_e32 v116, v36, v74
	global_store_dword v[32:33], v116, off
	v_lshl_add_u64 v[32:33], s[6:7], 0, v[84:85]
	s_waitcnt vmcnt(15)
	v_fmac_f32_e32 v55, v37, v74
	global_store_dword v[32:33], v55, off
	v_lshl_add_u64 v[32:33], s[6:7], 0, v[86:87]
	v_add_u32_e32 v55, 32, v64
	s_waitcnt vmcnt(15)
	v_fmac_f32_e32 v117, v38, v74
	global_store_dword v[32:33], v117, off
	v_lshl_add_u64 v[32:33], s[6:7], 0, v[88:89]
	s_waitcnt vmcnt(15)
	v_fmac_f32_e32 v119, v39, v74
	global_store_dword v[32:33], v119, off
	v_lshl_add_u64 v[32:33], s[6:7], 0, v[90:91]
	s_waitcnt vmcnt(15)
	v_fmac_f32_e32 v121, v40, v74
	global_store_dword v[32:33], v121, off
	v_lshl_add_u64 v[32:33], s[6:7], 0, v[92:93]
	s_waitcnt vmcnt(15)
	v_fmac_f32_e32 v123, v41, v74
	global_store_dword v[32:33], v123, off
	v_lshl_add_u64 v[32:33], s[6:7], 0, v[94:95]
	s_waitcnt vmcnt(15)
	v_fmac_f32_e32 v125, v42, v74
	global_store_dword v[32:33], v125, off
	v_lshl_add_u64 v[32:33], s[6:7], 0, v[100:101]
	s_waitcnt vmcnt(15)
	v_fmac_f32_e32 v127, v43, v74
	global_store_dword v[32:33], v127, off
	v_lshl_add_u64 v[32:33], s[6:7], 0, v[102:103]
	s_waitcnt vmcnt(15)
	v_fmac_f32_e32 v129, v44, v74
	global_store_dword v[32:33], v129, off
	v_lshl_add_u64 v[32:33], s[6:7], 0, v[104:105]
	s_waitcnt vmcnt(15)
	v_fmac_f32_e32 v131, v45, v74
	global_store_dword v[32:33], v131, off
	v_lshl_add_u64 v[32:33], s[6:7], 0, v[106:107]
	s_waitcnt vmcnt(15)
	v_fmac_f32_e32 v133, v46, v74
	global_store_dword v[32:33], v133, off
	v_lshl_add_u64 v[32:33], s[6:7], 0, v[108:109]
	s_waitcnt vmcnt(15)
	v_fmac_f32_e32 v110, v47, v74
	global_store_dword v[32:33], v110, off
	v_add_u32_e32 v32, s0, v55
	v_ashrrev_i32_e32 v33, 31, v32
	v_lshl_add_u64 v[32:33], v[32:33], 2, s[92:93]
	global_load_dword v74, v[32:33], off
	v_add_u32_e32 v32, v55, v65
	v_ashrrev_i32_e32 v33, 31, v32
	v_lshlrev_b64 v[32:33], 2, v[32:33]
	v_lshl_add_u64 v[34:35], s[8:9], 0, v[32:33]
	global_load_dword v82, v[34:35], off nt
	v_add_u32_e32 v34, v66, v55
	v_ashrrev_i32_e32 v35, 31, v34
	v_lshlrev_b64 v[34:35], 2, v[34:35]
	v_lshl_add_u64 v[36:37], s[8:9], 0, v[34:35]
	global_load_dword v83, v[36:37], off nt
	v_add_u32_e32 v36, v67, v55
	v_ashrrev_i32_e32 v37, 31, v36
	v_lshlrev_b64 v[36:37], 2, v[36:37]
	v_lshl_add_u64 v[38:39], s[8:9], 0, v[36:37]
	global_load_dword v84, v[38:39], off nt
	v_add_u32_e32 v38, v68, v55
	v_ashrrev_i32_e32 v39, 31, v38
	v_lshlrev_b64 v[38:39], 2, v[38:39]
	v_lshl_add_u64 v[40:41], s[8:9], 0, v[38:39]
	global_load_dword v85, v[40:41], off nt
	v_add_u32_e32 v40, v69, v55
	v_ashrrev_i32_e32 v41, 31, v40
	v_lshlrev_b64 v[40:41], 2, v[40:41]
	v_lshl_add_u64 v[42:43], s[8:9], 0, v[40:41]
	global_load_dword v86, v[42:43], off nt
	v_add_u32_e32 v42, v70, v55
	v_ashrrev_i32_e32 v43, 31, v42
	v_lshlrev_b64 v[42:43], 2, v[42:43]
	v_lshl_add_u64 v[44:45], s[8:9], 0, v[42:43]
	global_load_dword v87, v[44:45], off nt
	v_add_u32_e32 v44, v71, v55
	v_ashrrev_i32_e32 v45, 31, v44
	v_lshlrev_b64 v[44:45], 2, v[44:45]
	v_lshl_add_u64 v[46:47], s[8:9], 0, v[44:45]
	global_load_dword v88, v[46:47], off nt
	v_add_u32_e32 v46, v72, v55
	v_ashrrev_i32_e32 v47, 31, v46
	v_lshlrev_b64 v[46:47], 2, v[46:47]
	v_lshl_add_u64 v[56:57], s[8:9], 0, v[46:47]
	global_load_dword v89, v[56:57], off nt
	v_add_u32_e32 v56, v73, v55
	v_ashrrev_i32_e32 v57, 31, v56
	v_lshlrev_b64 v[56:57], 2, v[56:57]
	v_lshl_add_u64 v[58:59], s[8:9], 0, v[56:57]
	global_load_dword v90, v[58:59], off nt
	v_add_u32_e32 v58, v75, v55
	v_ashrrev_i32_e32 v59, 31, v58
	v_lshlrev_b64 v[58:59], 2, v[58:59]
	v_lshl_add_u64 v[60:61], s[8:9], 0, v[58:59]
	global_load_dword v75, v[60:61], off nt
	v_add_u32_e32 v60, v76, v55
	v_ashrrev_i32_e32 v61, 31, v60
	v_lshlrev_b64 v[60:61], 2, v[60:61]
	v_lshl_add_u64 v[62:63], s[8:9], 0, v[60:61]
	global_load_dword v76, v[62:63], off nt
	v_add_u32_e32 v62, v77, v55
	v_ashrrev_i32_e32 v63, 31, v62
	v_lshlrev_b64 v[62:63], 2, v[62:63]
	v_lshl_add_u64 v[64:65], s[8:9], 0, v[62:63]
	global_load_dword v77, v[64:65], off nt
	v_add_u32_e32 v64, v78, v55
	v_ashrrev_i32_e32 v65, 31, v64
	v_lshlrev_b64 v[64:65], 2, v[64:65]
	v_lshl_add_u64 v[66:67], s[8:9], 0, v[64:65]
	global_load_dword v78, v[66:67], off nt
	v_add_u32_e32 v66, v79, v55
	v_ashrrev_i32_e32 v67, 31, v66
	v_lshlrev_b64 v[66:67], 2, v[66:67]
	v_lshl_add_u64 v[68:69], s[8:9], 0, v[66:67]
	global_load_dword v79, v[68:69], off nt
	v_add_u32_e32 v68, v80, v55
	v_ashrrev_i32_e32 v69, 31, v68
	v_lshlrev_b64 v[68:69], 2, v[68:69]
	v_lshl_add_u64 v[70:71], s[8:9], 0, v[68:69]
	global_load_dword v80, v[70:71], off nt
	v_add_u32_e32 v70, v81, v55
	v_ashrrev_i32_e32 v71, 31, v70
	v_lshlrev_b64 v[70:71], 2, v[70:71]
	v_lshl_add_u64 v[72:73], s[8:9], 0, v[70:71]
	global_load_dword v72, v[72:73], off nt
	v_lshl_add_u64 v[32:33], s[6:7], 0, v[32:33]
	s_waitcnt vmcnt(15)
	v_fmac_f32_e32 v82, v16, v74
	global_store_dword v[32:33], v82, off
	s_waitcnt vmcnt(15)
	v_fmac_f32_e32 v83, v17, v74
	v_lshl_add_u64 v[16:17], s[6:7], 0, v[34:35]
	global_store_dword v[16:17], v83, off
	v_lshl_add_u64 v[16:17], s[6:7], 0, v[36:37]
	s_waitcnt vmcnt(15)
; DI int crow(int r, int h) { return (r & 3) + 8 * (r >> 2) + 4 * h; }
; DI void phase_outproj(const Params& p, int g, char* smem, int bid, int nb) {
;     ...
; #pragma unroll
;     for (int ni = 0; ni < 2; ++ni) {
;       const int col = nt * 128 + wn * 64 + ni * 32 + l31;
;       const float gt = mod[b * 6144 + 2048 + col];
; #pragma unroll
;       for (int mi = 0; mi < 2; ++mi) {
;         float xv[16];
; #pragma unroll
;         for (int r = 0; r < 16; ++r) xv[r] = __builtin_nontemporal_load(&xt[(wm * 64 + mi * 32 + crow(r, h)) * 1024 + col]);
; #pragma unroll
;         for (int r = 0; r < 16; ++r) ot[(wm * 64 + mi * 32 + crow(r, h)) * 1024 + col] = xv[r] + gt * acc[mi][ni][r];
;       }
;     }
	v_fmac_f32_e32 v84, v18, v74
	global_store_dword v[16:17], v84, off
	v_lshl_add_u64 v[16:17], s[6:7], 0, v[38:39]
	s_waitcnt vmcnt(15)
	v_fmac_f32_e32 v85, v19, v74
	global_store_dword v[16:17], v85, off
	v_lshl_add_u64 v[16:17], s[6:7], 0, v[40:41]
	s_waitcnt vmcnt(15)
	v_fmac_f32_e32 v86, v20, v74
	global_store_dword v[16:17], v86, off
	v_lshl_add_u64 v[16:17], s[6:7], 0, v[42:43]
	s_waitcnt vmcnt(15)
	v_fmac_f32_e32 v87, v21, v74
	global_store_dword v[16:17], v87, off
	v_lshl_add_u64 v[16:17], s[6:7], 0, v[44:45]
	s_waitcnt vmcnt(15)
	v_fmac_f32_e32 v88, v22, v74
	global_store_dword v[16:17], v88, off
	v_lshl_add_u64 v[16:17], s[6:7], 0, v[46:47]
	s_waitcnt vmcnt(15)
	v_fmac_f32_e32 v89, v23, v74
	global_store_dword v[16:17], v89, off
	v_lshl_add_u64 v[16:17], s[6:7], 0, v[56:57]
	s_waitcnt vmcnt(15)
	v_fmac_f32_e32 v90, v24, v74
	global_store_dword v[16:17], v90, off
	v_lshl_add_u64 v[16:17], s[6:7], 0, v[58:59]
	s_waitcnt vmcnt(15)
	v_fmac_f32_e32 v75, v25, v74
	global_store_dword v[16:17], v75, off
	v_lshl_add_u64 v[16:17], s[6:7], 0, v[60:61]
	s_waitcnt vmcnt(15)
	v_fmac_f32_e32 v76, v26, v74
	global_store_dword v[16:17], v76, off
	v_lshl_add_u64 v[16:17], s[6:7], 0, v[62:63]
	s_waitcnt vmcnt(15)
	v_fmac_f32_e32 v77, v27, v74
	global_store_dword v[16:17], v77, off
	v_lshl_add_u64 v[16:17], s[6:7], 0, v[64:65]
	s_waitcnt vmcnt(15)
	v_fmac_f32_e32 v78, v28, v74
	global_store_dword v[16:17], v78, off
	v_lshl_add_u64 v[16:17], s[6:7], 0, v[66:67]
	s_waitcnt vmcnt(15)
	v_fmac_f32_e32 v79, v29, v74
	global_store_dword v[16:17], v79, off
	v_lshl_add_u64 v[16:17], s[6:7], 0, v[68:69]
	s_waitcnt vmcnt(15)
	v_fmac_f32_e32 v80, v30, v74
	global_store_dword v[16:17], v80, off
	v_lshl_add_u64 v[16:17], s[6:7], 0, v[70:71]
	s_waitcnt vmcnt(15)
	v_fmac_f32_e32 v72, v31, v74
	global_store_dword v[16:17], v72, off
	v_add_u32_e32 v16, v48, v55
	v_ashrrev_i32_e32 v17, 31, v16
	v_lshlrev_b64 v[16:17], 2, v[16:17]
	v_lshl_add_u64 v[18:19], s[8:9], 0, v[16:17]
	global_load_dword v56, v[18:19], off nt
	v_add_u32_e32 v18, v49, v55
	v_ashrrev_i32_e32 v19, 31, v18
	v_lshlrev_b64 v[18:19], 2, v[18:19]
	v_lshl_add_u64 v[20:21], s[8:9], 0, v[18:19]
	global_load_dword v57, v[20:21], off nt
	v_add_u32_e32 v20, v50, v55
	v_ashrrev_i32_e32 v21, 31, v20
	v_lshlrev_b64 v[20:21], 2, v[20:21]
	v_lshl_add_u64 v[22:23], s[8:9], 0, v[20:21]
	global_load_dword v50, v[22:23], off nt
	v_add_u32_e32 v22, v51, v55
	v_ashrrev_i32_e32 v23, 31, v22
	v_lshlrev_b64 v[22:23], 2, v[22:23]
	v_lshl_add_u64 v[24:25], s[8:9], 0, v[22:23]
	global_load_dword v51, v[24:25], off nt
	v_add_u32_e32 v24, v52, v55
	v_ashrrev_i32_e32 v25, 31, v24
	v_lshlrev_b64 v[24:25], 2, v[24:25]
	v_lshl_add_u64 v[26:27], s[8:9], 0, v[24:25]
	global_load_dword v52, v[26:27], off nt
	v_add_u32_e32 v26, v53, v55
	v_ashrrev_i32_e32 v27, 31, v26
	v_lshlrev_b64 v[26:27], 2, v[26:27]
	v_lshl_add_u64 v[28:29], s[8:9], 0, v[26:27]
	global_load_dword v53, v[28:29], off nt
	v_add_u32_e32 v28, v54, v55
	v_ashrrev_i32_e32 v29, 31, v28
	v_lshlrev_b64 v[28:29], 2, v[28:29]
	v_lshl_add_u64 v[30:31], s[8:9], 0, v[28:29]
	global_load_dword v54, v[30:31], off nt
	v_add_u32_e32 v30, v118, v55
	v_ashrrev_i32_e32 v31, 31, v30
	v_lshlrev_b64 v[30:31], 2, v[30:31]
	v_lshl_add_u64 v[32:33], s[8:9], 0, v[30:31]
	global_load_dword v58, v[32:33], off nt
	v_add_u32_e32 v32, v120, v55
	v_ashrrev_i32_e32 v33, 31, v32
	v_lshlrev_b64 v[32:33], 2, v[32:33]
	v_lshl_add_u64 v[34:35], s[8:9], 0, v[32:33]
	global_load_dword v59, v[34:35], off nt
	v_add_u32_e32 v34, v122, v55
	v_ashrrev_i32_e32 v35, 31, v34
	v_lshlrev_b64 v[34:35], 2, v[34:35]
	v_lshl_add_u64 v[36:37], s[8:9], 0, v[34:35]
	global_load_dword v60, v[36:37], off nt
	v_add_u32_e32 v36, v124, v55
	v_ashrrev_i32_e32 v37, 31, v36
	v_lshlrev_b64 v[36:37], 2, v[36:37]
	v_lshl_add_u64 v[38:39], s[8:9], 0, v[36:37]
	global_load_dword v61, v[38:39], off nt
	v_add_u32_e32 v38, v126, v55
	v_ashrrev_i32_e32 v39, 31, v38
	v_lshlrev_b64 v[38:39], 2, v[38:39]
	v_lshl_add_u64 v[40:41], s[8:9], 0, v[38:39]
	global_load_dword v62, v[40:41], off nt
	v_add_u32_e32 v40, v128, v55
	v_ashrrev_i32_e32 v41, 31, v40
	v_lshlrev_b64 v[40:41], 2, v[40:41]
	v_lshl_add_u64 v[42:43], s[8:9], 0, v[40:41]
	global_load_dword v63, v[42:43], off nt
	v_add_u32_e32 v42, v130, v55
	v_ashrrev_i32_e32 v43, 31, v42
	v_lshlrev_b64 v[42:43], 2, v[42:43]
	v_lshl_add_u64 v[44:45], s[8:9], 0, v[42:43]
	global_load_dword v64, v[44:45], off nt
	v_add_u32_e32 v44, v132, v55
	v_ashrrev_i32_e32 v45, 31, v44
	v_lshlrev_b64 v[44:45], 2, v[44:45]
	v_lshl_add_u64 v[46:47], s[8:9], 0, v[44:45]
	global_load_dword v65, v[46:47], off nt
	v_add_u32_e32 v46, v134, v55
	v_ashrrev_i32_e32 v47, 31, v46
	v_lshlrev_b64 v[46:47], 2, v[46:47]
	v_lshl_add_u64 v[48:49], s[8:9], 0, v[46:47]
	global_load_dword v48, v[48:49], off nt
	v_lshl_add_u64 v[16:17], s[6:7], 0, v[16:17]
	s_waitcnt vmcnt(15)
	v_fmac_f32_e32 v56, v0, v74
	global_store_dword v[16:17], v56, off
	s_waitcnt vmcnt(15)
	v_fmac_f32_e32 v57, v1, v74
	v_lshl_add_u64 v[0:1], s[6:7], 0, v[18:19]
	global_store_dword v[0:1], v57, off
	v_lshl_add_u64 v[0:1], s[6:7], 0, v[20:21]
	s_waitcnt vmcnt(15)
	v_fmac_f32_e32 v50, v2, v74
	global_store_dword v[0:1], v50, off
	v_lshl_add_u64 v[0:1], s[6:7], 0, v[22:23]
	s_waitcnt vmcnt(15)
	v_fmac_f32_e32 v51, v3, v74
	global_store_dword v[0:1], v51, off
	v_lshl_add_u64 v[0:1], s[6:7], 0, v[24:25]
	s_waitcnt vmcnt(15)
	v_fmac_f32_e32 v52, v4, v74
	global_store_dword v[0:1], v52, off
	v_lshl_add_u64 v[0:1], s[6:7], 0, v[26:27]
	s_waitcnt vmcnt(15)
	v_fmac_f32_e32 v53, v5, v74
	global_store_dword v[0:1], v53, off
	v_lshl_add_u64 v[0:1], s[6:7], 0, v[28:29]
	s_waitcnt vmcnt(15)
	v_fmac_f32_e32 v54, v6, v74
	global_store_dword v[0:1], v54, off
	v_lshl_add_u64 v[0:1], s[6:7], 0, v[30:31]
	s_waitcnt vmcnt(15)
	v_fmac_f32_e32 v58, v7, v74
	global_store_dword v[0:1], v58, off
	v_lshl_add_u64 v[0:1], s[6:7], 0, v[32:33]
	s_waitcnt vmcnt(15)
	v_fmac_f32_e32 v59, v8, v74
	global_store_dword v[0:1], v59, off
	v_lshl_add_u64 v[0:1], s[6:7], 0, v[34:35]
	s_waitcnt vmcnt(15)
	v_fmac_f32_e32 v60, v9, v74
	global_store_dword v[0:1], v60, off
	v_lshl_add_u64 v[0:1], s[6:7], 0, v[36:37]
	s_waitcnt vmcnt(15)
	v_fmac_f32_e32 v61, v10, v74
	global_store_dword v[0:1], v61, off
	v_lshl_add_u64 v[0:1], s[6:7], 0, v[38:39]
	s_waitcnt vmcnt(15)
	v_fmac_f32_e32 v62, v11, v74
	global_store_dword v[0:1], v62, off
	v_lshl_add_u64 v[0:1], s[6:7], 0, v[40:41]
	s_waitcnt vmcnt(15)
	v_fmac_f32_e32 v63, v12, v74
	global_store_dword v[0:1], v63, off
	v_lshl_add_u64 v[0:1], s[6:7], 0, v[42:43]
	s_waitcnt vmcnt(15)
	v_fmac_f32_e32 v64, v13, v74
	global_store_dword v[0:1], v64, off
	v_lshl_add_u64 v[0:1], s[6:7], 0, v[44:45]
	s_waitcnt vmcnt(15)
	v_fmac_f32_e32 v65, v14, v74
	global_store_dword v[0:1], v65, off
	v_lshl_add_u64 v[0:1], s[6:7], 0, v[46:47]
	s_waitcnt vmcnt(15)
	v_fmac_f32_e32 v48, v15, v74
	global_store_dword v[0:1], v48, off
	s_cbranch_scc1 .LBB0_216

; template <bool SWAP>
; DI void gemm_tile(const bf16_t* __restrict__ A, int lda, const bf16_t* __restrict__ Bt, int ldb, int K, f32x16 (&acc)[2][2], bf16_t* As, bf16_t* Bs_unused) {
;     ...
;   const bf16_t* ga = A + (size_t)lr * lda + lc;
;   const bf16_t* gb = Bt + (size_t)lr * ldb + lc;
;   u32x4 ra0[4], rb0[4], ra1[4], rb1[4];
;   auto load_stage = [&](u32x4 (&ra)[4], u32x4 (&rb)[4], int t) __attribute__((always_inline)) {
; #pragma unroll
;     for (int i = 0; i < 4; ++i) { ra[i] = *(const u32x4*)(ga + (size_t)(32 * i) * lda + t * 64); rb[i] = *(const u32x4*)(gb + (size_t)(32 * i) * ldb + t * 64); }
;   };
;   auto write_stage = [&](const u32x4 (&ra)[4], const u32x4 (&rb)[4], int buf) __attribute__((always_inline)) {
;     bf16_t* Ad = As + buf * 2 * GT_IMG; bf16_t* Bd = Ad + GT_IMG;
; #pragma unroll
;     for (int i = 0; i < 4; ++i) { *(u32x4*)(Ad + (lr + 32 * i) * 72 + lc) = ra[i]; *(u32x4*)(Bd + (lr + 32 * i) * 72 + lc) = rb[i]; }
;   };
;   const int fr = lane & 31, fk = (lane >> 5) * 8;
;   const int pao = (wm * 64 + fr) * 72 + fk, pbo = GT_IMG + (wn * 64 + fr) * 72 + fk;
;   auto frag_read = [&](bf16x8 (&f)[4], const bf16_t* pa, const bf16_t* pb, int so) __attribute__((always_inline)) {
;     f[0] = *(const bf16x8*)(pa + so); f[1] = *(const bf16x8*)(pb + so); f[2] = *(const bf16x8*)(pb + 32 * 72 + so); f[3] = *(const bf16x8*)(pa + 32 * 72 + so);
;     ...
;   auto step = [&](int buf, u32x4 (&ra)[4], u32x4 (&rb)[4], bool do_write, bool do_load, int tload) __attribute__((always_inline)) {
;     const bf16_t* pa = As + buf * 2 * GT_IMG + pao; const bf16_t* pb = As + buf * 2 * GT_IMG + pbo;
;     bf16_t* Ad = As + (buf ^ 1) * 2 * GT_IMG; bf16_t* Bd = Ad + GT_IMG;
;     bf16x8 F0[4], F1[4];
;     frag_read(F0, pa, pb, 0);
;     __builtin_amdgcn_sched_barrier(0);
;     frag_read(F1, pa, pb, 16);
;     mfma4(F0);
;     __builtin_amdgcn_sched_barrier(0);
;     frag_read(F0, pa, pb, 32);
;     mfma4(F1);
;     if (do_write) {
; #pragma unroll
;       for (int i = 0; i < 4; ++i) *(u32x4*)(Ad + (lr + 32 * i) * 72 + lc) = ra[i];
;     }
;     __builtin_amdgcn_sched_barrier(0);
;     frag_read(F1, pa, pb, 48);
;     mfma4(F0);
;     if (do_write) {
; #pragma unroll
;       for (int i = 0; i < 4; ++i) *(u32x4*)(Bd + (lr + 32 * i) * 72 + lc) = rb[i];
;     }
;     __builtin_amdgcn_sched_barrier(0);
;     mfma4(F1);
;     if (do_load) load_stage(ra, rb, tload);
.LBB0_222:
	s_ashr_i32 s7, s6, 31
	s_add_i32 s13, s13, s14
	s_lshl_b64 s[0:1], s[6:7], 18
	v_readlane_b32 s7, v235, 61
	s_add_u32 s16, s7, s0
	v_readlane_b32 s7, v235, 62
	v_mov_b32_e32 v34, v195
	s_addc_u32 s17, s7, s1
	s_ashr_i32 s11, s10, 31
	s_lshl_b64 s[8:9], s[10:11], 18
	v_ashrrev_i32_e32 v32, 3, v34
	v_readlane_b32 s7, v235, 63
	v_ashrrev_i32_e32 v33, 31, v32
	s_add_u32 s18, s7, s8
	v_readlane_b32 s7, v233, 0
	v_lshlrev_b64 v[0:1], 11, v[32:33]
	s_waitcnt lgkmcnt(0)
	v_lshlrev_b32_e32 v4, 4, v34
	s_addc_u32 s19, s7, s9
	v_lshl_add_u64 v[2:3], s[16:17], 0, v[0:1]
	v_and_b32_e32 v192, 0x70, v4
	v_lshl_add_u64 v[80:81], v[2:3], 0, v[192:193]
	v_lshl_add_u64 v[0:1], s[18:19], 0, v[0:1]
	s_mov_b32 s18, 0x10000
	v_add_co_u32_e32 v84, vcc, s18, v80
	v_lshl_add_u64 v[82:83], v[0:1], 0, v[192:193]
	s_nop 0
	v_addc_co_u32_e32 v85, vcc, 0, v81, vcc
	v_add_co_u32_e32 v86, vcc, s18, v82
	s_mov_b32 s19, 0x20000
	s_nop 0
	v_addc_co_u32_e32 v87, vcc, 0, v83, vcc
	global_load_dwordx4 v[0:3], v[80:81], off
	global_load_dwordx4 v[4:7], v[82:83], off
	v_add_co_u32_e32 v88, vcc, s19, v80
	global_load_dwordx4 v[8:11], v[84:85], off
	global_load_dwordx4 v[12:15], v[86:87], off
	v_addc_co_u32_e32 v89, vcc, 0, v81, vcc
	v_add_co_u32_e32 v90, vcc, s19, v82
	s_mov_b32 s20, 0x30000
	s_nop 0
	v_addc_co_u32_e32 v91, vcc, 0, v83, vcc
	global_load_dwordx4 v[16:19], v[88:89], off
	global_load_dwordx4 v[20:23], v[90:91], off
	v_add_co_u32_e32 v92, vcc, s20, v80
	v_mul_lo_u32 v32, v32, s71
	s_nop 0
	v_addc_co_u32_e32 v93, vcc, 0, v81, vcc
	global_load_dwordx4 v[24:27], v[92:93], off
	v_add_co_u32_e32 v94, vcc, s20, v82
	v_add3_u32 v96, 32, v32, v192
	s_nop 0
	v_addc_co_u32_e32 v95, vcc, 0, v83, vcc
	global_load_dwordx4 v[28:31], v[94:95], off
	global_load_dwordx4 v[100:103], v[80:81], off offset:128
	global_load_dwordx4 v[104:107], v[82:83], off offset:128
	global_load_dwordx4 v[108:111], v[84:85], off offset:128
	global_load_dwordx4 v[112:115], v[86:87], off offset:128
	global_load_dwordx4 v[116:119], v[88:89], off offset:128
	global_load_dwordx4 v[120:123], v[90:91], off offset:128
	global_load_dwordx4 v[124:127], v[92:93], off offset:128
	global_load_dwordx4 v[128:131], v[94:95], off offset:128
	s_waitcnt vmcnt(63) expcnt(7) lgkmcnt(15)
	s_barrier
	v_add_u32_e32 v99, 0xd800, v96
	s_waitcnt vmcnt(15)
	ds_write_b128 v96, v[0:3]
	s_waitcnt vmcnt(14)
	ds_write_b128 v96, v[4:7] offset:18432
	s_waitcnt vmcnt(13)
	ds_write_b128 v96, v[8:11] offset:4608
	s_waitcnt vmcnt(12)
	ds_write_b128 v96, v[12:15] offset:23040
	s_waitcnt vmcnt(11)
	ds_write_b128 v96, v[16:19] offset:9216
	s_waitcnt vmcnt(10)
	ds_write_b128 v96, v[20:23] offset:27648
	s_waitcnt vmcnt(9)
	ds_write_b128 v96, v[24:27] offset:13824
	s_waitcnt vmcnt(8)
	ds_write_b128 v96, v[28:31] offset:32256
	global_load_dwordx4 v[132:135], v[80:81], off offset:256
	global_load_dwordx4 v[64:67], v[82:83], off offset:256
	global_load_dwordx4 v[136:139], v[84:85], off offset:256
	global_load_dwordx4 v[68:71], v[86:87], off offset:256
	global_load_dwordx4 v[140:143], v[88:89], off offset:256
	global_load_dwordx4 v[72:75], v[90:91], off offset:256
	global_load_dwordx4 v[148:151], v[92:93], off offset:256
	global_load_dwordx4 v[76:79], v[94:95], off offset:256
	v_lshrrev_b32_e32 v0, 2, v34
	v_lshrrev_b32_e32 v2, 1, v34
	v_and_b32_e32 v3, 31, v34
	v_and_b32_e32 v1, 0x5f, v34
	v_and_b32_e32 v0, 8, v0
	v_and_or_b32 v2, v2, s80, v3
	v_mad_u64_u32 v[2:3], s[16:17], v2, s72, v[0:1]
	v_lshl_add_u32 v97, v2, 1, 32
	v_mad_u32_u24 v0, v1, s72, v0
	s_waitcnt lgkmcnt(0)
	s_barrier
	v_lshl_add_u32 v98, v0, 1, 32
	ds_read_b128 v[16:19], v97
	ds_read_b128 v[20:23], v98 offset:18432
	ds_read_b128 v[24:27], v98 offset:23040
	ds_read_b128 v[28:31], v97 offset:4608
	ds_read_b128 v[152:155], v98 offset:18464
	ds_read_b128 v[156:159], v98 offset:23072
	ds_read_b128 v[160:163], v97 offset:32
	ds_read_b128 v[164:167], v97 offset:4640
	s_waitcnt lgkmcnt(6)
	v_mfma_f32_32x32x16_bf16 v[0:15], v[16:19], v[20:23], 0
	s_waitcnt lgkmcnt(5)
	v_mfma_f32_32x32x16_bf16 v[32:47], v[16:19], v[24:27], 0
	s_waitcnt lgkmcnt(4)
	v_mfma_f32_32x32x16_bf16 v[48:63], v[28:31], v[20:23], 0
	v_mfma_f32_32x32x16_bf16 v[16:31], v[28:31], v[24:27], 0
	s_waitcnt lgkmcnt(1)
	v_mfma_f32_32x32x16_bf16 v[0:15], v[160:163], v[152:155], v[0:15]
	v_mfma_f32_32x32x16_bf16 v[32:47], v[160:163], v[156:159], v[32:47]
	s_waitcnt lgkmcnt(0)
	v_mfma_f32_32x32x16_bf16 v[48:63], v[164:167], v[152:155], v[48:63]
	ds_read_b128 v[152:155], v98 offset:18496
	ds_read_b128 v[160:163], v98 offset:23104
	ds_read_b128 v[168:171], v97 offset:64
	ds_read_b128 v[172:175], v97 offset:4672
	s_waitcnt vmcnt(15)
	ds_write_b128 v96, v[100:103] offset:36864
	s_waitcnt vmcnt(13)
	ds_write_b128 v96, v[108:111] offset:41472
	s_waitcnt vmcnt(11)
	ds_write_b128 v96, v[116:119] offset:46080
	s_waitcnt vmcnt(9)
	ds_write_b128 v96, v[124:127] offset:50688
	v_mfma_f32_32x32x16_bf16 v[16:31], v[164:167], v[156:159], v[16:31]
	ds_read_b128 v[100:103], v98 offset:18528
	ds_read_b128 v[108:111], v98 offset:23136
	ds_read_b128 v[116:119], v97 offset:96
	ds_read_b128 v[124:127], v97 offset:4704
	s_waitcnt lgkmcnt(9)
	v_mfma_f32_32x32x16_bf16 v[0:15], v[168:171], v[152:155], v[0:15]
	ds_write_b128 v96, v[104:107] offset:55296
	ds_write_b128 v96, v[112:115] offset:59904
	ds_write_b128 v96, v[120:123] offset:64512
	s_waitcnt vmcnt(8)
	ds_write_b128 v99, v[128:131] offset:13824
	v_mfma_f32_32x32x16_bf16 v[32:47], v[168:171], v[160:163], v[32:47]
	s_waitcnt lgkmcnt(12)
	v_mfma_f32_32x32x16_bf16 v[48:63], v[172:175], v[152:155], v[48:63]
	v_mfma_f32_32x32x16_bf16 v[16:31], v[172:175], v[160:163], v[16:31]
	s_waitcnt lgkmcnt(0)
	s_barrier
; template <bool SWAP>
; DI void gemm_tile(const bf16_t* __restrict__ A, int lda, const bf16_t* __restrict__ Bt, int ldb, int K, f32x16 (&acc)[2][2], bf16_t* As, bf16_t* Bs_unused) {
;     ...
;   auto step = [&](int buf, u32x4 (&ra)[4], u32x4 (&rb)[4], bool do_write, bool do_load, int tload) __attribute__((always_inline)) {
;     const bf16_t* pa = As + buf * 2 * GT_IMG + pao; const bf16_t* pb = As + buf * 2 * GT_IMG + pbo;
;     bf16_t* Ad = As + (buf ^ 1) * 2 * GT_IMG; bf16_t* Bd = Ad + GT_IMG;
;     bf16x8 F0[4], F1[4];
;     frag_read(F0, pa, pb, 0);
;     __builtin_amdgcn_sched_barrier(0);
;     frag_read(F1, pa, pb, 16);
;     mfma4(F0);
;     __builtin_amdgcn_sched_barrier(0);
;     frag_read(F0, pa, pb, 32);
;     mfma4(F1);
;     if (do_write) {
; #pragma unroll
;       for (int i = 0; i < 4; ++i) *(u32x4*)(Ad + (lr + 32 * i) * 72 + lc) = ra[i];
;     }
;     __builtin_amdgcn_sched_barrier(0);
;     frag_read(F1, pa, pb, 48);
;     mfma4(F0);
;     if (do_write) {
; #pragma unroll
;       for (int i = 0; i < 4; ++i) *(u32x4*)(Bd + (lr + 32 * i) * 72 + lc) = rb[i];
;     }
;     __builtin_amdgcn_sched_barrier(0);
;     mfma4(F1);
;     if (do_load) load_stage(ra, rb, tload);
;     __builtin_amdgcn_sched_barrier(0);
;   };
;   const int nk = K >> 6;
;   load_stage(ra0, rb0, 0); load_stage(ra1, rb1, 1);
;   __syncthreads();
;   write_stage(ra0, rb0, 0);
;   load_stage(ra0, rb0, 2);
;   __syncthreads();
;   for (int kt = 0; kt < nk; kt += 2) {
;     step(0, ra1, rb1, true, kt + 3 < nk, kt + 3);
;     __syncthreads();
;     step(1, ra0, rb0, kt + 2 < nk, kt + 4 < nk, kt + 4);
;     __syncthreads();
	ds_read_b128 v[152:155], v98 offset:55296
	ds_read_b128 v[156:159], v98 offset:59904
	ds_read_b128 v[160:163], v97 offset:36864
	ds_read_b128 v[164:167], v97 offset:41472
	v_mfma_f32_32x32x16_bf16 v[0:15], v[116:119], v[100:103], v[0:15]
	v_mfma_f32_32x32x16_bf16 v[32:47], v[116:119], v[108:111], v[32:47]
	v_mfma_f32_32x32x16_bf16 v[48:63], v[124:127], v[100:103], v[48:63]
	v_mfma_f32_32x32x16_bf16 v[16:31], v[124:127], v[108:111], v[16:31]
	global_load_dwordx4 v[100:103], v[80:81], off offset:384
	global_load_dwordx4 v[104:107], v[82:83], off offset:384
	global_load_dwordx4 v[108:111], v[84:85], off offset:384
	global_load_dwordx4 v[112:115], v[86:87], off offset:384
	global_load_dwordx4 v[116:119], v[88:89], off offset:384
	global_load_dwordx4 v[120:123], v[90:91], off offset:384
	global_load_dwordx4 v[124:127], v[92:93], off offset:384
	global_load_dwordx4 v[128:131], v[94:95], off offset:384
	s_waitcnt lgkmcnt(1)
	v_mfma_f32_32x32x16_bf16 v[0:15], v[160:163], v[152:155], v[0:15]
	v_mfma_f32_32x32x16_bf16 v[32:47], v[160:163], v[156:159], v[32:47]
	s_waitcnt lgkmcnt(0)
	v_mfma_f32_32x32x16_bf16 v[48:63], v[164:167], v[152:155], v[48:63]
	ds_read_b128 v[152:155], v98 offset:55328
	ds_read_b128 v[160:163], v98 offset:59936
	ds_read_b128 v[168:171], v97 offset:36896
	ds_read_b128 v[172:175], v97 offset:41504
	v_mfma_f32_32x32x16_bf16 v[16:31], v[164:167], v[156:159], v[16:31]
	s_waitcnt lgkmcnt(1)
	v_mfma_f32_32x32x16_bf16 v[0:15], v[168:171], v[152:155], v[0:15]
	v_mfma_f32_32x32x16_bf16 v[32:47], v[168:171], v[160:163], v[32:47]
	s_waitcnt lgkmcnt(0)
	v_mfma_f32_32x32x16_bf16 v[48:63], v[172:175], v[152:155], v[48:63]
	ds_read_b128 v[152:155], v98 offset:55360
	ds_read_b128 v[156:159], v98 offset:59968
	ds_read_b128 v[164:167], v97 offset:36928
	ds_read_b128 v[168:171], v97 offset:41536
	s_waitcnt vmcnt(15)
	ds_write_b128 v96, v[132:135]
	s_waitcnt vmcnt(13)
	ds_write_b128 v96, v[136:139] offset:4608
	s_waitcnt vmcnt(11)
	ds_write_b128 v96, v[140:143] offset:9216
	s_waitcnt vmcnt(9)
	ds_write_b128 v96, v[148:151] offset:13824
	v_mfma_f32_32x32x16_bf16 v[16:31], v[172:175], v[160:163], v[16:31]
	ds_read_b128 v[132:135], v98 offset:55392
	ds_read_b128 v[136:139], v98 offset:60000
	ds_read_b128 v[140:143], v97 offset:36960
	ds_read_b128 v[148:151], v97 offset:41568
	s_waitcnt lgkmcnt(9)
	v_mfma_f32_32x32x16_bf16 v[0:15], v[164:167], v[152:155], v[0:15]
	ds_write_b128 v96, v[64:67] offset:18432
	ds_write_b128 v96, v[68:71] offset:23040
	ds_write_b128 v96, v[72:75] offset:27648
	s_waitcnt vmcnt(8)
	ds_write_b128 v96, v[76:79] offset:32256
	v_mfma_f32_32x32x16_bf16 v[32:47], v[164:167], v[156:159], v[32:47]
	s_waitcnt lgkmcnt(12)
	v_mfma_f32_32x32x16_bf16 v[48:63], v[168:171], v[152:155], v[48:63]
	v_mfma_f32_32x32x16_bf16 v[16:31], v[168:171], v[156:159], v[16:31]
	s_waitcnt lgkmcnt(0)
	s_barrier
	ds_read_b128 v[152:155], v98 offset:18432
	ds_read_b128 v[156:159], v98 offset:23040
	ds_read_b128 v[160:163], v97
	ds_read_b128 v[164:167], v97 offset:4608
	v_mfma_f32_32x32x16_bf16 v[0:15], v[140:143], v[132:135], v[0:15]
	v_mfma_f32_32x32x16_bf16 v[32:47], v[140:143], v[136:139], v[32:47]
	v_mfma_f32_32x32x16_bf16 v[48:63], v[148:151], v[132:135], v[48:63]
	v_mfma_f32_32x32x16_bf16 v[16:31], v[148:151], v[136:139], v[16:31]
	global_load_dwordx4 v[64:67], v[80:81], off offset:512
	global_load_dwordx4 v[68:71], v[82:83], off offset:512
	global_load_dwordx4 v[72:75], v[84:85], off offset:512
	global_load_dwordx4 v[76:79], v[86:87], off offset:512
	global_load_dwordx4 v[132:135], v[88:89], off offset:512
	global_load_dwordx4 v[136:139], v[90:91], off offset:512
	global_load_dwordx4 v[140:143], v[92:93], off offset:512
	global_load_dwordx4 v[148:151], v[94:95], off offset:512
	s_waitcnt lgkmcnt(1)
	v_mfma_f32_32x32x16_bf16 v[0:15], v[160:163], v[152:155], v[0:15]
	v_mfma_f32_32x32x16_bf16 v[32:47], v[160:163], v[156:159], v[32:47]
	s_waitcnt lgkmcnt(0)
	v_mfma_f32_32x32x16_bf16 v[48:63], v[164:167], v[152:155], v[48:63]
	ds_read_b128 v[152:155], v98 offset:18464
	ds_read_b128 v[160:163], v98 offset:23072
	ds_read_b128 v[168:171], v97 offset:32
	ds_read_b128 v[172:175], v97 offset:4640
	v_mfma_f32_32x32x16_bf16 v[16:31], v[164:167], v[156:159], v[16:31]
	s_waitcnt lgkmcnt(1)
	v_mfma_f32_32x32x16_bf16 v[0:15], v[168:171], v[152:155], v[0:15]
	v_mfma_f32_32x32x16_bf16 v[32:47], v[168:171], v[160:163], v[32:47]
	s_waitcnt lgkmcnt(0)
	v_mfma_f32_32x32x16_bf16 v[48:63], v[172:175], v[152:155], v[48:63]
	ds_read_b128 v[152:155], v98 offset:18496
	ds_read_b128 v[156:159], v98 offset:23104
	ds_read_b128 v[164:167], v97 offset:64
	ds_read_b128 v[168:171], v97 offset:4672
	s_waitcnt vmcnt(15)
	ds_write_b128 v96, v[100:103] offset:36864
	s_waitcnt vmcnt(13)
	ds_write_b128 v96, v[108:111] offset:41472
	s_waitcnt vmcnt(11)
	ds_write_b128 v96, v[116:119] offset:46080
	s_waitcnt vmcnt(9)
	ds_write_b128 v96, v[124:127] offset:50688
	v_mfma_f32_32x32x16_bf16 v[16:31], v[172:175], v[160:163], v[16:31]
	ds_read_b128 v[100:103], v98 offset:18528
	ds_read_b128 v[108:111], v98 offset:23136
	ds_read_b128 v[116:119], v97 offset:96
	ds_read_b128 v[124:127], v97 offset:4704
	s_waitcnt lgkmcnt(9)
	v_mfma_f32_32x32x16_bf16 v[0:15], v[164:167], v[152:155], v[0:15]
	ds_write_b128 v96, v[104:107] offset:55296
	ds_write_b128 v96, v[112:115] offset:59904
	ds_write_b128 v96, v[120:123] offset:64512
	s_waitcnt vmcnt(8)
	ds_write_b128 v99, v[128:131] offset:13824
	v_mfma_f32_32x32x16_bf16 v[32:47], v[164:167], v[156:159], v[32:47]
	s_waitcnt lgkmcnt(12)
	v_mfma_f32_32x32x16_bf16 v[48:63], v[168:171], v[152:155], v[48:63]
	v_mfma_f32_32x32x16_bf16 v[16:31], v[168:171], v[156:159], v[16:31]
	s_waitcnt lgkmcnt(0)
	s_barrier
; template <bool SWAP>
; DI void gemm_tile(const bf16_t* __restrict__ A, int lda, const bf16_t* __restrict__ Bt, int ldb, int K, f32x16 (&acc)[2][2], bf16_t* As, bf16_t* Bs_unused) {
;     ...
;   auto step = [&](int buf, u32x4 (&ra)[4], u32x4 (&rb)[4], bool do_write, bool do_load, int tload) __attribute__((always_inline)) {
;     const bf16_t* pa = As + buf * 2 * GT_IMG + pao; const bf16_t* pb = As + buf * 2 * GT_IMG + pbo;
;     bf16_t* Ad = As + (buf ^ 1) * 2 * GT_IMG; bf16_t* Bd = Ad + GT_IMG;
;     bf16x8 F0[4], F1[4];
;     frag_read(F0, pa, pb, 0);
;     __builtin_amdgcn_sched_barrier(0);
;     frag_read(F1, pa, pb, 16);
;     mfma4(F0);
;     __builtin_amdgcn_sched_barrier(0);
;     frag_read(F0, pa, pb, 32);
;     mfma4(F1);
;     if (do_write) {
; #pragma unroll
;       for (int i = 0; i < 4; ++i) *(u32x4*)(Ad + (lr + 32 * i) * 72 + lc) = ra[i];
;     }
;     __builtin_amdgcn_sched_barrier(0);
;     frag_read(F1, pa, pb, 48);
;     mfma4(F0);
;     if (do_write) {
; #pragma unroll
;       for (int i = 0; i < 4; ++i) *(u32x4*)(Bd + (lr + 32 * i) * 72 + lc) = rb[i];
;     }
;     __builtin_amdgcn_sched_barrier(0);
;     mfma4(F1);
;     if (do_load) load_stage(ra, rb, tload);
;     __builtin_amdgcn_sched_barrier(0);
;   };
;   const int nk = K >> 6;
;   load_stage(ra0, rb0, 0); load_stage(ra1, rb1, 1);
;   __syncthreads();
;   write_stage(ra0, rb0, 0);
;   load_stage(ra0, rb0, 2);
;   __syncthreads();
;   for (int kt = 0; kt < nk; kt += 2) {
;     step(0, ra1, rb1, true, kt + 3 < nk, kt + 3);
;     __syncthreads();
;     step(1, ra0, rb0, kt + 2 < nk, kt + 4 < nk, kt + 4);
;     __syncthreads();
	ds_read_b128 v[152:155], v98 offset:55296
	ds_read_b128 v[156:159], v98 offset:59904
	ds_read_b128 v[160:163], v97 offset:36864
	ds_read_b128 v[164:167], v97 offset:41472
	v_mfma_f32_32x32x16_bf16 v[0:15], v[116:119], v[100:103], v[0:15]
	v_mfma_f32_32x32x16_bf16 v[32:47], v[116:119], v[108:111], v[32:47]
	v_mfma_f32_32x32x16_bf16 v[48:63], v[124:127], v[100:103], v[48:63]
	v_mfma_f32_32x32x16_bf16 v[16:31], v[124:127], v[108:111], v[16:31]
	global_load_dwordx4 v[100:103], v[80:81], off offset:640
	global_load_dwordx4 v[104:107], v[82:83], off offset:640
	global_load_dwordx4 v[108:111], v[84:85], off offset:640
	global_load_dwordx4 v[112:115], v[86:87], off offset:640
	global_load_dwordx4 v[116:119], v[88:89], off offset:640
	global_load_dwordx4 v[120:123], v[90:91], off offset:640
	global_load_dwordx4 v[124:127], v[92:93], off offset:640
	global_load_dwordx4 v[128:131], v[94:95], off offset:640
	s_waitcnt lgkmcnt(1)
	v_mfma_f32_32x32x16_bf16 v[0:15], v[160:163], v[152:155], v[0:15]
	v_mfma_f32_32x32x16_bf16 v[32:47], v[160:163], v[156:159], v[32:47]
	s_waitcnt lgkmcnt(0)
	v_mfma_f32_32x32x16_bf16 v[48:63], v[164:167], v[152:155], v[48:63]
	ds_read_b128 v[152:155], v98 offset:55328
	ds_read_b128 v[160:163], v98 offset:59936
	ds_read_b128 v[168:171], v97 offset:36896
	ds_read_b128 v[172:175], v97 offset:41504
	v_mfma_f32_32x32x16_bf16 v[16:31], v[164:167], v[156:159], v[16:31]
	s_waitcnt lgkmcnt(1)
	v_mfma_f32_32x32x16_bf16 v[0:15], v[168:171], v[152:155], v[0:15]
	v_mfma_f32_32x32x16_bf16 v[32:47], v[168:171], v[160:163], v[32:47]
	s_waitcnt lgkmcnt(0)
	v_mfma_f32_32x32x16_bf16 v[48:63], v[172:175], v[152:155], v[48:63]
	ds_read_b128 v[152:155], v98 offset:55360
	ds_read_b128 v[156:159], v98 offset:59968
	ds_read_b128 v[164:167], v97 offset:36928
	ds_read_b128 v[168:171], v97 offset:41536
	s_waitcnt vmcnt(15)
	ds_write_b128 v96, v[64:67]
	s_waitcnt vmcnt(13)
	ds_write_b128 v96, v[72:75] offset:4608
	s_waitcnt vmcnt(11)
	ds_write_b128 v96, v[132:135] offset:9216
	s_waitcnt vmcnt(9)
	ds_write_b128 v96, v[140:143] offset:13824
	v_mfma_f32_32x32x16_bf16 v[16:31], v[172:175], v[160:163], v[16:31]
	ds_read_b128 v[64:67], v98 offset:55392
	ds_read_b128 v[72:75], v98 offset:60000
	ds_read_b128 v[132:135], v97 offset:36960
	ds_read_b128 v[140:143], v97 offset:41568
	s_waitcnt lgkmcnt(9)
	v_mfma_f32_32x32x16_bf16 v[0:15], v[164:167], v[152:155], v[0:15]
	ds_write_b128 v96, v[68:71] offset:18432
	ds_write_b128 v96, v[76:79] offset:23040
	ds_write_b128 v96, v[136:139] offset:27648
	s_waitcnt vmcnt(8)
	ds_write_b128 v96, v[148:151] offset:32256
	v_mfma_f32_32x32x16_bf16 v[32:47], v[164:167], v[156:159], v[32:47]
	s_waitcnt lgkmcnt(12)
	v_mfma_f32_32x32x16_bf16 v[48:63], v[168:171], v[152:155], v[48:63]
	v_mfma_f32_32x32x16_bf16 v[16:31], v[168:171], v[156:159], v[16:31]
	s_waitcnt lgkmcnt(0)
	s_barrier
	ds_read_b128 v[152:155], v98 offset:18432
	ds_read_b128 v[156:159], v98 offset:23040
	ds_read_b128 v[160:163], v97
	ds_read_b128 v[164:167], v97 offset:4608
	v_mfma_f32_32x32x16_bf16 v[0:15], v[132:135], v[64:67], v[0:15]
	v_mfma_f32_32x32x16_bf16 v[32:47], v[132:135], v[72:75], v[32:47]
	v_mfma_f32_32x32x16_bf16 v[48:63], v[140:143], v[64:67], v[48:63]
	v_mfma_f32_32x32x16_bf16 v[16:31], v[140:143], v[72:75], v[16:31]
	global_load_dwordx4 v[64:67], v[80:81], off offset:768
	global_load_dwordx4 v[68:71], v[82:83], off offset:768
	global_load_dwordx4 v[72:75], v[84:85], off offset:768
	global_load_dwordx4 v[76:79], v[86:87], off offset:768
	global_load_dwordx4 v[132:135], v[88:89], off offset:768
	global_load_dwordx4 v[136:139], v[90:91], off offset:768
	global_load_dwordx4 v[140:143], v[92:93], off offset:768
	global_load_dwordx4 v[148:151], v[94:95], off offset:768
	s_waitcnt lgkmcnt(1)
	v_mfma_f32_32x32x16_bf16 v[0:15], v[160:163], v[152:155], v[0:15]
	v_mfma_f32_32x32x16_bf16 v[32:47], v[160:163], v[156:159], v[32:47]
	s_waitcnt lgkmcnt(0)
	v_mfma_f32_32x32x16_bf16 v[48:63], v[164:167], v[152:155], v[48:63]
	ds_read_b128 v[152:155], v98 offset:18464
	ds_read_b128 v[160:163], v98 offset:23072
	ds_read_b128 v[168:171], v97 offset:32
	ds_read_b128 v[172:175], v97 offset:4640
	v_mfma_f32_32x32x16_bf16 v[16:31], v[164:167], v[156:159], v[16:31]
	s_waitcnt lgkmcnt(1)
	v_mfma_f32_32x32x16_bf16 v[0:15], v[168:171], v[152:155], v[0:15]
	v_mfma_f32_32x32x16_bf16 v[32:47], v[168:171], v[160:163], v[32:47]
	s_waitcnt lgkmcnt(0)
	v_mfma_f32_32x32x16_bf16 v[48:63], v[172:175], v[152:155], v[48:63]
	ds_read_b128 v[152:155], v98 offset:18496
	ds_read_b128 v[156:159], v98 offset:23104
	ds_read_b128 v[164:167], v97 offset:64
	ds_read_b128 v[168:171], v97 offset:4672
	s_waitcnt vmcnt(15)
	ds_write_b128 v96, v[100:103] offset:36864
	s_waitcnt vmcnt(13)
	ds_write_b128 v96, v[108:111] offset:41472
	s_waitcnt vmcnt(11)
	ds_write_b128 v96, v[116:119] offset:46080
	s_waitcnt vmcnt(9)
	ds_write_b128 v96, v[124:127] offset:50688
	v_mfma_f32_32x32x16_bf16 v[16:31], v[172:175], v[160:163], v[16:31]
	ds_read_b128 v[100:103], v98 offset:18528
	ds_read_b128 v[108:111], v98 offset:23136
	ds_read_b128 v[116:119], v97 offset:96
	ds_read_b128 v[124:127], v97 offset:4704
	s_waitcnt lgkmcnt(9)
	v_mfma_f32_32x32x16_bf16 v[0:15], v[164:167], v[152:155], v[0:15]
	ds_write_b128 v96, v[104:107] offset:55296
	ds_write_b128 v96, v[112:115] offset:59904
	ds_write_b128 v96, v[120:123] offset:64512
	s_waitcnt vmcnt(8)
	ds_write_b128 v99, v[128:131] offset:13824
	v_mfma_f32_32x32x16_bf16 v[32:47], v[164:167], v[156:159], v[32:47]
	s_waitcnt lgkmcnt(12)
	v_mfma_f32_32x32x16_bf16 v[48:63], v[168:171], v[152:155], v[48:63]
	v_mfma_f32_32x32x16_bf16 v[16:31], v[168:171], v[156:159], v[16:31]
	s_waitcnt lgkmcnt(0)
	s_barrier
; template <bool SWAP>
; DI void gemm_tile(const bf16_t* __restrict__ A, int lda, const bf16_t* __restrict__ Bt, int ldb, int K, f32x16 (&acc)[2][2], bf16_t* As, bf16_t* Bs_unused) {
;     ...
;   auto step = [&](int buf, u32x4 (&ra)[4], u32x4 (&rb)[4], bool do_write, bool do_load, int tload) __attribute__((always_inline)) {
;     const bf16_t* pa = As + buf * 2 * GT_IMG + pao; const bf16_t* pb = As + buf * 2 * GT_IMG + pbo;
;     bf16_t* Ad = As + (buf ^ 1) * 2 * GT_IMG; bf16_t* Bd = Ad + GT_IMG;
;     bf16x8 F0[4], F1[4];
;     frag_read(F0, pa, pb, 0);
;     __builtin_amdgcn_sched_barrier(0);
;     frag_read(F1, pa, pb, 16);
;     mfma4(F0);
;     __builtin_amdgcn_sched_barrier(0);
;     frag_read(F0, pa, pb, 32);
;     mfma4(F1);
;     if (do_write) {
; #pragma unroll
;       for (int i = 0; i < 4; ++i) *(u32x4*)(Ad + (lr + 32 * i) * 72 + lc) = ra[i];
;     }
;     __builtin_amdgcn_sched_barrier(0);
;     frag_read(F1, pa, pb, 48);
;     mfma4(F0);
;     if (do_write) {
; #pragma unroll
;       for (int i = 0; i < 4; ++i) *(u32x4*)(Bd + (lr + 32 * i) * 72 + lc) = rb[i];
;     }
;     __builtin_amdgcn_sched_barrier(0);
;     mfma4(F1);
;     if (do_load) load_stage(ra, rb, tload);
;     __builtin_amdgcn_sched_barrier(0);
;   };
;   const int nk = K >> 6;
;   load_stage(ra0, rb0, 0); load_stage(ra1, rb1, 1);
;   __syncthreads();
;   write_stage(ra0, rb0, 0);
;   load_stage(ra0, rb0, 2);
;   __syncthreads();
;   for (int kt = 0; kt < nk; kt += 2) {
;     step(0, ra1, rb1, true, kt + 3 < nk, kt + 3);
;     __syncthreads();
;     step(1, ra0, rb0, kt + 2 < nk, kt + 4 < nk, kt + 4);
;     __syncthreads();
	ds_read_b128 v[152:155], v98 offset:55296
	ds_read_b128 v[156:159], v98 offset:59904
	ds_read_b128 v[160:163], v97 offset:36864
	ds_read_b128 v[164:167], v97 offset:41472
	v_mfma_f32_32x32x16_bf16 v[0:15], v[116:119], v[100:103], v[0:15]
	v_mfma_f32_32x32x16_bf16 v[32:47], v[116:119], v[108:111], v[32:47]
	v_mfma_f32_32x32x16_bf16 v[48:63], v[124:127], v[100:103], v[48:63]
	v_mfma_f32_32x32x16_bf16 v[16:31], v[124:127], v[108:111], v[16:31]
	global_load_dwordx4 v[100:103], v[80:81], off offset:896
	global_load_dwordx4 v[104:107], v[82:83], off offset:896
	global_load_dwordx4 v[108:111], v[84:85], off offset:896
	global_load_dwordx4 v[112:115], v[86:87], off offset:896
	global_load_dwordx4 v[116:119], v[88:89], off offset:896
	global_load_dwordx4 v[120:123], v[90:91], off offset:896
	global_load_dwordx4 v[124:127], v[92:93], off offset:896
	global_load_dwordx4 v[128:131], v[94:95], off offset:896
	s_waitcnt lgkmcnt(1)
	v_mfma_f32_32x32x16_bf16 v[0:15], v[160:163], v[152:155], v[0:15]
	v_mfma_f32_32x32x16_bf16 v[32:47], v[160:163], v[156:159], v[32:47]
	s_waitcnt lgkmcnt(0)
	v_mfma_f32_32x32x16_bf16 v[48:63], v[164:167], v[152:155], v[48:63]
	ds_read_b128 v[152:155], v98 offset:55328
	ds_read_b128 v[160:163], v98 offset:59936
	ds_read_b128 v[168:171], v97 offset:36896
	ds_read_b128 v[172:175], v97 offset:41504
	v_mfma_f32_32x32x16_bf16 v[16:31], v[164:167], v[156:159], v[16:31]
	s_waitcnt lgkmcnt(1)
	v_mfma_f32_32x32x16_bf16 v[0:15], v[168:171], v[152:155], v[0:15]
	v_mfma_f32_32x32x16_bf16 v[32:47], v[168:171], v[160:163], v[32:47]
	s_waitcnt lgkmcnt(0)
	v_mfma_f32_32x32x16_bf16 v[48:63], v[172:175], v[152:155], v[48:63]
	ds_read_b128 v[152:155], v98 offset:55360
	ds_read_b128 v[156:159], v98 offset:59968
	ds_read_b128 v[164:167], v97 offset:36928
	ds_read_b128 v[168:171], v97 offset:41536
	s_waitcnt vmcnt(15)
	ds_write_b128 v96, v[64:67]
	s_waitcnt vmcnt(13)
	ds_write_b128 v96, v[72:75] offset:4608
	s_waitcnt vmcnt(11)
	ds_write_b128 v96, v[132:135] offset:9216
	s_waitcnt vmcnt(9)
	ds_write_b128 v96, v[140:143] offset:13824
	v_mfma_f32_32x32x16_bf16 v[16:31], v[172:175], v[160:163], v[16:31]
	ds_read_b128 v[64:67], v98 offset:55392
	ds_read_b128 v[72:75], v98 offset:60000
	ds_read_b128 v[132:135], v97 offset:36960
	ds_read_b128 v[140:143], v97 offset:41568
	s_waitcnt lgkmcnt(9)
	v_mfma_f32_32x32x16_bf16 v[0:15], v[164:167], v[152:155], v[0:15]
	ds_write_b128 v96, v[68:71] offset:18432
	ds_write_b128 v96, v[76:79] offset:23040
	ds_write_b128 v96, v[136:139] offset:27648
	s_waitcnt vmcnt(8)
	ds_write_b128 v96, v[148:151] offset:32256
	v_mfma_f32_32x32x16_bf16 v[32:47], v[164:167], v[156:159], v[32:47]
	s_waitcnt lgkmcnt(12)
	v_mfma_f32_32x32x16_bf16 v[48:63], v[168:171], v[152:155], v[48:63]
	v_mfma_f32_32x32x16_bf16 v[16:31], v[168:171], v[156:159], v[16:31]
	s_waitcnt lgkmcnt(0)
	s_barrier
	ds_read_b128 v[152:155], v98 offset:18432
	ds_read_b128 v[156:159], v98 offset:23040
	ds_read_b128 v[160:163], v97
	ds_read_b128 v[164:167], v97 offset:4608
	v_mfma_f32_32x32x16_bf16 v[0:15], v[132:135], v[64:67], v[0:15]
	v_mfma_f32_32x32x16_bf16 v[32:47], v[132:135], v[72:75], v[32:47]
	v_mfma_f32_32x32x16_bf16 v[48:63], v[140:143], v[64:67], v[48:63]
	v_mfma_f32_32x32x16_bf16 v[16:31], v[140:143], v[72:75], v[16:31]
	global_load_dwordx4 v[64:67], v[80:81], off offset:1024
	global_load_dwordx4 v[68:71], v[82:83], off offset:1024
	global_load_dwordx4 v[72:75], v[84:85], off offset:1024
	global_load_dwordx4 v[76:79], v[86:87], off offset:1024
	global_load_dwordx4 v[132:135], v[88:89], off offset:1024
	global_load_dwordx4 v[136:139], v[90:91], off offset:1024
	global_load_dwordx4 v[140:143], v[92:93], off offset:1024
	global_load_dwordx4 v[148:151], v[94:95], off offset:1024
	s_waitcnt lgkmcnt(1)
	v_mfma_f32_32x32x16_bf16 v[0:15], v[160:163], v[152:155], v[0:15]
	v_mfma_f32_32x32x16_bf16 v[32:47], v[160:163], v[156:159], v[32:47]
	s_waitcnt lgkmcnt(0)
	v_mfma_f32_32x32x16_bf16 v[48:63], v[164:167], v[152:155], v[48:63]
	ds_read_b128 v[152:155], v98 offset:18464
	ds_read_b128 v[160:163], v98 offset:23072
	ds_read_b128 v[168:171], v97 offset:32
	ds_read_b128 v[172:175], v97 offset:4640
	v_mfma_f32_32x32x16_bf16 v[16:31], v[164:167], v[156:159], v[16:31]
	s_waitcnt lgkmcnt(1)
	v_mfma_f32_32x32x16_bf16 v[0:15], v[168:171], v[152:155], v[0:15]
	v_mfma_f32_32x32x16_bf16 v[32:47], v[168:171], v[160:163], v[32:47]
	s_waitcnt lgkmcnt(0)
	v_mfma_f32_32x32x16_bf16 v[48:63], v[172:175], v[152:155], v[48:63]
	ds_read_b128 v[152:155], v98 offset:18496
	ds_read_b128 v[156:159], v98 offset:23104
	ds_read_b128 v[164:167], v97 offset:64
	ds_read_b128 v[168:171], v97 offset:4672
	s_waitcnt vmcnt(15)
	ds_write_b128 v96, v[100:103] offset:36864
	s_waitcnt vmcnt(13)
	ds_write_b128 v96, v[108:111] offset:41472
	s_waitcnt vmcnt(11)
	ds_write_b128 v96, v[116:119] offset:46080
	s_waitcnt vmcnt(9)
	ds_write_b128 v96, v[124:127] offset:50688
	v_mfma_f32_32x32x16_bf16 v[16:31], v[172:175], v[160:163], v[16:31]
	ds_read_b128 v[100:103], v98 offset:18528
	ds_read_b128 v[108:111], v98 offset:23136
	ds_read_b128 v[116:119], v97 offset:96
	ds_read_b128 v[124:127], v97 offset:4704
	s_waitcnt lgkmcnt(9)
	v_mfma_f32_32x32x16_bf16 v[0:15], v[164:167], v[152:155], v[0:15]
	ds_write_b128 v96, v[104:107] offset:55296
	ds_write_b128 v96, v[112:115] offset:59904
	ds_write_b128 v96, v[120:123] offset:64512
	s_waitcnt vmcnt(8)
	ds_write_b128 v99, v[128:131] offset:13824
	v_mfma_f32_32x32x16_bf16 v[32:47], v[164:167], v[156:159], v[32:47]
	s_waitcnt lgkmcnt(12)
	v_mfma_f32_32x32x16_bf16 v[48:63], v[168:171], v[152:155], v[48:63]
	v_mfma_f32_32x32x16_bf16 v[16:31], v[168:171], v[156:159], v[16:31]
	s_waitcnt lgkmcnt(0)
	s_barrier
; template <bool SWAP>
; DI void gemm_tile(const bf16_t* __restrict__ A, int lda, const bf16_t* __restrict__ Bt, int ldb, int K, f32x16 (&acc)[2][2], bf16_t* As, bf16_t* Bs_unused) {
;     ...
;   auto step = [&](int buf, u32x4 (&ra)[4], u32x4 (&rb)[4], bool do_write, bool do_load, int tload) __attribute__((always_inline)) {
;     const bf16_t* pa = As + buf * 2 * GT_IMG + pao; const bf16_t* pb = As + buf * 2 * GT_IMG + pbo;
;     bf16_t* Ad = As + (buf ^ 1) * 2 * GT_IMG; bf16_t* Bd = Ad + GT_IMG;
;     bf16x8 F0[4], F1[4];
;     frag_read(F0, pa, pb, 0);
;     __builtin_amdgcn_sched_barrier(0);
;     frag_read(F1, pa, pb, 16);
;     mfma4(F0);
;     __builtin_amdgcn_sched_barrier(0);
;     frag_read(F0, pa, pb, 32);
;     mfma4(F1);
;     if (do_write) {
; #pragma unroll
;       for (int i = 0; i < 4; ++i) *(u32x4*)(Ad + (lr + 32 * i) * 72 + lc) = ra[i];
;     }
;     __builtin_amdgcn_sched_barrier(0);
;     frag_read(F1, pa, pb, 48);
;     mfma4(F0);
;     if (do_write) {
; #pragma unroll
;       for (int i = 0; i < 4; ++i) *(u32x4*)(Bd + (lr + 32 * i) * 72 + lc) = rb[i];
;     }
;     __builtin_amdgcn_sched_barrier(0);
;     mfma4(F1);
;     if (do_load) load_stage(ra, rb, tload);
;     __builtin_amdgcn_sched_barrier(0);
;   };
;   const int nk = K >> 6;
;   load_stage(ra0, rb0, 0); load_stage(ra1, rb1, 1);
;   __syncthreads();
;   write_stage(ra0, rb0, 0);
;   load_stage(ra0, rb0, 2);
;   __syncthreads();
;   for (int kt = 0; kt < nk; kt += 2) {
;     step(0, ra1, rb1, true, kt + 3 < nk, kt + 3);
;     __syncthreads();
;     step(1, ra0, rb0, kt + 2 < nk, kt + 4 < nk, kt + 4);
;     __syncthreads();
	ds_read_b128 v[152:155], v98 offset:55296
	ds_read_b128 v[156:159], v98 offset:59904
	ds_read_b128 v[160:163], v97 offset:36864
	ds_read_b128 v[164:167], v97 offset:41472
	v_mfma_f32_32x32x16_bf16 v[0:15], v[116:119], v[100:103], v[0:15]
	v_mfma_f32_32x32x16_bf16 v[32:47], v[116:119], v[108:111], v[32:47]
	v_mfma_f32_32x32x16_bf16 v[48:63], v[124:127], v[100:103], v[48:63]
	v_mfma_f32_32x32x16_bf16 v[16:31], v[124:127], v[108:111], v[16:31]
	global_load_dwordx4 v[100:103], v[80:81], off offset:1152
	global_load_dwordx4 v[104:107], v[82:83], off offset:1152
	global_load_dwordx4 v[108:111], v[84:85], off offset:1152
	global_load_dwordx4 v[112:115], v[86:87], off offset:1152
	global_load_dwordx4 v[116:119], v[88:89], off offset:1152
	global_load_dwordx4 v[120:123], v[90:91], off offset:1152
	global_load_dwordx4 v[124:127], v[92:93], off offset:1152
	global_load_dwordx4 v[128:131], v[94:95], off offset:1152
	s_waitcnt lgkmcnt(1)
	v_mfma_f32_32x32x16_bf16 v[0:15], v[160:163], v[152:155], v[0:15]
	v_mfma_f32_32x32x16_bf16 v[32:47], v[160:163], v[156:159], v[32:47]
	s_waitcnt lgkmcnt(0)
	v_mfma_f32_32x32x16_bf16 v[48:63], v[164:167], v[152:155], v[48:63]
	ds_read_b128 v[152:155], v98 offset:55328
	ds_read_b128 v[160:163], v98 offset:59936
	ds_read_b128 v[168:171], v97 offset:36896
	ds_read_b128 v[172:175], v97 offset:41504
	v_mfma_f32_32x32x16_bf16 v[16:31], v[164:167], v[156:159], v[16:31]
	s_waitcnt lgkmcnt(1)
	v_mfma_f32_32x32x16_bf16 v[0:15], v[168:171], v[152:155], v[0:15]
	v_mfma_f32_32x32x16_bf16 v[32:47], v[168:171], v[160:163], v[32:47]
	s_waitcnt lgkmcnt(0)
	v_mfma_f32_32x32x16_bf16 v[48:63], v[172:175], v[152:155], v[48:63]
	ds_read_b128 v[152:155], v98 offset:55360
	ds_read_b128 v[156:159], v98 offset:59968
	ds_read_b128 v[164:167], v97 offset:36928
	ds_read_b128 v[168:171], v97 offset:41536
	s_waitcnt vmcnt(15)
	ds_write_b128 v96, v[64:67]
	s_waitcnt vmcnt(13)
	ds_write_b128 v96, v[72:75] offset:4608
	s_waitcnt vmcnt(11)
	ds_write_b128 v96, v[132:135] offset:9216
	s_waitcnt vmcnt(9)
	ds_write_b128 v96, v[140:143] offset:13824
	v_mfma_f32_32x32x16_bf16 v[16:31], v[172:175], v[160:163], v[16:31]
	ds_read_b128 v[64:67], v98 offset:55392
	ds_read_b128 v[72:75], v98 offset:60000
	ds_read_b128 v[132:135], v97 offset:36960
	ds_read_b128 v[140:143], v97 offset:41568
	s_waitcnt lgkmcnt(9)
	v_mfma_f32_32x32x16_bf16 v[0:15], v[164:167], v[152:155], v[0:15]
	ds_write_b128 v96, v[68:71] offset:18432
	ds_write_b128 v96, v[76:79] offset:23040
	ds_write_b128 v96, v[136:139] offset:27648
	s_waitcnt vmcnt(8)
	ds_write_b128 v96, v[148:151] offset:32256
	v_mfma_f32_32x32x16_bf16 v[32:47], v[164:167], v[156:159], v[32:47]
	s_waitcnt lgkmcnt(12)
	v_mfma_f32_32x32x16_bf16 v[48:63], v[168:171], v[152:155], v[48:63]
	v_mfma_f32_32x32x16_bf16 v[16:31], v[168:171], v[156:159], v[16:31]
	s_waitcnt lgkmcnt(0)
	s_barrier
	ds_read_b128 v[152:155], v98 offset:18432
	ds_read_b128 v[156:159], v98 offset:23040
	ds_read_b128 v[160:163], v97
	ds_read_b128 v[164:167], v97 offset:4608
	v_mfma_f32_32x32x16_bf16 v[0:15], v[132:135], v[64:67], v[0:15]
	v_mfma_f32_32x32x16_bf16 v[32:47], v[132:135], v[72:75], v[32:47]
	v_mfma_f32_32x32x16_bf16 v[48:63], v[140:143], v[64:67], v[48:63]
	v_mfma_f32_32x32x16_bf16 v[16:31], v[140:143], v[72:75], v[16:31]
	global_load_dwordx4 v[64:67], v[80:81], off offset:1280
	global_load_dwordx4 v[68:71], v[82:83], off offset:1280
	global_load_dwordx4 v[72:75], v[84:85], off offset:1280
	global_load_dwordx4 v[76:79], v[86:87], off offset:1280
	global_load_dwordx4 v[132:135], v[88:89], off offset:1280
	global_load_dwordx4 v[136:139], v[90:91], off offset:1280
	global_load_dwordx4 v[140:143], v[92:93], off offset:1280
	global_load_dwordx4 v[148:151], v[94:95], off offset:1280
	s_waitcnt lgkmcnt(1)
	v_mfma_f32_32x32x16_bf16 v[0:15], v[160:163], v[152:155], v[0:15]
	v_mfma_f32_32x32x16_bf16 v[32:47], v[160:163], v[156:159], v[32:47]
	s_waitcnt lgkmcnt(0)
	v_mfma_f32_32x32x16_bf16 v[48:63], v[164:167], v[152:155], v[48:63]
	ds_read_b128 v[152:155], v98 offset:18464
	ds_read_b128 v[160:163], v98 offset:23072
	ds_read_b128 v[168:171], v97 offset:32
	ds_read_b128 v[172:175], v97 offset:4640
	v_mfma_f32_32x32x16_bf16 v[16:31], v[164:167], v[156:159], v[16:31]
	s_waitcnt lgkmcnt(1)
	v_mfma_f32_32x32x16_bf16 v[0:15], v[168:171], v[152:155], v[0:15]
	v_mfma_f32_32x32x16_bf16 v[32:47], v[168:171], v[160:163], v[32:47]
	s_waitcnt lgkmcnt(0)
	v_mfma_f32_32x32x16_bf16 v[48:63], v[172:175], v[152:155], v[48:63]
	ds_read_b128 v[152:155], v98 offset:18496
	ds_read_b128 v[156:159], v98 offset:23104
	ds_read_b128 v[164:167], v97 offset:64
	ds_read_b128 v[168:171], v97 offset:4672
	s_waitcnt vmcnt(15)
	ds_write_b128 v96, v[100:103] offset:36864
	s_waitcnt vmcnt(13)
	ds_write_b128 v96, v[108:111] offset:41472
	s_waitcnt vmcnt(11)
	ds_write_b128 v96, v[116:119] offset:46080
	s_waitcnt vmcnt(9)
	ds_write_b128 v96, v[124:127] offset:50688
	v_mfma_f32_32x32x16_bf16 v[16:31], v[172:175], v[160:163], v[16:31]
	ds_read_b128 v[100:103], v98 offset:18528
	ds_read_b128 v[108:111], v98 offset:23136
	ds_read_b128 v[116:119], v97 offset:96
	ds_read_b128 v[124:127], v97 offset:4704
	s_waitcnt lgkmcnt(9)
	v_mfma_f32_32x32x16_bf16 v[0:15], v[164:167], v[152:155], v[0:15]
	ds_write_b128 v96, v[104:107] offset:55296
	ds_write_b128 v96, v[112:115] offset:59904
	ds_write_b128 v96, v[120:123] offset:64512
	s_waitcnt vmcnt(8)
	ds_write_b128 v99, v[128:131] offset:13824
	v_mfma_f32_32x32x16_bf16 v[32:47], v[164:167], v[156:159], v[32:47]
	s_waitcnt lgkmcnt(12)
	v_mfma_f32_32x32x16_bf16 v[48:63], v[168:171], v[152:155], v[48:63]
	v_mfma_f32_32x32x16_bf16 v[16:31], v[168:171], v[156:159], v[16:31]
	s_waitcnt lgkmcnt(0)
	s_barrier
; template <bool SWAP>
; DI void gemm_tile(const bf16_t* __restrict__ A, int lda, const bf16_t* __restrict__ Bt, int ldb, int K, f32x16 (&acc)[2][2], bf16_t* As, bf16_t* Bs_unused) {
;     ...
;   auto step = [&](int buf, u32x4 (&ra)[4], u32x4 (&rb)[4], bool do_write, bool do_load, int tload) __attribute__((always_inline)) {
;     const bf16_t* pa = As + buf * 2 * GT_IMG + pao; const bf16_t* pb = As + buf * 2 * GT_IMG + pbo;
;     bf16_t* Ad = As + (buf ^ 1) * 2 * GT_IMG; bf16_t* Bd = Ad + GT_IMG;
;     bf16x8 F0[4], F1[4];
;     frag_read(F0, pa, pb, 0);
;     __builtin_amdgcn_sched_barrier(0);
;     frag_read(F1, pa, pb, 16);
;     mfma4(F0);
;     __builtin_amdgcn_sched_barrier(0);
;     frag_read(F0, pa, pb, 32);
;     mfma4(F1);
;     if (do_write) {
; #pragma unroll
;       for (int i = 0; i < 4; ++i) *(u32x4*)(Ad + (lr + 32 * i) * 72 + lc) = ra[i];
;     }
;     __builtin_amdgcn_sched_barrier(0);
;     frag_read(F1, pa, pb, 48);
;     mfma4(F0);
;     if (do_write) {
; #pragma unroll
;       for (int i = 0; i < 4; ++i) *(u32x4*)(Bd + (lr + 32 * i) * 72 + lc) = rb[i];
;     }
;     __builtin_amdgcn_sched_barrier(0);
;     mfma4(F1);
;     if (do_load) load_stage(ra, rb, tload);
;     __builtin_amdgcn_sched_barrier(0);
;   };
;   const int nk = K >> 6;
;   load_stage(ra0, rb0, 0); load_stage(ra1, rb1, 1);
;   __syncthreads();
;   write_stage(ra0, rb0, 0);
;   load_stage(ra0, rb0, 2);
;   __syncthreads();
;   for (int kt = 0; kt < nk; kt += 2) {
;     step(0, ra1, rb1, true, kt + 3 < nk, kt + 3);
;     __syncthreads();
;     step(1, ra0, rb0, kt + 2 < nk, kt + 4 < nk, kt + 4);
;     __syncthreads();
	ds_read_b128 v[152:155], v98 offset:55296
	ds_read_b128 v[156:159], v98 offset:59904
	ds_read_b128 v[160:163], v97 offset:36864
	ds_read_b128 v[164:167], v97 offset:41472
	v_mfma_f32_32x32x16_bf16 v[0:15], v[116:119], v[100:103], v[0:15]
	v_mfma_f32_32x32x16_bf16 v[32:47], v[116:119], v[108:111], v[32:47]
	v_mfma_f32_32x32x16_bf16 v[48:63], v[124:127], v[100:103], v[48:63]
	v_mfma_f32_32x32x16_bf16 v[16:31], v[124:127], v[108:111], v[16:31]
	global_load_dwordx4 v[100:103], v[80:81], off offset:1408
	global_load_dwordx4 v[104:107], v[82:83], off offset:1408
	global_load_dwordx4 v[108:111], v[84:85], off offset:1408
	global_load_dwordx4 v[112:115], v[86:87], off offset:1408
	global_load_dwordx4 v[116:119], v[88:89], off offset:1408
	global_load_dwordx4 v[120:123], v[90:91], off offset:1408
	global_load_dwordx4 v[124:127], v[92:93], off offset:1408
	global_load_dwordx4 v[128:131], v[94:95], off offset:1408
	s_waitcnt lgkmcnt(1)
	v_mfma_f32_32x32x16_bf16 v[0:15], v[160:163], v[152:155], v[0:15]
	v_mfma_f32_32x32x16_bf16 v[32:47], v[160:163], v[156:159], v[32:47]
	s_waitcnt lgkmcnt(0)
	v_mfma_f32_32x32x16_bf16 v[48:63], v[164:167], v[152:155], v[48:63]
	ds_read_b128 v[152:155], v98 offset:55328
	ds_read_b128 v[160:163], v98 offset:59936
	ds_read_b128 v[168:171], v97 offset:36896
	ds_read_b128 v[172:175], v97 offset:41504
	v_mfma_f32_32x32x16_bf16 v[16:31], v[164:167], v[156:159], v[16:31]
	s_waitcnt lgkmcnt(1)
	v_mfma_f32_32x32x16_bf16 v[0:15], v[168:171], v[152:155], v[0:15]
	v_mfma_f32_32x32x16_bf16 v[32:47], v[168:171], v[160:163], v[32:47]
	s_waitcnt lgkmcnt(0)
	v_mfma_f32_32x32x16_bf16 v[48:63], v[172:175], v[152:155], v[48:63]
	ds_read_b128 v[152:155], v98 offset:55360
	ds_read_b128 v[156:159], v98 offset:59968
	ds_read_b128 v[164:167], v97 offset:36928
	ds_read_b128 v[168:171], v97 offset:41536
	s_waitcnt vmcnt(15)
	ds_write_b128 v96, v[64:67]
	s_waitcnt vmcnt(13)
	ds_write_b128 v96, v[72:75] offset:4608
	s_waitcnt vmcnt(11)
	ds_write_b128 v96, v[132:135] offset:9216
	s_waitcnt vmcnt(9)
	ds_write_b128 v96, v[140:143] offset:13824
	v_mfma_f32_32x32x16_bf16 v[16:31], v[172:175], v[160:163], v[16:31]
	ds_read_b128 v[64:67], v98 offset:55392
	ds_read_b128 v[72:75], v98 offset:60000
	ds_read_b128 v[132:135], v97 offset:36960
	ds_read_b128 v[140:143], v97 offset:41568
	s_waitcnt lgkmcnt(9)
	v_mfma_f32_32x32x16_bf16 v[0:15], v[164:167], v[152:155], v[0:15]
	ds_write_b128 v96, v[68:71] offset:18432
	ds_write_b128 v96, v[76:79] offset:23040
	ds_write_b128 v96, v[136:139] offset:27648
	s_waitcnt vmcnt(8)
	ds_write_b128 v96, v[148:151] offset:32256
	v_mfma_f32_32x32x16_bf16 v[32:47], v[164:167], v[156:159], v[32:47]
	s_waitcnt lgkmcnt(12)
	v_mfma_f32_32x32x16_bf16 v[48:63], v[168:171], v[152:155], v[48:63]
	v_mfma_f32_32x32x16_bf16 v[16:31], v[168:171], v[156:159], v[16:31]
	s_waitcnt lgkmcnt(0)
	s_barrier
	ds_read_b128 v[152:155], v98 offset:18432
	ds_read_b128 v[156:159], v98 offset:23040
	ds_read_b128 v[160:163], v97
	ds_read_b128 v[164:167], v97 offset:4608
	v_mfma_f32_32x32x16_bf16 v[0:15], v[132:135], v[64:67], v[0:15]
	v_mfma_f32_32x32x16_bf16 v[32:47], v[132:135], v[72:75], v[32:47]
	v_mfma_f32_32x32x16_bf16 v[48:63], v[140:143], v[64:67], v[48:63]
	v_mfma_f32_32x32x16_bf16 v[16:31], v[140:143], v[72:75], v[16:31]
	global_load_dwordx4 v[64:67], v[80:81], off offset:1536
	global_load_dwordx4 v[68:71], v[82:83], off offset:1536
	global_load_dwordx4 v[72:75], v[84:85], off offset:1536
	global_load_dwordx4 v[76:79], v[86:87], off offset:1536
	global_load_dwordx4 v[132:135], v[88:89], off offset:1536
	global_load_dwordx4 v[136:139], v[90:91], off offset:1536
	global_load_dwordx4 v[140:143], v[92:93], off offset:1536
	global_load_dwordx4 v[148:151], v[94:95], off offset:1536
	s_waitcnt lgkmcnt(1)
	v_mfma_f32_32x32x16_bf16 v[0:15], v[160:163], v[152:155], v[0:15]
	v_mfma_f32_32x32x16_bf16 v[32:47], v[160:163], v[156:159], v[32:47]
	s_waitcnt lgkmcnt(0)
	v_mfma_f32_32x32x16_bf16 v[48:63], v[164:167], v[152:155], v[48:63]
	ds_read_b128 v[152:155], v98 offset:18464
	ds_read_b128 v[160:163], v98 offset:23072
	ds_read_b128 v[168:171], v97 offset:32
	ds_read_b128 v[172:175], v97 offset:4640
	v_mfma_f32_32x32x16_bf16 v[16:31], v[164:167], v[156:159], v[16:31]
	s_waitcnt lgkmcnt(1)
	v_mfma_f32_32x32x16_bf16 v[0:15], v[168:171], v[152:155], v[0:15]
	v_mfma_f32_32x32x16_bf16 v[32:47], v[168:171], v[160:163], v[32:47]
	s_waitcnt lgkmcnt(0)
	v_mfma_f32_32x32x16_bf16 v[48:63], v[172:175], v[152:155], v[48:63]
	ds_read_b128 v[152:155], v98 offset:18496
	ds_read_b128 v[156:159], v98 offset:23104
	ds_read_b128 v[164:167], v97 offset:64
	ds_read_b128 v[168:171], v97 offset:4672
	s_waitcnt vmcnt(15)
	ds_write_b128 v96, v[100:103] offset:36864
	s_waitcnt vmcnt(13)
	ds_write_b128 v96, v[108:111] offset:41472
	s_waitcnt vmcnt(11)
	ds_write_b128 v96, v[116:119] offset:46080
	s_waitcnt vmcnt(9)
	ds_write_b128 v96, v[124:127] offset:50688
	v_mfma_f32_32x32x16_bf16 v[16:31], v[172:175], v[160:163], v[16:31]
	ds_read_b128 v[100:103], v98 offset:18528
	ds_read_b128 v[108:111], v98 offset:23136
	ds_read_b128 v[116:119], v97 offset:96
	ds_read_b128 v[124:127], v97 offset:4704
	s_waitcnt lgkmcnt(9)
	v_mfma_f32_32x32x16_bf16 v[0:15], v[164:167], v[152:155], v[0:15]
	ds_write_b128 v96, v[104:107] offset:55296
	ds_write_b128 v96, v[112:115] offset:59904
	ds_write_b128 v96, v[120:123] offset:64512
	s_waitcnt vmcnt(8)
	ds_write_b128 v99, v[128:131] offset:13824
	v_mfma_f32_32x32x16_bf16 v[32:47], v[164:167], v[156:159], v[32:47]
	s_waitcnt lgkmcnt(12)
	v_mfma_f32_32x32x16_bf16 v[48:63], v[168:171], v[152:155], v[48:63]
	v_mfma_f32_32x32x16_bf16 v[16:31], v[168:171], v[156:159], v[16:31]
	s_waitcnt lgkmcnt(0)
	s_barrier
; template <bool SWAP>
; DI void gemm_tile(const bf16_t* __restrict__ A, int lda, const bf16_t* __restrict__ Bt, int ldb, int K, f32x16 (&acc)[2][2], bf16_t* As, bf16_t* Bs_unused) {
;     ...
;   auto step = [&](int buf, u32x4 (&ra)[4], u32x4 (&rb)[4], bool do_write, bool do_load, int tload) __attribute__((always_inline)) {
;     const bf16_t* pa = As + buf * 2 * GT_IMG + pao; const bf16_t* pb = As + buf * 2 * GT_IMG + pbo;
;     bf16_t* Ad = As + (buf ^ 1) * 2 * GT_IMG; bf16_t* Bd = Ad + GT_IMG;
;     bf16x8 F0[4], F1[4];
;     frag_read(F0, pa, pb, 0);
;     __builtin_amdgcn_sched_barrier(0);
;     frag_read(F1, pa, pb, 16);
;     mfma4(F0);
;     __builtin_amdgcn_sched_barrier(0);
;     frag_read(F0, pa, pb, 32);
;     mfma4(F1);
;     if (do_write) {
; #pragma unroll
;       for (int i = 0; i < 4; ++i) *(u32x4*)(Ad + (lr + 32 * i) * 72 + lc) = ra[i];
;     }
;     __builtin_amdgcn_sched_barrier(0);
;     frag_read(F1, pa, pb, 48);
;     mfma4(F0);
;     if (do_write) {
; #pragma unroll
;       for (int i = 0; i < 4; ++i) *(u32x4*)(Bd + (lr + 32 * i) * 72 + lc) = rb[i];
;     }
;     __builtin_amdgcn_sched_barrier(0);
;     mfma4(F1);
;     if (do_load) load_stage(ra, rb, tload);
;     __builtin_amdgcn_sched_barrier(0);
;   };
;   const int nk = K >> 6;
;   load_stage(ra0, rb0, 0); load_stage(ra1, rb1, 1);
;   __syncthreads();
;   write_stage(ra0, rb0, 0);
;   load_stage(ra0, rb0, 2);
;   __syncthreads();
;   for (int kt = 0; kt < nk; kt += 2) {
;     step(0, ra1, rb1, true, kt + 3 < nk, kt + 3);
;     __syncthreads();
;     step(1, ra0, rb0, kt + 2 < nk, kt + 4 < nk, kt + 4);
;     __syncthreads();
	ds_read_b128 v[152:155], v98 offset:55296
	ds_read_b128 v[156:159], v98 offset:59904
	ds_read_b128 v[160:163], v97 offset:36864
	ds_read_b128 v[164:167], v97 offset:41472
	v_mfma_f32_32x32x16_bf16 v[0:15], v[116:119], v[100:103], v[0:15]
	v_mfma_f32_32x32x16_bf16 v[32:47], v[116:119], v[108:111], v[32:47]
	v_mfma_f32_32x32x16_bf16 v[48:63], v[124:127], v[100:103], v[48:63]
	v_mfma_f32_32x32x16_bf16 v[16:31], v[124:127], v[108:111], v[16:31]
	global_load_dwordx4 v[100:103], v[80:81], off offset:1664
	global_load_dwordx4 v[104:107], v[82:83], off offset:1664
	global_load_dwordx4 v[108:111], v[84:85], off offset:1664
	global_load_dwordx4 v[112:115], v[86:87], off offset:1664
	global_load_dwordx4 v[116:119], v[88:89], off offset:1664
	global_load_dwordx4 v[120:123], v[90:91], off offset:1664
	global_load_dwordx4 v[124:127], v[92:93], off offset:1664
	global_load_dwordx4 v[128:131], v[94:95], off offset:1664
	s_waitcnt lgkmcnt(1)
	v_mfma_f32_32x32x16_bf16 v[0:15], v[160:163], v[152:155], v[0:15]
	v_mfma_f32_32x32x16_bf16 v[32:47], v[160:163], v[156:159], v[32:47]
	s_waitcnt lgkmcnt(0)
	v_mfma_f32_32x32x16_bf16 v[48:63], v[164:167], v[152:155], v[48:63]
	ds_read_b128 v[152:155], v98 offset:55328
	ds_read_b128 v[160:163], v98 offset:59936
	ds_read_b128 v[168:171], v97 offset:36896
	ds_read_b128 v[172:175], v97 offset:41504
	v_mfma_f32_32x32x16_bf16 v[16:31], v[164:167], v[156:159], v[16:31]
	s_waitcnt lgkmcnt(1)
	v_mfma_f32_32x32x16_bf16 v[0:15], v[168:171], v[152:155], v[0:15]
	v_mfma_f32_32x32x16_bf16 v[32:47], v[168:171], v[160:163], v[32:47]
	s_waitcnt lgkmcnt(0)
	v_mfma_f32_32x32x16_bf16 v[48:63], v[172:175], v[152:155], v[48:63]
	ds_read_b128 v[152:155], v98 offset:55360
	ds_read_b128 v[156:159], v98 offset:59968
	ds_read_b128 v[164:167], v97 offset:36928
	ds_read_b128 v[168:171], v97 offset:41536
	s_waitcnt vmcnt(15)
	ds_write_b128 v96, v[64:67]
	s_waitcnt vmcnt(13)
	ds_write_b128 v96, v[72:75] offset:4608
	s_waitcnt vmcnt(11)
	ds_write_b128 v96, v[132:135] offset:9216
	s_waitcnt vmcnt(9)
	ds_write_b128 v96, v[140:143] offset:13824
	v_mfma_f32_32x32x16_bf16 v[16:31], v[172:175], v[160:163], v[16:31]
	ds_read_b128 v[64:67], v98 offset:55392
	ds_read_b128 v[72:75], v98 offset:60000
	ds_read_b128 v[132:135], v97 offset:36960
	ds_read_b128 v[140:143], v97 offset:41568
	s_waitcnt lgkmcnt(9)
	v_mfma_f32_32x32x16_bf16 v[0:15], v[164:167], v[152:155], v[0:15]
	ds_write_b128 v96, v[68:71] offset:18432
	ds_write_b128 v96, v[76:79] offset:23040
	ds_write_b128 v96, v[136:139] offset:27648
	s_waitcnt vmcnt(8)
	ds_write_b128 v96, v[148:151] offset:32256
	v_mfma_f32_32x32x16_bf16 v[32:47], v[164:167], v[156:159], v[32:47]
	s_waitcnt lgkmcnt(12)
	v_mfma_f32_32x32x16_bf16 v[48:63], v[168:171], v[152:155], v[48:63]
	v_mfma_f32_32x32x16_bf16 v[16:31], v[168:171], v[156:159], v[16:31]
	s_waitcnt lgkmcnt(0)
	s_barrier
	ds_read_b128 v[152:155], v98 offset:18432
	ds_read_b128 v[156:159], v98 offset:23040
	ds_read_b128 v[160:163], v97
	ds_read_b128 v[164:167], v97 offset:4608
	v_mfma_f32_32x32x16_bf16 v[0:15], v[132:135], v[64:67], v[0:15]
	v_mfma_f32_32x32x16_bf16 v[32:47], v[132:135], v[72:75], v[32:47]
	v_mfma_f32_32x32x16_bf16 v[48:63], v[140:143], v[64:67], v[48:63]
	v_mfma_f32_32x32x16_bf16 v[16:31], v[140:143], v[72:75], v[16:31]
	global_load_dwordx4 v[64:67], v[80:81], off offset:1792
	global_load_dwordx4 v[68:71], v[82:83], off offset:1792
	global_load_dwordx4 v[72:75], v[84:85], off offset:1792
	global_load_dwordx4 v[76:79], v[86:87], off offset:1792
	global_load_dwordx4 v[132:135], v[88:89], off offset:1792
	global_load_dwordx4 v[136:139], v[90:91], off offset:1792
	global_load_dwordx4 v[140:143], v[92:93], off offset:1792
	global_load_dwordx4 v[148:151], v[94:95], off offset:1792
	s_waitcnt lgkmcnt(1)
	v_mfma_f32_32x32x16_bf16 v[0:15], v[160:163], v[152:155], v[0:15]
	v_mfma_f32_32x32x16_bf16 v[32:47], v[160:163], v[156:159], v[32:47]
	s_waitcnt lgkmcnt(0)
	v_mfma_f32_32x32x16_bf16 v[48:63], v[164:167], v[152:155], v[48:63]
	ds_read_b128 v[152:155], v98 offset:18464
	ds_read_b128 v[160:163], v98 offset:23072
	ds_read_b128 v[168:171], v97 offset:32
	ds_read_b128 v[172:175], v97 offset:4640
	v_mfma_f32_32x32x16_bf16 v[16:31], v[164:167], v[156:159], v[16:31]
	s_waitcnt lgkmcnt(1)
	v_mfma_f32_32x32x16_bf16 v[0:15], v[168:171], v[152:155], v[0:15]
	v_mfma_f32_32x32x16_bf16 v[32:47], v[168:171], v[160:163], v[32:47]
	s_waitcnt lgkmcnt(0)
	v_mfma_f32_32x32x16_bf16 v[48:63], v[172:175], v[152:155], v[48:63]
	ds_read_b128 v[152:155], v98 offset:18496
	ds_read_b128 v[156:159], v98 offset:23104
	ds_read_b128 v[164:167], v97 offset:64
	ds_read_b128 v[168:171], v97 offset:4672
	s_waitcnt vmcnt(15)
	ds_write_b128 v96, v[100:103] offset:36864
	s_waitcnt vmcnt(13)
	ds_write_b128 v96, v[108:111] offset:41472
	s_waitcnt vmcnt(11)
	ds_write_b128 v96, v[116:119] offset:46080
	s_waitcnt vmcnt(9)
	ds_write_b128 v96, v[124:127] offset:50688
	v_mfma_f32_32x32x16_bf16 v[16:31], v[172:175], v[160:163], v[16:31]
	ds_read_b128 v[100:103], v98 offset:18528
	ds_read_b128 v[108:111], v98 offset:23136
	ds_read_b128 v[116:119], v97 offset:96
	ds_read_b128 v[124:127], v97 offset:4704
	s_waitcnt lgkmcnt(9)
	v_mfma_f32_32x32x16_bf16 v[0:15], v[164:167], v[152:155], v[0:15]
	ds_write_b128 v96, v[104:107] offset:55296
	ds_write_b128 v96, v[112:115] offset:59904
	ds_write_b128 v96, v[120:123] offset:64512
	s_waitcnt vmcnt(8)
	ds_write_b128 v99, v[128:131] offset:13824
	v_mfma_f32_32x32x16_bf16 v[32:47], v[164:167], v[156:159], v[32:47]
	s_waitcnt lgkmcnt(12)
	v_mfma_f32_32x32x16_bf16 v[48:63], v[168:171], v[152:155], v[48:63]
	v_mfma_f32_32x32x16_bf16 v[16:31], v[168:171], v[156:159], v[16:31]
	s_waitcnt lgkmcnt(5)
	v_mfma_f32_32x32x16_bf16 v[0:15], v[116:119], v[100:103], v[0:15]
	v_mfma_f32_32x32x16_bf16 v[32:47], v[116:119], v[108:111], v[32:47]
	s_waitcnt lgkmcnt(4)
	v_mfma_f32_32x32x16_bf16 v[48:63], v[124:127], v[100:103], v[48:63]
	v_mfma_f32_32x32x16_bf16 v[16:31], v[124:127], v[108:111], v[16:31]
	global_load_dwordx4 v[100:103], v[80:81], off offset:1920
	s_nop 0
	global_load_dwordx4 v[80:83], v[82:83], off offset:1920
	s_nop 0
	global_load_dwordx4 v[104:107], v[84:85], off offset:1920
	s_nop 0
	global_load_dwordx4 v[84:87], v[86:87], off offset:1920
	s_nop 0
	global_load_dwordx4 v[108:111], v[88:89], off offset:1920
	s_nop 0
	global_load_dwordx4 v[88:91], v[90:91], off offset:1920
	s_nop 0
	global_load_dwordx4 v[112:115], v[92:93], off offset:1920
	s_nop 0
	global_load_dwordx4 v[92:95], v[94:95], off offset:1920
	s_waitcnt lgkmcnt(0)
	s_barrier
; template <bool SWAP>
; DI void gemm_tile(const bf16_t* __restrict__ A, int lda, const bf16_t* __restrict__ Bt, int ldb, int K, f32x16 (&acc)[2][2], bf16_t* As, bf16_t* Bs_unused) {
;     ...
;   auto step = [&](int buf, u32x4 (&ra)[4], u32x4 (&rb)[4], bool do_write, bool do_load, int tload) __attribute__((always_inline)) {
;     const bf16_t* pa = As + buf * 2 * GT_IMG + pao; const bf16_t* pb = As + buf * 2 * GT_IMG + pbo;
;     bf16_t* Ad = As + (buf ^ 1) * 2 * GT_IMG; bf16_t* Bd = Ad + GT_IMG;
;     bf16x8 F0[4], F1[4];
;     frag_read(F0, pa, pb, 0);
;     __builtin_amdgcn_sched_barrier(0);
;     frag_read(F1, pa, pb, 16);
;     mfma4(F0);
;     __builtin_amdgcn_sched_barrier(0);
;     frag_read(F0, pa, pb, 32);
;     mfma4(F1);
;     if (do_write) {
; #pragma unroll
;       for (int i = 0; i < 4; ++i) *(u32x4*)(Ad + (lr + 32 * i) * 72 + lc) = ra[i];
;     }
;     __builtin_amdgcn_sched_barrier(0);
;     frag_read(F1, pa, pb, 48);
;     mfma4(F0);
;     if (do_write) {
; #pragma unroll
;       for (int i = 0; i < 4; ++i) *(u32x4*)(Bd + (lr + 32 * i) * 72 + lc) = rb[i];
;     }
;     __builtin_amdgcn_sched_barrier(0);
;     mfma4(F1);
;     if (do_load) load_stage(ra, rb, tload);
;     __builtin_amdgcn_sched_barrier(0);
;   };
;   const int nk = K >> 6;
;   load_stage(ra0, rb0, 0); load_stage(ra1, rb1, 1);
;   __syncthreads();
;   write_stage(ra0, rb0, 0);
;   load_stage(ra0, rb0, 2);
;   __syncthreads();
;   for (int kt = 0; kt < nk; kt += 2) {
;     step(0, ra1, rb1, true, kt + 3 < nk, kt + 3);
;     __syncthreads();
;     step(1, ra0, rb0, kt + 2 < nk, kt + 4 < nk, kt + 4);
;     __syncthreads();
	ds_read_b128 v[116:119], v98 offset:55296
	ds_read_b128 v[120:123], v98 offset:59904
	ds_read_b128 v[124:127], v97 offset:36864
	ds_read_b128 v[128:131], v97 offset:41472
	s_waitcnt lgkmcnt(1)
	v_mfma_f32_32x32x16_bf16 v[0:15], v[124:127], v[116:119], v[0:15]
	v_mfma_f32_32x32x16_bf16 v[32:47], v[124:127], v[120:123], v[32:47]
	s_waitcnt lgkmcnt(0)
	v_mfma_f32_32x32x16_bf16 v[48:63], v[128:131], v[116:119], v[48:63]
	ds_read_b128 v[116:119], v98 offset:55328
	ds_read_b128 v[124:127], v98 offset:59936
	ds_read_b128 v[152:155], v97 offset:36896
	ds_read_b128 v[156:159], v97 offset:41504
	v_mfma_f32_32x32x16_bf16 v[16:31], v[128:131], v[120:123], v[16:31]
	s_waitcnt lgkmcnt(1)
	v_mfma_f32_32x32x16_bf16 v[0:15], v[152:155], v[116:119], v[0:15]
	v_mfma_f32_32x32x16_bf16 v[32:47], v[152:155], v[124:127], v[32:47]
	s_waitcnt lgkmcnt(0)
	v_mfma_f32_32x32x16_bf16 v[48:63], v[156:159], v[116:119], v[48:63]
	ds_read_b128 v[116:119], v98 offset:55360
	ds_read_b128 v[120:123], v98 offset:59968
	ds_read_b128 v[128:131], v97 offset:36928
	ds_read_b128 v[152:155], v97 offset:41536
	s_waitcnt vmcnt(15)
	ds_write_b128 v96, v[64:67]
	s_waitcnt vmcnt(13)
	ds_write_b128 v96, v[72:75] offset:4608
	s_waitcnt vmcnt(11)
	ds_write_b128 v96, v[132:135] offset:9216
	s_waitcnt vmcnt(9)
	ds_write_b128 v96, v[140:143] offset:13824
	v_mfma_f32_32x32x16_bf16 v[16:31], v[156:159], v[124:127], v[16:31]
	s_waitcnt lgkmcnt(5)
	v_mfma_f32_32x32x16_bf16 v[0:15], v[128:131], v[116:119], v[0:15]
	s_waitcnt lgkmcnt(4)
	v_mfma_f32_32x32x16_bf16 v[48:63], v[152:155], v[116:119], v[48:63]
	ds_read_b128 v[64:67], v98 offset:55392
	ds_read_b128 v[72:75], v98 offset:60000
	ds_read_b128 v[116:119], v97 offset:36960
	ds_read_b128 v[124:127], v97 offset:41568
	ds_write_b128 v96, v[68:71] offset:18432
	ds_write_b128 v96, v[76:79] offset:23040
	ds_write_b128 v96, v[136:139] offset:27648
	s_waitcnt vmcnt(8)
	ds_write_b128 v96, v[148:151] offset:32256
	v_mfma_f32_32x32x16_bf16 v[32:47], v[128:131], v[120:123], v[32:47]
	v_mfma_f32_32x32x16_bf16 v[16:31], v[152:155], v[120:123], v[16:31]
	s_waitcnt lgkmcnt(5)
	v_mfma_f32_32x32x16_bf16 v[0:15], v[116:119], v[64:67], v[0:15]
	v_mfma_f32_32x32x16_bf16 v[32:47], v[116:119], v[72:75], v[32:47]
	s_waitcnt lgkmcnt(4)
	v_mfma_f32_32x32x16_bf16 v[48:63], v[124:127], v[64:67], v[48:63]
	v_mfma_f32_32x32x16_bf16 v[16:31], v[124:127], v[72:75], v[16:31]
	s_waitcnt lgkmcnt(0)
	s_barrier
	ds_read_b128 v[64:67], v98 offset:18432
	ds_read_b128 v[68:71], v98 offset:23040
	ds_read_b128 v[72:75], v97
	ds_read_b128 v[76:79], v97 offset:4608
	s_waitcnt lgkmcnt(1)
	v_mfma_f32_32x32x16_bf16 v[0:15], v[72:75], v[64:67], v[0:15]
	v_mfma_f32_32x32x16_bf16 v[32:47], v[72:75], v[68:71], v[32:47]
	s_waitcnt lgkmcnt(0)
	v_mfma_f32_32x32x16_bf16 v[48:63], v[76:79], v[64:67], v[48:63]
	ds_read_b128 v[64:67], v98 offset:18464
	ds_read_b128 v[72:75], v98 offset:23072
	ds_read_b128 v[116:119], v97 offset:32
	ds_read_b128 v[120:123], v97 offset:4640
	v_mfma_f32_32x32x16_bf16 v[16:31], v[76:79], v[68:71], v[16:31]
	s_waitcnt lgkmcnt(1)
	v_mfma_f32_32x32x16_bf16 v[0:15], v[116:119], v[64:67], v[0:15]
	v_mfma_f32_32x32x16_bf16 v[32:47], v[116:119], v[72:75], v[32:47]
	s_waitcnt lgkmcnt(0)
	v_mfma_f32_32x32x16_bf16 v[48:63], v[120:123], v[64:67], v[48:63]
	ds_read_b128 v[64:67], v98 offset:18496
	ds_read_b128 v[68:71], v98 offset:23104
	ds_read_b128 v[76:79], v97 offset:64
	ds_read_b128 v[116:119], v97 offset:4672
	s_waitcnt vmcnt(7)
	ds_write_b128 v96, v[100:103] offset:36864
	s_waitcnt vmcnt(5)
	ds_write_b128 v96, v[104:107] offset:41472
	s_waitcnt vmcnt(3)
	ds_write_b128 v96, v[108:111] offset:46080
	s_waitcnt vmcnt(1)
	ds_write_b128 v96, v[112:115] offset:50688
	v_mfma_f32_32x32x16_bf16 v[16:31], v[120:123], v[72:75], v[16:31]
	s_waitcnt lgkmcnt(5)
	v_mfma_f32_32x32x16_bf16 v[0:15], v[76:79], v[64:67], v[0:15]
	v_mfma_f32_32x32x16_bf16 v[32:47], v[76:79], v[68:71], v[32:47]
	s_waitcnt lgkmcnt(4)
	v_mfma_f32_32x32x16_bf16 v[48:63], v[116:119], v[64:67], v[48:63]
	ds_read_b128 v[64:67], v98 offset:18528
	ds_read_b128 v[72:75], v98 offset:23136
	ds_read_b128 v[76:79], v97 offset:96
	ds_read_b128 v[100:103], v97 offset:4704
	ds_write_b128 v96, v[80:83] offset:55296
	ds_write_b128 v96, v[84:87] offset:59904
	ds_write_b128 v96, v[88:91] offset:64512
	s_waitcnt vmcnt(0)
	ds_write_b128 v99, v[92:95] offset:13824
	v_mfma_f32_32x32x16_bf16 v[16:31], v[116:119], v[68:71], v[16:31]
	s_waitcnt lgkmcnt(5)
	v_mfma_f32_32x32x16_bf16 v[0:15], v[76:79], v[64:67], v[0:15]
	v_mfma_f32_32x32x16_bf16 v[32:47], v[76:79], v[72:75], v[32:47]
	s_waitcnt lgkmcnt(4)
	v_mfma_f32_32x32x16_bf16 v[48:63], v[100:103], v[64:67], v[48:63]
	v_mfma_f32_32x32x16_bf16 v[16:31], v[100:103], v[72:75], v[16:31]
	s_waitcnt lgkmcnt(0)
	s_barrier
; #define OPAQUE(x) asm volatile("" : "+v"(x))
; DI float bf2f(bf16_t v) { return __uint_as_float(((unsigned)v) << 16); }
; DI int crow(int r, int h) { return (r & 3) + 8 * (r >> 2) + 4 * h; }
; template <bool SWAP>
; DI void gemm_tile(const bf16_t* __restrict__ A, int lda, const bf16_t* __restrict__ Bt, int ldb, int K, f32x16 (&acc)[2][2], bf16_t* As, bf16_t* Bs_unused) {
;     ...
;     frag_read(F1, pa, pb, 48);
;     mfma4(F0);
;     if (do_write) {
; #pragma unroll
;       for (int i = 0; i < 4; ++i) *(u32x4*)(Bd + (lr + 32 * i) * 72 + lc) = rb[i];
;     }
;     __builtin_amdgcn_sched_barrier(0);
;     mfma4(F1);
;     if (do_load) load_stage(ra, rb, tload);
;     __builtin_amdgcn_sched_barrier(0);
;   };
;   const int nk = K >> 6;
;   load_stage(ra0, rb0, 0); load_stage(ra1, rb1, 1);
;   __syncthreads();
;   write_stage(ra0, rb0, 0);
;   load_stage(ra0, rb0, 2);
;   __syncthreads();
;   for (int kt = 0; kt < nk; kt += 2) {
;     step(0, ra1, rb1, true, kt + 3 < nk, kt + 3);
;     __syncthreads();
;     step(1, ra0, rb0, kt + 2 < nk, kt + 4 < nk, kt + 4);
;     __syncthreads();
; DI void phase_merge(const Params& p, int g, char* smem, int bid, int nb) {
;     ...
;     int wm = wm_, wn = wn_, h = h_, l31 = l31_; OPAQUE(wm); OPAQUE(wn); OPAQUE(h); OPAQUE(l31);
;     const bf16_t* pt = proj + (size_t)mt * 128 * NPROJ; bf16_t* mgt = mg + (size_t)mt * 128 * 1024;
; #pragma unroll
;     for (int mi = 0; mi < 2; ++mi)
; #pragma unroll
;       for (int ni = 0; ni < 2; ++ni)
; #pragma unroll
;         for (int r = 0; r < 16; ++r) {
;           const int off = (wm * 64 + mi * 32 + crow(r, h)) * NPROJ + nt * 128 + wn * 64 + ni * 32 + l31;
;           const float sga = bf2f(pt[off + PGA]), sgb = fmaxf(bf2f(pt[off + PGB]), 1e-20f);
;           acc[mi][ni][r] *= sga * __builtin_amdgcn_rcpf(sgb);
;           if (r == 15) asm volatile("" ::: "memory");
;         }
	ds_read_b128 v[64:67], v98 offset:55296
	ds_read_b128 v[68:71], v98 offset:59904
	ds_read_b128 v[72:75], v97 offset:36864
	ds_read_b128 v[76:79], v97 offset:41472
	s_waitcnt lgkmcnt(1)
	v_mfma_f32_32x32x16_bf16 v[0:15], v[72:75], v[64:67], v[0:15]
	v_mfma_f32_32x32x16_bf16 v[32:47], v[72:75], v[68:71], v[32:47]
	s_waitcnt lgkmcnt(0)
	v_mfma_f32_32x32x16_bf16 v[48:63], v[76:79], v[64:67], v[48:63]
	ds_read_b128 v[64:67], v98 offset:55328
	ds_read_b128 v[72:75], v98 offset:59936
	ds_read_b128 v[80:83], v97 offset:36896
	ds_read_b128 v[84:87], v97 offset:41504
	v_mfma_f32_32x32x16_bf16 v[16:31], v[76:79], v[68:71], v[16:31]
	s_waitcnt lgkmcnt(1)
	v_mfma_f32_32x32x16_bf16 v[0:15], v[80:83], v[64:67], v[0:15]
	v_mfma_f32_32x32x16_bf16 v[32:47], v[80:83], v[72:75], v[32:47]
	s_waitcnt lgkmcnt(0)
	v_mfma_f32_32x32x16_bf16 v[48:63], v[84:87], v[64:67], v[48:63]
	v_mfma_f32_32x32x16_bf16 v[16:31], v[84:87], v[72:75], v[16:31]
	ds_read_b128 v[64:67], v97 offset:41536
	ds_read_b128 v[68:71], v98 offset:59968
	ds_read_b128 v[72:75], v98 offset:55360
	ds_read_b128 v[76:79], v97 offset:36928
	s_waitcnt lgkmcnt(0)
	v_mfma_f32_32x32x16_bf16 v[0:15], v[76:79], v[72:75], v[0:15]
	v_mfma_f32_32x32x16_bf16 v[32:47], v[76:79], v[68:71], v[32:47]
	v_mfma_f32_32x32x16_bf16 v[48:63], v[64:67], v[72:75], v[48:63]
	v_mfma_f32_32x32x16_bf16 v[16:31], v[64:67], v[68:71], v[16:31]
	ds_read_b128 v[64:67], v97 offset:41568
	ds_read_b128 v[68:71], v98 offset:60000
	ds_read_b128 v[72:75], v98 offset:55392
	ds_read_b128 v[76:79], v97 offset:36960
	s_waitcnt lgkmcnt(0)
	v_mfma_f32_32x32x16_bf16 v[0:15], v[76:79], v[72:75], v[0:15]
	v_mfma_f32_32x32x16_bf16 v[32:47], v[76:79], v[68:71], v[32:47]
	v_mfma_f32_32x32x16_bf16 v[48:63], v[64:67], v[72:75], v[48:63]
	v_mfma_f32_32x32x16_bf16 v[16:31], v[64:67], v[68:71], v[16:31]
	v_mov_b32_e32 v148, v144
	s_mov_b32 s11, 0x50000
	s_barrier
	v_mov_b32_e32 v149, v145
	v_mov_b32_e32 v150, v146
	s_mul_hi_i32 s7, s6, 0x140000
	s_mul_i32 s6, s6, 0x140000
	v_mul_lo_u32 v64, v148, s11
	s_movk_i32 s11, 0x5000
	s_add_u32 s6, s94, s6
	v_mad_u64_u32 v[64:65], s[16:17], v150, s11, v[64:65]
	v_mov_b32_e32 v151, v147
	s_addc_u32 s7, s95, s7
	s_lshl_b32 s10, s10, 7
	v_lshlrev_b32_e32 v65, 6, v149
	v_add_u32_e32 v79, 0x1400, v64
	v_add3_u32 v65, v65, s10, v151
	v_add_u32_e32 v66, v64, v65
	v_ashrrev_i32_e32 v67, 31, v66
	v_lshl_add_u64 v[66:67], v[66:67], 1, s[6:7]
	v_add_u32_e32 v70, v79, v65
	v_add_co_u32_e32 v68, vcc, s75, v66
	v_ashrrev_i32_e32 v71, 31, v70
	s_nop 0
	v_addc_co_u32_e32 v69, vcc, 0, v67, vcc
	v_lshl_add_u64 v[70:71], v[70:71], 1, s[6:7]
	v_add_co_u32_e32 v72, vcc, s75, v70
	global_load_ushort v68, v[68:69], off
	s_nop 0
	v_addc_co_u32_e32 v73, vcc, 0, v71, vcc
	v_add_co_u32_e32 v70, vcc, s81, v70
	v_add_u32_e32 v80, 0x2800, v64
	s_nop 0
	v_addc_co_u32_e32 v71, vcc, 0, v71, vcc
	v_add_co_u32_e32 v66, vcc, s81, v66
	global_load_ushort v70, v[70:71], off offset:2048
	s_nop 0
	v_addc_co_u32_e32 v67, vcc, 0, v67, vcc
	global_load_ushort v66, v[66:67], off offset:2048
	v_add_u32_e32 v81, 0x3c00, v64
	global_load_ushort v69, v[72:73], off
	v_mov_b32_e32 v155, v195
	s_add_u32 s16, s63, s0
	s_addc_u32 s17, s70, s1
	v_readlane_b32 s11, v233, 1
	s_add_u32 s8, s11, s8
	v_readlane_b32 s11, v233, 2
	s_addc_u32 s9, s11, s9
	s_waitcnt vmcnt(3)
	v_lshlrev_b32_e32 v68, 16, v68
	v_max_f32_e32 v68, v68, v68
	v_max_f32_e32 v68, 0x1e3ce508, v68
	v_rcp_f32_e32 v68, v68
	s_waitcnt vmcnt(2)
	v_lshlrev_b32_e32 v67, 16, v70
	v_add_u32_e32 v70, v81, v65
	v_ashrrev_i32_e32 v71, 31, v70
	s_waitcnt vmcnt(1)
	v_lshlrev_b32_e32 v66, 16, v66
	v_lshl_add_u64 v[70:71], v[70:71], 1, s[6:7]
	s_waitcnt vmcnt(0)
	v_lshlrev_b32_e32 v69, 16, v69
	v_max_f32_e32 v69, v69, v69
	v_max_f32_e32 v69, 0x1e3ce508, v69
	v_rcp_f32_e32 v69, v69
	s_nop 0
	v_pk_mul_f32 v[66:67], v[68:69], v[66:67]
	s_nop 0
	v_pk_mul_f32 v[0:1], v[0:1], v[66:67]
	v_add_u32_e32 v66, v80, v65
	v_ashrrev_i32_e32 v67, 31, v66
	v_lshl_add_u64 v[66:67], v[66:67], 1, s[6:7]
	v_add_co_u32_e32 v68, vcc, s75, v66
	s_nop 1
	v_addc_co_u32_e32 v69, vcc, 0, v67, vcc
	v_add_co_u32_e32 v72, vcc, s75, v70
	global_load_ushort v68, v[68:69], off
	s_nop 0
	v_addc_co_u32_e32 v73, vcc, 0, v71, vcc
	global_load_ushort v69, v[72:73], off
	v_add_co_u32_e32 v66, vcc, s81, v66
	s_waitcnt vmcnt(1)
	v_lshlrev_b32_e32 v68, 16, v68
	v_addc_co_u32_e32 v67, vcc, 0, v67, vcc
	global_load_ushort v72, v[66:67], off offset:2048
	v_add_co_u32_e32 v66, vcc, s81, v70
	s_waitcnt vmcnt(1)
	v_lshlrev_b32_e32 v69, 16, v69
	v_addc_co_u32_e32 v67, vcc, 0, v71, vcc
	global_load_ushort v66, v[66:67], off offset:2048
	v_max_f32_e32 v68, v68, v68
	v_max_f32_e32 v69, v69, v69
	v_max_f32_e32 v68, 0x1e3ce508, v68
	v_max_f32_e32 v69, 0x1e3ce508, v69
	v_rcp_f32_e32 v68, v68
	v_rcp_f32_e32 v69, v69
	s_waitcnt vmcnt(0)
	v_lshlrev_b32_e32 v67, 16, v66
	v_lshlrev_b32_e32 v66, 16, v72
	v_pk_mul_f32 v[66:67], v[68:69], v[66:67]
	s_nop 0
	v_pk_mul_f32 v[2:3], v[2:3], v[66:67]
	v_add_u32_e32 v66, 0xa000, v64
	v_add_u32_e32 v68, v66, v65
	v_ashrrev_i32_e32 v69, 31, v68
	v_lshl_add_u64 v[68:69], v[68:69], 1, s[6:7]
	v_add_co_u32_e32 v70, vcc, s75, v68
	s_nop 1
	v_addc_co_u32_e32 v71, vcc, 0, v69, vcc
	global_load_ushort v67, v[70:71], off
	s_waitcnt vmcnt(0)
	v_lshlrev_b32_e32 v67, 16, v67
	v_max_f32_e32 v67, v67, v67
	v_max_f32_e32 v67, 0x1e3ce508, v67
	v_rcp_f32_e32 v70, v67
	v_add_u32_e32 v67, 0xb400, v64
	v_add_u32_e32 v72, v67, v65
	v_ashrrev_i32_e32 v73, 31, v72
	v_lshl_add_u64 v[72:73], v[72:73], 1, s[6:7]
	v_add_co_u32_e32 v74, vcc, s75, v72
	s_nop 1
	v_addc_co_u32_e32 v75, vcc, 0, v73, vcc
	global_load_ushort v71, v[74:75], off
	v_add_co_u32_e32 v68, vcc, s81, v68
	s_waitcnt vmcnt(0)
; DI float bf2f(bf16_t v) { return __uint_as_float(((unsigned)v) << 16); }
; DI int crow(int r, int h) { return (r & 3) + 8 * (r >> 2) + 4 * h; }
; DI void phase_merge(const Params& p, int g, char* smem, int bid, int nb) {
;     ...
;     const bf16_t* pt = proj + (size_t)mt * 128 * NPROJ; bf16_t* mgt = mg + (size_t)mt * 128 * 1024;
; #pragma unroll
;     for (int mi = 0; mi < 2; ++mi)
; #pragma unroll
;       for (int ni = 0; ni < 2; ++ni)
; #pragma unroll
;         for (int r = 0; r < 16; ++r) {
;           const int off = (wm * 64 + mi * 32 + crow(r, h)) * NPROJ + nt * 128 + wn * 64 + ni * 32 + l31;
;           const float sga = bf2f(pt[off + PGA]), sgb = fmaxf(bf2f(pt[off + PGB]), 1e-20f);
;           acc[mi][ni][r] *= sga * __builtin_amdgcn_rcpf(sgb);
;           if (r == 15) asm volatile("" ::: "memory");
;         }
	v_lshlrev_b32_e32 v71, 16, v71
	v_addc_co_u32_e32 v69, vcc, 0, v69, vcc
	global_load_ushort v74, v[68:69], off offset:2048
	v_add_co_u32_e32 v68, vcc, s81, v72
	v_max_f32_e32 v71, v71, v71
	s_nop 0
	v_addc_co_u32_e32 v69, vcc, 0, v73, vcc
	global_load_ushort v68, v[68:69], off offset:2048
	v_max_f32_e32 v71, 0x1e3ce508, v71
	v_rcp_f32_e32 v71, v71
	s_waitcnt vmcnt(0)
	v_lshlrev_b32_e32 v69, 16, v68
	v_lshlrev_b32_e32 v68, 16, v74
	v_pk_mul_f32 v[68:69], v[70:71], v[68:69]
	s_nop 0
	v_pk_mul_f32 v[4:5], v[4:5], v[68:69]
	v_add_u32_e32 v68, 0xc800, v64
	v_add_u32_e32 v70, v68, v65
	v_ashrrev_i32_e32 v71, 31, v70
	v_lshl_add_u64 v[70:71], v[70:71], 1, s[6:7]
	v_add_co_u32_e32 v72, vcc, s75, v70
	s_nop 1
	v_addc_co_u32_e32 v73, vcc, 0, v71, vcc
	global_load_ushort v69, v[72:73], off
	s_waitcnt vmcnt(0)
	v_lshlrev_b32_e32 v69, 16, v69
	v_max_f32_e32 v69, v69, v69
	v_max_f32_e32 v69, 0x1e3ce508, v69
	v_rcp_f32_e32 v72, v69
	v_add_u32_e32 v69, 0xdc00, v64
	v_add_u32_e32 v74, v69, v65
	v_ashrrev_i32_e32 v75, 31, v74
	v_lshl_add_u64 v[74:75], v[74:75], 1, s[6:7]
	v_add_co_u32_e32 v76, vcc, s75, v74
	s_nop 1
	v_addc_co_u32_e32 v77, vcc, 0, v75, vcc
	global_load_ushort v73, v[76:77], off
	v_add_co_u32_e32 v70, vcc, s81, v70
	s_waitcnt vmcnt(0)
	v_lshlrev_b32_e32 v73, 16, v73
	v_addc_co_u32_e32 v71, vcc, 0, v71, vcc
	global_load_ushort v76, v[70:71], off offset:2048
	v_add_co_u32_e32 v70, vcc, s81, v74
	v_max_f32_e32 v73, v73, v73
	s_nop 0
	v_addc_co_u32_e32 v71, vcc, 0, v75, vcc
	global_load_ushort v70, v[70:71], off offset:2048
	v_max_f32_e32 v73, 0x1e3ce508, v73
	v_rcp_f32_e32 v73, v73
	v_add_u32_e32 v74, 0x14000, v64
	v_add_u32_e32 v75, 0x15400, v64
	s_waitcnt vmcnt(0)
	v_lshlrev_b32_e32 v71, 16, v70
	v_lshlrev_b32_e32 v70, 16, v76
	v_pk_mul_f32 v[70:71], v[72:73], v[70:71]
	v_add_u32_e32 v76, v75, v65
	v_pk_mul_f32 v[6:7], v[6:7], v[70:71]
	v_add_u32_e32 v70, v74, v65
	v_ashrrev_i32_e32 v71, 31, v70
	v_lshl_add_u64 v[70:71], v[70:71], 1, s[6:7]
	v_add_co_u32_e32 v72, vcc, s75, v70
	v_ashrrev_i32_e32 v77, 31, v76
	s_nop 0
	v_addc_co_u32_e32 v73, vcc, 0, v71, vcc
	v_lshl_add_u64 v[76:77], v[76:77], 1, s[6:7]
	v_add_co_u32_e32 v82, vcc, s75, v76
	global_load_ushort v72, v[72:73], off
	s_nop 0
	v_addc_co_u32_e32 v83, vcc, 0, v77, vcc
	v_add_co_u32_e32 v70, vcc, s81, v70
	s_nop 1
	v_addc_co_u32_e32 v71, vcc, 0, v71, vcc
	global_load_ushort v78, v[70:71], off offset:2048
	global_load_ushort v73, v[82:83], off
	v_add_co_u32_e32 v70, vcc, s81, v76
	v_add_u32_e32 v76, 0x16800, v64
	s_nop 0
	v_addc_co_u32_e32 v71, vcc, 0, v77, vcc
	global_load_ushort v70, v[70:71], off offset:2048
	v_add_u32_e32 v77, 0x17c00, v64
	v_add_u32_e32 v82, v77, v65
	v_ashrrev_i32_e32 v83, 31, v82
	v_lshl_add_u64 v[82:83], v[82:83], 1, s[6:7]
	s_waitcnt vmcnt(3)
	v_lshlrev_b32_e32 v72, 16, v72
	v_max_f32_e32 v72, v72, v72
	v_max_f32_e32 v72, 0x1e3ce508, v72
	v_rcp_f32_e32 v72, v72
	s_waitcnt vmcnt(1)
	v_lshlrev_b32_e32 v73, 16, v73
	v_max_f32_e32 v73, v73, v73
	v_max_f32_e32 v73, 0x1e3ce508, v73
	v_rcp_f32_e32 v73, v73
	s_waitcnt vmcnt(0)
	v_lshlrev_b32_e32 v71, 16, v70
	v_lshlrev_b32_e32 v70, 16, v78
	v_pk_mul_f32 v[70:71], v[72:73], v[70:71]
	s_nop 0
	v_pk_mul_f32 v[8:9], v[8:9], v[70:71]
	v_add_u32_e32 v70, v76, v65
	v_ashrrev_i32_e32 v71, 31, v70
	v_lshl_add_u64 v[70:71], v[70:71], 1, s[6:7]
	v_add_co_u32_e32 v72, vcc, s75, v70
	s_nop 1
	v_addc_co_u32_e32 v73, vcc, 0, v71, vcc
	v_add_co_u32_e32 v84, vcc, s75, v82
	global_load_ushort v72, v[72:73], off
	s_nop 0
	v_addc_co_u32_e32 v85, vcc, 0, v83, vcc
	v_add_co_u32_e32 v70, vcc, s81, v70
	s_nop 1
	v_addc_co_u32_e32 v71, vcc, 0, v71, vcc
	global_load_ushort v78, v[70:71], off offset:2048
	global_load_ushort v73, v[84:85], off
	v_add_co_u32_e32 v70, vcc, s81, v82
	s_waitcnt vmcnt(2)
	v_lshlrev_b32_e32 v72, 16, v72
	v_addc_co_u32_e32 v71, vcc, 0, v83, vcc
	global_load_ushort v70, v[70:71], off offset:2048
	v_max_f32_e32 v72, v72, v72
	v_max_f32_e32 v72, 0x1e3ce508, v72
	v_rcp_f32_e32 v72, v72
	s_waitcnt vmcnt(1)
	v_lshlrev_b32_e32 v73, 16, v73
	v_max_f32_e32 v73, v73, v73
	v_max_f32_e32 v73, 0x1e3ce508, v73
	v_rcp_f32_e32 v73, v73
	s_waitcnt vmcnt(0)
	v_lshlrev_b32_e32 v71, 16, v70
	v_lshlrev_b32_e32 v70, 16, v78
	v_pk_mul_f32 v[70:71], v[72:73], v[70:71]
	v_add_u32_e32 v78, 0x1e000, v64
	v_pk_mul_f32 v[10:11], v[10:11], v[70:71]
	v_add_u32_e32 v70, v78, v65
	v_ashrrev_i32_e32 v71, 31, v70
	v_lshl_add_u64 v[70:71], v[70:71], 1, s[6:7]
	v_add_co_u32_e32 v72, vcc, s75, v70
	s_nop 1
	v_addc_co_u32_e32 v73, vcc, 0, v71, vcc
	global_load_ushort v72, v[72:73], off
	s_waitcnt vmcnt(0)
	v_lshlrev_b32_e32 v72, 16, v72
	v_max_f32_e32 v72, v72, v72
	v_max_f32_e32 v72, 0x1e3ce508, v72
	v_rcp_f32_e32 v82, v72
	v_add_u32_e32 v72, 0x1f400, v64
	v_add_u32_e32 v84, v72, v65
	v_ashrrev_i32_e32 v85, 31, v84
	v_lshl_add_u64 v[84:85], v[84:85], 1, s[6:7]
	v_add_co_u32_e32 v86, vcc, s75, v84
	s_nop 1
	v_addc_co_u32_e32 v87, vcc, 0, v85, vcc
	global_load_ushort v73, v[86:87], off
	v_add_co_u32_e32 v70, vcc, s81, v70
	s_waitcnt vmcnt(0)
	v_lshlrev_b32_e32 v73, 16, v73
	v_max_f32_e32 v73, v73, v73
	v_max_f32_e32 v73, 0x1e3ce508, v73
	v_addc_co_u32_e32 v71, vcc, 0, v71, vcc
	v_rcp_f32_e32 v83, v73
	global_load_ushort v73, v[70:71], off offset:2048
	v_add_co_u32_e32 v70, vcc, s81, v84
	s_nop 1
	v_addc_co_u32_e32 v71, vcc, 0, v85, vcc
	global_load_ushort v70, v[70:71], off offset:2048
	s_waitcnt vmcnt(0)
; DI float bf2f(bf16_t v) { return __uint_as_float(((unsigned)v) << 16); }
; DI int crow(int r, int h) { return (r & 3) + 8 * (r >> 2) + 4 * h; }
; DI void phase_merge(const Params& p, int g, char* smem, int bid, int nb) {
;     ...
;     const bf16_t* pt = proj + (size_t)mt * 128 * NPROJ; bf16_t* mgt = mg + (size_t)mt * 128 * 1024;
; #pragma unroll
;     for (int mi = 0; mi < 2; ++mi)
; #pragma unroll
;       for (int ni = 0; ni < 2; ++ni)
; #pragma unroll
;         for (int r = 0; r < 16; ++r) {
;           const int off = (wm * 64 + mi * 32 + crow(r, h)) * NPROJ + nt * 128 + wn * 64 + ni * 32 + l31;
;           const float sga = bf2f(pt[off + PGA]), sgb = fmaxf(bf2f(pt[off + PGB]), 1e-20f);
;           acc[mi][ni][r] *= sga * __builtin_amdgcn_rcpf(sgb);
;           if (r == 15) asm volatile("" ::: "memory");
;         }
	v_lshlrev_b32_e32 v71, 16, v70
	v_lshlrev_b32_e32 v70, 16, v73
	v_pk_mul_f32 v[70:71], v[82:83], v[70:71]
	v_add_u32_e32 v73, 0x20800, v64
	v_pk_mul_f32 v[12:13], v[12:13], v[70:71]
	v_add_u32_e32 v70, v73, v65
	v_ashrrev_i32_e32 v71, 31, v70
	v_lshl_add_u64 v[82:83], v[70:71], 1, s[6:7]
	v_add_co_u32_e32 v70, vcc, s75, v82
	s_nop 1
	v_addc_co_u32_e32 v71, vcc, 0, v83, vcc
	global_load_ushort v70, v[70:71], off
	v_add_u32_e32 v71, 0x21c00, v64
	v_add_u32_e32 v86, v71, v65
	v_ashrrev_i32_e32 v87, 31, v86
	v_lshl_add_u64 v[86:87], v[86:87], 1, s[6:7]
	v_add_co_u32_e32 v88, vcc, s75, v86
	s_waitcnt vmcnt(0)
	v_lshlrev_b32_e32 v70, 16, v70
	v_max_f32_e32 v70, v70, v70
	v_max_f32_e32 v70, 0x1e3ce508, v70
	v_addc_co_u32_e32 v89, vcc, 0, v87, vcc
	v_rcp_f32_e32 v84, v70
	global_load_ushort v70, v[88:89], off
	v_add_co_u32_e32 v82, vcc, s81, v82
	s_waitcnt vmcnt(0)
	v_lshlrev_b32_e32 v70, 16, v70
	v_max_f32_e32 v70, v70, v70
	v_max_f32_e32 v70, 0x1e3ce508, v70
	v_addc_co_u32_e32 v83, vcc, 0, v83, vcc
	v_rcp_f32_e32 v85, v70
	global_load_ushort v70, v[82:83], off offset:2048
	v_add_co_u32_e32 v82, vcc, s81, v86
	s_nop 1
	v_addc_co_u32_e32 v83, vcc, 0, v87, vcc
	global_load_ushort v82, v[82:83], off offset:2048
	s_waitcnt vmcnt(0)
	v_lshlrev_b32_e32 v83, 16, v82
	v_lshlrev_b32_e32 v82, 16, v70
	v_pk_mul_f32 v[82:83], v[84:85], v[82:83]
	v_add_u32_e32 v70, 32, v65
	v_pk_mul_f32 v[14:15], v[14:15], v[82:83]
	v_add_u32_e32 v82, v70, v64
	v_ashrrev_i32_e32 v83, 31, v82
	v_lshl_add_u64 v[82:83], v[82:83], 1, s[6:7]
	v_add_u32_e32 v86, v79, v70
	v_add_co_u32_e32 v84, vcc, s75, v82
	v_ashrrev_i32_e32 v87, 31, v86
	s_nop 0
	v_addc_co_u32_e32 v85, vcc, 0, v83, vcc
	v_lshl_add_u64 v[86:87], v[86:87], 1, s[6:7]
	v_add_co_u32_e32 v88, vcc, s75, v86
	global_load_ushort v84, v[84:85], off
	s_nop 0
	v_addc_co_u32_e32 v89, vcc, 0, v87, vcc
	global_load_ushort v79, v[88:89], off
	v_add_co_u32_e32 v82, vcc, s81, v82
	s_waitcnt vmcnt(1)
	v_lshlrev_b32_e32 v84, 16, v84
	v_addc_co_u32_e32 v83, vcc, 0, v83, vcc
	s_waitcnt vmcnt(0)
	v_lshlrev_b32_e32 v79, 16, v79
	v_max_f32_e32 v79, v79, v79
	v_max_f32_e32 v79, 0x1e3ce508, v79
	v_rcp_f32_e32 v85, v79
	global_load_ushort v79, v[82:83], off offset:2048
	v_add_co_u32_e32 v82, vcc, s81, v86
	v_max_f32_e32 v84, v84, v84
	s_nop 0
	v_addc_co_u32_e32 v83, vcc, 0, v87, vcc
	global_load_ushort v82, v[82:83], off offset:2048
	v_max_f32_e32 v84, 0x1e3ce508, v84
	v_rcp_f32_e32 v84, v84
	s_waitcnt vmcnt(0)
	v_lshlrev_b32_e32 v83, 16, v82
	v_lshlrev_b32_e32 v82, 16, v79
	v_pk_mul_f32 v[82:83], v[84:85], v[82:83]
	s_nop 0
	v_pk_mul_f32 v[32:33], v[32:33], v[82:83]
	v_add_u32_e32 v82, v80, v70
	v_ashrrev_i32_e32 v83, 31, v82
	v_lshl_add_u64 v[82:83], v[82:83], 1, s[6:7]
	v_add_co_u32_e32 v84, vcc, s75, v82
	s_nop 1
	v_addc_co_u32_e32 v85, vcc, 0, v83, vcc
	global_load_ushort v79, v[84:85], off
	v_add_u32_e32 v84, v81, v70
	v_ashrrev_i32_e32 v85, 31, v84
	v_lshl_add_u64 v[84:85], v[84:85], 1, s[6:7]
	v_add_co_u32_e32 v86, vcc, s75, v84
	s_waitcnt vmcnt(0)
	v_lshlrev_b32_e32 v79, 16, v79
	v_max_f32_e32 v79, v79, v79
	v_max_f32_e32 v79, 0x1e3ce508, v79
	v_addc_co_u32_e32 v87, vcc, 0, v85, vcc
	v_rcp_f32_e32 v80, v79
	global_load_ushort v79, v[86:87], off
	v_add_co_u32_e32 v82, vcc, s81, v82
	s_waitcnt vmcnt(0)
	v_lshlrev_b32_e32 v79, 16, v79
	v_max_f32_e32 v79, v79, v79
	v_max_f32_e32 v79, 0x1e3ce508, v79
	v_addc_co_u32_e32 v83, vcc, 0, v83, vcc
	v_rcp_f32_e32 v81, v79
	global_load_ushort v79, v[82:83], off offset:2048
	v_add_co_u32_e32 v82, vcc, s81, v84
	s_nop 1
	v_addc_co_u32_e32 v83, vcc, 0, v85, vcc
	global_load_ushort v82, v[82:83], off offset:2048
	s_waitcnt vmcnt(0)
	v_lshlrev_b32_e32 v83, 16, v82
	v_lshlrev_b32_e32 v82, 16, v79
	v_pk_mul_f32 v[80:81], v[80:81], v[82:83]
	s_nop 0
	v_pk_mul_f32 v[34:35], v[34:35], v[80:81]
	v_add_u32_e32 v80, v66, v70
	v_ashrrev_i32_e32 v81, 31, v80
	v_lshl_add_u64 v[80:81], v[80:81], 1, s[6:7]
	v_add_co_u32_e32 v82, vcc, s75, v80
	s_nop 1
	v_addc_co_u32_e32 v83, vcc, 0, v81, vcc
	global_load_ushort v66, v[82:83], off
	v_add_u32_e32 v82, v67, v70
	v_ashrrev_i32_e32 v83, 31, v82
	v_lshl_add_u64 v[82:83], v[82:83], 1, s[6:7]
	v_add_co_u32_e32 v84, vcc, s75, v82
	s_waitcnt vmcnt(0)
	v_lshlrev_b32_e32 v66, 16, v66
	v_addc_co_u32_e32 v85, vcc, 0, v83, vcc
	global_load_ushort v67, v[84:85], off
	v_add_co_u32_e32 v80, vcc, s81, v80
	v_max_f32_e32 v66, v66, v66
	s_nop 0
	v_addc_co_u32_e32 v81, vcc, 0, v81, vcc
	global_load_ushort v79, v[80:81], off offset:2048
	v_add_co_u32_e32 v80, vcc, s81, v82
	v_max_f32_e32 v66, 0x1e3ce508, v66
	s_nop 0
	v_addc_co_u32_e32 v81, vcc, 0, v83, vcc
	global_load_ushort v80, v[80:81], off offset:2048
	v_rcp_f32_e32 v66, v66
	s_waitcnt vmcnt(2)
	v_lshlrev_b32_e32 v67, 16, v67
	v_max_f32_e32 v67, v67, v67
	v_max_f32_e32 v67, 0x1e3ce508, v67
	v_rcp_f32_e32 v67, v67
	s_waitcnt vmcnt(0)
	v_lshlrev_b32_e32 v81, 16, v80
	v_lshlrev_b32_e32 v80, 16, v79
	v_pk_mul_f32 v[66:67], v[66:67], v[80:81]
	s_nop 0
	v_pk_mul_f32 v[36:37], v[36:37], v[66:67]
	v_add_u32_e32 v66, v68, v70
	v_ashrrev_i32_e32 v67, 31, v66
	v_lshl_add_u64 v[66:67], v[66:67], 1, s[6:7]
	v_add_co_u32_e32 v80, vcc, s75, v66
	s_nop 1
	v_addc_co_u32_e32 v81, vcc, 0, v67, vcc
	global_load_ushort v68, v[80:81], off
	v_add_u32_e32 v80, v69, v70
	v_ashrrev_i32_e32 v81, 31, v80
	v_lshl_add_u64 v[80:81], v[80:81], 1, s[6:7]
	v_add_co_u32_e32 v82, vcc, s75, v80
	s_waitcnt vmcnt(0)
	v_lshlrev_b32_e32 v68, 16, v68
	v_addc_co_u32_e32 v83, vcc, 0, v81, vcc
	global_load_ushort v69, v[82:83], off
	v_add_co_u32_e32 v66, vcc, s81, v66
	v_max_f32_e32 v68, v68, v68
	s_nop 0
	v_addc_co_u32_e32 v67, vcc, 0, v67, vcc
	global_load_ushort v79, v[66:67], off offset:2048
	v_add_co_u32_e32 v66, vcc, s81, v80
	v_max_f32_e32 v68, 0x1e3ce508, v68
	s_nop 0
	v_addc_co_u32_e32 v67, vcc, 0, v81, vcc
	global_load_ushort v66, v[66:67], off offset:2048
	v_rcp_f32_e32 v68, v68
	s_waitcnt vmcnt(2)
; DI float bf2f(bf16_t v) { return __uint_as_float(((unsigned)v) << 16); }
; DI int crow(int r, int h) { return (r & 3) + 8 * (r >> 2) + 4 * h; }
; DI void phase_merge(const Params& p, int g, char* smem, int bid, int nb) {
;     ...
;     const bf16_t* pt = proj + (size_t)mt * 128 * NPROJ; bf16_t* mgt = mg + (size_t)mt * 128 * 1024;
; #pragma unroll
;     for (int mi = 0; mi < 2; ++mi)
; #pragma unroll
;       for (int ni = 0; ni < 2; ++ni)
; #pragma unroll
;         for (int r = 0; r < 16; ++r) {
;           const int off = (wm * 64 + mi * 32 + crow(r, h)) * NPROJ + nt * 128 + wn * 64 + ni * 32 + l31;
;           const float sga = bf2f(pt[off + PGA]), sgb = fmaxf(bf2f(pt[off + PGB]), 1e-20f);
;           acc[mi][ni][r] *= sga * __builtin_amdgcn_rcpf(sgb);
;           if (r == 15) asm volatile("" ::: "memory");
;         }
	v_lshlrev_b32_e32 v69, 16, v69
	v_max_f32_e32 v69, v69, v69
	v_max_f32_e32 v69, 0x1e3ce508, v69
	v_rcp_f32_e32 v69, v69
	s_waitcnt vmcnt(0)
	v_lshlrev_b32_e32 v67, 16, v66
	v_lshlrev_b32_e32 v66, 16, v79
	v_pk_mul_f32 v[66:67], v[68:69], v[66:67]
	s_nop 0
	v_pk_mul_f32 v[38:39], v[38:39], v[66:67]
	v_add_u32_e32 v66, v74, v70
	v_ashrrev_i32_e32 v67, 31, v66
	v_lshl_add_u64 v[66:67], v[66:67], 1, s[6:7]
	v_add_u32_e32 v74, v75, v70
	v_add_co_u32_e32 v68, vcc, s75, v66
	v_ashrrev_i32_e32 v75, 31, v74
	s_nop 0
	v_addc_co_u32_e32 v69, vcc, 0, v67, vcc
	v_lshl_add_u64 v[74:75], v[74:75], 1, s[6:7]
	v_add_co_u32_e32 v80, vcc, s75, v74
	global_load_ushort v68, v[68:69], off
	s_nop 0
	v_addc_co_u32_e32 v81, vcc, 0, v75, vcc
	v_add_co_u32_e32 v66, vcc, s81, v66
	s_nop 1
	v_addc_co_u32_e32 v67, vcc, 0, v67, vcc
	global_load_ushort v79, v[66:67], off offset:2048
	global_load_ushort v69, v[80:81], off
	v_add_co_u32_e32 v66, vcc, s81, v74
	v_add_u32_e32 v74, v77, v70
	s_nop 0
	v_addc_co_u32_e32 v67, vcc, 0, v75, vcc
	global_load_ushort v66, v[66:67], off offset:2048
	v_ashrrev_i32_e32 v75, 31, v74
	v_lshl_add_u64 v[74:75], v[74:75], 1, s[6:7]
	s_waitcnt vmcnt(3)
	v_lshlrev_b32_e32 v68, 16, v68
	v_max_f32_e32 v68, v68, v68
	v_max_f32_e32 v68, 0x1e3ce508, v68
	v_rcp_f32_e32 v68, v68
	s_waitcnt vmcnt(1)
	v_lshlrev_b32_e32 v69, 16, v69
	v_max_f32_e32 v69, v69, v69
	v_max_f32_e32 v69, 0x1e3ce508, v69
	v_rcp_f32_e32 v69, v69
	s_waitcnt vmcnt(0)
	v_lshlrev_b32_e32 v67, 16, v66
	v_lshlrev_b32_e32 v66, 16, v79
	v_pk_mul_f32 v[66:67], v[68:69], v[66:67]
	s_nop 0
	v_pk_mul_f32 v[40:41], v[40:41], v[66:67]
	v_add_u32_e32 v66, v76, v70
	v_ashrrev_i32_e32 v67, 31, v66
	v_lshl_add_u64 v[66:67], v[66:67], 1, s[6:7]
	v_add_co_u32_e32 v68, vcc, s75, v66
	s_nop 1
	v_addc_co_u32_e32 v69, vcc, 0, v67, vcc
	v_add_co_u32_e32 v76, vcc, s75, v74
	global_load_ushort v68, v[68:69], off
	s_nop 0
	v_addc_co_u32_e32 v77, vcc, 0, v75, vcc
	global_load_ushort v69, v[76:77], off
	v_add_co_u32_e32 v66, vcc, s81, v66
	s_waitcnt vmcnt(1)
	v_lshlrev_b32_e32 v68, 16, v68
	v_addc_co_u32_e32 v67, vcc, 0, v67, vcc
	global_load_ushort v76, v[66:67], off offset:2048
	v_add_co_u32_e32 v66, vcc, s81, v74
	s_waitcnt vmcnt(1)
	v_lshlrev_b32_e32 v69, 16, v69
	v_addc_co_u32_e32 v67, vcc, 0, v75, vcc
	global_load_ushort v66, v[66:67], off offset:2048
	v_max_f32_e32 v68, v68, v68
	v_max_f32_e32 v69, v69, v69
	v_max_f32_e32 v68, 0x1e3ce508, v68
	v_max_f32_e32 v69, 0x1e3ce508, v69
	v_rcp_f32_e32 v68, v68
	v_rcp_f32_e32 v69, v69
	v_add_u32_e32 v74, v72, v70
	v_ashrrev_i32_e32 v75, 31, v74
	v_lshl_add_u64 v[74:75], v[74:75], 1, s[6:7]
	s_waitcnt vmcnt(0)
	v_lshlrev_b32_e32 v67, 16, v66
	v_lshlrev_b32_e32 v66, 16, v76
	v_pk_mul_f32 v[66:67], v[68:69], v[66:67]
	s_nop 0
	v_pk_mul_f32 v[42:43], v[42:43], v[66:67]
	v_add_u32_e32 v66, v78, v70
	v_ashrrev_i32_e32 v67, 31, v66
	v_lshl_add_u64 v[66:67], v[66:67], 1, s[6:7]
	v_add_co_u32_e32 v68, vcc, s75, v66
	s_nop 1
	v_addc_co_u32_e32 v69, vcc, 0, v67, vcc
	v_add_co_u32_e32 v76, vcc, s75, v74
	global_load_ushort v68, v[68:69], off
	s_nop 0
	v_addc_co_u32_e32 v77, vcc, 0, v75, vcc
	v_add_co_u32_e32 v66, vcc, s81, v66
	s_nop 1
	v_addc_co_u32_e32 v67, vcc, 0, v67, vcc
	global_load_ushort v72, v[66:67], off offset:2048
	global_load_ushort v69, v[76:77], off
	v_add_co_u32_e32 v66, vcc, s81, v74
	s_waitcnt vmcnt(2)
	v_lshlrev_b32_e32 v68, 16, v68
	v_addc_co_u32_e32 v67, vcc, 0, v75, vcc
	global_load_ushort v66, v[66:67], off offset:2048
	v_max_f32_e32 v68, v68, v68
	v_max_f32_e32 v68, 0x1e3ce508, v68
	v_rcp_f32_e32 v68, v68
	s_waitcnt vmcnt(1)
	v_lshlrev_b32_e32 v69, 16, v69
	v_max_f32_e32 v69, v69, v69
	v_max_f32_e32 v69, 0x1e3ce508, v69
	v_rcp_f32_e32 v69, v69
	s_waitcnt vmcnt(0)
	v_lshlrev_b32_e32 v67, 16, v66
	v_lshlrev_b32_e32 v66, 16, v72
	v_pk_mul_f32 v[66:67], v[68:69], v[66:67]
	v_add_u32_e32 v72, v71, v70
	v_pk_mul_f32 v[44:45], v[44:45], v[66:67]
	v_add_u32_e32 v66, v73, v70
	v_ashrrev_i32_e32 v67, 31, v66
	v_lshl_add_u64 v[66:67], v[66:67], 1, s[6:7]
	v_add_co_u32_e32 v68, vcc, s75, v66
	v_ashrrev_i32_e32 v73, 31, v72
	s_nop 0
	v_addc_co_u32_e32 v69, vcc, 0, v67, vcc
	v_lshl_add_u64 v[72:73], v[72:73], 1, s[6:7]
	v_add_co_u32_e32 v74, vcc, s75, v72
	global_load_ushort v68, v[68:69], off
	s_nop 0
	v_addc_co_u32_e32 v75, vcc, 0, v73, vcc
	v_add_co_u32_e32 v66, vcc, s81, v66
	s_nop 1
	v_addc_co_u32_e32 v67, vcc, 0, v67, vcc
	global_load_ushort v71, v[66:67], off offset:2048
	global_load_ushort v69, v[74:75], off
	v_add_co_u32_e32 v66, vcc, s81, v72
	s_waitcnt vmcnt(2)
	v_lshlrev_b32_e32 v68, 16, v68
	v_addc_co_u32_e32 v67, vcc, 0, v73, vcc
	global_load_ushort v66, v[66:67], off offset:2048
	v_max_f32_e32 v68, v68, v68
	v_max_f32_e32 v68, 0x1e3ce508, v68
	v_rcp_f32_e32 v68, v68
	s_waitcnt vmcnt(1)
	v_lshlrev_b32_e32 v69, 16, v69
	v_max_f32_e32 v69, v69, v69
	v_max_f32_e32 v69, 0x1e3ce508, v69
	v_rcp_f32_e32 v69, v69
	s_waitcnt vmcnt(0)
	v_lshlrev_b32_e32 v67, 16, v66
	v_lshlrev_b32_e32 v66, 16, v71
	v_pk_mul_f32 v[66:67], v[68:69], v[66:67]
	s_nop 0
	v_pk_mul_f32 v[46:47], v[46:47], v[66:67]
	v_add_u32_e32 v66, 0x28000, v64
	v_add_u32_e32 v68, v66, v65
	v_ashrrev_i32_e32 v69, 31, v68
	v_lshl_add_u64 v[68:69], v[68:69], 1, s[6:7]
	v_add_co_u32_e32 v72, vcc, s75, v68
	s_nop 1
	v_addc_co_u32_e32 v73, vcc, 0, v69, vcc
	global_load_ushort v67, v[72:73], off
	s_waitcnt vmcnt(0)
	v_lshlrev_b32_e32 v67, 16, v67
	v_max_f32_e32 v67, v67, v67
	v_max_f32_e32 v67, 0x1e3ce508, v67
	v_rcp_f32_e32 v72, v67
	v_add_u32_e32 v67, 0x29400, v64
	v_add_u32_e32 v74, v67, v65
	v_ashrrev_i32_e32 v75, 31, v74
	v_lshl_add_u64 v[74:75], v[74:75], 1, s[6:7]
	v_add_co_u32_e32 v76, vcc, s75, v74
	s_nop 1
	v_addc_co_u32_e32 v77, vcc, 0, v75, vcc
	global_load_ushort v71, v[76:77], off
	v_add_co_u32_e32 v68, vcc, s81, v68
	s_waitcnt vmcnt(0)
; DI float bf2f(bf16_t v) { return __uint_as_float(((unsigned)v) << 16); }
; DI int crow(int r, int h) { return (r & 3) + 8 * (r >> 2) + 4 * h; }
; DI void phase_merge(const Params& p, int g, char* smem, int bid, int nb) {
;     ...
;     const bf16_t* pt = proj + (size_t)mt * 128 * NPROJ; bf16_t* mgt = mg + (size_t)mt * 128 * 1024;
; #pragma unroll
;     for (int mi = 0; mi < 2; ++mi)
; #pragma unroll
;       for (int ni = 0; ni < 2; ++ni)
; #pragma unroll
;         for (int r = 0; r < 16; ++r) {
;           const int off = (wm * 64 + mi * 32 + crow(r, h)) * NPROJ + nt * 128 + wn * 64 + ni * 32 + l31;
;           const float sga = bf2f(pt[off + PGA]), sgb = fmaxf(bf2f(pt[off + PGB]), 1e-20f);
;           acc[mi][ni][r] *= sga * __builtin_amdgcn_rcpf(sgb);
;           if (r == 15) asm volatile("" ::: "memory");
;         }
	v_lshlrev_b32_e32 v71, 16, v71
	v_max_f32_e32 v71, v71, v71
	v_max_f32_e32 v71, 0x1e3ce508, v71
	v_addc_co_u32_e32 v69, vcc, 0, v69, vcc
	v_rcp_f32_e32 v73, v71
	global_load_ushort v71, v[68:69], off offset:2048
	v_add_co_u32_e32 v68, vcc, s81, v74
	s_nop 1
	v_addc_co_u32_e32 v69, vcc, 0, v75, vcc
	global_load_ushort v68, v[68:69], off offset:2048
	s_waitcnt vmcnt(0)
	v_lshlrev_b32_e32 v69, 16, v68
	v_lshlrev_b32_e32 v68, 16, v71
	v_pk_mul_f32 v[68:69], v[72:73], v[68:69]
	s_nop 0
	v_pk_mul_f32 v[48:49], v[48:49], v[68:69]
	v_add_u32_e32 v68, 0x2a800, v64
	v_add_u32_e32 v72, v68, v65
	v_ashrrev_i32_e32 v73, 31, v72
	v_lshl_add_u64 v[72:73], v[72:73], 1, s[6:7]
	v_add_co_u32_e32 v74, vcc, s75, v72
	s_nop 1
	v_addc_co_u32_e32 v75, vcc, 0, v73, vcc
	global_load_ushort v69, v[74:75], off
	s_waitcnt vmcnt(0)
	v_lshlrev_b32_e32 v69, 16, v69
	v_max_f32_e32 v69, v69, v69
	v_max_f32_e32 v69, 0x1e3ce508, v69
	v_rcp_f32_e32 v74, v69
	v_add_u32_e32 v69, 0x2bc00, v64
	v_add_u32_e32 v76, v69, v65
	v_ashrrev_i32_e32 v77, 31, v76
	v_lshl_add_u64 v[76:77], v[76:77], 1, s[6:7]
	v_add_co_u32_e32 v78, vcc, s75, v76
	s_nop 1
	v_addc_co_u32_e32 v79, vcc, 0, v77, vcc
	global_load_ushort v71, v[78:79], off
	v_add_co_u32_e32 v72, vcc, s81, v72
	s_waitcnt vmcnt(0)
	v_lshlrev_b32_e32 v71, 16, v71
	v_max_f32_e32 v71, v71, v71
	v_max_f32_e32 v71, 0x1e3ce508, v71
	v_addc_co_u32_e32 v73, vcc, 0, v73, vcc
	v_rcp_f32_e32 v75, v71
	global_load_ushort v71, v[72:73], off offset:2048
	v_add_co_u32_e32 v72, vcc, s81, v76
	s_nop 1
	v_addc_co_u32_e32 v73, vcc, 0, v77, vcc
	global_load_ushort v72, v[72:73], off offset:2048
	s_waitcnt vmcnt(0)
	v_lshlrev_b32_e32 v73, 16, v72
	v_lshlrev_b32_e32 v72, 16, v71
	v_pk_mul_f32 v[72:73], v[74:75], v[72:73]
	v_add_u32_e32 v75, 0x32000, v64
	v_pk_mul_f32 v[50:51], v[50:51], v[72:73]
	v_add_u32_e32 v72, v75, v65
	v_ashrrev_i32_e32 v73, 31, v72
	v_lshl_add_u64 v[72:73], v[72:73], 1, s[6:7]
	v_add_co_u32_e32 v76, vcc, s75, v72
	s_nop 1
	v_addc_co_u32_e32 v77, vcc, 0, v73, vcc
	global_load_ushort v71, v[76:77], off
	v_add_u32_e32 v77, 0x33400, v64
	v_add_u32_e32 v80, v77, v65
	v_ashrrev_i32_e32 v81, 31, v80
	v_lshl_add_u64 v[80:81], v[80:81], 1, s[6:7]
	v_add_co_u32_e32 v82, vcc, s75, v80
	v_add_u32_e32 v76, 0x35c00, v64
	s_nop 0
	v_addc_co_u32_e32 v83, vcc, 0, v81, vcc
	v_add_co_u32_e32 v72, vcc, s81, v72
	s_waitcnt vmcnt(0)
	v_lshlrev_b32_e32 v71, 16, v71
	v_max_f32_e32 v71, v71, v71
	v_max_f32_e32 v71, 0x1e3ce508, v71
	v_rcp_f32_e32 v78, v71
	global_load_ushort v71, v[82:83], off
	v_addc_co_u32_e32 v73, vcc, 0, v73, vcc
	v_add_u32_e32 v82, v76, v65
	v_ashrrev_i32_e32 v83, 31, v82
	v_lshl_add_u64 v[82:83], v[82:83], 1, s[6:7]
	s_waitcnt vmcnt(0)
	v_lshlrev_b32_e32 v71, 16, v71
	v_max_f32_e32 v71, v71, v71
	v_max_f32_e32 v71, 0x1e3ce508, v71
	v_rcp_f32_e32 v79, v71
	global_load_ushort v71, v[72:73], off offset:2048
	v_add_co_u32_e32 v72, vcc, s81, v80
	s_nop 1
	v_addc_co_u32_e32 v73, vcc, 0, v81, vcc
	global_load_ushort v72, v[72:73], off offset:2048
	s_waitcnt vmcnt(0)
	v_lshlrev_b32_e32 v73, 16, v72
	v_lshlrev_b32_e32 v72, 16, v71
	v_pk_mul_f32 v[72:73], v[78:79], v[72:73]
	v_add_u32_e32 v78, 0x34800, v64
	v_pk_mul_f32 v[52:53], v[52:53], v[72:73]
	v_add_u32_e32 v72, v78, v65
	v_ashrrev_i32_e32 v73, 31, v72
	v_lshl_add_u64 v[72:73], v[72:73], 1, s[6:7]
	v_add_co_u32_e32 v80, vcc, s75, v72
	s_nop 1
	v_addc_co_u32_e32 v81, vcc, 0, v73, vcc
	global_load_ushort v71, v[80:81], off
	v_add_co_u32_e32 v84, vcc, s75, v82
	s_waitcnt vmcnt(0)
	v_lshlrev_b32_e32 v71, 16, v71
	v_max_f32_e32 v71, v71, v71
	v_max_f32_e32 v71, 0x1e3ce508, v71
	v_addc_co_u32_e32 v85, vcc, 0, v83, vcc
	v_rcp_f32_e32 v80, v71
	global_load_ushort v71, v[84:85], off
	v_add_co_u32_e32 v72, vcc, s81, v72
	s_waitcnt vmcnt(0)
	v_lshlrev_b32_e32 v71, 16, v71
	v_max_f32_e32 v71, v71, v71
	v_max_f32_e32 v71, 0x1e3ce508, v71
	v_addc_co_u32_e32 v73, vcc, 0, v73, vcc
	v_rcp_f32_e32 v81, v71
	global_load_ushort v71, v[72:73], off offset:2048
	v_add_co_u32_e32 v72, vcc, s81, v82
	s_nop 1
	v_addc_co_u32_e32 v73, vcc, 0, v83, vcc
	global_load_ushort v72, v[72:73], off offset:2048
	s_waitcnt vmcnt(0)
	v_lshlrev_b32_e32 v73, 16, v72
	v_lshlrev_b32_e32 v72, 16, v71
	v_pk_mul_f32 v[72:73], v[80:81], v[72:73]
	s_nop 0
	v_pk_mul_f32 v[54:55], v[54:55], v[72:73]
	v_add_u32_e32 v72, 0x3c000, v64
	v_add_u32_e32 v80, v72, v65
	v_ashrrev_i32_e32 v81, 31, v80
	v_lshl_add_u64 v[80:81], v[80:81], 1, s[6:7]
	v_add_co_u32_e32 v82, vcc, s75, v80
	s_nop 1
	v_addc_co_u32_e32 v83, vcc, 0, v81, vcc
	global_load_ushort v71, v[82:83], off
	s_waitcnt vmcnt(0)
	v_lshlrev_b32_e32 v71, 16, v71
	v_max_f32_e32 v71, v71, v71
	v_max_f32_e32 v71, 0x1e3ce508, v71
	v_rcp_f32_e32 v82, v71
	v_add_u32_e32 v71, 0x3d400, v64
	v_add_u32_e32 v84, v71, v65
	v_ashrrev_i32_e32 v85, 31, v84
	v_lshl_add_u64 v[84:85], v[84:85], 1, s[6:7]
	v_add_co_u32_e32 v86, vcc, s75, v84
	s_nop 1
	v_addc_co_u32_e32 v87, vcc, 0, v85, vcc
	global_load_ushort v73, v[86:87], off
	v_add_co_u32_e32 v80, vcc, s81, v80
	s_waitcnt vmcnt(0)
	v_lshlrev_b32_e32 v73, 16, v73
	v_max_f32_e32 v73, v73, v73
	v_max_f32_e32 v73, 0x1e3ce508, v73
	v_addc_co_u32_e32 v81, vcc, 0, v81, vcc
	v_rcp_f32_e32 v83, v73
	global_load_ushort v73, v[80:81], off offset:2048
	v_add_co_u32_e32 v80, vcc, s81, v84
	s_nop 1
	v_addc_co_u32_e32 v81, vcc, 0, v85, vcc
	global_load_ushort v74, v[80:81], off offset:2048
	s_waitcnt vmcnt(1)
	v_lshlrev_b32_e32 v80, 16, v73
	v_add_u32_e32 v73, 0x3e800, v64
	s_waitcnt vmcnt(0)
; DI float bf2f(bf16_t v) { return __uint_as_float(((unsigned)v) << 16); }
; DI int crow(int r, int h) { return (r & 3) + 8 * (r >> 2) + 4 * h; }
; DI void phase_merge(const Params& p, int g, char* smem, int bid, int nb) {
;     ...
;     const bf16_t* pt = proj + (size_t)mt * 128 * NPROJ; bf16_t* mgt = mg + (size_t)mt * 128 * 1024;
; #pragma unroll
;     for (int mi = 0; mi < 2; ++mi)
; #pragma unroll
;       for (int ni = 0; ni < 2; ++ni)
; #pragma unroll
;         for (int r = 0; r < 16; ++r) {
;           const int off = (wm * 64 + mi * 32 + crow(r, h)) * NPROJ + nt * 128 + wn * 64 + ni * 32 + l31;
;           const float sga = bf2f(pt[off + PGA]), sgb = fmaxf(bf2f(pt[off + PGB]), 1e-20f);
;           acc[mi][ni][r] *= sga * __builtin_amdgcn_rcpf(sgb);
;           if (r == 15) asm volatile("" ::: "memory");
;         }
	v_lshlrev_b32_e32 v81, 16, v74
	v_pk_mul_f32 v[80:81], v[82:83], v[80:81]
	s_nop 0
	v_pk_mul_f32 v[56:57], v[56:57], v[80:81]
	v_add_u32_e32 v80, v73, v65
	v_ashrrev_i32_e32 v81, 31, v80
	v_lshl_add_u64 v[80:81], v[80:81], 1, s[6:7]
	v_add_co_u32_e32 v82, vcc, s75, v80
	s_nop 1
	v_addc_co_u32_e32 v83, vcc, 0, v81, vcc
	global_load_ushort v74, v[82:83], off
	s_waitcnt vmcnt(0)
	v_lshlrev_b32_e32 v74, 16, v74
	v_max_f32_e32 v74, v74, v74
	v_max_f32_e32 v74, 0x1e3ce508, v74
	v_rcp_f32_e32 v82, v74
	v_add_u32_e32 v74, 0x3fc00, v64
	v_add_u32_e32 v84, v74, v65
	v_ashrrev_i32_e32 v85, 31, v84
	v_lshl_add_u64 v[84:85], v[84:85], 1, s[6:7]
	v_add_co_u32_e32 v86, vcc, s75, v84
	s_nop 1
	v_addc_co_u32_e32 v87, vcc, 0, v85, vcc
	global_load_ushort v79, v[86:87], off
	v_add_co_u32_e32 v80, vcc, s81, v80
	s_waitcnt vmcnt(0)
	v_lshlrev_b32_e32 v79, 16, v79
	v_max_f32_e32 v79, v79, v79
	v_max_f32_e32 v79, 0x1e3ce508, v79
	v_addc_co_u32_e32 v81, vcc, 0, v81, vcc
	v_rcp_f32_e32 v83, v79
	global_load_ushort v79, v[80:81], off offset:2048
	v_add_co_u32_e32 v80, vcc, s81, v84
	s_nop 1
	v_addc_co_u32_e32 v81, vcc, 0, v85, vcc
	global_load_ushort v80, v[80:81], off offset:2048
	s_waitcnt vmcnt(0)
	v_lshlrev_b32_e32 v81, 16, v80
	v_lshlrev_b32_e32 v80, 16, v79
	v_pk_mul_f32 v[80:81], v[82:83], v[80:81]
	v_add_u32_e32 v79, 0x46000, v64
	v_pk_mul_f32 v[58:59], v[58:59], v[80:81]
	v_add_u32_e32 v80, v79, v65
	v_ashrrev_i32_e32 v81, 31, v80
	v_lshl_add_u64 v[82:83], v[80:81], 1, s[6:7]
	v_add_co_u32_e32 v80, vcc, s75, v82
	s_nop 1
	v_addc_co_u32_e32 v81, vcc, 0, v83, vcc
	global_load_ushort v80, v[80:81], off
	s_waitcnt vmcnt(0)
	v_lshlrev_b32_e32 v80, 16, v80
	v_max_f32_e32 v80, v80, v80
	v_max_f32_e32 v80, 0x1e3ce508, v80
	v_rcp_f32_e32 v84, v80
	v_add_u32_e32 v80, 0x47400, v64
	v_add_u32_e32 v86, v80, v65
	v_ashrrev_i32_e32 v87, 31, v86
	v_lshl_add_u64 v[86:87], v[86:87], 1, s[6:7]
	v_add_co_u32_e32 v88, vcc, s75, v86
	s_nop 1
	v_addc_co_u32_e32 v89, vcc, 0, v87, vcc
	global_load_ushort v81, v[88:89], off
	v_add_co_u32_e32 v82, vcc, s81, v82
	s_waitcnt vmcnt(0)
	v_lshlrev_b32_e32 v81, 16, v81
	v_max_f32_e32 v81, v81, v81
	v_max_f32_e32 v81, 0x1e3ce508, v81
	v_addc_co_u32_e32 v83, vcc, 0, v83, vcc
	v_rcp_f32_e32 v85, v81
	global_load_ushort v81, v[82:83], off offset:2048
	v_add_co_u32_e32 v82, vcc, s81, v86
	s_nop 1
	v_addc_co_u32_e32 v83, vcc, 0, v87, vcc
	global_load_ushort v82, v[82:83], off offset:2048
	s_waitcnt vmcnt(0)
	v_lshlrev_b32_e32 v83, 16, v82
	v_lshlrev_b32_e32 v82, 16, v81
	v_pk_mul_f32 v[82:83], v[84:85], v[82:83]
	v_add_u32_e32 v81, 0x48800, v64
	v_pk_mul_f32 v[60:61], v[60:61], v[82:83]
	v_add_u32_e32 v82, v81, v65
	v_ashrrev_i32_e32 v83, 31, v82
	v_lshl_add_u64 v[84:85], v[82:83], 1, s[6:7]
	v_add_co_u32_e32 v82, vcc, s75, v84
	s_nop 1
	v_addc_co_u32_e32 v83, vcc, 0, v85, vcc
	global_load_ushort v82, v[82:83], off
	s_waitcnt vmcnt(0)
	v_lshlrev_b32_e32 v82, 16, v82
	v_max_f32_e32 v82, v82, v82
	v_max_f32_e32 v82, 0x1e3ce508, v82
	v_rcp_f32_e32 v86, v82
	v_add_u32_e32 v82, 0x49c00, v64
	v_add_u32_e32 v64, v82, v65
	v_ashrrev_i32_e32 v65, 31, v64
	v_lshl_add_u64 v[64:65], v[64:65], 1, s[6:7]
	v_add_co_u32_e32 v88, vcc, s75, v64
	s_nop 1
	v_addc_co_u32_e32 v89, vcc, 0, v65, vcc
	global_load_ushort v83, v[88:89], off
	v_add_co_u32_e32 v84, vcc, s81, v84
	s_waitcnt vmcnt(0)
	v_lshlrev_b32_e32 v83, 16, v83
	v_addc_co_u32_e32 v85, vcc, 0, v85, vcc
	v_max_f32_e32 v83, v83, v83
	v_add_co_u32_e32 v64, vcc, s81, v64
	v_max_f32_e32 v83, 0x1e3ce508, v83
	s_nop 0
	v_addc_co_u32_e32 v65, vcc, 0, v65, vcc
	v_rcp_f32_e32 v87, v83
	global_load_ushort v83, v[84:85], off offset:2048
	s_nop 0
	global_load_ushort v64, v[64:65], off offset:2048
	s_waitcnt vmcnt(0)
	v_lshlrev_b32_e32 v65, 16, v64
	v_lshlrev_b32_e32 v64, 16, v83
	v_pk_mul_f32 v[64:65], v[86:87], v[64:65]
	s_nop 0
	v_pk_mul_f32 v[62:63], v[62:63], v[64:65]
	v_add_u32_e32 v64, v66, v70
	v_ashrrev_i32_e32 v65, 31, v64
	v_lshl_add_u64 v[64:65], v[64:65], 1, s[6:7]
	v_add_co_u32_e32 v84, vcc, s75, v64
	s_nop 1
	v_addc_co_u32_e32 v85, vcc, 0, v65, vcc
	global_load_ushort v66, v[84:85], off
	v_add_u32_e32 v84, v67, v70
	v_ashrrev_i32_e32 v85, 31, v84
	v_lshl_add_u64 v[84:85], v[84:85], 1, s[6:7]
	v_add_co_u32_e32 v86, vcc, s75, v84
	s_waitcnt vmcnt(0)
	v_lshlrev_b32_e32 v66, 16, v66
	v_addc_co_u32_e32 v87, vcc, 0, v85, vcc
	global_load_ushort v67, v[86:87], off
	v_add_co_u32_e32 v64, vcc, s81, v64
	v_max_f32_e32 v66, v66, v66
	s_nop 0
	v_addc_co_u32_e32 v65, vcc, 0, v65, vcc
	global_load_ushort v83, v[64:65], off offset:2048
	v_add_co_u32_e32 v64, vcc, s81, v84
	v_max_f32_e32 v66, 0x1e3ce508, v66
	s_nop 0
	v_addc_co_u32_e32 v65, vcc, 0, v85, vcc
	global_load_ushort v64, v[64:65], off offset:2048
	v_rcp_f32_e32 v66, v66
	s_waitcnt vmcnt(2)
	v_lshlrev_b32_e32 v67, 16, v67
	v_max_f32_e32 v67, v67, v67
	v_max_f32_e32 v67, 0x1e3ce508, v67
	v_rcp_f32_e32 v67, v67
	s_waitcnt vmcnt(0)
	v_lshlrev_b32_e32 v65, 16, v64
	v_lshlrev_b32_e32 v64, 16, v83
	v_pk_mul_f32 v[64:65], v[66:67], v[64:65]
	s_nop 0
	v_pk_mul_f32 v[16:17], v[16:17], v[64:65]
	v_add_u32_e32 v64, v68, v70
	v_ashrrev_i32_e32 v65, 31, v64
	v_lshl_add_u64 v[64:65], v[64:65], 1, s[6:7]
	v_add_u32_e32 v68, v69, v70
	v_add_co_u32_e32 v66, vcc, s75, v64
	v_ashrrev_i32_e32 v69, 31, v68
	s_nop 0
	v_addc_co_u32_e32 v67, vcc, 0, v65, vcc
	v_lshl_add_u64 v[68:69], v[68:69], 1, s[6:7]
	v_add_co_u32_e32 v84, vcc, s75, v68
	global_load_ushort v66, v[66:67], off
	s_nop 0
	v_addc_co_u32_e32 v85, vcc, 0, v69, vcc
	v_add_co_u32_e32 v64, vcc, s81, v64
	s_nop 1
	v_addc_co_u32_e32 v65, vcc, 0, v65, vcc
	global_load_ushort v83, v[64:65], off offset:2048
	global_load_ushort v67, v[84:85], off
	v_add_co_u32_e32 v64, vcc, s81, v68
	v_add_u32_e32 v68, v77, v70
	s_nop 0
	v_addc_co_u32_e32 v65, vcc, 0, v69, vcc
	global_load_ushort v64, v[64:65], off offset:2048
	v_ashrrev_i32_e32 v69, 31, v68
	v_lshl_add_u64 v[68:69], v[68:69], 1, s[6:7]
	s_waitcnt vmcnt(3)
; DI float bf2f(bf16_t v) { return __uint_as_float(((unsigned)v) << 16); }
; DI int crow(int r, int h) { return (r & 3) + 8 * (r >> 2) + 4 * h; }
; DI void phase_merge(const Params& p, int g, char* smem, int bid, int nb) {
;     ...
;     const bf16_t* pt = proj + (size_t)mt * 128 * NPROJ; bf16_t* mgt = mg + (size_t)mt * 128 * 1024;
; #pragma unroll
;     for (int mi = 0; mi < 2; ++mi)
; #pragma unroll
;       for (int ni = 0; ni < 2; ++ni)
; #pragma unroll
;         for (int r = 0; r < 16; ++r) {
;           const int off = (wm * 64 + mi * 32 + crow(r, h)) * NPROJ + nt * 128 + wn * 64 + ni * 32 + l31;
;           const float sga = bf2f(pt[off + PGA]), sgb = fmaxf(bf2f(pt[off + PGB]), 1e-20f);
;           acc[mi][ni][r] *= sga * __builtin_amdgcn_rcpf(sgb);
;           if (r == 15) asm volatile("" ::: "memory");
;         }
	v_lshlrev_b32_e32 v66, 16, v66
	v_max_f32_e32 v66, v66, v66
	v_max_f32_e32 v66, 0x1e3ce508, v66
	v_rcp_f32_e32 v66, v66
	s_waitcnt vmcnt(1)
	v_lshlrev_b32_e32 v67, 16, v67
	v_max_f32_e32 v67, v67, v67
	v_max_f32_e32 v67, 0x1e3ce508, v67
	v_rcp_f32_e32 v67, v67
	s_waitcnt vmcnt(0)
	v_lshlrev_b32_e32 v65, 16, v64
	v_lshlrev_b32_e32 v64, 16, v83
	v_pk_mul_f32 v[64:65], v[66:67], v[64:65]
	s_nop 0
	v_pk_mul_f32 v[18:19], v[18:19], v[64:65]
	v_add_u32_e32 v64, v75, v70
	v_ashrrev_i32_e32 v65, 31, v64
	v_lshl_add_u64 v[64:65], v[64:65], 1, s[6:7]
	v_add_co_u32_e32 v66, vcc, s75, v64
	s_nop 1
	v_addc_co_u32_e32 v67, vcc, 0, v65, vcc
	v_add_co_u32_e32 v84, vcc, s75, v68
	global_load_ushort v66, v[66:67], off
	s_nop 0
	v_addc_co_u32_e32 v85, vcc, 0, v69, vcc
	v_add_co_u32_e32 v64, vcc, s81, v64
	s_nop 1
	v_addc_co_u32_e32 v65, vcc, 0, v65, vcc
	global_load_ushort v75, v[64:65], off offset:2048
	global_load_ushort v67, v[84:85], off
	v_add_co_u32_e32 v64, vcc, s81, v68
	v_add_u32_e32 v68, v76, v70
	s_nop 0
	v_addc_co_u32_e32 v65, vcc, 0, v69, vcc
	global_load_ushort v64, v[64:65], off offset:2048
	v_ashrrev_i32_e32 v69, 31, v68
	v_lshl_add_u64 v[68:69], v[68:69], 1, s[6:7]
	s_waitcnt vmcnt(3)
	v_lshlrev_b32_e32 v66, 16, v66
	v_max_f32_e32 v66, v66, v66
	v_max_f32_e32 v66, 0x1e3ce508, v66
	v_rcp_f32_e32 v66, v66
	s_waitcnt vmcnt(1)
	v_lshlrev_b32_e32 v67, 16, v67
	v_max_f32_e32 v67, v67, v67
	v_max_f32_e32 v67, 0x1e3ce508, v67
	v_rcp_f32_e32 v67, v67
	s_waitcnt vmcnt(0)
	v_lshlrev_b32_e32 v65, 16, v64
	v_lshlrev_b32_e32 v64, 16, v75
	v_pk_mul_f32 v[64:65], v[66:67], v[64:65]
	s_nop 0
	v_pk_mul_f32 v[20:21], v[20:21], v[64:65]
	v_add_u32_e32 v64, v78, v70
	v_ashrrev_i32_e32 v65, 31, v64
	v_lshl_add_u64 v[66:67], v[64:65], 1, s[6:7]
	v_add_co_u32_e32 v64, vcc, s75, v66
	s_nop 1
	v_addc_co_u32_e32 v65, vcc, 0, v67, vcc
	v_add_co_u32_e32 v76, vcc, s75, v68
	global_load_ushort v64, v[64:65], off
	s_nop 0
	v_addc_co_u32_e32 v77, vcc, 0, v69, vcc
	v_add_co_u32_e32 v66, vcc, s81, v66
	s_nop 1
	v_addc_co_u32_e32 v67, vcc, 0, v67, vcc
	global_load_ushort v75, v[66:67], off offset:2048
	global_load_ushort v65, v[76:77], off
	v_add_co_u32_e32 v66, vcc, s81, v68
	v_add_u32_e32 v68, v71, v70
	s_nop 0
	v_addc_co_u32_e32 v67, vcc, 0, v69, vcc
	global_load_ushort v66, v[66:67], off offset:2048
	v_ashrrev_i32_e32 v69, 31, v68
	v_lshl_add_u64 v[68:69], v[68:69], 1, s[6:7]
	s_waitcnt vmcnt(3)
	v_lshlrev_b32_e32 v64, 16, v64
	v_max_f32_e32 v64, v64, v64
	v_max_f32_e32 v64, 0x1e3ce508, v64
	v_rcp_f32_e32 v64, v64
	s_waitcnt vmcnt(1)
	v_lshlrev_b32_e32 v65, 16, v65
	v_max_f32_e32 v65, v65, v65
	v_max_f32_e32 v65, 0x1e3ce508, v65
	v_rcp_f32_e32 v65, v65
	s_waitcnt vmcnt(0)
	v_lshlrev_b32_e32 v67, 16, v66
	v_lshlrev_b32_e32 v66, 16, v75
	v_pk_mul_f32 v[64:65], v[64:65], v[66:67]
	s_nop 0
	v_pk_mul_f32 v[22:23], v[22:23], v[64:65]
	v_add_u32_e32 v64, v72, v70
	v_ashrrev_i32_e32 v65, 31, v64
	v_lshl_add_u64 v[64:65], v[64:65], 1, s[6:7]
	v_add_co_u32_e32 v66, vcc, s75, v64
	s_nop 1
	v_addc_co_u32_e32 v67, vcc, 0, v65, vcc
	v_add_co_u32_e32 v76, vcc, s75, v68
	global_load_ushort v66, v[66:67], off
	s_nop 0
	v_addc_co_u32_e32 v77, vcc, 0, v69, vcc
	v_add_co_u32_e32 v64, vcc, s81, v64
	s_nop 1
	v_addc_co_u32_e32 v65, vcc, 0, v65, vcc
	global_load_ushort v71, v[64:65], off offset:2048
	global_load_ushort v67, v[76:77], off
	v_add_co_u32_e32 v64, vcc, s81, v68
	v_add_u32_e32 v68, v74, v70
	s_nop 0
	v_addc_co_u32_e32 v65, vcc, 0, v69, vcc
	global_load_ushort v64, v[64:65], off offset:2048
	v_ashrrev_i32_e32 v69, 31, v68
	v_lshl_add_u64 v[68:69], v[68:69], 1, s[6:7]
	s_waitcnt vmcnt(3)
	v_lshlrev_b32_e32 v66, 16, v66
	v_max_f32_e32 v66, v66, v66
	v_max_f32_e32 v66, 0x1e3ce508, v66
	v_rcp_f32_e32 v66, v66
	s_waitcnt vmcnt(1)
	v_lshlrev_b32_e32 v67, 16, v67
	v_max_f32_e32 v67, v67, v67
	v_max_f32_e32 v67, 0x1e3ce508, v67
	v_rcp_f32_e32 v67, v67
	s_waitcnt vmcnt(0)
	v_lshlrev_b32_e32 v65, 16, v64
	v_lshlrev_b32_e32 v64, 16, v71
	v_pk_mul_f32 v[64:65], v[66:67], v[64:65]
	s_nop 0
	v_pk_mul_f32 v[24:25], v[24:25], v[64:65]
	v_add_u32_e32 v64, v73, v70
	v_ashrrev_i32_e32 v65, 31, v64
	v_lshl_add_u64 v[64:65], v[64:65], 1, s[6:7]
	v_add_co_u32_e32 v66, vcc, s75, v64
	s_nop 1
	v_addc_co_u32_e32 v67, vcc, 0, v65, vcc
	v_add_co_u32_e32 v72, vcc, s75, v68
	global_load_ushort v66, v[66:67], off
	s_nop 0
	v_addc_co_u32_e32 v73, vcc, 0, v69, vcc
	v_add_co_u32_e32 v64, vcc, s81, v64
	s_nop 1
	v_addc_co_u32_e32 v65, vcc, 0, v65, vcc
	global_load_ushort v71, v[64:65], off offset:2048
	global_load_ushort v67, v[72:73], off
	v_add_co_u32_e32 v64, vcc, s81, v68
	v_add_u32_e32 v68, v80, v70
	s_nop 0
	v_addc_co_u32_e32 v65, vcc, 0, v69, vcc
	global_load_ushort v64, v[64:65], off offset:2048
	v_ashrrev_i32_e32 v69, 31, v68
	v_lshl_add_u64 v[68:69], v[68:69], 1, s[6:7]
	s_waitcnt vmcnt(3)
	v_lshlrev_b32_e32 v66, 16, v66
	v_max_f32_e32 v66, v66, v66
	v_max_f32_e32 v66, 0x1e3ce508, v66
	v_rcp_f32_e32 v66, v66
	s_waitcnt vmcnt(1)
	v_lshlrev_b32_e32 v67, 16, v67
	v_max_f32_e32 v67, v67, v67
	v_max_f32_e32 v67, 0x1e3ce508, v67
	v_rcp_f32_e32 v67, v67
	s_waitcnt vmcnt(0)
	v_lshlrev_b32_e32 v65, 16, v64
	v_lshlrev_b32_e32 v64, 16, v71
	v_pk_mul_f32 v[64:65], v[66:67], v[64:65]
	s_nop 0
	v_pk_mul_f32 v[26:27], v[26:27], v[64:65]
	v_add_u32_e32 v64, v79, v70
	v_ashrrev_i32_e32 v65, 31, v64
	v_lshl_add_u64 v[64:65], v[64:65], 1, s[6:7]
	v_add_co_u32_e32 v66, vcc, s75, v64
	s_nop 1
	v_addc_co_u32_e32 v67, vcc, 0, v65, vcc
	v_add_co_u32_e32 v72, vcc, s75, v68
	global_load_ushort v66, v[66:67], off
	s_nop 0
	v_addc_co_u32_e32 v73, vcc, 0, v69, vcc
	v_add_co_u32_e32 v64, vcc, s81, v64
	s_nop 1
	v_addc_co_u32_e32 v65, vcc, 0, v65, vcc
	global_load_ushort v71, v[64:65], off offset:2048
	global_load_ushort v67, v[72:73], off
	v_add_co_u32_e32 v64, vcc, s81, v68
	v_add_u32_e32 v68, v82, v70
	s_nop 0
	v_addc_co_u32_e32 v65, vcc, 0, v69, vcc
	global_load_ushort v64, v[64:65], off offset:2048
	v_ashrrev_i32_e32 v69, 31, v68
	v_lshl_add_u64 v[68:69], v[68:69], 1, s[6:7]
	s_waitcnt vmcnt(3)
; template <bool SWAP>
; DI void gemm_tile(const bf16_t* __restrict__ A, int lda, const bf16_t* __restrict__ Bt, int ldb, int K, f32x16 (&acc)[2][2], bf16_t* As, bf16_t* Bs_unused) {
;     ...
;   const int lr = tid >> 3, lc = (tid & 7) * 8;
;   const bf16_t* ga = A + (size_t)lr * lda + lc;
;   const bf16_t* gb = Bt + (size_t)lr * ldb + lc;
;   u32x4 ra0[4], rb0[4], ra1[4], rb1[4];
;   auto load_stage = [&](u32x4 (&ra)[4], u32x4 (&rb)[4], int t) __attribute__((always_inline)) {
; #pragma unroll
;     for (int i = 0; i < 4; ++i) { ra[i] = *(const u32x4*)(ga + (size_t)(32 * i) * lda + t * 64); rb[i] = *(const u32x4*)(gb + (size_t)(32 * i) * ldb + t * 64); }
;   };
;   auto write_stage = [&](const u32x4 (&ra)[4], const u32x4 (&rb)[4], int buf) __attribute__((always_inline)) {
;     bf16_t* Ad = As + buf * 2 * GT_IMG; bf16_t* Bd = Ad + GT_IMG;
; #pragma unroll
;     for (int i = 0; i < 4; ++i) { *(u32x4*)(Ad + (lr + 32 * i) * 72 + lc) = ra[i]; *(u32x4*)(Bd + (lr + 32 * i) * 72 + lc) = rb[i]; }
;   };
;   const int fr = lane & 31, fk = (lane >> 5) * 8;
;   const int pao = (wm * 64 + fr) * 72 + fk, pbo = GT_IMG + (wn * 64 + fr) * 72 + fk;
;   auto frag_read = [&](bf16x8 (&f)[4], const bf16_t* pa, const bf16_t* pb, int so) __attribute__((always_inline)) {
;     f[0] = *(const bf16x8*)(pa + so); f[1] = *(const bf16x8*)(pb + so); f[2] = *(const bf16x8*)(pb + 32 * 72 + so); f[3] = *(const bf16x8*)(pa + 32 * 72 + so);
;   };
;   auto mfma4 = [&](const bf16x8 (&f)[4]) __attribute__((always_inline)) {
;     if (SWAP) {
;       acc[0][0] = MFMA32(f[1], f[0], acc[0][0]); acc[0][1] = MFMA32(f[2], f[0], acc[0][1]);
;       acc[1][0] = MFMA32(f[1], f[3], acc[1][0]); acc[1][1] = MFMA32(f[2], f[3], acc[1][1]);
; DI void phase_merge(const Params& p, int g, char* smem, int bid, int nb) {
;     ...
;     const bf16_t* pt = proj + (size_t)mt * 128 * NPROJ; bf16_t* mgt = mg + (size_t)mt * 128 * 1024;
; #pragma unroll
;     for (int mi = 0; mi < 2; ++mi)
; #pragma unroll
;       for (int ni = 0; ni < 2; ++ni)
; #pragma unroll
;         for (int r = 0; r < 16; ++r) {
;           const int off = (wm * 64 + mi * 32 + crow(r, h)) * NPROJ + nt * 128 + wn * 64 + ni * 32 + l31;
;           const float sga = bf2f(pt[off + PGA]), sgb = fmaxf(bf2f(pt[off + PGB]), 1e-20f);
;           acc[mi][ni][r] *= sga * __builtin_amdgcn_rcpf(sgb);
;           if (r == 15) asm volatile("" ::: "memory");
;         }
	v_lshlrev_b32_e32 v66, 16, v66
	v_max_f32_e32 v66, v66, v66
	v_max_f32_e32 v66, 0x1e3ce508, v66
	v_rcp_f32_e32 v66, v66
	s_waitcnt vmcnt(1)
	v_lshlrev_b32_e32 v67, 16, v67
	v_max_f32_e32 v67, v67, v67
	v_max_f32_e32 v67, 0x1e3ce508, v67
	v_rcp_f32_e32 v67, v67
	s_waitcnt vmcnt(0)
	v_lshlrev_b32_e32 v65, 16, v64
	v_lshlrev_b32_e32 v64, 16, v71
	v_pk_mul_f32 v[64:65], v[66:67], v[64:65]
	s_nop 0
	v_pk_mul_f32 v[28:29], v[28:29], v[64:65]
	v_add_u32_e32 v64, v81, v70
	v_ashrrev_i32_e32 v65, 31, v64
	v_lshl_add_u64 v[64:65], v[64:65], 1, s[6:7]
	v_add_co_u32_e32 v66, vcc, s75, v64
	s_nop 1
	v_addc_co_u32_e32 v67, vcc, 0, v65, vcc
	v_add_co_u32_e32 v70, vcc, s75, v68
	global_load_ushort v66, v[66:67], off
	s_nop 0
	v_addc_co_u32_e32 v71, vcc, 0, v69, vcc
	global_load_ushort v67, v[70:71], off
	v_add_co_u32_e32 v64, vcc, s81, v64
	s_waitcnt vmcnt(1)
	v_lshlrev_b32_e32 v66, 16, v66
	v_addc_co_u32_e32 v65, vcc, 0, v65, vcc
	global_load_ushort v70, v[64:65], off offset:2048
	v_add_co_u32_e32 v64, vcc, s81, v68
	s_waitcnt vmcnt(1)
	v_lshlrev_b32_e32 v67, 16, v67
	v_addc_co_u32_e32 v65, vcc, 0, v69, vcc
	global_load_ushort v64, v[64:65], off offset:2048
	v_max_f32_e32 v66, v66, v66
	v_max_f32_e32 v67, v67, v67
	v_max_f32_e32 v66, 0x1e3ce508, v66
	v_max_f32_e32 v67, 0x1e3ce508, v67
	v_rcp_f32_e32 v66, v66
	v_rcp_f32_e32 v67, v67
	s_waitcnt vmcnt(0)
	v_lshlrev_b32_e32 v65, 16, v64
	v_lshlrev_b32_e32 v64, 16, v70
	v_ashrrev_i32_e32 v152, 3, v155
	v_pk_mul_f32 v[64:65], v[66:67], v[64:65]
	v_ashrrev_i32_e32 v153, 31, v152
	v_pk_mul_f32 v[30:31], v[30:31], v[64:65]
	v_lshlrev_b64 v[64:65], 11, v[152:153]
	v_lshlrev_b32_e32 v68, 4, v155
	v_lshl_add_u64 v[66:67], s[16:17], 0, v[64:65]
	v_and_b32_e32 v192, 0x70, v68
	v_lshl_add_u64 v[128:129], v[66:67], 0, v[192:193]
	v_lshl_add_u64 v[64:65], s[8:9], 0, v[64:65]
	v_add_co_u32_e32 v132, vcc, s18, v128
	v_lshl_add_u64 v[130:131], v[64:65], 0, v[192:193]
	s_nop 0
	v_addc_co_u32_e32 v133, vcc, 0, v129, vcc
	v_add_co_u32_e32 v134, vcc, s18, v130
	global_load_dwordx4 v[64:67], v[128:129], off
	global_load_dwordx4 v[68:71], v[130:131], off
	v_addc_co_u32_e32 v135, vcc, 0, v131, vcc
	v_add_co_u32_e32 v136, vcc, s19, v128
	global_load_dwordx4 v[72:75], v[132:133], off
	global_load_dwordx4 v[76:79], v[134:135], off
	v_addc_co_u32_e32 v137, vcc, 0, v129, vcc
	v_add_co_u32_e32 v138, vcc, s19, v130
	global_load_dwordx4 v[80:83], v[136:137], off
	s_nop 0
	v_addc_co_u32_e32 v139, vcc, 0, v131, vcc
	v_add_co_u32_e32 v140, vcc, s20, v128
	global_load_dwordx4 v[84:87], v[138:139], off
	s_nop 0
	v_addc_co_u32_e32 v141, vcc, 0, v129, vcc
	global_load_dwordx4 v[88:91], v[140:141], off
	v_add_co_u32_e32 v142, vcc, s20, v130
	v_mul_lo_u32 v152, v152, s71
	s_nop 0
	v_addc_co_u32_e32 v143, vcc, 0, v131, vcc
	global_load_dwordx4 v[92:95], v[142:143], off
	global_load_dwordx4 v[112:115], v[128:129], off offset:128
	global_load_dwordx4 v[96:99], v[130:131], off offset:128
	global_load_dwordx4 v[116:119], v[132:133], off offset:128
	global_load_dwordx4 v[100:103], v[134:135], off offset:128
	global_load_dwordx4 v[120:123], v[136:137], off offset:128
	global_load_dwordx4 v[104:107], v[138:139], off offset:128
	global_load_dwordx4 v[124:127], v[140:141], off offset:128
	global_load_dwordx4 v[108:111], v[142:143], off offset:128
	v_add3_u32 v152, 32, v152, v192
	s_barrier
	s_waitcnt vmcnt(15)
	ds_write_b128 v152, v[64:67]
	s_waitcnt vmcnt(14)
	ds_write_b128 v152, v[68:71] offset:18432
	s_waitcnt vmcnt(13)
	ds_write_b128 v152, v[72:75] offset:4608
	s_waitcnt vmcnt(12)
	ds_write_b128 v152, v[76:79] offset:23040
	s_waitcnt vmcnt(11)
	ds_write_b128 v152, v[80:83] offset:9216
	s_waitcnt vmcnt(10)
	ds_write_b128 v152, v[84:87] offset:27648
	s_waitcnt vmcnt(9)
	ds_write_b128 v152, v[88:91] offset:13824
	s_waitcnt vmcnt(8)
	ds_write_b128 v152, v[92:95] offset:32256
	global_load_dwordx4 v[80:83], v[128:129], off offset:256
	global_load_dwordx4 v[64:67], v[130:131], off offset:256
	global_load_dwordx4 v[84:87], v[132:133], off offset:256
	global_load_dwordx4 v[68:71], v[134:135], off offset:256
	global_load_dwordx4 v[88:91], v[136:137], off offset:256
	global_load_dwordx4 v[72:75], v[138:139], off offset:256
	global_load_dwordx4 v[92:95], v[140:141], off offset:256
	global_load_dwordx4 v[76:79], v[142:143], off offset:256
	v_lshrrev_b32_e32 v153, 2, v155
	v_and_b32_e32 v158, 0x5f, v155
	v_and_b32_e32 v154, 8, v153
	v_lshrrev_b32_e32 v153, 1, v155
	v_and_b32_e32 v155, 31, v155
	v_and_or_b32 v153, v153, s80, v155
	v_mad_u64_u32 v[156:157], s[8:9], v153, s72, v[154:155]
	v_lshl_add_u32 v153, v156, 1, 32
	v_mad_u32_u24 v154, v158, s72, v154
	s_waitcnt lgkmcnt(0)
	s_barrier
; template <bool SWAP>
; DI void gemm_tile(const bf16_t* __restrict__ A, int lda, const bf16_t* __restrict__ Bt, int ldb, int K, f32x16 (&acc)[2][2], bf16_t* As, bf16_t* Bs_unused) {
;     ...
;   auto step = [&](int buf, u32x4 (&ra)[4], u32x4 (&rb)[4], bool do_write, bool do_load, int tload) __attribute__((always_inline)) {
;     const bf16_t* pa = As + buf * 2 * GT_IMG + pao; const bf16_t* pb = As + buf * 2 * GT_IMG + pbo;
;     bf16_t* Ad = As + (buf ^ 1) * 2 * GT_IMG; bf16_t* Bd = Ad + GT_IMG;
;     bf16x8 F0[4], F1[4];
;     frag_read(F0, pa, pb, 0);
;     __builtin_amdgcn_sched_barrier(0);
;     frag_read(F1, pa, pb, 16);
;     mfma4(F0);
;     __builtin_amdgcn_sched_barrier(0);
;     frag_read(F0, pa, pb, 32);
;     mfma4(F1);
;     if (do_write) {
; #pragma unroll
;       for (int i = 0; i < 4; ++i) *(u32x4*)(Ad + (lr + 32 * i) * 72 + lc) = ra[i];
;     }
;     __builtin_amdgcn_sched_barrier(0);
;     frag_read(F1, pa, pb, 48);
;     mfma4(F0);
;     if (do_write) {
; #pragma unroll
;       for (int i = 0; i < 4; ++i) *(u32x4*)(Bd + (lr + 32 * i) * 72 + lc) = rb[i];
;     }
;     __builtin_amdgcn_sched_barrier(0);
;     mfma4(F1);
;     if (do_load) load_stage(ra, rb, tload);
;     __builtin_amdgcn_sched_barrier(0);
;   };
;   const int nk = K >> 6;
;   load_stage(ra0, rb0, 0); load_stage(ra1, rb1, 1);
;   __syncthreads();
;   write_stage(ra0, rb0, 0);
;   load_stage(ra0, rb0, 2);
;   __syncthreads();
;   for (int kt = 0; kt < nk; kt += 2) {
;     step(0, ra1, rb1, true, kt + 3 < nk, kt + 3);
;     __syncthreads();
;     step(1, ra0, rb0, kt + 2 < nk, kt + 4 < nk, kt + 4);
;     __syncthreads();
	v_lshl_add_u32 v154, v154, 1, 32
	ds_read_b128 v[156:159], v153
	ds_read_b128 v[160:163], v154 offset:18432
	ds_read_b128 v[164:167], v154 offset:23040
	ds_read_b128 v[168:171], v153 offset:4608
	v_add_u32_e32 v155, 0xd800, v152
	s_waitcnt lgkmcnt(2)
	v_mfma_f32_32x32x16_bf16 v[0:15], v[156:159], v[160:163], v[0:15]
	s_waitcnt lgkmcnt(1)
	v_mfma_f32_32x32x16_bf16 v[32:47], v[156:159], v[164:167], v[32:47]
	s_waitcnt lgkmcnt(0)
	v_mfma_f32_32x32x16_bf16 v[48:63], v[168:171], v[160:163], v[48:63]
	ds_read_b128 v[156:159], v154 offset:18464
	ds_read_b128 v[160:163], v154 offset:23072
	ds_read_b128 v[172:175], v153 offset:32
	ds_read_b128 v[176:179], v153 offset:4640
	v_mfma_f32_32x32x16_bf16 v[16:31], v[168:171], v[164:167], v[16:31]
	s_waitcnt lgkmcnt(1)
	v_mfma_f32_32x32x16_bf16 v[0:15], v[172:175], v[156:159], v[0:15]
	v_mfma_f32_32x32x16_bf16 v[32:47], v[172:175], v[160:163], v[32:47]
	s_waitcnt lgkmcnt(0)
	v_mfma_f32_32x32x16_bf16 v[48:63], v[176:179], v[156:159], v[48:63]
	ds_read_b128 v[156:159], v154 offset:18496
	ds_read_b128 v[164:167], v154 offset:23104
	ds_read_b128 v[168:171], v153 offset:64
	ds_read_b128 v[172:175], v153 offset:4672
	s_waitcnt vmcnt(15)
	ds_write_b128 v152, v[112:115] offset:36864
	s_waitcnt vmcnt(13)
	ds_write_b128 v152, v[116:119] offset:41472
	s_waitcnt vmcnt(11)
	ds_write_b128 v152, v[120:123] offset:46080
	s_waitcnt vmcnt(9)
	ds_write_b128 v152, v[124:127] offset:50688
	v_mfma_f32_32x32x16_bf16 v[16:31], v[176:179], v[160:163], v[16:31]
	ds_read_b128 v[112:115], v154 offset:18528
	ds_read_b128 v[116:119], v154 offset:23136
	ds_read_b128 v[120:123], v153 offset:96
	ds_read_b128 v[124:127], v153 offset:4704
	s_waitcnt lgkmcnt(9)
	v_mfma_f32_32x32x16_bf16 v[0:15], v[168:171], v[156:159], v[0:15]
	ds_write_b128 v152, v[96:99] offset:55296
	ds_write_b128 v152, v[100:103] offset:59904
	ds_write_b128 v152, v[104:107] offset:64512
	s_waitcnt vmcnt(8)
	ds_write_b128 v155, v[108:111] offset:13824
	v_mfma_f32_32x32x16_bf16 v[32:47], v[168:171], v[164:167], v[32:47]
	s_waitcnt lgkmcnt(12)
	v_mfma_f32_32x32x16_bf16 v[48:63], v[172:175], v[156:159], v[48:63]
	v_mfma_f32_32x32x16_bf16 v[16:31], v[172:175], v[164:167], v[16:31]
	s_waitcnt lgkmcnt(0)
	s_barrier
	ds_read_b128 v[156:159], v154 offset:55296
	ds_read_b128 v[160:163], v154 offset:59904
	ds_read_b128 v[164:167], v153 offset:36864
	ds_read_b128 v[168:171], v153 offset:41472
	v_mfma_f32_32x32x16_bf16 v[0:15], v[120:123], v[112:115], v[0:15]
	v_mfma_f32_32x32x16_bf16 v[32:47], v[120:123], v[116:119], v[32:47]
	v_mfma_f32_32x32x16_bf16 v[48:63], v[124:127], v[112:115], v[48:63]
	v_mfma_f32_32x32x16_bf16 v[16:31], v[124:127], v[116:119], v[16:31]
	global_load_dwordx4 v[96:99], v[128:129], off offset:384
	global_load_dwordx4 v[100:103], v[130:131], off offset:384
	global_load_dwordx4 v[104:107], v[132:133], off offset:384
	global_load_dwordx4 v[108:111], v[134:135], off offset:384
	global_load_dwordx4 v[112:115], v[136:137], off offset:384
	global_load_dwordx4 v[116:119], v[138:139], off offset:384
	global_load_dwordx4 v[120:123], v[140:141], off offset:384
	global_load_dwordx4 v[124:127], v[142:143], off offset:384
	s_waitcnt lgkmcnt(1)
	v_mfma_f32_32x32x16_bf16 v[0:15], v[164:167], v[156:159], v[0:15]
	v_mfma_f32_32x32x16_bf16 v[32:47], v[164:167], v[160:163], v[32:47]
	s_waitcnt lgkmcnt(0)
	v_mfma_f32_32x32x16_bf16 v[48:63], v[168:171], v[156:159], v[48:63]
	ds_read_b128 v[156:159], v154 offset:55328
	ds_read_b128 v[164:167], v154 offset:59936
	ds_read_b128 v[172:175], v153 offset:36896
	ds_read_b128 v[176:179], v153 offset:41504
	v_mfma_f32_32x32x16_bf16 v[16:31], v[168:171], v[160:163], v[16:31]
	s_waitcnt lgkmcnt(1)
	v_mfma_f32_32x32x16_bf16 v[0:15], v[172:175], v[156:159], v[0:15]
	v_mfma_f32_32x32x16_bf16 v[32:47], v[172:175], v[164:167], v[32:47]
	s_waitcnt lgkmcnt(0)
	v_mfma_f32_32x32x16_bf16 v[48:63], v[176:179], v[156:159], v[48:63]
	ds_read_b128 v[156:159], v154 offset:55360
	ds_read_b128 v[160:163], v154 offset:59968
	ds_read_b128 v[168:171], v153 offset:36928
	ds_read_b128 v[172:175], v153 offset:41536
	s_waitcnt vmcnt(15)
	ds_write_b128 v152, v[80:83]
	s_waitcnt vmcnt(13)
	ds_write_b128 v152, v[84:87] offset:4608
	s_waitcnt vmcnt(11)
	ds_write_b128 v152, v[88:91] offset:9216
	s_waitcnt vmcnt(9)
	ds_write_b128 v152, v[92:95] offset:13824
	v_mfma_f32_32x32x16_bf16 v[16:31], v[176:179], v[164:167], v[16:31]
	ds_read_b128 v[80:83], v154 offset:55392
	ds_read_b128 v[84:87], v154 offset:60000
	ds_read_b128 v[88:91], v153 offset:36960
	ds_read_b128 v[92:95], v153 offset:41568
	s_waitcnt lgkmcnt(9)
	v_mfma_f32_32x32x16_bf16 v[0:15], v[168:171], v[156:159], v[0:15]
	ds_write_b128 v152, v[64:67] offset:18432
	ds_write_b128 v152, v[68:71] offset:23040
	ds_write_b128 v152, v[72:75] offset:27648
	s_waitcnt vmcnt(8)
	ds_write_b128 v152, v[76:79] offset:32256
	v_mfma_f32_32x32x16_bf16 v[32:47], v[168:171], v[160:163], v[32:47]
	s_waitcnt lgkmcnt(12)
	v_mfma_f32_32x32x16_bf16 v[48:63], v[172:175], v[156:159], v[48:63]
	v_mfma_f32_32x32x16_bf16 v[16:31], v[172:175], v[160:163], v[16:31]
	s_waitcnt lgkmcnt(0)
	s_barrier
; template <bool SWAP>
; DI void gemm_tile(const bf16_t* __restrict__ A, int lda, const bf16_t* __restrict__ Bt, int ldb, int K, f32x16 (&acc)[2][2], bf16_t* As, bf16_t* Bs_unused) {
;     ...
;   auto step = [&](int buf, u32x4 (&ra)[4], u32x4 (&rb)[4], bool do_write, bool do_load, int tload) __attribute__((always_inline)) {
;     const bf16_t* pa = As + buf * 2 * GT_IMG + pao; const bf16_t* pb = As + buf * 2 * GT_IMG + pbo;
;     bf16_t* Ad = As + (buf ^ 1) * 2 * GT_IMG; bf16_t* Bd = Ad + GT_IMG;
;     bf16x8 F0[4], F1[4];
;     frag_read(F0, pa, pb, 0);
;     __builtin_amdgcn_sched_barrier(0);
;     frag_read(F1, pa, pb, 16);
;     mfma4(F0);
;     __builtin_amdgcn_sched_barrier(0);
;     frag_read(F0, pa, pb, 32);
;     mfma4(F1);
;     if (do_write) {
; #pragma unroll
;       for (int i = 0; i < 4; ++i) *(u32x4*)(Ad + (lr + 32 * i) * 72 + lc) = ra[i];
;     }
;     __builtin_amdgcn_sched_barrier(0);
;     frag_read(F1, pa, pb, 48);
;     mfma4(F0);
;     if (do_write) {
; #pragma unroll
;       for (int i = 0; i < 4; ++i) *(u32x4*)(Bd + (lr + 32 * i) * 72 + lc) = rb[i];
;     }
;     __builtin_amdgcn_sched_barrier(0);
;     mfma4(F1);
;     if (do_load) load_stage(ra, rb, tload);
;     __builtin_amdgcn_sched_barrier(0);
;   };
;   const int nk = K >> 6;
;   load_stage(ra0, rb0, 0); load_stage(ra1, rb1, 1);
;   __syncthreads();
;   write_stage(ra0, rb0, 0);
;   load_stage(ra0, rb0, 2);
;   __syncthreads();
;   for (int kt = 0; kt < nk; kt += 2) {
;     step(0, ra1, rb1, true, kt + 3 < nk, kt + 3);
;     __syncthreads();
;     step(1, ra0, rb0, kt + 2 < nk, kt + 4 < nk, kt + 4);
;     __syncthreads();
	ds_read_b128 v[156:159], v154 offset:18432
	ds_read_b128 v[160:163], v154 offset:23040
	ds_read_b128 v[164:167], v153
	ds_read_b128 v[168:171], v153 offset:4608
	v_mfma_f32_32x32x16_bf16 v[0:15], v[88:91], v[80:83], v[0:15]
	v_mfma_f32_32x32x16_bf16 v[32:47], v[88:91], v[84:87], v[32:47]
	v_mfma_f32_32x32x16_bf16 v[48:63], v[92:95], v[80:83], v[48:63]
	v_mfma_f32_32x32x16_bf16 v[16:31], v[92:95], v[84:87], v[16:31]
	global_load_dwordx4 v[64:67], v[128:129], off offset:512
	global_load_dwordx4 v[68:71], v[130:131], off offset:512
	global_load_dwordx4 v[72:75], v[132:133], off offset:512
	global_load_dwordx4 v[76:79], v[134:135], off offset:512
	global_load_dwordx4 v[80:83], v[136:137], off offset:512
	global_load_dwordx4 v[84:87], v[138:139], off offset:512
	global_load_dwordx4 v[88:91], v[140:141], off offset:512
	global_load_dwordx4 v[92:95], v[142:143], off offset:512
	s_waitcnt lgkmcnt(1)
	v_mfma_f32_32x32x16_bf16 v[0:15], v[164:167], v[156:159], v[0:15]
	v_mfma_f32_32x32x16_bf16 v[32:47], v[164:167], v[160:163], v[32:47]
	s_waitcnt lgkmcnt(0)
	v_mfma_f32_32x32x16_bf16 v[48:63], v[168:171], v[156:159], v[48:63]
	ds_read_b128 v[156:159], v154 offset:18464
	ds_read_b128 v[164:167], v154 offset:23072
	ds_read_b128 v[172:175], v153 offset:32
	ds_read_b128 v[176:179], v153 offset:4640
	v_mfma_f32_32x32x16_bf16 v[16:31], v[168:171], v[160:163], v[16:31]
	s_waitcnt lgkmcnt(1)
	v_mfma_f32_32x32x16_bf16 v[0:15], v[172:175], v[156:159], v[0:15]
	v_mfma_f32_32x32x16_bf16 v[32:47], v[172:175], v[164:167], v[32:47]
	s_waitcnt lgkmcnt(0)
	v_mfma_f32_32x32x16_bf16 v[48:63], v[176:179], v[156:159], v[48:63]
	ds_read_b128 v[156:159], v154 offset:18496
	ds_read_b128 v[160:163], v154 offset:23104
	ds_read_b128 v[168:171], v153 offset:64
	ds_read_b128 v[172:175], v153 offset:4672
	s_waitcnt vmcnt(15)
	ds_write_b128 v152, v[96:99] offset:36864
	s_waitcnt vmcnt(13)
	ds_write_b128 v152, v[104:107] offset:41472
	s_waitcnt vmcnt(11)
	ds_write_b128 v152, v[112:115] offset:46080
	s_waitcnt vmcnt(9)
	ds_write_b128 v152, v[120:123] offset:50688
	v_mfma_f32_32x32x16_bf16 v[16:31], v[176:179], v[164:167], v[16:31]
	ds_read_b128 v[96:99], v154 offset:18528
	ds_read_b128 v[104:107], v154 offset:23136
	ds_read_b128 v[112:115], v153 offset:96
	ds_read_b128 v[120:123], v153 offset:4704
	s_waitcnt lgkmcnt(9)
	v_mfma_f32_32x32x16_bf16 v[0:15], v[168:171], v[156:159], v[0:15]
	ds_write_b128 v152, v[100:103] offset:55296
	ds_write_b128 v152, v[108:111] offset:59904
	ds_write_b128 v152, v[116:119] offset:64512
	s_waitcnt vmcnt(8)
	ds_write_b128 v155, v[124:127] offset:13824
	v_mfma_f32_32x32x16_bf16 v[32:47], v[168:171], v[160:163], v[32:47]
	s_waitcnt lgkmcnt(12)
	v_mfma_f32_32x32x16_bf16 v[48:63], v[172:175], v[156:159], v[48:63]
	v_mfma_f32_32x32x16_bf16 v[16:31], v[172:175], v[160:163], v[16:31]
	s_waitcnt lgkmcnt(0)
	s_barrier
	ds_read_b128 v[156:159], v154 offset:55296
	ds_read_b128 v[160:163], v154 offset:59904
	ds_read_b128 v[164:167], v153 offset:36864
	ds_read_b128 v[168:171], v153 offset:41472
	v_mfma_f32_32x32x16_bf16 v[0:15], v[112:115], v[96:99], v[0:15]
	v_mfma_f32_32x32x16_bf16 v[32:47], v[112:115], v[104:107], v[32:47]
	v_mfma_f32_32x32x16_bf16 v[48:63], v[120:123], v[96:99], v[48:63]
	v_mfma_f32_32x32x16_bf16 v[16:31], v[120:123], v[104:107], v[16:31]
	global_load_dwordx4 v[96:99], v[128:129], off offset:640
	global_load_dwordx4 v[100:103], v[130:131], off offset:640
	global_load_dwordx4 v[104:107], v[132:133], off offset:640
	global_load_dwordx4 v[108:111], v[134:135], off offset:640
	global_load_dwordx4 v[112:115], v[136:137], off offset:640
	global_load_dwordx4 v[116:119], v[138:139], off offset:640
	global_load_dwordx4 v[120:123], v[140:141], off offset:640
	global_load_dwordx4 v[124:127], v[142:143], off offset:640
	s_waitcnt lgkmcnt(1)
	v_mfma_f32_32x32x16_bf16 v[0:15], v[164:167], v[156:159], v[0:15]
	v_mfma_f32_32x32x16_bf16 v[32:47], v[164:167], v[160:163], v[32:47]
	s_waitcnt lgkmcnt(0)
	v_mfma_f32_32x32x16_bf16 v[48:63], v[168:171], v[156:159], v[48:63]
	ds_read_b128 v[156:159], v154 offset:55328
	ds_read_b128 v[164:167], v154 offset:59936
	ds_read_b128 v[172:175], v153 offset:36896
	ds_read_b128 v[176:179], v153 offset:41504
	v_mfma_f32_32x32x16_bf16 v[16:31], v[168:171], v[160:163], v[16:31]
	s_waitcnt lgkmcnt(1)
	v_mfma_f32_32x32x16_bf16 v[0:15], v[172:175], v[156:159], v[0:15]
	v_mfma_f32_32x32x16_bf16 v[32:47], v[172:175], v[164:167], v[32:47]
	s_waitcnt lgkmcnt(0)
	v_mfma_f32_32x32x16_bf16 v[48:63], v[176:179], v[156:159], v[48:63]
	ds_read_b128 v[156:159], v154 offset:55360
	ds_read_b128 v[160:163], v154 offset:59968
	ds_read_b128 v[168:171], v153 offset:36928
	ds_read_b128 v[172:175], v153 offset:41536
	s_waitcnt vmcnt(15)
	ds_write_b128 v152, v[64:67]
	s_waitcnt vmcnt(13)
	ds_write_b128 v152, v[72:75] offset:4608
	s_waitcnt vmcnt(11)
	ds_write_b128 v152, v[80:83] offset:9216
	s_waitcnt vmcnt(9)
	ds_write_b128 v152, v[88:91] offset:13824
	v_mfma_f32_32x32x16_bf16 v[16:31], v[176:179], v[164:167], v[16:31]
	ds_read_b128 v[64:67], v154 offset:55392
	ds_read_b128 v[72:75], v154 offset:60000
	ds_read_b128 v[80:83], v153 offset:36960
	ds_read_b128 v[88:91], v153 offset:41568
	s_waitcnt lgkmcnt(9)
	v_mfma_f32_32x32x16_bf16 v[0:15], v[168:171], v[156:159], v[0:15]
	ds_write_b128 v152, v[68:71] offset:18432
	ds_write_b128 v152, v[76:79] offset:23040
	ds_write_b128 v152, v[84:87] offset:27648
	s_waitcnt vmcnt(8)
	ds_write_b128 v152, v[92:95] offset:32256
	v_mfma_f32_32x32x16_bf16 v[32:47], v[168:171], v[160:163], v[32:47]
	s_waitcnt lgkmcnt(12)
	v_mfma_f32_32x32x16_bf16 v[48:63], v[172:175], v[156:159], v[48:63]
	v_mfma_f32_32x32x16_bf16 v[16:31], v[172:175], v[160:163], v[16:31]
	s_waitcnt lgkmcnt(0)
	s_barrier
; template <bool SWAP>
; DI void gemm_tile(const bf16_t* __restrict__ A, int lda, const bf16_t* __restrict__ Bt, int ldb, int K, f32x16 (&acc)[2][2], bf16_t* As, bf16_t* Bs_unused) {
;     ...
;   auto step = [&](int buf, u32x4 (&ra)[4], u32x4 (&rb)[4], bool do_write, bool do_load, int tload) __attribute__((always_inline)) {
;     const bf16_t* pa = As + buf * 2 * GT_IMG + pao; const bf16_t* pb = As + buf * 2 * GT_IMG + pbo;
;     bf16_t* Ad = As + (buf ^ 1) * 2 * GT_IMG; bf16_t* Bd = Ad + GT_IMG;
;     bf16x8 F0[4], F1[4];
;     frag_read(F0, pa, pb, 0);
;     __builtin_amdgcn_sched_barrier(0);
;     frag_read(F1, pa, pb, 16);
;     mfma4(F0);
;     __builtin_amdgcn_sched_barrier(0);
;     frag_read(F0, pa, pb, 32);
;     mfma4(F1);
;     if (do_write) {
; #pragma unroll
;       for (int i = 0; i < 4; ++i) *(u32x4*)(Ad + (lr + 32 * i) * 72 + lc) = ra[i];
;     }
;     __builtin_amdgcn_sched_barrier(0);
;     frag_read(F1, pa, pb, 48);
;     mfma4(F0);
;     if (do_write) {
; #pragma unroll
;       for (int i = 0; i < 4; ++i) *(u32x4*)(Bd + (lr + 32 * i) * 72 + lc) = rb[i];
;     }
;     __builtin_amdgcn_sched_barrier(0);
;     mfma4(F1);
;     if (do_load) load_stage(ra, rb, tload);
;     __builtin_amdgcn_sched_barrier(0);
;   };
;   const int nk = K >> 6;
;   load_stage(ra0, rb0, 0); load_stage(ra1, rb1, 1);
;   __syncthreads();
;   write_stage(ra0, rb0, 0);
;   load_stage(ra0, rb0, 2);
;   __syncthreads();
;   for (int kt = 0; kt < nk; kt += 2) {
;     step(0, ra1, rb1, true, kt + 3 < nk, kt + 3);
;     __syncthreads();
;     step(1, ra0, rb0, kt + 2 < nk, kt + 4 < nk, kt + 4);
;     __syncthreads();
	ds_read_b128 v[156:159], v154 offset:18432
	ds_read_b128 v[160:163], v154 offset:23040
	ds_read_b128 v[164:167], v153
	ds_read_b128 v[168:171], v153 offset:4608
	v_mfma_f32_32x32x16_bf16 v[0:15], v[80:83], v[64:67], v[0:15]
	v_mfma_f32_32x32x16_bf16 v[32:47], v[80:83], v[72:75], v[32:47]
	v_mfma_f32_32x32x16_bf16 v[48:63], v[88:91], v[64:67], v[48:63]
	v_mfma_f32_32x32x16_bf16 v[16:31], v[88:91], v[72:75], v[16:31]
	global_load_dwordx4 v[64:67], v[128:129], off offset:768
	global_load_dwordx4 v[68:71], v[130:131], off offset:768
	global_load_dwordx4 v[72:75], v[132:133], off offset:768
	global_load_dwordx4 v[76:79], v[134:135], off offset:768
	global_load_dwordx4 v[80:83], v[136:137], off offset:768
	global_load_dwordx4 v[84:87], v[138:139], off offset:768
	global_load_dwordx4 v[88:91], v[140:141], off offset:768
	global_load_dwordx4 v[92:95], v[142:143], off offset:768
	s_waitcnt lgkmcnt(1)
	v_mfma_f32_32x32x16_bf16 v[0:15], v[164:167], v[156:159], v[0:15]
	v_mfma_f32_32x32x16_bf16 v[32:47], v[164:167], v[160:163], v[32:47]
	s_waitcnt lgkmcnt(0)
	v_mfma_f32_32x32x16_bf16 v[48:63], v[168:171], v[156:159], v[48:63]
	ds_read_b128 v[156:159], v154 offset:18464
	ds_read_b128 v[164:167], v154 offset:23072
	ds_read_b128 v[172:175], v153 offset:32
	ds_read_b128 v[176:179], v153 offset:4640
	v_mfma_f32_32x32x16_bf16 v[16:31], v[168:171], v[160:163], v[16:31]
	s_waitcnt lgkmcnt(1)
	v_mfma_f32_32x32x16_bf16 v[0:15], v[172:175], v[156:159], v[0:15]
	v_mfma_f32_32x32x16_bf16 v[32:47], v[172:175], v[164:167], v[32:47]
	s_waitcnt lgkmcnt(0)
	v_mfma_f32_32x32x16_bf16 v[48:63], v[176:179], v[156:159], v[48:63]
	ds_read_b128 v[156:159], v154 offset:18496
	ds_read_b128 v[160:163], v154 offset:23104
	ds_read_b128 v[168:171], v153 offset:64
	ds_read_b128 v[172:175], v153 offset:4672
	s_waitcnt vmcnt(15)
	ds_write_b128 v152, v[96:99] offset:36864
	s_waitcnt vmcnt(13)
	ds_write_b128 v152, v[104:107] offset:41472
	s_waitcnt vmcnt(11)
	ds_write_b128 v152, v[112:115] offset:46080
	s_waitcnt vmcnt(9)
	ds_write_b128 v152, v[120:123] offset:50688
	v_mfma_f32_32x32x16_bf16 v[16:31], v[176:179], v[164:167], v[16:31]
	ds_read_b128 v[96:99], v154 offset:18528
	ds_read_b128 v[104:107], v154 offset:23136
	ds_read_b128 v[112:115], v153 offset:96
	ds_read_b128 v[120:123], v153 offset:4704
	s_waitcnt lgkmcnt(9)
	v_mfma_f32_32x32x16_bf16 v[0:15], v[168:171], v[156:159], v[0:15]
	ds_write_b128 v152, v[100:103] offset:55296
	ds_write_b128 v152, v[108:111] offset:59904
	ds_write_b128 v152, v[116:119] offset:64512
	s_waitcnt vmcnt(8)
	ds_write_b128 v155, v[124:127] offset:13824
	v_mfma_f32_32x32x16_bf16 v[32:47], v[168:171], v[160:163], v[32:47]
	s_waitcnt lgkmcnt(12)
	v_mfma_f32_32x32x16_bf16 v[48:63], v[172:175], v[156:159], v[48:63]
	v_mfma_f32_32x32x16_bf16 v[16:31], v[172:175], v[160:163], v[16:31]
	s_waitcnt lgkmcnt(0)
	s_barrier
	ds_read_b128 v[156:159], v154 offset:55296
	ds_read_b128 v[160:163], v154 offset:59904
	ds_read_b128 v[164:167], v153 offset:36864
	ds_read_b128 v[168:171], v153 offset:41472
	v_mfma_f32_32x32x16_bf16 v[0:15], v[112:115], v[96:99], v[0:15]
	v_mfma_f32_32x32x16_bf16 v[32:47], v[112:115], v[104:107], v[32:47]
	v_mfma_f32_32x32x16_bf16 v[48:63], v[120:123], v[96:99], v[48:63]
	v_mfma_f32_32x32x16_bf16 v[16:31], v[120:123], v[104:107], v[16:31]
	global_load_dwordx4 v[96:99], v[128:129], off offset:896
	global_load_dwordx4 v[100:103], v[130:131], off offset:896
	global_load_dwordx4 v[104:107], v[132:133], off offset:896
	global_load_dwordx4 v[108:111], v[134:135], off offset:896
	global_load_dwordx4 v[112:115], v[136:137], off offset:896
	global_load_dwordx4 v[116:119], v[138:139], off offset:896
	global_load_dwordx4 v[120:123], v[140:141], off offset:896
	global_load_dwordx4 v[124:127], v[142:143], off offset:896
	s_waitcnt lgkmcnt(1)
	v_mfma_f32_32x32x16_bf16 v[0:15], v[164:167], v[156:159], v[0:15]
	v_mfma_f32_32x32x16_bf16 v[32:47], v[164:167], v[160:163], v[32:47]
	s_waitcnt lgkmcnt(0)
	v_mfma_f32_32x32x16_bf16 v[48:63], v[168:171], v[156:159], v[48:63]
	ds_read_b128 v[156:159], v154 offset:55328
	ds_read_b128 v[164:167], v154 offset:59936
	ds_read_b128 v[172:175], v153 offset:36896
	ds_read_b128 v[176:179], v153 offset:41504
	v_mfma_f32_32x32x16_bf16 v[16:31], v[168:171], v[160:163], v[16:31]
	s_waitcnt lgkmcnt(1)
	v_mfma_f32_32x32x16_bf16 v[0:15], v[172:175], v[156:159], v[0:15]
	v_mfma_f32_32x32x16_bf16 v[32:47], v[172:175], v[164:167], v[32:47]
	s_waitcnt lgkmcnt(0)
	v_mfma_f32_32x32x16_bf16 v[48:63], v[176:179], v[156:159], v[48:63]
	ds_read_b128 v[156:159], v154 offset:55360
	ds_read_b128 v[160:163], v154 offset:59968
	ds_read_b128 v[168:171], v153 offset:36928
	ds_read_b128 v[172:175], v153 offset:41536
	s_waitcnt vmcnt(15)
	ds_write_b128 v152, v[64:67]
	s_waitcnt vmcnt(13)
	ds_write_b128 v152, v[72:75] offset:4608
	s_waitcnt vmcnt(11)
	ds_write_b128 v152, v[80:83] offset:9216
	s_waitcnt vmcnt(9)
	ds_write_b128 v152, v[88:91] offset:13824
	v_mfma_f32_32x32x16_bf16 v[16:31], v[176:179], v[164:167], v[16:31]
	ds_read_b128 v[64:67], v154 offset:55392
	ds_read_b128 v[72:75], v154 offset:60000
	ds_read_b128 v[80:83], v153 offset:36960
	ds_read_b128 v[88:91], v153 offset:41568
	s_waitcnt lgkmcnt(9)
	v_mfma_f32_32x32x16_bf16 v[0:15], v[168:171], v[156:159], v[0:15]
	ds_write_b128 v152, v[68:71] offset:18432
	ds_write_b128 v152, v[76:79] offset:23040
	ds_write_b128 v152, v[84:87] offset:27648
	s_waitcnt vmcnt(8)
	ds_write_b128 v152, v[92:95] offset:32256
	v_mfma_f32_32x32x16_bf16 v[32:47], v[168:171], v[160:163], v[32:47]
	s_waitcnt lgkmcnt(12)
	v_mfma_f32_32x32x16_bf16 v[48:63], v[172:175], v[156:159], v[48:63]
	v_mfma_f32_32x32x16_bf16 v[16:31], v[172:175], v[160:163], v[16:31]
	s_waitcnt lgkmcnt(0)
	s_barrier
; template <bool SWAP>
; DI void gemm_tile(const bf16_t* __restrict__ A, int lda, const bf16_t* __restrict__ Bt, int ldb, int K, f32x16 (&acc)[2][2], bf16_t* As, bf16_t* Bs_unused) {
;     ...
;   auto step = [&](int buf, u32x4 (&ra)[4], u32x4 (&rb)[4], bool do_write, bool do_load, int tload) __attribute__((always_inline)) {
;     const bf16_t* pa = As + buf * 2 * GT_IMG + pao; const bf16_t* pb = As + buf * 2 * GT_IMG + pbo;
;     bf16_t* Ad = As + (buf ^ 1) * 2 * GT_IMG; bf16_t* Bd = Ad + GT_IMG;
;     bf16x8 F0[4], F1[4];
;     frag_read(F0, pa, pb, 0);
;     __builtin_amdgcn_sched_barrier(0);
;     frag_read(F1, pa, pb, 16);
;     mfma4(F0);
;     __builtin_amdgcn_sched_barrier(0);
;     frag_read(F0, pa, pb, 32);
;     mfma4(F1);
;     if (do_write) {
; #pragma unroll
;       for (int i = 0; i < 4; ++i) *(u32x4*)(Ad + (lr + 32 * i) * 72 + lc) = ra[i];
;     }
;     __builtin_amdgcn_sched_barrier(0);
;     frag_read(F1, pa, pb, 48);
;     mfma4(F0);
;     if (do_write) {
; #pragma unroll
;       for (int i = 0; i < 4; ++i) *(u32x4*)(Bd + (lr + 32 * i) * 72 + lc) = rb[i];
;     }
;     __builtin_amdgcn_sched_barrier(0);
;     mfma4(F1);
;     if (do_load) load_stage(ra, rb, tload);
;     __builtin_amdgcn_sched_barrier(0);
;   };
;   const int nk = K >> 6;
;   load_stage(ra0, rb0, 0); load_stage(ra1, rb1, 1);
;   __syncthreads();
;   write_stage(ra0, rb0, 0);
;   load_stage(ra0, rb0, 2);
;   __syncthreads();
;   for (int kt = 0; kt < nk; kt += 2) {
;     step(0, ra1, rb1, true, kt + 3 < nk, kt + 3);
;     __syncthreads();
;     step(1, ra0, rb0, kt + 2 < nk, kt + 4 < nk, kt + 4);
;     __syncthreads();
	ds_read_b128 v[156:159], v154 offset:18432
	ds_read_b128 v[160:163], v154 offset:23040
	ds_read_b128 v[164:167], v153
	ds_read_b128 v[168:171], v153 offset:4608
	v_mfma_f32_32x32x16_bf16 v[0:15], v[80:83], v[64:67], v[0:15]
	v_mfma_f32_32x32x16_bf16 v[32:47], v[80:83], v[72:75], v[32:47]
	v_mfma_f32_32x32x16_bf16 v[48:63], v[88:91], v[64:67], v[48:63]
	v_mfma_f32_32x32x16_bf16 v[16:31], v[88:91], v[72:75], v[16:31]
	global_load_dwordx4 v[64:67], v[128:129], off offset:1024
	global_load_dwordx4 v[68:71], v[130:131], off offset:1024
	global_load_dwordx4 v[72:75], v[132:133], off offset:1024
	global_load_dwordx4 v[76:79], v[134:135], off offset:1024
	global_load_dwordx4 v[80:83], v[136:137], off offset:1024
	global_load_dwordx4 v[84:87], v[138:139], off offset:1024
	global_load_dwordx4 v[88:91], v[140:141], off offset:1024
	global_load_dwordx4 v[92:95], v[142:143], off offset:1024
	s_waitcnt lgkmcnt(1)
	v_mfma_f32_32x32x16_bf16 v[0:15], v[164:167], v[156:159], v[0:15]
	v_mfma_f32_32x32x16_bf16 v[32:47], v[164:167], v[160:163], v[32:47]
	s_waitcnt lgkmcnt(0)
	v_mfma_f32_32x32x16_bf16 v[48:63], v[168:171], v[156:159], v[48:63]
	ds_read_b128 v[156:159], v154 offset:18464
	ds_read_b128 v[164:167], v154 offset:23072
	ds_read_b128 v[172:175], v153 offset:32
	ds_read_b128 v[176:179], v153 offset:4640
	v_mfma_f32_32x32x16_bf16 v[16:31], v[168:171], v[160:163], v[16:31]
	s_waitcnt lgkmcnt(1)
	v_mfma_f32_32x32x16_bf16 v[0:15], v[172:175], v[156:159], v[0:15]
	v_mfma_f32_32x32x16_bf16 v[32:47], v[172:175], v[164:167], v[32:47]
	s_waitcnt lgkmcnt(0)
	v_mfma_f32_32x32x16_bf16 v[48:63], v[176:179], v[156:159], v[48:63]
	ds_read_b128 v[156:159], v154 offset:18496
	ds_read_b128 v[160:163], v154 offset:23104
	ds_read_b128 v[168:171], v153 offset:64
	ds_read_b128 v[172:175], v153 offset:4672
	s_waitcnt vmcnt(15)
	ds_write_b128 v152, v[96:99] offset:36864
	s_waitcnt vmcnt(13)
	ds_write_b128 v152, v[104:107] offset:41472
	s_waitcnt vmcnt(11)
	ds_write_b128 v152, v[112:115] offset:46080
	s_waitcnt vmcnt(9)
	ds_write_b128 v152, v[120:123] offset:50688
	v_mfma_f32_32x32x16_bf16 v[16:31], v[176:179], v[164:167], v[16:31]
	ds_read_b128 v[96:99], v154 offset:18528
	ds_read_b128 v[104:107], v154 offset:23136
	ds_read_b128 v[112:115], v153 offset:96
	ds_read_b128 v[120:123], v153 offset:4704
	s_waitcnt lgkmcnt(9)
	v_mfma_f32_32x32x16_bf16 v[0:15], v[168:171], v[156:159], v[0:15]
	ds_write_b128 v152, v[100:103] offset:55296
	ds_write_b128 v152, v[108:111] offset:59904
	ds_write_b128 v152, v[116:119] offset:64512
	s_waitcnt vmcnt(8)
	ds_write_b128 v155, v[124:127] offset:13824
	v_mfma_f32_32x32x16_bf16 v[32:47], v[168:171], v[160:163], v[32:47]
	s_waitcnt lgkmcnt(12)
	v_mfma_f32_32x32x16_bf16 v[48:63], v[172:175], v[156:159], v[48:63]
	v_mfma_f32_32x32x16_bf16 v[16:31], v[172:175], v[160:163], v[16:31]
	s_waitcnt lgkmcnt(0)
	s_barrier
	ds_read_b128 v[156:159], v154 offset:55296
	ds_read_b128 v[160:163], v154 offset:59904
	ds_read_b128 v[164:167], v153 offset:36864
	ds_read_b128 v[168:171], v153 offset:41472
	v_mfma_f32_32x32x16_bf16 v[0:15], v[112:115], v[96:99], v[0:15]
	v_mfma_f32_32x32x16_bf16 v[32:47], v[112:115], v[104:107], v[32:47]
	v_mfma_f32_32x32x16_bf16 v[48:63], v[120:123], v[96:99], v[48:63]
	v_mfma_f32_32x32x16_bf16 v[16:31], v[120:123], v[104:107], v[16:31]
	global_load_dwordx4 v[96:99], v[128:129], off offset:1152
	global_load_dwordx4 v[100:103], v[130:131], off offset:1152
	global_load_dwordx4 v[104:107], v[132:133], off offset:1152
	global_load_dwordx4 v[108:111], v[134:135], off offset:1152
	global_load_dwordx4 v[112:115], v[136:137], off offset:1152
	global_load_dwordx4 v[116:119], v[138:139], off offset:1152
	global_load_dwordx4 v[120:123], v[140:141], off offset:1152
	global_load_dwordx4 v[124:127], v[142:143], off offset:1152
	s_waitcnt lgkmcnt(1)
	v_mfma_f32_32x32x16_bf16 v[0:15], v[164:167], v[156:159], v[0:15]
	v_mfma_f32_32x32x16_bf16 v[32:47], v[164:167], v[160:163], v[32:47]
	s_waitcnt lgkmcnt(0)
	v_mfma_f32_32x32x16_bf16 v[48:63], v[168:171], v[156:159], v[48:63]
	ds_read_b128 v[156:159], v154 offset:55328
	ds_read_b128 v[164:167], v154 offset:59936
	ds_read_b128 v[172:175], v153 offset:36896
	ds_read_b128 v[176:179], v153 offset:41504
	v_mfma_f32_32x32x16_bf16 v[16:31], v[168:171], v[160:163], v[16:31]
	s_waitcnt lgkmcnt(1)
	v_mfma_f32_32x32x16_bf16 v[0:15], v[172:175], v[156:159], v[0:15]
	v_mfma_f32_32x32x16_bf16 v[32:47], v[172:175], v[164:167], v[32:47]
	s_waitcnt lgkmcnt(0)
	v_mfma_f32_32x32x16_bf16 v[48:63], v[176:179], v[156:159], v[48:63]
	ds_read_b128 v[156:159], v154 offset:55360
	ds_read_b128 v[160:163], v154 offset:59968
	ds_read_b128 v[168:171], v153 offset:36928
	ds_read_b128 v[172:175], v153 offset:41536
	s_waitcnt vmcnt(15)
	ds_write_b128 v152, v[64:67]
	s_waitcnt vmcnt(13)
	ds_write_b128 v152, v[72:75] offset:4608
	s_waitcnt vmcnt(11)
	ds_write_b128 v152, v[80:83] offset:9216
	s_waitcnt vmcnt(9)
	ds_write_b128 v152, v[88:91] offset:13824
	v_mfma_f32_32x32x16_bf16 v[16:31], v[176:179], v[164:167], v[16:31]
	ds_read_b128 v[64:67], v154 offset:55392
	ds_read_b128 v[72:75], v154 offset:60000
	ds_read_b128 v[80:83], v153 offset:36960
	ds_read_b128 v[88:91], v153 offset:41568
	s_waitcnt lgkmcnt(9)
	v_mfma_f32_32x32x16_bf16 v[0:15], v[168:171], v[156:159], v[0:15]
	ds_write_b128 v152, v[68:71] offset:18432
	ds_write_b128 v152, v[76:79] offset:23040
	ds_write_b128 v152, v[84:87] offset:27648
	s_waitcnt vmcnt(8)
	ds_write_b128 v152, v[92:95] offset:32256
	v_mfma_f32_32x32x16_bf16 v[32:47], v[168:171], v[160:163], v[32:47]
	s_waitcnt lgkmcnt(12)
	v_mfma_f32_32x32x16_bf16 v[48:63], v[172:175], v[156:159], v[48:63]
	v_mfma_f32_32x32x16_bf16 v[16:31], v[172:175], v[160:163], v[16:31]
	s_waitcnt lgkmcnt(0)
	s_barrier
; template <bool SWAP>
; DI void gemm_tile(const bf16_t* __restrict__ A, int lda, const bf16_t* __restrict__ Bt, int ldb, int K, f32x16 (&acc)[2][2], bf16_t* As, bf16_t* Bs_unused) {
;     ...
;   auto step = [&](int buf, u32x4 (&ra)[4], u32x4 (&rb)[4], bool do_write, bool do_load, int tload) __attribute__((always_inline)) {
;     const bf16_t* pa = As + buf * 2 * GT_IMG + pao; const bf16_t* pb = As + buf * 2 * GT_IMG + pbo;
;     bf16_t* Ad = As + (buf ^ 1) * 2 * GT_IMG; bf16_t* Bd = Ad + GT_IMG;
;     bf16x8 F0[4], F1[4];
;     frag_read(F0, pa, pb, 0);
;     __builtin_amdgcn_sched_barrier(0);
;     frag_read(F1, pa, pb, 16);
;     mfma4(F0);
;     __builtin_amdgcn_sched_barrier(0);
;     frag_read(F0, pa, pb, 32);
;     mfma4(F1);
;     if (do_write) {
; #pragma unroll
;       for (int i = 0; i < 4; ++i) *(u32x4*)(Ad + (lr + 32 * i) * 72 + lc) = ra[i];
;     }
;     __builtin_amdgcn_sched_barrier(0);
;     frag_read(F1, pa, pb, 48);
;     mfma4(F0);
;     if (do_write) {
; #pragma unroll
;       for (int i = 0; i < 4; ++i) *(u32x4*)(Bd + (lr + 32 * i) * 72 + lc) = rb[i];
;     }
;     __builtin_amdgcn_sched_barrier(0);
;     mfma4(F1);
;     if (do_load) load_stage(ra, rb, tload);
;     __builtin_amdgcn_sched_barrier(0);
;   };
;   const int nk = K >> 6;
;   load_stage(ra0, rb0, 0); load_stage(ra1, rb1, 1);
;   __syncthreads();
;   write_stage(ra0, rb0, 0);
;   load_stage(ra0, rb0, 2);
;   __syncthreads();
;   for (int kt = 0; kt < nk; kt += 2) {
;     step(0, ra1, rb1, true, kt + 3 < nk, kt + 3);
;     __syncthreads();
;     step(1, ra0, rb0, kt + 2 < nk, kt + 4 < nk, kt + 4);
;     __syncthreads();
	ds_read_b128 v[156:159], v154 offset:18432
	ds_read_b128 v[160:163], v154 offset:23040
	ds_read_b128 v[164:167], v153
	ds_read_b128 v[168:171], v153 offset:4608
	v_mfma_f32_32x32x16_bf16 v[0:15], v[80:83], v[64:67], v[0:15]
	v_mfma_f32_32x32x16_bf16 v[32:47], v[80:83], v[72:75], v[32:47]
	v_mfma_f32_32x32x16_bf16 v[48:63], v[88:91], v[64:67], v[48:63]
	v_mfma_f32_32x32x16_bf16 v[16:31], v[88:91], v[72:75], v[16:31]
	global_load_dwordx4 v[64:67], v[128:129], off offset:1280
	global_load_dwordx4 v[68:71], v[130:131], off offset:1280
	global_load_dwordx4 v[72:75], v[132:133], off offset:1280
	global_load_dwordx4 v[76:79], v[134:135], off offset:1280
	global_load_dwordx4 v[80:83], v[136:137], off offset:1280
	global_load_dwordx4 v[84:87], v[138:139], off offset:1280
	global_load_dwordx4 v[88:91], v[140:141], off offset:1280
	global_load_dwordx4 v[92:95], v[142:143], off offset:1280
	s_waitcnt lgkmcnt(1)
	v_mfma_f32_32x32x16_bf16 v[0:15], v[164:167], v[156:159], v[0:15]
	v_mfma_f32_32x32x16_bf16 v[32:47], v[164:167], v[160:163], v[32:47]
	s_waitcnt lgkmcnt(0)
	v_mfma_f32_32x32x16_bf16 v[48:63], v[168:171], v[156:159], v[48:63]
	ds_read_b128 v[156:159], v154 offset:18464
	ds_read_b128 v[164:167], v154 offset:23072
	ds_read_b128 v[172:175], v153 offset:32
	ds_read_b128 v[176:179], v153 offset:4640
	v_mfma_f32_32x32x16_bf16 v[16:31], v[168:171], v[160:163], v[16:31]
	s_waitcnt lgkmcnt(1)
	v_mfma_f32_32x32x16_bf16 v[0:15], v[172:175], v[156:159], v[0:15]
	v_mfma_f32_32x32x16_bf16 v[32:47], v[172:175], v[164:167], v[32:47]
	s_waitcnt lgkmcnt(0)
	v_mfma_f32_32x32x16_bf16 v[48:63], v[176:179], v[156:159], v[48:63]
	ds_read_b128 v[156:159], v154 offset:18496
	ds_read_b128 v[160:163], v154 offset:23104
	ds_read_b128 v[168:171], v153 offset:64
	ds_read_b128 v[172:175], v153 offset:4672
	s_waitcnt vmcnt(15)
	ds_write_b128 v152, v[96:99] offset:36864
	s_waitcnt vmcnt(13)
	ds_write_b128 v152, v[104:107] offset:41472
	s_waitcnt vmcnt(11)
	ds_write_b128 v152, v[112:115] offset:46080
	s_waitcnt vmcnt(9)
	ds_write_b128 v152, v[120:123] offset:50688
	v_mfma_f32_32x32x16_bf16 v[16:31], v[176:179], v[164:167], v[16:31]
	ds_read_b128 v[96:99], v154 offset:18528
	ds_read_b128 v[104:107], v154 offset:23136
	ds_read_b128 v[112:115], v153 offset:96
	ds_read_b128 v[120:123], v153 offset:4704
	s_waitcnt lgkmcnt(9)
	v_mfma_f32_32x32x16_bf16 v[0:15], v[168:171], v[156:159], v[0:15]
	ds_write_b128 v152, v[100:103] offset:55296
	ds_write_b128 v152, v[108:111] offset:59904
	ds_write_b128 v152, v[116:119] offset:64512
	s_waitcnt vmcnt(8)
	ds_write_b128 v155, v[124:127] offset:13824
	v_mfma_f32_32x32x16_bf16 v[32:47], v[168:171], v[160:163], v[32:47]
	s_waitcnt lgkmcnt(12)
	v_mfma_f32_32x32x16_bf16 v[48:63], v[172:175], v[156:159], v[48:63]
	v_mfma_f32_32x32x16_bf16 v[16:31], v[172:175], v[160:163], v[16:31]
	s_waitcnt lgkmcnt(0)
	s_barrier
	ds_read_b128 v[156:159], v154 offset:55296
	ds_read_b128 v[160:163], v154 offset:59904
	ds_read_b128 v[164:167], v153 offset:36864
	ds_read_b128 v[168:171], v153 offset:41472
	v_mfma_f32_32x32x16_bf16 v[0:15], v[112:115], v[96:99], v[0:15]
	v_mfma_f32_32x32x16_bf16 v[32:47], v[112:115], v[104:107], v[32:47]
	v_mfma_f32_32x32x16_bf16 v[48:63], v[120:123], v[96:99], v[48:63]
	v_mfma_f32_32x32x16_bf16 v[16:31], v[120:123], v[104:107], v[16:31]
	global_load_dwordx4 v[96:99], v[128:129], off offset:1408
	global_load_dwordx4 v[100:103], v[130:131], off offset:1408
	global_load_dwordx4 v[104:107], v[132:133], off offset:1408
	global_load_dwordx4 v[108:111], v[134:135], off offset:1408
	global_load_dwordx4 v[112:115], v[136:137], off offset:1408
	global_load_dwordx4 v[116:119], v[138:139], off offset:1408
	global_load_dwordx4 v[120:123], v[140:141], off offset:1408
	global_load_dwordx4 v[124:127], v[142:143], off offset:1408
	s_waitcnt lgkmcnt(1)
	v_mfma_f32_32x32x16_bf16 v[0:15], v[164:167], v[156:159], v[0:15]
	v_mfma_f32_32x32x16_bf16 v[32:47], v[164:167], v[160:163], v[32:47]
	s_waitcnt lgkmcnt(0)
	v_mfma_f32_32x32x16_bf16 v[48:63], v[168:171], v[156:159], v[48:63]
	ds_read_b128 v[156:159], v154 offset:55328
	ds_read_b128 v[164:167], v154 offset:59936
	ds_read_b128 v[172:175], v153 offset:36896
	ds_read_b128 v[176:179], v153 offset:41504
	v_mfma_f32_32x32x16_bf16 v[16:31], v[168:171], v[160:163], v[16:31]
	s_waitcnt lgkmcnt(1)
	v_mfma_f32_32x32x16_bf16 v[0:15], v[172:175], v[156:159], v[0:15]
	v_mfma_f32_32x32x16_bf16 v[32:47], v[172:175], v[164:167], v[32:47]
	s_waitcnt lgkmcnt(0)
	v_mfma_f32_32x32x16_bf16 v[48:63], v[176:179], v[156:159], v[48:63]
	ds_read_b128 v[156:159], v154 offset:55360
	ds_read_b128 v[160:163], v154 offset:59968
	ds_read_b128 v[168:171], v153 offset:36928
	ds_read_b128 v[172:175], v153 offset:41536
	s_waitcnt vmcnt(15)
	ds_write_b128 v152, v[64:67]
	s_waitcnt vmcnt(13)
	ds_write_b128 v152, v[72:75] offset:4608
	s_waitcnt vmcnt(11)
	ds_write_b128 v152, v[80:83] offset:9216
	s_waitcnt vmcnt(9)
	ds_write_b128 v152, v[88:91] offset:13824
	v_mfma_f32_32x32x16_bf16 v[16:31], v[176:179], v[164:167], v[16:31]
	ds_read_b128 v[64:67], v154 offset:55392
	ds_read_b128 v[72:75], v154 offset:60000
	ds_read_b128 v[80:83], v153 offset:36960
	ds_read_b128 v[88:91], v153 offset:41568
	s_waitcnt lgkmcnt(9)
	v_mfma_f32_32x32x16_bf16 v[0:15], v[168:171], v[156:159], v[0:15]
	ds_write_b128 v152, v[68:71] offset:18432
	ds_write_b128 v152, v[76:79] offset:23040
	ds_write_b128 v152, v[84:87] offset:27648
	s_waitcnt vmcnt(8)
	ds_write_b128 v152, v[92:95] offset:32256
	v_mfma_f32_32x32x16_bf16 v[32:47], v[168:171], v[160:163], v[32:47]
	s_waitcnt lgkmcnt(12)
	v_mfma_f32_32x32x16_bf16 v[48:63], v[172:175], v[156:159], v[48:63]
	v_mfma_f32_32x32x16_bf16 v[16:31], v[172:175], v[160:163], v[16:31]
	s_waitcnt lgkmcnt(0)
	s_barrier
; template <bool SWAP>
; DI void gemm_tile(const bf16_t* __restrict__ A, int lda, const bf16_t* __restrict__ Bt, int ldb, int K, f32x16 (&acc)[2][2], bf16_t* As, bf16_t* Bs_unused) {
;     ...
;   auto step = [&](int buf, u32x4 (&ra)[4], u32x4 (&rb)[4], bool do_write, bool do_load, int tload) __attribute__((always_inline)) {
;     const bf16_t* pa = As + buf * 2 * GT_IMG + pao; const bf16_t* pb = As + buf * 2 * GT_IMG + pbo;
;     bf16_t* Ad = As + (buf ^ 1) * 2 * GT_IMG; bf16_t* Bd = Ad + GT_IMG;
;     bf16x8 F0[4], F1[4];
;     frag_read(F0, pa, pb, 0);
;     __builtin_amdgcn_sched_barrier(0);
;     frag_read(F1, pa, pb, 16);
;     mfma4(F0);
;     __builtin_amdgcn_sched_barrier(0);
;     frag_read(F0, pa, pb, 32);
;     mfma4(F1);
;     if (do_write) {
; #pragma unroll
;       for (int i = 0; i < 4; ++i) *(u32x4*)(Ad + (lr + 32 * i) * 72 + lc) = ra[i];
;     }
;     __builtin_amdgcn_sched_barrier(0);
;     frag_read(F1, pa, pb, 48);
;     mfma4(F0);
;     if (do_write) {
; #pragma unroll
;       for (int i = 0; i < 4; ++i) *(u32x4*)(Bd + (lr + 32 * i) * 72 + lc) = rb[i];
;     }
;     __builtin_amdgcn_sched_barrier(0);
;     mfma4(F1);
;     if (do_load) load_stage(ra, rb, tload);
;     __builtin_amdgcn_sched_barrier(0);
;   };
;   const int nk = K >> 6;
;   load_stage(ra0, rb0, 0); load_stage(ra1, rb1, 1);
;   __syncthreads();
;   write_stage(ra0, rb0, 0);
;   load_stage(ra0, rb0, 2);
;   __syncthreads();
;   for (int kt = 0; kt < nk; kt += 2) {
;     step(0, ra1, rb1, true, kt + 3 < nk, kt + 3);
;     __syncthreads();
;     step(1, ra0, rb0, kt + 2 < nk, kt + 4 < nk, kt + 4);
;     __syncthreads();
	ds_read_b128 v[156:159], v154 offset:18432
	ds_read_b128 v[160:163], v154 offset:23040
	ds_read_b128 v[164:167], v153
	ds_read_b128 v[168:171], v153 offset:4608
	v_mfma_f32_32x32x16_bf16 v[0:15], v[80:83], v[64:67], v[0:15]
	v_mfma_f32_32x32x16_bf16 v[32:47], v[80:83], v[72:75], v[32:47]
	v_mfma_f32_32x32x16_bf16 v[48:63], v[88:91], v[64:67], v[48:63]
	v_mfma_f32_32x32x16_bf16 v[16:31], v[88:91], v[72:75], v[16:31]
	global_load_dwordx4 v[64:67], v[128:129], off offset:1536
	global_load_dwordx4 v[68:71], v[130:131], off offset:1536
	global_load_dwordx4 v[72:75], v[132:133], off offset:1536
	global_load_dwordx4 v[76:79], v[134:135], off offset:1536
	global_load_dwordx4 v[80:83], v[136:137], off offset:1536
	global_load_dwordx4 v[84:87], v[138:139], off offset:1536
	global_load_dwordx4 v[88:91], v[140:141], off offset:1536
	global_load_dwordx4 v[92:95], v[142:143], off offset:1536
	s_waitcnt lgkmcnt(1)
	v_mfma_f32_32x32x16_bf16 v[0:15], v[164:167], v[156:159], v[0:15]
	v_mfma_f32_32x32x16_bf16 v[32:47], v[164:167], v[160:163], v[32:47]
	s_waitcnt lgkmcnt(0)
	v_mfma_f32_32x32x16_bf16 v[48:63], v[168:171], v[156:159], v[48:63]
	ds_read_b128 v[156:159], v154 offset:18464
	ds_read_b128 v[164:167], v154 offset:23072
	ds_read_b128 v[172:175], v153 offset:32
	ds_read_b128 v[176:179], v153 offset:4640
	v_mfma_f32_32x32x16_bf16 v[16:31], v[168:171], v[160:163], v[16:31]
	s_waitcnt lgkmcnt(1)
	v_mfma_f32_32x32x16_bf16 v[0:15], v[172:175], v[156:159], v[0:15]
	v_mfma_f32_32x32x16_bf16 v[32:47], v[172:175], v[164:167], v[32:47]
	s_waitcnt lgkmcnt(0)
	v_mfma_f32_32x32x16_bf16 v[48:63], v[176:179], v[156:159], v[48:63]
	ds_read_b128 v[156:159], v154 offset:18496
	ds_read_b128 v[160:163], v154 offset:23104
	ds_read_b128 v[168:171], v153 offset:64
	ds_read_b128 v[172:175], v153 offset:4672
	s_waitcnt vmcnt(15)
	ds_write_b128 v152, v[96:99] offset:36864
	s_waitcnt vmcnt(13)
	ds_write_b128 v152, v[104:107] offset:41472
	s_waitcnt vmcnt(11)
	ds_write_b128 v152, v[112:115] offset:46080
	s_waitcnt vmcnt(9)
	ds_write_b128 v152, v[120:123] offset:50688
	v_mfma_f32_32x32x16_bf16 v[16:31], v[176:179], v[164:167], v[16:31]
	ds_read_b128 v[96:99], v154 offset:18528
	ds_read_b128 v[104:107], v154 offset:23136
	ds_read_b128 v[112:115], v153 offset:96
	ds_read_b128 v[120:123], v153 offset:4704
	s_waitcnt lgkmcnt(9)
	v_mfma_f32_32x32x16_bf16 v[0:15], v[168:171], v[156:159], v[0:15]
	ds_write_b128 v152, v[100:103] offset:55296
	ds_write_b128 v152, v[108:111] offset:59904
	ds_write_b128 v152, v[116:119] offset:64512
	s_waitcnt vmcnt(8)
	ds_write_b128 v155, v[124:127] offset:13824
	v_mfma_f32_32x32x16_bf16 v[32:47], v[168:171], v[160:163], v[32:47]
	s_waitcnt lgkmcnt(12)
	v_mfma_f32_32x32x16_bf16 v[48:63], v[172:175], v[156:159], v[48:63]
	v_mfma_f32_32x32x16_bf16 v[16:31], v[172:175], v[160:163], v[16:31]
	s_waitcnt lgkmcnt(0)
	s_barrier
	ds_read_b128 v[156:159], v154 offset:55296
	ds_read_b128 v[160:163], v154 offset:59904
	ds_read_b128 v[164:167], v153 offset:36864
	ds_read_b128 v[168:171], v153 offset:41472
	v_mfma_f32_32x32x16_bf16 v[0:15], v[112:115], v[96:99], v[0:15]
	v_mfma_f32_32x32x16_bf16 v[32:47], v[112:115], v[104:107], v[32:47]
	v_mfma_f32_32x32x16_bf16 v[48:63], v[120:123], v[96:99], v[48:63]
	v_mfma_f32_32x32x16_bf16 v[16:31], v[120:123], v[104:107], v[16:31]
	global_load_dwordx4 v[96:99], v[128:129], off offset:1664
	global_load_dwordx4 v[100:103], v[130:131], off offset:1664
	global_load_dwordx4 v[104:107], v[132:133], off offset:1664
	global_load_dwordx4 v[108:111], v[134:135], off offset:1664
	global_load_dwordx4 v[112:115], v[136:137], off offset:1664
	global_load_dwordx4 v[116:119], v[138:139], off offset:1664
	global_load_dwordx4 v[120:123], v[140:141], off offset:1664
	global_load_dwordx4 v[124:127], v[142:143], off offset:1664
	s_waitcnt lgkmcnt(1)
	v_mfma_f32_32x32x16_bf16 v[0:15], v[164:167], v[156:159], v[0:15]
	v_mfma_f32_32x32x16_bf16 v[32:47], v[164:167], v[160:163], v[32:47]
	s_waitcnt lgkmcnt(0)
	v_mfma_f32_32x32x16_bf16 v[48:63], v[168:171], v[156:159], v[48:63]
	ds_read_b128 v[156:159], v154 offset:55328
	ds_read_b128 v[164:167], v154 offset:59936
	ds_read_b128 v[172:175], v153 offset:36896
	ds_read_b128 v[176:179], v153 offset:41504
	v_mfma_f32_32x32x16_bf16 v[16:31], v[168:171], v[160:163], v[16:31]
	s_waitcnt lgkmcnt(1)
	v_mfma_f32_32x32x16_bf16 v[0:15], v[172:175], v[156:159], v[0:15]
	v_mfma_f32_32x32x16_bf16 v[32:47], v[172:175], v[164:167], v[32:47]
	s_waitcnt lgkmcnt(0)
	v_mfma_f32_32x32x16_bf16 v[48:63], v[176:179], v[156:159], v[48:63]
	ds_read_b128 v[156:159], v154 offset:55360
	ds_read_b128 v[160:163], v154 offset:59968
	ds_read_b128 v[168:171], v153 offset:36928
	ds_read_b128 v[172:175], v153 offset:41536
	s_waitcnt vmcnt(15)
	ds_write_b128 v152, v[64:67]
	s_waitcnt vmcnt(13)
	ds_write_b128 v152, v[72:75] offset:4608
	s_waitcnt vmcnt(11)
	ds_write_b128 v152, v[80:83] offset:9216
	s_waitcnt vmcnt(9)
	ds_write_b128 v152, v[88:91] offset:13824
	v_mfma_f32_32x32x16_bf16 v[16:31], v[176:179], v[164:167], v[16:31]
	ds_read_b128 v[64:67], v154 offset:55392
	ds_read_b128 v[72:75], v154 offset:60000
	ds_read_b128 v[80:83], v153 offset:36960
	ds_read_b128 v[88:91], v153 offset:41568
	s_waitcnt lgkmcnt(9)
	v_mfma_f32_32x32x16_bf16 v[0:15], v[168:171], v[156:159], v[0:15]
	ds_write_b128 v152, v[68:71] offset:18432
	ds_write_b128 v152, v[76:79] offset:23040
	ds_write_b128 v152, v[84:87] offset:27648
	s_waitcnt vmcnt(8)
	ds_write_b128 v152, v[92:95] offset:32256
	v_mfma_f32_32x32x16_bf16 v[32:47], v[168:171], v[160:163], v[32:47]
	s_waitcnt lgkmcnt(12)
	v_mfma_f32_32x32x16_bf16 v[48:63], v[172:175], v[156:159], v[48:63]
	v_mfma_f32_32x32x16_bf16 v[16:31], v[172:175], v[160:163], v[16:31]
	s_waitcnt lgkmcnt(0)
	s_barrier
; template <bool SWAP>
; DI void gemm_tile(const bf16_t* __restrict__ A, int lda, const bf16_t* __restrict__ Bt, int ldb, int K, f32x16 (&acc)[2][2], bf16_t* As, bf16_t* Bs_unused) {
;     ...
;   auto step = [&](int buf, u32x4 (&ra)[4], u32x4 (&rb)[4], bool do_write, bool do_load, int tload) __attribute__((always_inline)) {
;     const bf16_t* pa = As + buf * 2 * GT_IMG + pao; const bf16_t* pb = As + buf * 2 * GT_IMG + pbo;
;     bf16_t* Ad = As + (buf ^ 1) * 2 * GT_IMG; bf16_t* Bd = Ad + GT_IMG;
;     bf16x8 F0[4], F1[4];
;     frag_read(F0, pa, pb, 0);
;     __builtin_amdgcn_sched_barrier(0);
;     frag_read(F1, pa, pb, 16);
;     mfma4(F0);
;     __builtin_amdgcn_sched_barrier(0);
;     frag_read(F0, pa, pb, 32);
;     mfma4(F1);
;     if (do_write) {
; #pragma unroll
;       for (int i = 0; i < 4; ++i) *(u32x4*)(Ad + (lr + 32 * i) * 72 + lc) = ra[i];
;     }
;     __builtin_amdgcn_sched_barrier(0);
;     frag_read(F1, pa, pb, 48);
;     mfma4(F0);
;     if (do_write) {
; #pragma unroll
;       for (int i = 0; i < 4; ++i) *(u32x4*)(Bd + (lr + 32 * i) * 72 + lc) = rb[i];
;     }
;     __builtin_amdgcn_sched_barrier(0);
;     mfma4(F1);
;     if (do_load) load_stage(ra, rb, tload);
;     __builtin_amdgcn_sched_barrier(0);
;   };
;   const int nk = K >> 6;
;   load_stage(ra0, rb0, 0); load_stage(ra1, rb1, 1);
;   __syncthreads();
;   write_stage(ra0, rb0, 0);
;   load_stage(ra0, rb0, 2);
;   __syncthreads();
;   for (int kt = 0; kt < nk; kt += 2) {
;     step(0, ra1, rb1, true, kt + 3 < nk, kt + 3);
;     __syncthreads();
;     step(1, ra0, rb0, kt + 2 < nk, kt + 4 < nk, kt + 4);
;     __syncthreads();
	ds_read_b128 v[156:159], v154 offset:18432
	ds_read_b128 v[160:163], v154 offset:23040
	ds_read_b128 v[164:167], v153
	ds_read_b128 v[168:171], v153 offset:4608
	v_mfma_f32_32x32x16_bf16 v[0:15], v[80:83], v[64:67], v[0:15]
	v_mfma_f32_32x32x16_bf16 v[32:47], v[80:83], v[72:75], v[32:47]
	v_mfma_f32_32x32x16_bf16 v[48:63], v[88:91], v[64:67], v[48:63]
	v_mfma_f32_32x32x16_bf16 v[16:31], v[88:91], v[72:75], v[16:31]
	global_load_dwordx4 v[64:67], v[128:129], off offset:1792
	global_load_dwordx4 v[68:71], v[130:131], off offset:1792
	global_load_dwordx4 v[72:75], v[132:133], off offset:1792
	global_load_dwordx4 v[76:79], v[134:135], off offset:1792
	global_load_dwordx4 v[80:83], v[136:137], off offset:1792
	global_load_dwordx4 v[84:87], v[138:139], off offset:1792
	global_load_dwordx4 v[88:91], v[140:141], off offset:1792
	global_load_dwordx4 v[92:95], v[142:143], off offset:1792
	s_waitcnt lgkmcnt(1)
	v_mfma_f32_32x32x16_bf16 v[0:15], v[164:167], v[156:159], v[0:15]
	v_mfma_f32_32x32x16_bf16 v[32:47], v[164:167], v[160:163], v[32:47]
	s_waitcnt lgkmcnt(0)
	v_mfma_f32_32x32x16_bf16 v[48:63], v[168:171], v[156:159], v[48:63]
	ds_read_b128 v[156:159], v154 offset:18464
	ds_read_b128 v[164:167], v154 offset:23072
	ds_read_b128 v[172:175], v153 offset:32
	ds_read_b128 v[176:179], v153 offset:4640
	v_mfma_f32_32x32x16_bf16 v[16:31], v[168:171], v[160:163], v[16:31]
	s_waitcnt lgkmcnt(1)
	v_mfma_f32_32x32x16_bf16 v[0:15], v[172:175], v[156:159], v[0:15]
	v_mfma_f32_32x32x16_bf16 v[32:47], v[172:175], v[164:167], v[32:47]
	s_waitcnt lgkmcnt(0)
	v_mfma_f32_32x32x16_bf16 v[48:63], v[176:179], v[156:159], v[48:63]
	ds_read_b128 v[156:159], v154 offset:18496
	ds_read_b128 v[160:163], v154 offset:23104
	ds_read_b128 v[168:171], v153 offset:64
	ds_read_b128 v[172:175], v153 offset:4672
	s_waitcnt vmcnt(15)
	ds_write_b128 v152, v[96:99] offset:36864
	s_waitcnt vmcnt(13)
	ds_write_b128 v152, v[104:107] offset:41472
	s_waitcnt vmcnt(11)
	ds_write_b128 v152, v[112:115] offset:46080
	s_waitcnt vmcnt(9)
	ds_write_b128 v152, v[120:123] offset:50688
	v_mfma_f32_32x32x16_bf16 v[16:31], v[176:179], v[164:167], v[16:31]
	ds_read_b128 v[96:99], v154 offset:18528
	ds_read_b128 v[104:107], v154 offset:23136
	ds_read_b128 v[112:115], v153 offset:96
	ds_read_b128 v[120:123], v153 offset:4704
	s_waitcnt lgkmcnt(9)
	v_mfma_f32_32x32x16_bf16 v[0:15], v[168:171], v[156:159], v[0:15]
	ds_write_b128 v152, v[100:103] offset:55296
	ds_write_b128 v152, v[108:111] offset:59904
	ds_write_b128 v152, v[116:119] offset:64512
	s_waitcnt vmcnt(8)
	ds_write_b128 v155, v[124:127] offset:13824
	v_mfma_f32_32x32x16_bf16 v[32:47], v[168:171], v[160:163], v[32:47]
	s_waitcnt lgkmcnt(12)
	v_mfma_f32_32x32x16_bf16 v[48:63], v[172:175], v[156:159], v[48:63]
	v_mfma_f32_32x32x16_bf16 v[16:31], v[172:175], v[160:163], v[16:31]
	s_waitcnt lgkmcnt(5)
	v_mfma_f32_32x32x16_bf16 v[0:15], v[112:115], v[96:99], v[0:15]
	v_mfma_f32_32x32x16_bf16 v[32:47], v[112:115], v[104:107], v[32:47]
	s_waitcnt lgkmcnt(4)
	v_mfma_f32_32x32x16_bf16 v[48:63], v[120:123], v[96:99], v[48:63]
	v_mfma_f32_32x32x16_bf16 v[16:31], v[120:123], v[104:107], v[16:31]
	global_load_dwordx4 v[96:99], v[128:129], off offset:1920
	global_load_dwordx4 v[100:103], v[130:131], off offset:1920
	global_load_dwordx4 v[104:107], v[132:133], off offset:1920
	global_load_dwordx4 v[108:111], v[134:135], off offset:1920
	global_load_dwordx4 v[112:115], v[136:137], off offset:1920
	global_load_dwordx4 v[116:119], v[138:139], off offset:1920
	global_load_dwordx4 v[120:123], v[140:141], off offset:1920
	global_load_dwordx4 v[124:127], v[142:143], off offset:1920
	s_waitcnt lgkmcnt(0)
	s_barrier
	ds_read_b128 v[128:131], v154 offset:55296
	ds_read_b128 v[132:135], v154 offset:59904
	ds_read_b128 v[136:139], v153 offset:36864
	ds_read_b128 v[140:143], v153 offset:41472
	s_waitcnt lgkmcnt(1)
	v_mfma_f32_32x32x16_bf16 v[0:15], v[136:139], v[128:131], v[0:15]
	v_mfma_f32_32x32x16_bf16 v[32:47], v[136:139], v[132:135], v[32:47]
	s_waitcnt lgkmcnt(0)
	v_mfma_f32_32x32x16_bf16 v[48:63], v[140:143], v[128:131], v[48:63]
	ds_read_b128 v[128:131], v154 offset:55328
	ds_read_b128 v[136:139], v154 offset:59936
	ds_read_b128 v[156:159], v153 offset:36896
	ds_read_b128 v[160:163], v153 offset:41504
	v_mfma_f32_32x32x16_bf16 v[16:31], v[140:143], v[132:135], v[16:31]
	s_waitcnt lgkmcnt(1)
	v_mfma_f32_32x32x16_bf16 v[0:15], v[156:159], v[128:131], v[0:15]
	v_mfma_f32_32x32x16_bf16 v[32:47], v[156:159], v[136:139], v[32:47]
	s_waitcnt lgkmcnt(0)
	v_mfma_f32_32x32x16_bf16 v[48:63], v[160:163], v[128:131], v[48:63]
	ds_read_b128 v[128:131], v154 offset:55360
	ds_read_b128 v[132:135], v154 offset:59968
	ds_read_b128 v[140:143], v153 offset:36928
	ds_read_b128 v[156:159], v153 offset:41536
	s_waitcnt vmcnt(15)
	ds_write_b128 v152, v[64:67]
	s_waitcnt vmcnt(13)
	ds_write_b128 v152, v[72:75] offset:4608
	s_waitcnt vmcnt(11)
	ds_write_b128 v152, v[80:83] offset:9216
	s_waitcnt vmcnt(9)
	ds_write_b128 v152, v[88:91] offset:13824
	v_mfma_f32_32x32x16_bf16 v[16:31], v[160:163], v[136:139], v[16:31]
	ds_read_b128 v[64:67], v154 offset:55392
	ds_read_b128 v[72:75], v154 offset:60000
	ds_read_b128 v[80:83], v153 offset:36960
	ds_read_b128 v[88:91], v153 offset:41568
	s_waitcnt lgkmcnt(9)
	v_mfma_f32_32x32x16_bf16 v[0:15], v[140:143], v[128:131], v[0:15]
	ds_write_b128 v152, v[68:71] offset:18432
	ds_write_b128 v152, v[76:79] offset:23040
	ds_write_b128 v152, v[84:87] offset:27648
	s_waitcnt vmcnt(8)
	ds_write_b128 v152, v[92:95] offset:32256
	v_mfma_f32_32x32x16_bf16 v[32:47], v[140:143], v[132:135], v[32:47]
	s_waitcnt lgkmcnt(12)
	v_mfma_f32_32x32x16_bf16 v[48:63], v[156:159], v[128:131], v[48:63]
	v_mfma_f32_32x32x16_bf16 v[16:31], v[156:159], v[132:135], v[16:31]
	s_waitcnt lgkmcnt(5)
	v_mfma_f32_32x32x16_bf16 v[0:15], v[80:83], v[64:67], v[0:15]
	v_mfma_f32_32x32x16_bf16 v[32:47], v[80:83], v[72:75], v[32:47]
	s_waitcnt lgkmcnt(4)
	v_mfma_f32_32x32x16_bf16 v[48:63], v[88:91], v[64:67], v[48:63]
	v_mfma_f32_32x32x16_bf16 v[16:31], v[88:91], v[72:75], v[16:31]
	s_waitcnt lgkmcnt(0)
	s_barrier
; DI int crow(int r, int h) { return (r & 3) + 8 * (r >> 2) + 4 * h; }
; template <bool SWAP>
; DI void gemm_tile(const bf16_t* __restrict__ A, int lda, const bf16_t* __restrict__ Bt, int ldb, int K, f32x16 (&acc)[2][2], bf16_t* As, bf16_t* Bs_unused) {
;     ...
;   auto step = [&](int buf, u32x4 (&ra)[4], u32x4 (&rb)[4], bool do_write, bool do_load, int tload) __attribute__((always_inline)) {
;     const bf16_t* pa = As + buf * 2 * GT_IMG + pao; const bf16_t* pb = As + buf * 2 * GT_IMG + pbo;
;     bf16_t* Ad = As + (buf ^ 1) * 2 * GT_IMG; bf16_t* Bd = Ad + GT_IMG;
;     bf16x8 F0[4], F1[4];
;     frag_read(F0, pa, pb, 0);
;     __builtin_amdgcn_sched_barrier(0);
;     frag_read(F1, pa, pb, 16);
;     mfma4(F0);
;     __builtin_amdgcn_sched_barrier(0);
;     frag_read(F0, pa, pb, 32);
;     mfma4(F1);
;     if (do_write) {
; #pragma unroll
;       for (int i = 0; i < 4; ++i) *(u32x4*)(Ad + (lr + 32 * i) * 72 + lc) = ra[i];
;     }
;     __builtin_amdgcn_sched_barrier(0);
;     frag_read(F1, pa, pb, 48);
;     mfma4(F0);
;     if (do_write) {
; #pragma unroll
;       for (int i = 0; i < 4; ++i) *(u32x4*)(Bd + (lr + 32 * i) * 72 + lc) = rb[i];
;     }
;     __builtin_amdgcn_sched_barrier(0);
;     mfma4(F1);
;     if (do_load) load_stage(ra, rb, tload);
;     __builtin_amdgcn_sched_barrier(0);
;   };
;   const int nk = K >> 6;
;   load_stage(ra0, rb0, 0); load_stage(ra1, rb1, 1);
;   __syncthreads();
;   write_stage(ra0, rb0, 0);
;   load_stage(ra0, rb0, 2);
;   __syncthreads();
;   for (int kt = 0; kt < nk; kt += 2) {
;     step(0, ra1, rb1, true, kt + 3 < nk, kt + 3);
;     __syncthreads();
;     step(1, ra0, rb0, kt + 2 < nk, kt + 4 < nk, kt + 4);
;     __syncthreads();
;   }
; DI void phase_merge(const Params& p, int g, char* smem, int bid, int nb) {
;     ...
;         bf16_t gb16[16];
; #pragma unroll
;         for (int r = 0; r < 16; ++r) gb16[r] = pt[(wm * 64 + mi * 32 + crow(r, h)) * NPROJ + nt * 128 + wn * 64 + ni * 32 + l31 + PGB];
	ds_read_b128 v[64:67], v154 offset:18432
	ds_read_b128 v[68:71], v154 offset:23040
	ds_read_b128 v[72:75], v153
	ds_read_b128 v[76:79], v153 offset:4608
	s_waitcnt lgkmcnt(1)
	v_mfma_f32_32x32x16_bf16 v[0:15], v[72:75], v[64:67], v[0:15]
	v_mfma_f32_32x32x16_bf16 v[32:47], v[72:75], v[68:71], v[32:47]
	s_waitcnt lgkmcnt(0)
	v_mfma_f32_32x32x16_bf16 v[48:63], v[76:79], v[64:67], v[48:63]
	ds_read_b128 v[64:67], v154 offset:18464
	ds_read_b128 v[72:75], v154 offset:23072
	ds_read_b128 v[80:83], v153 offset:32
	ds_read_b128 v[84:87], v153 offset:4640
	v_mfma_f32_32x32x16_bf16 v[16:31], v[76:79], v[68:71], v[16:31]
	s_waitcnt lgkmcnt(1)
	v_mfma_f32_32x32x16_bf16 v[0:15], v[80:83], v[64:67], v[0:15]
	v_mfma_f32_32x32x16_bf16 v[32:47], v[80:83], v[72:75], v[32:47]
	s_waitcnt lgkmcnt(0)
	v_mfma_f32_32x32x16_bf16 v[48:63], v[84:87], v[64:67], v[48:63]
	ds_read_b128 v[64:67], v154 offset:18496
	ds_read_b128 v[68:71], v154 offset:23104
	ds_read_b128 v[76:79], v153 offset:64
	ds_read_b128 v[80:83], v153 offset:4672
	s_waitcnt vmcnt(7)
	ds_write_b128 v152, v[96:99] offset:36864
	s_waitcnt vmcnt(5)
	ds_write_b128 v152, v[104:107] offset:41472
	s_waitcnt vmcnt(3)
	ds_write_b128 v152, v[112:115] offset:46080
	s_waitcnt vmcnt(1)
	ds_write_b128 v152, v[120:123] offset:50688
	v_mfma_f32_32x32x16_bf16 v[16:31], v[84:87], v[72:75], v[16:31]
	s_waitcnt lgkmcnt(5)
	v_mfma_f32_32x32x16_bf16 v[0:15], v[76:79], v[64:67], v[0:15]
	v_mfma_f32_32x32x16_bf16 v[32:47], v[76:79], v[68:71], v[32:47]
	s_waitcnt lgkmcnt(4)
	v_mfma_f32_32x32x16_bf16 v[48:63], v[80:83], v[64:67], v[48:63]
	ds_read_b128 v[64:67], v154 offset:18528
	ds_read_b128 v[72:75], v154 offset:23136
	ds_read_b128 v[76:79], v153 offset:96
	ds_read_b128 v[84:87], v153 offset:4704
	ds_write_b128 v152, v[100:103] offset:55296
	ds_write_b128 v152, v[108:111] offset:59904
	ds_write_b128 v152, v[116:119] offset:64512
	s_waitcnt vmcnt(0)
	ds_write_b128 v155, v[124:127] offset:13824
	v_mfma_f32_32x32x16_bf16 v[16:31], v[80:83], v[68:71], v[16:31]
	s_waitcnt lgkmcnt(5)
	v_mfma_f32_32x32x16_bf16 v[0:15], v[76:79], v[64:67], v[0:15]
	v_mfma_f32_32x32x16_bf16 v[32:47], v[76:79], v[72:75], v[32:47]
	s_waitcnt lgkmcnt(4)
	v_mfma_f32_32x32x16_bf16 v[48:63], v[84:87], v[64:67], v[48:63]
	v_mfma_f32_32x32x16_bf16 v[16:31], v[84:87], v[72:75], v[16:31]
	s_waitcnt lgkmcnt(0)
	s_barrier
	ds_read_b128 v[64:67], v154 offset:55296
	ds_read_b128 v[68:71], v154 offset:59904
	ds_read_b128 v[72:75], v153 offset:36864
	ds_read_b128 v[76:79], v153 offset:41472
	s_waitcnt lgkmcnt(1)
	v_mfma_f32_32x32x16_bf16 v[0:15], v[72:75], v[64:67], v[0:15]
	v_mfma_f32_32x32x16_bf16 v[32:47], v[72:75], v[68:71], v[32:47]
	s_waitcnt lgkmcnt(0)
	v_mfma_f32_32x32x16_bf16 v[48:63], v[76:79], v[64:67], v[48:63]
	ds_read_b128 v[64:67], v154 offset:55328
	ds_read_b128 v[72:75], v154 offset:59936
	ds_read_b128 v[80:83], v153 offset:36896
	ds_read_b128 v[84:87], v153 offset:41504
	v_mfma_f32_32x32x16_bf16 v[16:31], v[76:79], v[68:71], v[16:31]
	s_waitcnt lgkmcnt(1)
	v_mfma_f32_32x32x16_bf16 v[0:15], v[80:83], v[64:67], v[0:15]
	v_mfma_f32_32x32x16_bf16 v[32:47], v[80:83], v[72:75], v[32:47]
	s_waitcnt lgkmcnt(0)
	v_mfma_f32_32x32x16_bf16 v[48:63], v[84:87], v[64:67], v[48:63]
	v_mfma_f32_32x32x16_bf16 v[16:31], v[84:87], v[72:75], v[16:31]
	ds_read_b128 v[64:67], v153 offset:41536
	ds_read_b128 v[68:71], v154 offset:59968
	ds_read_b128 v[72:75], v154 offset:55360
	ds_read_b128 v[76:79], v153 offset:36928
	s_waitcnt lgkmcnt(0)
	v_mfma_f32_32x32x16_bf16 v[0:15], v[76:79], v[72:75], v[0:15]
	v_mfma_f32_32x32x16_bf16 v[32:47], v[76:79], v[68:71], v[32:47]
	v_mfma_f32_32x32x16_bf16 v[48:63], v[64:67], v[72:75], v[48:63]
	v_mfma_f32_32x32x16_bf16 v[16:31], v[64:67], v[68:71], v[16:31]
	ds_read_b128 v[64:67], v153 offset:41568
	ds_read_b128 v[68:71], v154 offset:60000
	ds_read_b128 v[72:75], v154 offset:55392
	ds_read_b128 v[76:79], v153 offset:36960
	s_waitcnt lgkmcnt(0)
	v_mfma_f32_32x32x16_bf16 v[0:15], v[76:79], v[72:75], v[0:15]
	v_mfma_f32_32x32x16_bf16 v[32:47], v[76:79], v[68:71], v[32:47]
	v_mfma_f32_32x32x16_bf16 v[48:63], v[64:67], v[72:75], v[48:63]
	v_mfma_f32_32x32x16_bf16 v[16:31], v[64:67], v[68:71], v[16:31]
	s_barrier
	s_movk_i32 s8, 0x1400
	v_lshlrev_b32_e32 v64, 6, v148
	v_lshl_add_u32 v65, v150, 2, v64
	v_lshlrev_b32_e32 v64, 6, v149
	v_mul_lo_u32 v66, v65, s8
	v_add3_u32 v64, v64, s10, v151
	v_add_u32_e32 v68, v66, v64
	v_ashrrev_i32_e32 v69, 31, v68
	v_lshl_add_u64 v[68:69], v[68:69], 1, s[6:7]
	v_add_co_u32_e32 v68, vcc, s75, v68
	v_add_u32_e32 v98, 0x1400, v66
	s_nop 0
	v_addc_co_u32_e32 v69, vcc, 0, v69, vcc
	global_load_ushort v101, v[68:69], off
	v_add_u32_e32 v70, v98, v64
	v_ashrrev_i32_e32 v71, 31, v70
	v_lshl_add_u64 v[70:71], v[70:71], 1, s[6:7]
	v_add_co_u32_e32 v70, vcc, s75, v70
	v_add_u32_e32 v67, 0x2800, v66
	s_nop 0
	v_addc_co_u32_e32 v71, vcc, 0, v71, vcc
	global_load_ushort v113, v[70:71], off
	v_add_u32_e32 v72, v67, v64
	v_ashrrev_i32_e32 v73, 31, v72
	v_add_u32_e32 v99, 0x3c00, v66
	v_lshl_add_u64 v[72:73], v[72:73], 1, s[6:7]
	v_add_u32_e32 v74, v99, v64
	v_ashrrev_i32_e32 v75, 31, v74
	v_add_co_u32_e32 v70, vcc, s75, v72
	v_lshl_add_u64 v[74:75], v[74:75], 1, s[6:7]
	s_nop 0
	v_addc_co_u32_e32 v71, vcc, 0, v73, vcc
	v_add_co_u32_e32 v72, vcc, s75, v74
	v_add_u32_e32 v100, 0xa000, v66
	s_nop 0
	v_addc_co_u32_e32 v73, vcc, 0, v75, vcc
	global_load_ushort v114, v[70:71], off
	global_load_ushort v115, v[72:73], off
	v_add_u32_e32 v76, v100, v64
	v_ashrrev_i32_e32 v77, 31, v76
	v_add_u32_e32 v102, 0xb400, v66
	v_lshl_add_u64 v[76:77], v[76:77], 1, s[6:7]
	v_add_u32_e32 v68, v102, v64
	v_ashrrev_i32_e32 v69, 31, v68
; DI float bf2f(bf16_t v) { return __uint_as_float(((unsigned)v) << 16); }
; DI bf16_t f2bf(float x) { return (bf16_t)(pk_bf16(x, 0.f) & 0xffffu); }
; DI int crow(int r, int h) { return (r & 3) + 8 * (r >> 2) + 4 * h; }
; DI void phase_merge(const Params& p, int g, char* smem, int bid, int nb) {
;     ...
; #pragma unroll
;     for (int mi = 0; mi < 2; ++mi)
; #pragma unroll
;       for (int ni = 0; ni < 2; ++ni)
;       {
;         bf16_t gb16[16];
; #pragma unroll
;         for (int r = 0; r < 16; ++r) gb16[r] = pt[(wm * 64 + mi * 32 + crow(r, h)) * NPROJ + nt * 128 + wn * 64 + ni * 32 + l31 + PGB];
; #pragma unroll
;         for (int r = 0; r < 16; ++r) {
;           const int rl = wm * 64 + mi * 32 + crow(r, h), cl = nt * 128 + wn * 64 + ni * 32 + l31;
;           mgt[rl * 1024 + cl] = f2bf(acc[mi][ni][r] * fmaxf(bf2f(gb16[r]), 1e-20f));
;         }
	v_add_u32_e32 v103, 0xc800, v66
	v_add_co_u32_e32 v70, vcc, s75, v76
	v_lshl_add_u64 v[68:69], v[68:69], 1, s[6:7]
	v_add_u32_e32 v78, v103, v64
	v_addc_co_u32_e32 v71, vcc, 0, v77, vcc
	v_ashrrev_i32_e32 v79, 31, v78
	v_add_u32_e32 v104, 0xdc00, v66
	v_add_co_u32_e32 v68, vcc, s75, v68
	v_lshl_add_u64 v[78:79], v[78:79], 1, s[6:7]
	v_add_u32_e32 v80, v104, v64
	v_addc_co_u32_e32 v69, vcc, 0, v69, vcc
	v_ashrrev_i32_e32 v81, 31, v80
	v_add_co_u32_e32 v72, vcc, s75, v78
	v_lshl_add_u64 v[80:81], v[80:81], 1, s[6:7]
	s_nop 0
	v_addc_co_u32_e32 v73, vcc, 0, v79, vcc
	v_add_co_u32_e32 v74, vcc, s75, v80
	v_add_u32_e32 v105, 0x14000, v66
	s_nop 0
	v_addc_co_u32_e32 v75, vcc, 0, v81, vcc
	global_load_ushort v116, v[70:71], off
	global_load_ushort v117, v[68:69], off
	global_load_ushort v118, v[72:73], off
	global_load_ushort v119, v[74:75], off
	v_add_u32_e32 v82, v105, v64
	v_ashrrev_i32_e32 v83, 31, v82
	v_add_u32_e32 v106, 0x15400, v66
	v_lshl_add_u64 v[82:83], v[82:83], 1, s[6:7]
	v_add_u32_e32 v84, v106, v64
	v_ashrrev_i32_e32 v85, 31, v84
	v_add_u32_e32 v107, 0x16800, v66
	v_add_co_u32_e32 v70, vcc, s75, v82
	v_lshl_add_u64 v[84:85], v[84:85], 1, s[6:7]
	v_add_u32_e32 v86, v107, v64
	v_addc_co_u32_e32 v71, vcc, 0, v83, vcc
	v_ashrrev_i32_e32 v87, 31, v86
	v_add_u32_e32 v108, 0x17c00, v66
	v_lshl_add_u64 v[86:87], v[86:87], 1, s[6:7]
	v_add_u32_e32 v88, v108, v64
	v_ashrrev_i32_e32 v89, 31, v88
	v_add_u32_e32 v109, 0x1e000, v66
	v_lshl_add_u64 v[88:89], v[88:89], 1, s[6:7]
	s_waitcnt vmcnt(7)
	v_lshlrev_b32_e32 v68, 16, v101
	global_load_ushort v101, v[70:71], off
	v_add_co_u32_e32 v70, vcc, s75, v84
	v_add_u32_e32 v90, v109, v64
	s_nop 0
	v_addc_co_u32_e32 v71, vcc, 0, v85, vcc
	v_add_co_u32_e32 v72, vcc, s75, v86
	v_ashrrev_i32_e32 v91, 31, v90
	s_nop 0
	v_addc_co_u32_e32 v73, vcc, 0, v87, vcc
	v_add_u32_e32 v110, 0x1f400, v66
	v_add_co_u32_e32 v74, vcc, s75, v88
	v_lshl_add_u64 v[90:91], v[90:91], 1, s[6:7]
	v_add_u32_e32 v92, v110, v64
	v_addc_co_u32_e32 v75, vcc, 0, v89, vcc
	v_ashrrev_i32_e32 v93, 31, v92
	v_add_u32_e32 v111, 0x20800, v66
	v_add_co_u32_e32 v76, vcc, s75, v90
	v_lshl_add_u64 v[92:93], v[92:93], 1, s[6:7]
	v_add_u32_e32 v94, v111, v64
	v_addc_co_u32_e32 v77, vcc, 0, v91, vcc
	v_ashrrev_i32_e32 v95, 31, v94
	v_add_u32_e32 v112, 0x21c00, v66
	v_add_co_u32_e32 v78, vcc, s75, v92
	v_lshl_add_u64 v[94:95], v[94:95], 1, s[6:7]
	v_add_u32_e32 v96, v112, v64
	v_addc_co_u32_e32 v79, vcc, 0, v93, vcc
	v_ashrrev_i32_e32 v97, 31, v96
	v_add_co_u32_e32 v80, vcc, s75, v94
	v_lshl_add_u64 v[96:97], v[96:97], 1, s[6:7]
	s_nop 0
	v_addc_co_u32_e32 v81, vcc, 0, v95, vcc
	v_add_co_u32_e32 v82, vcc, s75, v96
	v_max_f32_e32 v68, v68, v68
	s_nop 0
	v_addc_co_u32_e32 v83, vcc, 0, v97, vcc
	global_load_ushort v70, v[70:71], off
	s_nop 0
	global_load_ushort v71, v[72:73], off
	s_nop 0
	global_load_ushort v72, v[74:75], off
	global_load_ushort v73, v[76:77], off
	s_nop 0
	global_load_ushort v74, v[78:79], off
	global_load_ushort v75, v[80:81], off
	global_load_ushort v76, v[82:83], off
	v_max_f32_e32 v68, 0x1e3ce508, v68
	v_lshlrev_b32_e32 v65, 10, v65
	s_add_u32 s0, s4, s0
	v_mul_f32_e32 v0, v0, v68
	v_add_u32_e32 v68, v65, v64
	s_addc_u32 s1, s5, s1
	v_ashrrev_i32_e32 v69, 31, v68
	v_cvt_pk_bf16_f32 v0, v0, s0
	v_lshl_add_u64 v[68:69], v[68:69], 1, s[0:1]
	global_store_short v[68:69], v0, off
	s_waitcnt vmcnt(15)
	v_lshlrev_b32_e32 v0, 16, v113
	v_max_f32_e32 v0, v0, v0
	v_max_f32_e32 v0, 0x1e3ce508, v0
	v_mul_f32_e32 v0, v1, v0
	v_or_b32_e32 v84, 0x400, v65
	v_cvt_pk_bf16_f32 v68, v0, s0
	v_add_u32_e32 v0, v84, v64
	v_ashrrev_i32_e32 v1, 31, v0
	v_lshl_add_u64 v[0:1], v[0:1], 1, s[0:1]
	global_store_short v[0:1], v68, off
	s_waitcnt vmcnt(15)
	v_lshlrev_b32_e32 v0, 16, v114
	v_max_f32_e32 v0, v0, v0
	v_max_f32_e32 v0, 0x1e3ce508, v0
	v_mul_f32_e32 v0, v2, v0
	v_or_b32_e32 v85, 0x800, v65
	v_cvt_pk_bf16_f32 v2, v0, s0
	v_add_u32_e32 v0, v85, v64
	v_ashrrev_i32_e32 v1, 31, v0
	v_lshl_add_u64 v[0:1], v[0:1], 1, s[0:1]
	global_store_short v[0:1], v2, off
	s_waitcnt vmcnt(15)
	v_lshlrev_b32_e32 v0, 16, v115
	v_max_f32_e32 v0, v0, v0
	v_max_f32_e32 v0, 0x1e3ce508, v0
	v_mul_f32_e32 v0, v3, v0
	v_or_b32_e32 v86, 0xc00, v65
	v_cvt_pk_bf16_f32 v2, v0, s0
	v_add_u32_e32 v0, v86, v64
	v_ashrrev_i32_e32 v1, 31, v0
	v_lshl_add_u64 v[0:1], v[0:1], 1, s[0:1]
	global_store_short v[0:1], v2, off
	s_waitcnt vmcnt(15)
	v_lshlrev_b32_e32 v0, 16, v116
	v_max_f32_e32 v0, v0, v0
	v_max_f32_e32 v0, 0x1e3ce508, v0
	v_mul_f32_e32 v0, v4, v0
	v_add_u32_e32 v87, 0x2000, v65
	v_cvt_pk_bf16_f32 v2, v0, s0
	v_add_u32_e32 v0, v87, v64
	v_ashrrev_i32_e32 v1, 31, v0
	v_lshl_add_u64 v[0:1], v[0:1], 1, s[0:1]
	global_store_short v[0:1], v2, off
	s_waitcnt vmcnt(15)
	v_lshlrev_b32_e32 v0, 16, v117
	v_max_f32_e32 v0, v0, v0
	v_max_f32_e32 v0, 0x1e3ce508, v0
	v_mul_f32_e32 v0, v5, v0
	v_add_u32_e32 v88, 0x2400, v65
	v_cvt_pk_bf16_f32 v2, v0, s0
	v_add_u32_e32 v0, v88, v64
	v_ashrrev_i32_e32 v1, 31, v0
	v_lshl_add_u64 v[0:1], v[0:1], 1, s[0:1]
	global_store_short v[0:1], v2, off
	s_waitcnt vmcnt(15)
	v_lshlrev_b32_e32 v0, 16, v118
	v_max_f32_e32 v0, v0, v0
	v_max_f32_e32 v0, 0x1e3ce508, v0
	v_mul_f32_e32 v0, v6, v0
	v_add_u32_e32 v89, 0x2800, v65
	v_cvt_pk_bf16_f32 v2, v0, s0
	v_add_u32_e32 v0, v89, v64
	v_ashrrev_i32_e32 v1, 31, v0
	v_lshl_add_u64 v[0:1], v[0:1], 1, s[0:1]
	global_store_short v[0:1], v2, off
	s_waitcnt vmcnt(15)
	v_lshlrev_b32_e32 v0, 16, v119
	v_max_f32_e32 v0, v0, v0
	v_max_f32_e32 v0, 0x1e3ce508, v0
	v_mul_f32_e32 v0, v7, v0
	v_add_u32_e32 v90, 0x2c00, v65
	v_cvt_pk_bf16_f32 v2, v0, s0
	v_add_u32_e32 v0, v90, v64
	v_ashrrev_i32_e32 v1, 31, v0
	v_lshl_add_u64 v[0:1], v[0:1], 1, s[0:1]
	global_store_short v[0:1], v2, off
	s_waitcnt vmcnt(15)
; DI float bf2f(bf16_t v) { return __uint_as_float(((unsigned)v) << 16); }
; DI bf16_t f2bf(float x) { return (bf16_t)(pk_bf16(x, 0.f) & 0xffffu); }
; DI int crow(int r, int h) { return (r & 3) + 8 * (r >> 2) + 4 * h; }
; DI void phase_merge(const Params& p, int g, char* smem, int bid, int nb) {
;     ...
; #pragma unroll
;     for (int mi = 0; mi < 2; ++mi)
; #pragma unroll
;       for (int ni = 0; ni < 2; ++ni)
;       {
;         bf16_t gb16[16];
; #pragma unroll
;         for (int r = 0; r < 16; ++r) gb16[r] = pt[(wm * 64 + mi * 32 + crow(r, h)) * NPROJ + nt * 128 + wn * 64 + ni * 32 + l31 + PGB];
; #pragma unroll
;         for (int r = 0; r < 16; ++r) {
;           const int rl = wm * 64 + mi * 32 + crow(r, h), cl = nt * 128 + wn * 64 + ni * 32 + l31;
;           mgt[rl * 1024 + cl] = f2bf(acc[mi][ni][r] * fmaxf(bf2f(gb16[r]), 1e-20f));
;         }
	v_lshlrev_b32_e32 v0, 16, v101
	v_max_f32_e32 v0, v0, v0
	v_max_f32_e32 v0, 0x1e3ce508, v0
	v_mul_f32_e32 v0, v8, v0
	v_add_u32_e32 v91, 0x4000, v65
	v_cvt_pk_bf16_f32 v2, v0, s0
	v_add_u32_e32 v0, v91, v64
	v_ashrrev_i32_e32 v1, 31, v0
	v_lshl_add_u64 v[0:1], v[0:1], 1, s[0:1]
	global_store_short v[0:1], v2, off
	s_waitcnt vmcnt(15)
	v_lshlrev_b32_e32 v0, 16, v70
	v_max_f32_e32 v0, v0, v0
	v_max_f32_e32 v0, 0x1e3ce508, v0
	v_mul_f32_e32 v0, v9, v0
	v_add_u32_e32 v92, 0x4400, v65
	v_cvt_pk_bf16_f32 v2, v0, s0
	v_add_u32_e32 v0, v92, v64
	v_ashrrev_i32_e32 v1, 31, v0
	v_lshl_add_u64 v[0:1], v[0:1], 1, s[0:1]
	global_store_short v[0:1], v2, off
	s_waitcnt vmcnt(15)
	v_lshlrev_b32_e32 v0, 16, v71
	v_max_f32_e32 v0, v0, v0
	v_max_f32_e32 v0, 0x1e3ce508, v0
	v_mul_f32_e32 v0, v10, v0
	v_add_u32_e32 v93, 0x4800, v65
	v_cvt_pk_bf16_f32 v2, v0, s0
	v_add_u32_e32 v0, v93, v64
	v_ashrrev_i32_e32 v1, 31, v0
	v_lshl_add_u64 v[0:1], v[0:1], 1, s[0:1]
	global_store_short v[0:1], v2, off
	s_waitcnt vmcnt(15)
	v_lshlrev_b32_e32 v0, 16, v72
	v_max_f32_e32 v0, v0, v0
	v_max_f32_e32 v0, 0x1e3ce508, v0
	v_mul_f32_e32 v0, v11, v0
	v_add_u32_e32 v94, 0x4c00, v65
	v_cvt_pk_bf16_f32 v2, v0, s0
	v_add_u32_e32 v0, v94, v64
	v_ashrrev_i32_e32 v1, 31, v0
	v_lshl_add_u64 v[0:1], v[0:1], 1, s[0:1]
	global_store_short v[0:1], v2, off
	s_waitcnt vmcnt(15)
	v_lshlrev_b32_e32 v0, 16, v73
	v_max_f32_e32 v0, v0, v0
	v_max_f32_e32 v0, 0x1e3ce508, v0
	v_mul_f32_e32 v0, v12, v0
	v_add_u32_e32 v95, 0x6000, v65
	v_cvt_pk_bf16_f32 v2, v0, s0
	v_add_u32_e32 v0, v95, v64
	v_ashrrev_i32_e32 v1, 31, v0
	v_lshl_add_u64 v[0:1], v[0:1], 1, s[0:1]
	global_store_short v[0:1], v2, off
	s_waitcnt vmcnt(15)
	v_lshlrev_b32_e32 v0, 16, v74
	v_max_f32_e32 v0, v0, v0
	v_max_f32_e32 v0, 0x1e3ce508, v0
	v_mul_f32_e32 v0, v13, v0
	v_add_u32_e32 v96, 0x6400, v65
	v_cvt_pk_bf16_f32 v2, v0, s0
	v_add_u32_e32 v0, v96, v64
	v_ashrrev_i32_e32 v1, 31, v0
	v_lshl_add_u64 v[0:1], v[0:1], 1, s[0:1]
	global_store_short v[0:1], v2, off
	s_waitcnt vmcnt(15)
	v_lshlrev_b32_e32 v0, 16, v75
	v_max_f32_e32 v0, v0, v0
	v_max_f32_e32 v0, 0x1e3ce508, v0
	v_mul_f32_e32 v0, v14, v0
	v_add_u32_e32 v97, 0x6800, v65
	v_cvt_pk_bf16_f32 v2, v0, s0
	v_add_u32_e32 v0, v97, v64
	v_ashrrev_i32_e32 v1, 31, v0
	v_lshl_add_u64 v[0:1], v[0:1], 1, s[0:1]
	global_store_short v[0:1], v2, off
	s_waitcnt vmcnt(15)
	v_lshlrev_b32_e32 v0, 16, v76
	v_max_f32_e32 v0, v0, v0
	v_max_f32_e32 v0, 0x1e3ce508, v0
	v_mul_f32_e32 v0, v15, v0
	v_add_u32_e32 v101, 0x6c00, v65
	v_cvt_pk_bf16_f32 v2, v0, s0
	v_add_u32_e32 v0, v101, v64
	v_ashrrev_i32_e32 v1, 31, v0
	v_lshl_add_u64 v[0:1], v[0:1], 1, s[0:1]
	global_store_short v[0:1], v2, off
	v_add_u32_e32 v0, 32, v64
	v_add_u32_e32 v2, v0, v66
	v_ashrrev_i32_e32 v3, 31, v2
	v_lshl_add_u64 v[2:3], v[2:3], 1, s[6:7]
	v_add_co_u32_e32 v2, vcc, s75, v2
	v_add_u32_e32 v4, v98, v0
	s_nop 0
	v_addc_co_u32_e32 v3, vcc, 0, v3, vcc
	global_load_ushort v1, v[2:3], off
	v_ashrrev_i32_e32 v5, 31, v4
	v_lshl_add_u64 v[2:3], v[4:5], 1, s[6:7]
	v_add_co_u32_e32 v2, vcc, s75, v2
	v_add_u32_e32 v4, v67, v0
	s_nop 0
	v_addc_co_u32_e32 v3, vcc, 0, v3, vcc
	global_load_ushort v67, v[2:3], off
	v_ashrrev_i32_e32 v5, 31, v4
	v_lshl_add_u64 v[4:5], v[4:5], 1, s[6:7]
	v_add_u32_e32 v6, v99, v0
	v_ashrrev_i32_e32 v7, 31, v6
	v_add_co_u32_e32 v2, vcc, s75, v4
	v_lshl_add_u64 v[6:7], v[6:7], 1, s[6:7]
	s_nop 0
	v_addc_co_u32_e32 v3, vcc, 0, v5, vcc
	v_add_co_u32_e32 v4, vcc, s75, v6
	v_add_u32_e32 v8, v100, v0
	s_nop 0
	v_addc_co_u32_e32 v5, vcc, 0, v7, vcc
	global_load_ushort v98, v[2:3], off
	global_load_ushort v99, v[4:5], off
	v_ashrrev_i32_e32 v9, 31, v8
	v_lshl_add_u64 v[8:9], v[8:9], 1, s[6:7]
	v_add_u32_e32 v10, v102, v0
	v_ashrrev_i32_e32 v11, 31, v10
	v_add_co_u32_e32 v2, vcc, s75, v8
	v_lshl_add_u64 v[10:11], v[10:11], 1, s[6:7]
	v_add_u32_e32 v12, v103, v0
	v_addc_co_u32_e32 v3, vcc, 0, v9, vcc
	v_ashrrev_i32_e32 v13, 31, v12
	v_add_co_u32_e32 v4, vcc, s75, v10
	v_lshl_add_u64 v[12:13], v[12:13], 1, s[6:7]
	v_add_u32_e32 v14, v104, v0
	v_addc_co_u32_e32 v5, vcc, 0, v11, vcc
	v_ashrrev_i32_e32 v15, 31, v14
	v_add_co_u32_e32 v6, vcc, s75, v12
	v_lshl_add_u64 v[14:15], v[14:15], 1, s[6:7]
	s_nop 0
	v_addc_co_u32_e32 v7, vcc, 0, v13, vcc
	v_add_co_u32_e32 v8, vcc, s75, v14
	v_add_u32_e32 v68, v105, v0
	s_nop 0
	v_addc_co_u32_e32 v9, vcc, 0, v15, vcc
	global_load_ushort v100, v[2:3], off
	global_load_ushort v102, v[4:5], off
	global_load_ushort v103, v[6:7], off
	global_load_ushort v104, v[8:9], off
	v_ashrrev_i32_e32 v69, 31, v68
	v_lshl_add_u64 v[68:69], v[68:69], 1, s[6:7]
	v_add_u32_e32 v70, v106, v0
	v_ashrrev_i32_e32 v71, 31, v70
	v_add_co_u32_e32 v4, vcc, s75, v68
	v_lshl_add_u64 v[70:71], v[70:71], 1, s[6:7]
	v_add_u32_e32 v72, v107, v0
	v_addc_co_u32_e32 v5, vcc, 0, v69, vcc
	v_ashrrev_i32_e32 v73, 31, v72
	v_lshl_add_u64 v[72:73], v[72:73], 1, s[6:7]
	v_add_u32_e32 v74, v108, v0
	v_ashrrev_i32_e32 v75, 31, v74
	v_lshl_add_u64 v[74:75], v[74:75], 1, s[6:7]
	v_add_u32_e32 v76, v109, v0
	v_ashrrev_i32_e32 v77, 31, v76
	v_lshl_add_u64 v[76:77], v[76:77], 1, s[6:7]
	v_add_u32_e32 v78, v110, v0
	v_ashrrev_i32_e32 v79, 31, v78
	v_lshl_add_u64 v[78:79], v[78:79], 1, s[6:7]
	v_add_u32_e32 v80, v111, v0
	v_ashrrev_i32_e32 v81, 31, v80
	v_lshl_add_u64 v[80:81], v[80:81], 1, s[6:7]
	v_add_u32_e32 v82, v112, v0
	v_ashrrev_i32_e32 v83, 31, v82
	v_lshl_add_u64 v[82:83], v[82:83], 1, s[6:7]
	s_waitcnt vmcnt(7)
; DI float bf2f(bf16_t v) { return __uint_as_float(((unsigned)v) << 16); }
; DI bf16_t f2bf(float x) { return (bf16_t)(pk_bf16(x, 0.f) & 0xffffu); }
; DI int crow(int r, int h) { return (r & 3) + 8 * (r >> 2) + 4 * h; }
; DI void phase_merge(const Params& p, int g, char* smem, int bid, int nb) {
;     ...
; #pragma unroll
;     for (int mi = 0; mi < 2; ++mi)
; #pragma unroll
;       for (int ni = 0; ni < 2; ++ni)
;       {
;         bf16_t gb16[16];
; #pragma unroll
;         for (int r = 0; r < 16; ++r) gb16[r] = pt[(wm * 64 + mi * 32 + crow(r, h)) * NPROJ + nt * 128 + wn * 64 + ni * 32 + l31 + PGB];
; #pragma unroll
;         for (int r = 0; r < 16; ++r) {
;           const int rl = wm * 64 + mi * 32 + crow(r, h), cl = nt * 128 + wn * 64 + ni * 32 + l31;
;           mgt[rl * 1024 + cl] = f2bf(acc[mi][ni][r] * fmaxf(bf2f(gb16[r]), 1e-20f));
;         }
	v_lshlrev_b32_e32 v1, 16, v1
	v_max_f32_e32 v1, v1, v1
	v_max_f32_e32 v1, 0x1e3ce508, v1
	v_mul_f32_e32 v1, v32, v1
	global_load_ushort v32, v[4:5], off
	v_add_co_u32_e32 v4, vcc, s75, v70
	v_add_u32_e32 v2, v0, v65
	s_nop 0
	v_addc_co_u32_e32 v5, vcc, 0, v71, vcc
	v_add_co_u32_e32 v6, vcc, s75, v72
	v_ashrrev_i32_e32 v3, 31, v2
	s_nop 0
	v_addc_co_u32_e32 v7, vcc, 0, v73, vcc
	v_add_co_u32_e32 v8, vcc, s75, v74
	v_cvt_pk_bf16_f32 v1, v1, s0
	s_nop 0
	v_addc_co_u32_e32 v9, vcc, 0, v75, vcc
	v_add_co_u32_e32 v10, vcc, s75, v76
	v_lshl_add_u64 v[2:3], v[2:3], 1, s[0:1]
	s_nop 0
	v_addc_co_u32_e32 v11, vcc, 0, v77, vcc
	v_add_co_u32_e32 v12, vcc, s75, v78
	v_add_u32_e32 v70, 0x32000, v66
	s_nop 0
	v_addc_co_u32_e32 v13, vcc, 0, v79, vcc
	v_add_co_u32_e32 v14, vcc, s75, v80
	v_add_u32_e32 v72, 0x33400, v66
	s_nop 0
	v_addc_co_u32_e32 v15, vcc, 0, v81, vcc
	v_add_co_u32_e32 v68, vcc, s75, v82
	v_add_u32_e32 v73, 0x34800, v66
	s_nop 0
	v_addc_co_u32_e32 v69, vcc, 0, v83, vcc
	global_load_ushort v4, v[4:5], off
	s_nop 0
	global_load_ushort v5, v[6:7], off
	s_nop 0
	global_load_ushort v6, v[8:9], off
	global_load_ushort v7, v[10:11], off
	s_nop 0
	global_load_ushort v8, v[12:13], off
	global_load_ushort v9, v[14:15], off
	global_load_ushort v10, v[68:69], off
	v_add_u32_e32 v68, 0x2a800, v66
	global_store_short v[2:3], v1, off
	s_waitcnt vmcnt(15)
	v_lshlrev_b32_e32 v1, 16, v67
	v_max_f32_e32 v1, v1, v1
	v_max_f32_e32 v1, 0x1e3ce508, v1
	v_add_u32_e32 v2, v84, v0
	v_mul_f32_e32 v1, v33, v1
	v_ashrrev_i32_e32 v3, 31, v2
	v_cvt_pk_bf16_f32 v1, v1, s0
	v_lshl_add_u64 v[2:3], v[2:3], 1, s[0:1]
	global_store_short v[2:3], v1, off
	s_waitcnt vmcnt(15)
	v_lshlrev_b32_e32 v1, 16, v98
	v_max_f32_e32 v1, v1, v1
	v_max_f32_e32 v1, 0x1e3ce508, v1
	v_add_u32_e32 v2, v85, v0
	v_mul_f32_e32 v1, v34, v1
	v_ashrrev_i32_e32 v3, 31, v2
	v_cvt_pk_bf16_f32 v1, v1, s0
	v_lshl_add_u64 v[2:3], v[2:3], 1, s[0:1]
	global_store_short v[2:3], v1, off
	s_waitcnt vmcnt(15)
	v_lshlrev_b32_e32 v1, 16, v99
	v_max_f32_e32 v1, v1, v1
	v_max_f32_e32 v1, 0x1e3ce508, v1
	v_add_u32_e32 v2, v86, v0
	v_mul_f32_e32 v1, v35, v1
	v_ashrrev_i32_e32 v3, 31, v2
	v_cvt_pk_bf16_f32 v1, v1, s0
	v_lshl_add_u64 v[2:3], v[2:3], 1, s[0:1]
	global_store_short v[2:3], v1, off
	s_waitcnt vmcnt(15)
	v_lshlrev_b32_e32 v1, 16, v100
	v_max_f32_e32 v1, v1, v1
	v_max_f32_e32 v1, 0x1e3ce508, v1
	v_add_u32_e32 v2, v87, v0
	v_mul_f32_e32 v1, v36, v1
	v_ashrrev_i32_e32 v3, 31, v2
	v_cvt_pk_bf16_f32 v1, v1, s0
	v_lshl_add_u64 v[2:3], v[2:3], 1, s[0:1]
	global_store_short v[2:3], v1, off
	s_waitcnt vmcnt(15)
	v_lshlrev_b32_e32 v1, 16, v102
	v_max_f32_e32 v1, v1, v1
	v_max_f32_e32 v1, 0x1e3ce508, v1
	v_add_u32_e32 v2, v88, v0
	v_mul_f32_e32 v1, v37, v1
	v_ashrrev_i32_e32 v3, 31, v2
	v_cvt_pk_bf16_f32 v1, v1, s0
	v_lshl_add_u64 v[2:3], v[2:3], 1, s[0:1]
	global_store_short v[2:3], v1, off
	s_waitcnt vmcnt(15)
	v_lshlrev_b32_e32 v1, 16, v103
	v_max_f32_e32 v1, v1, v1
	v_max_f32_e32 v1, 0x1e3ce508, v1
	v_add_u32_e32 v2, v89, v0
	v_mul_f32_e32 v1, v38, v1
	v_ashrrev_i32_e32 v3, 31, v2
	v_cvt_pk_bf16_f32 v1, v1, s0
	v_lshl_add_u64 v[2:3], v[2:3], 1, s[0:1]
	global_store_short v[2:3], v1, off
	s_waitcnt vmcnt(15)
	v_lshlrev_b32_e32 v1, 16, v104
	v_max_f32_e32 v1, v1, v1
	v_max_f32_e32 v1, 0x1e3ce508, v1
	v_add_u32_e32 v2, v90, v0
	v_mul_f32_e32 v1, v39, v1
	v_ashrrev_i32_e32 v3, 31, v2
	v_cvt_pk_bf16_f32 v1, v1, s0
	v_lshl_add_u64 v[2:3], v[2:3], 1, s[0:1]
	global_store_short v[2:3], v1, off
	s_waitcnt vmcnt(15)
	v_lshlrev_b32_e32 v1, 16, v32
	v_max_f32_e32 v1, v1, v1
	v_max_f32_e32 v1, 0x1e3ce508, v1
	v_add_u32_e32 v2, v91, v0
	v_mul_f32_e32 v1, v40, v1
	v_ashrrev_i32_e32 v3, 31, v2
	v_cvt_pk_bf16_f32 v1, v1, s0
	v_lshl_add_u64 v[2:3], v[2:3], 1, s[0:1]
	global_store_short v[2:3], v1, off
	s_waitcnt vmcnt(15)
	v_lshlrev_b32_e32 v1, 16, v4
	v_max_f32_e32 v1, v1, v1
	v_max_f32_e32 v1, 0x1e3ce508, v1
	v_add_u32_e32 v2, v92, v0
	v_mul_f32_e32 v1, v41, v1
	v_ashrrev_i32_e32 v3, 31, v2
	v_cvt_pk_bf16_f32 v1, v1, s0
	v_lshl_add_u64 v[2:3], v[2:3], 1, s[0:1]
	global_store_short v[2:3], v1, off
	s_waitcnt vmcnt(15)
	v_lshlrev_b32_e32 v1, 16, v5
	v_max_f32_e32 v1, v1, v1
	v_max_f32_e32 v1, 0x1e3ce508, v1
	v_add_u32_e32 v2, v93, v0
	v_mul_f32_e32 v1, v42, v1
	v_ashrrev_i32_e32 v3, 31, v2
	v_cvt_pk_bf16_f32 v1, v1, s0
	v_lshl_add_u64 v[2:3], v[2:3], 1, s[0:1]
	global_store_short v[2:3], v1, off
	s_waitcnt vmcnt(15)
	v_lshlrev_b32_e32 v1, 16, v6
	v_max_f32_e32 v1, v1, v1
	v_max_f32_e32 v1, 0x1e3ce508, v1
	v_add_u32_e32 v2, v94, v0
	v_mul_f32_e32 v1, v43, v1
	v_ashrrev_i32_e32 v3, 31, v2
	v_cvt_pk_bf16_f32 v1, v1, s0
	v_lshl_add_u64 v[2:3], v[2:3], 1, s[0:1]
	global_store_short v[2:3], v1, off
	s_waitcnt vmcnt(15)
	v_lshlrev_b32_e32 v1, 16, v7
	v_max_f32_e32 v1, v1, v1
	v_max_f32_e32 v1, 0x1e3ce508, v1
	v_add_u32_e32 v2, v95, v0
	v_mul_f32_e32 v1, v44, v1
	v_ashrrev_i32_e32 v3, 31, v2
	v_cvt_pk_bf16_f32 v1, v1, s0
	v_lshl_add_u64 v[2:3], v[2:3], 1, s[0:1]
	global_store_short v[2:3], v1, off
	s_waitcnt vmcnt(15)
	v_lshlrev_b32_e32 v1, 16, v8
	v_max_f32_e32 v1, v1, v1
	v_max_f32_e32 v1, 0x1e3ce508, v1
	v_add_u32_e32 v2, v96, v0
	v_mul_f32_e32 v1, v45, v1
	v_ashrrev_i32_e32 v3, 31, v2
	v_cvt_pk_bf16_f32 v1, v1, s0
	v_lshl_add_u64 v[2:3], v[2:3], 1, s[0:1]
	global_store_short v[2:3], v1, off
	s_waitcnt vmcnt(15)
	v_lshlrev_b32_e32 v1, 16, v9
	v_max_f32_e32 v1, v1, v1
	v_max_f32_e32 v1, 0x1e3ce508, v1
	v_add_u32_e32 v2, v97, v0
	v_mul_f32_e32 v1, v46, v1
	v_ashrrev_i32_e32 v3, 31, v2
	v_cvt_pk_bf16_f32 v1, v1, s0
	v_lshl_add_u64 v[2:3], v[2:3], 1, s[0:1]
	global_store_short v[2:3], v1, off
	s_waitcnt vmcnt(15)
; DI float bf2f(bf16_t v) { return __uint_as_float(((unsigned)v) << 16); }
; DI bf16_t f2bf(float x) { return (bf16_t)(pk_bf16(x, 0.f) & 0xffffu); }
; DI int crow(int r, int h) { return (r & 3) + 8 * (r >> 2) + 4 * h; }
; DI void phase_merge(const Params& p, int g, char* smem, int bid, int nb) {
;     ...
; #pragma unroll
;     for (int mi = 0; mi < 2; ++mi)
; #pragma unroll
;       for (int ni = 0; ni < 2; ++ni)
;       {
;         bf16_t gb16[16];
; #pragma unroll
;         for (int r = 0; r < 16; ++r) gb16[r] = pt[(wm * 64 + mi * 32 + crow(r, h)) * NPROJ + nt * 128 + wn * 64 + ni * 32 + l31 + PGB];
; #pragma unroll
;         for (int r = 0; r < 16; ++r) {
;           const int rl = wm * 64 + mi * 32 + crow(r, h), cl = nt * 128 + wn * 64 + ni * 32 + l31;
;           mgt[rl * 1024 + cl] = f2bf(acc[mi][ni][r] * fmaxf(bf2f(gb16[r]), 1e-20f));
;         }
	v_lshlrev_b32_e32 v1, 16, v10
	v_max_f32_e32 v1, v1, v1
	v_max_f32_e32 v1, 0x1e3ce508, v1
	v_add_u32_e32 v2, v101, v0
	v_mul_f32_e32 v1, v47, v1
	v_ashrrev_i32_e32 v3, 31, v2
	v_cvt_pk_bf16_f32 v1, v1, s0
	v_lshl_add_u64 v[2:3], v[2:3], 1, s[0:1]
	global_store_short v[2:3], v1, off
	v_add_u32_e32 v1, 0x28000, v66
	v_add_u32_e32 v2, v1, v64
	v_ashrrev_i32_e32 v3, 31, v2
	v_lshl_add_u64 v[2:3], v[2:3], 1, s[6:7]
	v_add_co_u32_e32 v2, vcc, s75, v2
	v_add_u32_e32 v67, 0x29400, v66
	s_nop 0
	v_addc_co_u32_e32 v3, vcc, 0, v3, vcc
	global_load_ushort v71, v[2:3], off
	v_add_u32_e32 v4, v67, v64
	v_ashrrev_i32_e32 v5, 31, v4
	v_lshl_add_u64 v[4:5], v[4:5], 1, s[6:7]
	v_add_co_u32_e32 v4, vcc, s75, v4
	v_add_u32_e32 v6, v68, v64
	s_nop 0
	v_addc_co_u32_e32 v5, vcc, 0, v5, vcc
	global_load_ushort v82, v[4:5], off
	v_ashrrev_i32_e32 v7, 31, v6
	v_add_u32_e32 v69, 0x2bc00, v66
	v_lshl_add_u64 v[6:7], v[6:7], 1, s[6:7]
	v_add_u32_e32 v8, v69, v64
	v_ashrrev_i32_e32 v9, 31, v8
	v_add_co_u32_e32 v4, vcc, s75, v6
	v_lshl_add_u64 v[8:9], v[8:9], 1, s[6:7]
	s_nop 0
	v_addc_co_u32_e32 v5, vcc, 0, v7, vcc
	v_add_co_u32_e32 v6, vcc, s75, v8
	v_add_u32_e32 v10, v70, v64
	s_nop 0
	v_addc_co_u32_e32 v7, vcc, 0, v9, vcc
	global_load_ushort v83, v[4:5], off
	global_load_ushort v84, v[6:7], off
	v_ashrrev_i32_e32 v11, 31, v10
	v_lshl_add_u64 v[10:11], v[10:11], 1, s[6:7]
	v_add_u32_e32 v2, v72, v64
	v_ashrrev_i32_e32 v3, 31, v2
	v_add_co_u32_e32 v4, vcc, s75, v10
	v_lshl_add_u64 v[2:3], v[2:3], 1, s[6:7]
	v_add_u32_e32 v12, v73, v64
	v_addc_co_u32_e32 v5, vcc, 0, v11, vcc
	v_ashrrev_i32_e32 v13, 31, v12
	v_add_u32_e32 v74, 0x35c00, v66
	v_add_co_u32_e32 v2, vcc, s75, v2
	v_lshl_add_u64 v[12:13], v[12:13], 1, s[6:7]
	v_add_u32_e32 v14, v74, v64
	v_addc_co_u32_e32 v3, vcc, 0, v3, vcc
	v_ashrrev_i32_e32 v15, 31, v14
	v_add_co_u32_e32 v6, vcc, s75, v12
	v_lshl_add_u64 v[14:15], v[14:15], 1, s[6:7]
	s_nop 0
	v_addc_co_u32_e32 v7, vcc, 0, v13, vcc
	v_add_co_u32_e32 v8, vcc, s75, v14
	v_add_u32_e32 v75, 0x3c000, v66
	s_nop 0
	v_addc_co_u32_e32 v9, vcc, 0, v15, vcc
	global_load_ushort v85, v[4:5], off
	global_load_ushort v86, v[2:3], off
	global_load_ushort v87, v[6:7], off
	global_load_ushort v88, v[8:9], off
	v_add_u32_e32 v32, v75, v64
	v_ashrrev_i32_e32 v33, 31, v32
	v_add_u32_e32 v76, 0x3d400, v66
	v_lshl_add_u64 v[32:33], v[32:33], 1, s[6:7]
	v_add_u32_e32 v34, v76, v64
	v_ashrrev_i32_e32 v35, 31, v34
	v_add_u32_e32 v77, 0x3e800, v66
	v_add_co_u32_e32 v4, vcc, s75, v32
	v_lshl_add_u64 v[34:35], v[34:35], 1, s[6:7]
	v_add_u32_e32 v36, v77, v64
	v_addc_co_u32_e32 v5, vcc, 0, v33, vcc
	v_ashrrev_i32_e32 v37, 31, v36
	v_add_u32_e32 v78, 0x3fc00, v66
	global_load_ushort v89, v[4:5], off
	v_add_co_u32_e32 v4, vcc, s75, v34
	v_lshl_add_u64 v[36:37], v[36:37], 1, s[6:7]
	v_add_u32_e32 v38, v78, v64
	v_addc_co_u32_e32 v5, vcc, 0, v35, vcc
	v_ashrrev_i32_e32 v39, 31, v38
	v_add_u32_e32 v79, 0x46000, v66
	v_add_co_u32_e32 v6, vcc, s75, v36
	v_lshl_add_u64 v[38:39], v[38:39], 1, s[6:7]
	v_add_u32_e32 v40, v79, v64
	v_addc_co_u32_e32 v7, vcc, 0, v37, vcc
	v_ashrrev_i32_e32 v41, 31, v40
	v_add_u32_e32 v80, 0x47400, v66
	v_add_co_u32_e32 v8, vcc, s75, v38
	v_lshl_add_u64 v[40:41], v[40:41], 1, s[6:7]
	v_add_u32_e32 v42, v80, v64
	v_addc_co_u32_e32 v9, vcc, 0, v39, vcc
	v_ashrrev_i32_e32 v43, 31, v42
	v_add_u32_e32 v81, 0x48800, v66
	v_add_co_u32_e32 v10, vcc, s75, v40
	v_lshl_add_u64 v[42:43], v[42:43], 1, s[6:7]
	v_add_u32_e32 v44, v81, v64
	v_addc_co_u32_e32 v11, vcc, 0, v41, vcc
	v_ashrrev_i32_e32 v45, 31, v44
	v_add_u32_e32 v66, 0x49c00, v66
	v_add_co_u32_e32 v12, vcc, s75, v42
	v_lshl_add_u64 v[44:45], v[44:45], 1, s[6:7]
	v_add_u32_e32 v46, v66, v64
	v_addc_co_u32_e32 v13, vcc, 0, v43, vcc
	v_ashrrev_i32_e32 v47, 31, v46
	v_add_co_u32_e32 v14, vcc, s75, v44
	v_lshl_add_u64 v[46:47], v[46:47], 1, s[6:7]
	s_nop 0
	v_addc_co_u32_e32 v15, vcc, 0, v45, vcc
	v_add_co_u32_e32 v32, vcc, s75, v46
	s_waitcnt vmcnt(8)
	v_lshlrev_b32_e32 v2, 16, v71
	v_addc_co_u32_e32 v33, vcc, 0, v47, vcc
	global_load_ushort v4, v[4:5], off
	s_nop 0
	global_load_ushort v5, v[6:7], off
	s_nop 0
	global_load_ushort v6, v[8:9], off
	global_load_ushort v7, v[10:11], off
	s_nop 0
	global_load_ushort v8, v[12:13], off
	global_load_ushort v9, v[14:15], off
	global_load_ushort v10, v[32:33], off
	v_max_f32_e32 v2, v2, v2
	v_max_f32_e32 v2, 0x1e3ce508, v2
	v_mul_f32_e32 v2, v48, v2
	v_add_u32_e32 v71, 0x8000, v65
	v_cvt_pk_bf16_f32 v48, v2, s0
	v_add_u32_e32 v2, v71, v64
	v_ashrrev_i32_e32 v3, 31, v2
	v_lshl_add_u64 v[2:3], v[2:3], 1, s[0:1]
	global_store_short v[2:3], v48, off
	s_waitcnt vmcnt(15)
	v_lshlrev_b32_e32 v2, 16, v82
	v_max_f32_e32 v2, v2, v2
	v_max_f32_e32 v2, 0x1e3ce508, v2
	v_mul_f32_e32 v2, v49, v2
	v_add_u32_e32 v48, 0x8400, v65
	v_cvt_pk_bf16_f32 v11, v2, s0
	v_add_u32_e32 v2, v48, v64
	v_ashrrev_i32_e32 v3, 31, v2
	v_lshl_add_u64 v[2:3], v[2:3], 1, s[0:1]
	global_store_short v[2:3], v11, off
	s_waitcnt vmcnt(15)
	v_lshlrev_b32_e32 v2, 16, v83
	v_max_f32_e32 v2, v2, v2
	v_max_f32_e32 v2, 0x1e3ce508, v2
	v_mul_f32_e32 v2, v50, v2
	v_add_u32_e32 v49, 0x8800, v65
	v_cvt_pk_bf16_f32 v11, v2, s0
	v_add_u32_e32 v2, v49, v64
	v_ashrrev_i32_e32 v3, 31, v2
	v_lshl_add_u64 v[2:3], v[2:3], 1, s[0:1]
	global_store_short v[2:3], v11, off
	s_waitcnt vmcnt(15)
	v_lshlrev_b32_e32 v2, 16, v84
	v_max_f32_e32 v2, v2, v2
	v_max_f32_e32 v2, 0x1e3ce508, v2
	v_mul_f32_e32 v2, v51, v2
	v_add_u32_e32 v50, 0x8c00, v65
	v_cvt_pk_bf16_f32 v11, v2, s0
	v_add_u32_e32 v2, v50, v64
	v_ashrrev_i32_e32 v3, 31, v2
	v_lshl_add_u64 v[2:3], v[2:3], 1, s[0:1]
	global_store_short v[2:3], v11, off
	s_waitcnt vmcnt(15)
; DI float bf2f(bf16_t v) { return __uint_as_float(((unsigned)v) << 16); }
; DI bf16_t f2bf(float x) { return (bf16_t)(pk_bf16(x, 0.f) & 0xffffu); }
; DI int crow(int r, int h) { return (r & 3) + 8 * (r >> 2) + 4 * h; }
; DI void phase_merge(const Params& p, int g, char* smem, int bid, int nb) {
;     ...
; #pragma unroll
;     for (int mi = 0; mi < 2; ++mi)
; #pragma unroll
;       for (int ni = 0; ni < 2; ++ni)
;       {
;         bf16_t gb16[16];
; #pragma unroll
;         for (int r = 0; r < 16; ++r) gb16[r] = pt[(wm * 64 + mi * 32 + crow(r, h)) * NPROJ + nt * 128 + wn * 64 + ni * 32 + l31 + PGB];
; #pragma unroll
;         for (int r = 0; r < 16; ++r) {
;           const int rl = wm * 64 + mi * 32 + crow(r, h), cl = nt * 128 + wn * 64 + ni * 32 + l31;
;           mgt[rl * 1024 + cl] = f2bf(acc[mi][ni][r] * fmaxf(bf2f(gb16[r]), 1e-20f));
;         }
	v_lshlrev_b32_e32 v2, 16, v85
	v_max_f32_e32 v2, v2, v2
	v_max_f32_e32 v2, 0x1e3ce508, v2
	v_mul_f32_e32 v2, v52, v2
	v_add_u32_e32 v51, 0xa000, v65
	v_cvt_pk_bf16_f32 v11, v2, s0
	v_add_u32_e32 v2, v51, v64
	v_ashrrev_i32_e32 v3, 31, v2
	v_lshl_add_u64 v[2:3], v[2:3], 1, s[0:1]
	global_store_short v[2:3], v11, off
	s_waitcnt vmcnt(15)
	v_lshlrev_b32_e32 v2, 16, v86
	v_max_f32_e32 v2, v2, v2
	v_max_f32_e32 v2, 0x1e3ce508, v2
	v_mul_f32_e32 v2, v53, v2
	v_add_u32_e32 v52, 0xa400, v65
	v_cvt_pk_bf16_f32 v11, v2, s0
	v_add_u32_e32 v2, v52, v64
	v_ashrrev_i32_e32 v3, 31, v2
	v_lshl_add_u64 v[2:3], v[2:3], 1, s[0:1]
	global_store_short v[2:3], v11, off
	s_waitcnt vmcnt(15)
	v_lshlrev_b32_e32 v2, 16, v87
	v_max_f32_e32 v2, v2, v2
	v_max_f32_e32 v2, 0x1e3ce508, v2
	v_mul_f32_e32 v2, v54, v2
	v_add_u32_e32 v53, 0xa800, v65
	v_cvt_pk_bf16_f32 v11, v2, s0
	v_add_u32_e32 v2, v53, v64
	v_ashrrev_i32_e32 v3, 31, v2
	v_lshl_add_u64 v[2:3], v[2:3], 1, s[0:1]
	global_store_short v[2:3], v11, off
	s_waitcnt vmcnt(15)
	v_lshlrev_b32_e32 v2, 16, v88
	v_max_f32_e32 v2, v2, v2
	v_max_f32_e32 v2, 0x1e3ce508, v2
	v_mul_f32_e32 v2, v55, v2
	v_add_u32_e32 v54, 0xac00, v65
	v_cvt_pk_bf16_f32 v11, v2, s0
	v_add_u32_e32 v2, v54, v64
	v_ashrrev_i32_e32 v3, 31, v2
	v_lshl_add_u64 v[2:3], v[2:3], 1, s[0:1]
	global_store_short v[2:3], v11, off
	s_waitcnt vmcnt(15)
	v_lshlrev_b32_e32 v2, 16, v89
	v_max_f32_e32 v2, v2, v2
	v_max_f32_e32 v2, 0x1e3ce508, v2
	v_mul_f32_e32 v2, v56, v2
	v_add_u32_e32 v55, 0xc000, v65
	v_cvt_pk_bf16_f32 v11, v2, s0
	v_add_u32_e32 v2, v55, v64
	v_ashrrev_i32_e32 v3, 31, v2
	v_lshl_add_u64 v[2:3], v[2:3], 1, s[0:1]
	global_store_short v[2:3], v11, off
	s_waitcnt vmcnt(15)
	v_lshlrev_b32_e32 v2, 16, v4
	v_max_f32_e32 v2, v2, v2
	v_max_f32_e32 v2, 0x1e3ce508, v2
	v_mul_f32_e32 v2, v57, v2
	v_add_u32_e32 v56, 0xc400, v65
	v_cvt_pk_bf16_f32 v4, v2, s0
	v_add_u32_e32 v2, v56, v64
	v_ashrrev_i32_e32 v3, 31, v2
	v_lshl_add_u64 v[2:3], v[2:3], 1, s[0:1]
	global_store_short v[2:3], v4, off
	s_waitcnt vmcnt(15)
	v_lshlrev_b32_e32 v2, 16, v5
	v_max_f32_e32 v2, v2, v2
	v_max_f32_e32 v2, 0x1e3ce508, v2
	v_mul_f32_e32 v2, v58, v2
	v_add_u32_e32 v57, 0xc800, v65
	v_cvt_pk_bf16_f32 v4, v2, s0
	v_add_u32_e32 v2, v57, v64
	v_ashrrev_i32_e32 v3, 31, v2
	v_lshl_add_u64 v[2:3], v[2:3], 1, s[0:1]
	global_store_short v[2:3], v4, off
	s_waitcnt vmcnt(15)
	v_lshlrev_b32_e32 v2, 16, v6
	v_max_f32_e32 v2, v2, v2
	v_max_f32_e32 v2, 0x1e3ce508, v2
	v_mul_f32_e32 v2, v59, v2
	v_add_u32_e32 v58, 0xcc00, v65
	v_cvt_pk_bf16_f32 v4, v2, s0
	v_add_u32_e32 v2, v58, v64
	v_ashrrev_i32_e32 v3, 31, v2
	v_lshl_add_u64 v[2:3], v[2:3], 1, s[0:1]
	global_store_short v[2:3], v4, off
	s_waitcnt vmcnt(15)
	v_lshlrev_b32_e32 v2, 16, v7
	v_max_f32_e32 v2, v2, v2
	v_max_f32_e32 v2, 0x1e3ce508, v2
	v_mul_f32_e32 v2, v60, v2
	v_add_u32_e32 v59, 0xe000, v65
	v_cvt_pk_bf16_f32 v4, v2, s0
	v_add_u32_e32 v2, v59, v64
	v_ashrrev_i32_e32 v3, 31, v2
	v_lshl_add_u64 v[2:3], v[2:3], 1, s[0:1]
	global_store_short v[2:3], v4, off
	s_waitcnt vmcnt(15)
	v_lshlrev_b32_e32 v2, 16, v8
	v_max_f32_e32 v2, v2, v2
	v_max_f32_e32 v2, 0x1e3ce508, v2
	v_mul_f32_e32 v2, v61, v2
	v_add_u32_e32 v60, 0xe400, v65
	v_cvt_pk_bf16_f32 v4, v2, s0
	v_add_u32_e32 v2, v60, v64
	v_ashrrev_i32_e32 v3, 31, v2
	v_lshl_add_u64 v[2:3], v[2:3], 1, s[0:1]
	global_store_short v[2:3], v4, off
	s_waitcnt vmcnt(15)
	v_lshlrev_b32_e32 v2, 16, v9
	v_max_f32_e32 v2, v2, v2
	v_max_f32_e32 v2, 0x1e3ce508, v2
	v_mul_f32_e32 v2, v62, v2
	v_add_u32_e32 v61, 0xe800, v65
	v_cvt_pk_bf16_f32 v4, v2, s0
	v_add_u32_e32 v2, v61, v64
	v_ashrrev_i32_e32 v3, 31, v2
	v_lshl_add_u64 v[2:3], v[2:3], 1, s[0:1]
	global_store_short v[2:3], v4, off
	s_waitcnt vmcnt(15)
	v_lshlrev_b32_e32 v2, 16, v10
	v_max_f32_e32 v2, v2, v2
	v_max_f32_e32 v2, 0x1e3ce508, v2
	v_mul_f32_e32 v2, v63, v2
	v_add_u32_e32 v62, 0xec00, v65
	v_cvt_pk_bf16_f32 v4, v2, s0
	v_add_u32_e32 v2, v62, v64
	v_ashrrev_i32_e32 v3, 31, v2
	v_lshl_add_u64 v[2:3], v[2:3], 1, s[0:1]
	global_store_short v[2:3], v4, off
	v_add_u32_e32 v2, v1, v0
	v_ashrrev_i32_e32 v3, 31, v2
	v_lshl_add_u64 v[2:3], v[2:3], 1, s[6:7]
	v_add_co_u32_e32 v2, vcc, s75, v2
	v_add_u32_e32 v4, v67, v0
	s_nop 0
	v_addc_co_u32_e32 v3, vcc, 0, v3, vcc
	global_load_ushort v1, v[2:3], off
	v_ashrrev_i32_e32 v5, 31, v4
	v_lshl_add_u64 v[2:3], v[4:5], 1, s[6:7]
	v_add_co_u32_e32 v2, vcc, s75, v2
	v_add_u32_e32 v4, v68, v0
	s_nop 0
	v_addc_co_u32_e32 v3, vcc, 0, v3, vcc
	global_load_ushort v63, v[2:3], off
	v_ashrrev_i32_e32 v5, 31, v4
	v_lshl_add_u64 v[4:5], v[4:5], 1, s[6:7]
	v_add_u32_e32 v6, v69, v0
	v_ashrrev_i32_e32 v7, 31, v6
	v_add_co_u32_e32 v2, vcc, s75, v4
	v_lshl_add_u64 v[6:7], v[6:7], 1, s[6:7]
	s_nop 0
	v_addc_co_u32_e32 v3, vcc, 0, v5, vcc
	v_add_co_u32_e32 v4, vcc, s75, v6
	v_add_u32_e32 v8, v70, v0
	s_nop 0
	v_addc_co_u32_e32 v5, vcc, 0, v7, vcc
	global_load_ushort v64, v[2:3], off
	global_load_ushort v65, v[4:5], off
	v_ashrrev_i32_e32 v9, 31, v8
	v_lshl_add_u64 v[8:9], v[8:9], 1, s[6:7]
	v_add_u32_e32 v10, v72, v0
	v_ashrrev_i32_e32 v11, 31, v10
	v_add_co_u32_e32 v2, vcc, s75, v8
	v_lshl_add_u64 v[10:11], v[10:11], 1, s[6:7]
	v_add_u32_e32 v12, v73, v0
	v_addc_co_u32_e32 v3, vcc, 0, v9, vcc
	v_ashrrev_i32_e32 v13, 31, v12
	v_add_co_u32_e32 v4, vcc, s75, v10
	v_lshl_add_u64 v[12:13], v[12:13], 1, s[6:7]
	v_add_u32_e32 v14, v74, v0
	v_addc_co_u32_e32 v5, vcc, 0, v11, vcc
	v_ashrrev_i32_e32 v15, 31, v14
	v_add_co_u32_e32 v6, vcc, s75, v12
	v_lshl_add_u64 v[14:15], v[14:15], 1, s[6:7]
	s_nop 0
	v_addc_co_u32_e32 v7, vcc, 0, v13, vcc
	v_add_co_u32_e32 v8, vcc, s75, v14
	v_add_u32_e32 v46, v66, v0
	s_nop 0
	v_addc_co_u32_e32 v9, vcc, 0, v15, vcc
	global_load_ushort v66, v[2:3], off
	global_load_ushort v67, v[4:5], off
	global_load_ushort v68, v[6:7], off
	global_load_ushort v69, v[8:9], off
	v_add_u32_e32 v32, v75, v0
	v_ashrrev_i32_e32 v33, 31, v32
	v_lshl_add_u64 v[32:33], v[32:33], 1, s[6:7]
	v_add_u32_e32 v34, v76, v0
	v_ashrrev_i32_e32 v35, 31, v34
	v_add_co_u32_e32 v4, vcc, s75, v32
	v_lshl_add_u64 v[34:35], v[34:35], 1, s[6:7]
	v_add_u32_e32 v36, v77, v0
	v_addc_co_u32_e32 v5, vcc, 0, v33, vcc
	v_ashrrev_i32_e32 v37, 31, v36
	v_lshl_add_u64 v[36:37], v[36:37], 1, s[6:7]
	v_add_u32_e32 v38, v78, v0
	v_ashrrev_i32_e32 v39, 31, v38
	v_lshl_add_u64 v[38:39], v[38:39], 1, s[6:7]
	v_add_u32_e32 v40, v79, v0
	v_ashrrev_i32_e32 v41, 31, v40
	v_lshl_add_u64 v[40:41], v[40:41], 1, s[6:7]
	v_add_u32_e32 v42, v80, v0
	v_ashrrev_i32_e32 v43, 31, v42
	v_lshl_add_u64 v[42:43], v[42:43], 1, s[6:7]
	v_add_u32_e32 v44, v81, v0
	v_ashrrev_i32_e32 v45, 31, v44
	v_lshl_add_u64 v[44:45], v[44:45], 1, s[6:7]
	v_ashrrev_i32_e32 v47, 31, v46
	v_lshl_add_u64 v[46:47], v[46:47], 1, s[6:7]
	s_waitcnt vmcnt(7)
; DI float bf2f(bf16_t v) { return __uint_as_float(((unsigned)v) << 16); }
; DI bf16_t f2bf(float x) { return (bf16_t)(pk_bf16(x, 0.f) & 0xffffu); }
; DI int crow(int r, int h) { return (r & 3) + 8 * (r >> 2) + 4 * h; }
; DI void phase_merge(const Params& p, int g, char* smem, int bid, int nb) {
;     ...
;   while (ts.next(mt, nt)) {
;     ...
; #pragma unroll
;     for (int mi = 0; mi < 2; ++mi)
; #pragma unroll
;       for (int ni = 0; ni < 2; ++ni)
;       {
;         bf16_t gb16[16];
; #pragma unroll
;         for (int r = 0; r < 16; ++r) gb16[r] = pt[(wm * 64 + mi * 32 + crow(r, h)) * NPROJ + nt * 128 + wn * 64 + ni * 32 + l31 + PGB];
; #pragma unroll
;         for (int r = 0; r < 16; ++r) {
;           const int rl = wm * 64 + mi * 32 + crow(r, h), cl = nt * 128 + wn * 64 + ni * 32 + l31;
;           mgt[rl * 1024 + cl] = f2bf(acc[mi][ni][r] * fmaxf(bf2f(gb16[r]), 1e-20f));
;         }
	v_lshlrev_b32_e32 v1, 16, v1
	v_max_f32_e32 v1, v1, v1
	v_max_f32_e32 v1, 0x1e3ce508, v1
	v_mul_f32_e32 v1, v16, v1
	global_load_ushort v16, v[4:5], off
	v_add_co_u32_e32 v4, vcc, s75, v34
	v_add_u32_e32 v2, v71, v0
	s_nop 0
	v_addc_co_u32_e32 v5, vcc, 0, v35, vcc
	v_add_co_u32_e32 v6, vcc, s75, v36
	v_ashrrev_i32_e32 v3, 31, v2
	s_nop 0
	v_addc_co_u32_e32 v7, vcc, 0, v37, vcc
	v_add_co_u32_e32 v8, vcc, s75, v38
	v_cvt_pk_bf16_f32 v1, v1, s0
	s_nop 0
	v_addc_co_u32_e32 v9, vcc, 0, v39, vcc
	v_add_co_u32_e32 v10, vcc, s75, v40
	v_lshl_add_u64 v[2:3], v[2:3], 1, s[0:1]
	s_nop 0
	v_addc_co_u32_e32 v11, vcc, 0, v41, vcc
	v_add_co_u32_e32 v12, vcc, s75, v42
	s_cmp_ge_i32 s13, s15
	s_nop 0
	v_addc_co_u32_e32 v13, vcc, 0, v43, vcc
	v_add_co_u32_e32 v14, vcc, s75, v44
	s_nop 1
	v_addc_co_u32_e32 v15, vcc, 0, v45, vcc
	v_add_co_u32_e32 v32, vcc, s75, v46
	s_nop 1
	v_addc_co_u32_e32 v33, vcc, 0, v47, vcc
	global_load_ushort v4, v[4:5], off
	s_nop 0
	global_load_ushort v5, v[6:7], off
	s_nop 0
	global_load_ushort v6, v[8:9], off
	global_load_ushort v7, v[10:11], off
	s_nop 0
	global_load_ushort v8, v[12:13], off
	global_load_ushort v9, v[14:15], off
	global_load_ushort v10, v[32:33], off
	s_nop 0
	global_store_short v[2:3], v1, off
	s_waitcnt vmcnt(15)
	v_lshlrev_b32_e32 v1, 16, v63
	v_max_f32_e32 v1, v1, v1
	v_max_f32_e32 v1, 0x1e3ce508, v1
	v_add_u32_e32 v2, v48, v0
	v_mul_f32_e32 v1, v17, v1
	v_ashrrev_i32_e32 v3, 31, v2
	v_cvt_pk_bf16_f32 v1, v1, s0
	v_lshl_add_u64 v[2:3], v[2:3], 1, s[0:1]
	global_store_short v[2:3], v1, off
	s_waitcnt vmcnt(15)
	v_lshlrev_b32_e32 v1, 16, v64
	v_max_f32_e32 v1, v1, v1
	v_max_f32_e32 v1, 0x1e3ce508, v1
	v_add_u32_e32 v2, v49, v0
	v_mul_f32_e32 v1, v18, v1
	v_ashrrev_i32_e32 v3, 31, v2
	v_cvt_pk_bf16_f32 v1, v1, s0
	v_lshl_add_u64 v[2:3], v[2:3], 1, s[0:1]
	global_store_short v[2:3], v1, off
	s_waitcnt vmcnt(15)
	v_lshlrev_b32_e32 v1, 16, v65
	v_max_f32_e32 v1, v1, v1
	v_max_f32_e32 v1, 0x1e3ce508, v1
	v_add_u32_e32 v2, v50, v0
	v_mul_f32_e32 v1, v19, v1
	v_ashrrev_i32_e32 v3, 31, v2
	v_cvt_pk_bf16_f32 v1, v1, s0
	v_lshl_add_u64 v[2:3], v[2:3], 1, s[0:1]
	global_store_short v[2:3], v1, off
	s_waitcnt vmcnt(15)
	v_lshlrev_b32_e32 v1, 16, v66
	v_max_f32_e32 v1, v1, v1
	v_max_f32_e32 v1, 0x1e3ce508, v1
	v_add_u32_e32 v2, v51, v0
	v_mul_f32_e32 v1, v20, v1
	v_ashrrev_i32_e32 v3, 31, v2
	v_cvt_pk_bf16_f32 v1, v1, s0
	v_lshl_add_u64 v[2:3], v[2:3], 1, s[0:1]
	global_store_short v[2:3], v1, off
	s_waitcnt vmcnt(15)
	v_lshlrev_b32_e32 v1, 16, v67
	v_max_f32_e32 v1, v1, v1
	v_max_f32_e32 v1, 0x1e3ce508, v1
	v_add_u32_e32 v2, v52, v0
	v_mul_f32_e32 v1, v21, v1
	v_ashrrev_i32_e32 v3, 31, v2
	v_cvt_pk_bf16_f32 v1, v1, s0
	v_lshl_add_u64 v[2:3], v[2:3], 1, s[0:1]
	global_store_short v[2:3], v1, off
	s_waitcnt vmcnt(15)
	v_lshlrev_b32_e32 v1, 16, v68
	v_max_f32_e32 v1, v1, v1
	v_max_f32_e32 v1, 0x1e3ce508, v1
	v_add_u32_e32 v2, v53, v0
	v_mul_f32_e32 v1, v22, v1
	v_ashrrev_i32_e32 v3, 31, v2
	v_cvt_pk_bf16_f32 v1, v1, s0
	v_lshl_add_u64 v[2:3], v[2:3], 1, s[0:1]
	global_store_short v[2:3], v1, off
	s_waitcnt vmcnt(15)
	v_lshlrev_b32_e32 v1, 16, v69
	v_max_f32_e32 v1, v1, v1
	v_max_f32_e32 v1, 0x1e3ce508, v1
	v_add_u32_e32 v2, v54, v0
	v_mul_f32_e32 v1, v23, v1
	v_ashrrev_i32_e32 v3, 31, v2
	v_cvt_pk_bf16_f32 v1, v1, s0
	v_lshl_add_u64 v[2:3], v[2:3], 1, s[0:1]
	global_store_short v[2:3], v1, off
	s_waitcnt vmcnt(15)
	v_lshlrev_b32_e32 v1, 16, v16
	v_max_f32_e32 v1, v1, v1
	v_max_f32_e32 v1, 0x1e3ce508, v1
	v_add_u32_e32 v2, v55, v0
	v_mul_f32_e32 v1, v24, v1
	v_ashrrev_i32_e32 v3, 31, v2
	v_cvt_pk_bf16_f32 v1, v1, s0
	v_lshl_add_u64 v[2:3], v[2:3], 1, s[0:1]
	global_store_short v[2:3], v1, off
	s_waitcnt vmcnt(15)
	v_lshlrev_b32_e32 v1, 16, v4
	v_max_f32_e32 v1, v1, v1
	v_max_f32_e32 v1, 0x1e3ce508, v1
	v_add_u32_e32 v2, v56, v0
	v_mul_f32_e32 v1, v25, v1
	v_ashrrev_i32_e32 v3, 31, v2
	v_cvt_pk_bf16_f32 v1, v1, s0
	v_lshl_add_u64 v[2:3], v[2:3], 1, s[0:1]
	global_store_short v[2:3], v1, off
	s_waitcnt vmcnt(15)
	v_lshlrev_b32_e32 v1, 16, v5
	v_max_f32_e32 v1, v1, v1
	v_max_f32_e32 v1, 0x1e3ce508, v1
	v_add_u32_e32 v2, v57, v0
	v_mul_f32_e32 v1, v26, v1
	v_ashrrev_i32_e32 v3, 31, v2
	v_cvt_pk_bf16_f32 v1, v1, s0
	v_lshl_add_u64 v[2:3], v[2:3], 1, s[0:1]
	global_store_short v[2:3], v1, off
	s_waitcnt vmcnt(15)
	v_lshlrev_b32_e32 v1, 16, v6
	v_max_f32_e32 v1, v1, v1
	v_max_f32_e32 v1, 0x1e3ce508, v1
	v_add_u32_e32 v2, v58, v0
	v_mul_f32_e32 v1, v27, v1
	v_ashrrev_i32_e32 v3, 31, v2
	v_cvt_pk_bf16_f32 v1, v1, s0
	v_lshl_add_u64 v[2:3], v[2:3], 1, s[0:1]
	global_store_short v[2:3], v1, off
	s_waitcnt vmcnt(15)
	v_lshlrev_b32_e32 v1, 16, v7
	v_max_f32_e32 v1, v1, v1
	v_max_f32_e32 v1, 0x1e3ce508, v1
	v_add_u32_e32 v2, v59, v0
	v_mul_f32_e32 v1, v28, v1
	v_ashrrev_i32_e32 v3, 31, v2
	v_cvt_pk_bf16_f32 v1, v1, s0
	v_lshl_add_u64 v[2:3], v[2:3], 1, s[0:1]
	global_store_short v[2:3], v1, off
	s_waitcnt vmcnt(15)
	v_lshlrev_b32_e32 v1, 16, v8
	v_max_f32_e32 v1, v1, v1
	v_max_f32_e32 v1, 0x1e3ce508, v1
	v_add_u32_e32 v2, v60, v0
	v_mul_f32_e32 v1, v29, v1
	v_ashrrev_i32_e32 v3, 31, v2
	v_cvt_pk_bf16_f32 v1, v1, s0
	v_lshl_add_u64 v[2:3], v[2:3], 1, s[0:1]
	global_store_short v[2:3], v1, off
	s_waitcnt vmcnt(15)
	v_lshlrev_b32_e32 v1, 16, v9
	v_max_f32_e32 v1, v1, v1
	v_max_f32_e32 v1, 0x1e3ce508, v1
	v_add_u32_e32 v2, v61, v0
	v_mul_f32_e32 v1, v30, v1
	v_ashrrev_i32_e32 v3, 31, v2
	v_cvt_pk_bf16_f32 v1, v1, s0
	v_lshl_add_u64 v[2:3], v[2:3], 1, s[0:1]
	global_store_short v[2:3], v1, off
	s_waitcnt vmcnt(15)
	v_lshlrev_b32_e32 v1, 16, v10
	v_max_f32_e32 v1, v1, v1
	v_max_f32_e32 v1, 0x1e3ce508, v1
	v_mul_f32_e32 v1, v31, v1
	v_add_u32_e32 v0, v62, v0
	v_cvt_pk_bf16_f32 v2, v1, s0
	v_ashrrev_i32_e32 v1, 31, v0
	v_lshl_add_u64 v[0:1], v[0:1], 1, s[0:1]
	global_store_short v[0:1], v2, off
	s_cbranch_scc1 .LBB0_227

; template <bool SWAP>
; DI void gemm_tile(const bf16_t* __restrict__ A, int lda, const bf16_t* __restrict__ Bt, int ldb, int K, f32x16 (&acc)[2][2], bf16_t* As, bf16_t* Bs_unused) {
;     ...
;   const int tid = TID(), lane = tid & 63, wave = tid >> 6, wm = wave >> 1, wn = wave & 1;
;   const int lr = tid >> 3, lc = (tid & 7) * 8;
;   const bf16_t* ga = A + (size_t)lr * lda + lc;
;   const bf16_t* gb = Bt + (size_t)lr * ldb + lc;
;   u32x4 ra0[4], rb0[4], ra1[4], rb1[4];
;   auto load_stage = [&](u32x4 (&ra)[4], u32x4 (&rb)[4], int t) __attribute__((always_inline)) {
; #pragma unroll
;     for (int i = 0; i < 4; ++i) { ra[i] = *(const u32x4*)(ga + (size_t)(32 * i) * lda + t * 64); rb[i] = *(const u32x4*)(gb + (size_t)(32 * i) * ldb + t * 64); }
;   };
;   auto write_stage = [&](const u32x4 (&ra)[4], const u32x4 (&rb)[4], int buf) __attribute__((always_inline)) {
;     bf16_t* Ad = As + buf * 2 * GT_IMG; bf16_t* Bd = Ad + GT_IMG;
; #pragma unroll
;     for (int i = 0; i < 4; ++i) { *(u32x4*)(Ad + (lr + 32 * i) * 72 + lc) = ra[i]; *(u32x4*)(Bd + (lr + 32 * i) * 72 + lc) = rb[i]; }
;   };
;   const int fr = lane & 31, fk = (lane >> 5) * 8;
;   const int pao = (wm * 64 + fr) * 72 + fk, pbo = GT_IMG + (wn * 64 + fr) * 72 + fk;
;   auto frag_read = [&](bf16x8 (&f)[4], const bf16_t* pa, const bf16_t* pb, int so) __attribute__((always_inline)) {
;     f[0] = *(const bf16x8*)(pa + so); f[1] = *(const bf16x8*)(pb + so); f[2] = *(const bf16x8*)(pb + 32 * 72 + so); f[3] = *(const bf16x8*)(pa + 32 * 72 + so);
;     ...
;   auto step = [&](int buf, u32x4 (&ra)[4], u32x4 (&rb)[4], bool do_write, bool do_load, int tload) __attribute__((always_inline)) {
;     const bf16_t* pa = As + buf * 2 * GT_IMG + pao; const bf16_t* pb = As + buf * 2 * GT_IMG + pbo;
;     bf16_t* Ad = As + (buf ^ 1) * 2 * GT_IMG; bf16_t* Bd = Ad + GT_IMG;
;     bf16x8 F0[4], F1[4];
;     frag_read(F0, pa, pb, 0);
;     __builtin_amdgcn_sched_barrier(0);
;     frag_read(F1, pa, pb, 16);
;     mfma4(F0);
;     __builtin_amdgcn_sched_barrier(0);
;     frag_read(F0, pa, pb, 32);
;     mfma4(F1);
;     if (do_write) {
; #pragma unroll
;       for (int i = 0; i < 4; ++i) *(u32x4*)(Ad + (lr + 32 * i) * 72 + lc) = ra[i];
;     }
;     __builtin_amdgcn_sched_barrier(0);
;     frag_read(F1, pa, pb, 48);
;     mfma4(F0);
;     if (do_write) {
; #pragma unroll
.LBB0_367:
	s_andn2_b64 vcc, exec, s[14:15]
	s_cbranch_vccnz .LBB0_369
	v_mov_b32_e32 v34, v195
	s_nop 0
	v_ashrrev_i32_e32 v32, 3, v34
	v_ashrrev_i32_e32 v33, 31, v32
	v_lshlrev_b64 v[0:1], 11, v[32:33]
	s_waitcnt lgkmcnt(0)
	v_lshlrev_b32_e32 v4, 4, v34
	v_lshl_add_u64 v[2:3], s[0:1], 0, v[0:1]
	v_and_b32_e32 v192, 0x70, v4
	v_lshl_add_u64 v[84:85], v[2:3], 0, v[192:193]
	v_lshl_add_u64 v[0:1], s[6:7], 0, v[0:1]
	v_add_co_u32_e32 v88, vcc, 0x10000, v84
	v_lshl_add_u64 v[86:87], v[0:1], 0, v[192:193]
	s_nop 0
	v_addc_co_u32_e32 v89, vcc, 0, v85, vcc
	v_add_co_u32_e32 v90, vcc, 0x10000, v86
	global_load_dwordx4 v[0:3], v[84:85], off
	global_load_dwordx4 v[4:7], v[86:87], off
	v_addc_co_u32_e32 v91, vcc, 0, v87, vcc
	v_add_co_u32_e32 v92, vcc, 0x20000, v84
	global_load_dwordx4 v[8:11], v[88:89], off
	global_load_dwordx4 v[12:15], v[90:91], off
	v_addc_co_u32_e32 v93, vcc, 0, v85, vcc
	v_add_co_u32_e32 v94, vcc, 0x20000, v86
	global_load_dwordx4 v[16:19], v[92:93], off
	s_nop 0
	v_addc_co_u32_e32 v95, vcc, 0, v87, vcc
	v_add_co_u32_e32 v96, vcc, 0x30000, v84
	global_load_dwordx4 v[20:23], v[94:95], off
	s_nop 0
	v_addc_co_u32_e32 v97, vcc, 0, v85, vcc
	global_load_dwordx4 v[24:27], v[96:97], off
	v_add_co_u32_e32 v98, vcc, 0x30000, v86
	v_mul_lo_u32 v32, v32, s71
	s_nop 0
	v_addc_co_u32_e32 v99, vcc, 0, v87, vcc
	global_load_dwordx4 v[28:31], v[98:99], off
	global_load_dwordx4 v[104:107], v[84:85], off offset:128
	global_load_dwordx4 v[80:83], v[86:87], off offset:128
	global_load_dwordx4 v[108:111], v[88:89], off offset:128
	global_load_dwordx4 v[112:115], v[90:91], off offset:128
	global_load_dwordx4 v[116:119], v[92:93], off offset:128
	global_load_dwordx4 v[124:127], v[94:95], off offset:128
	global_load_dwordx4 v[128:131], v[96:97], off offset:128
	global_load_dwordx4 v[132:135], v[98:99], off offset:128
	v_add3_u32 v100, 32, v32, v192
	s_waitcnt lgkmcnt(0)
	s_barrier
	v_add_u32_e32 v103, 0xd800, v100
	s_waitcnt vmcnt(15)
	ds_write_b128 v100, v[0:3]
	s_waitcnt vmcnt(14)
	ds_write_b128 v100, v[4:7] offset:18432
	s_waitcnt vmcnt(13)
	ds_write_b128 v100, v[8:11] offset:4608
	s_waitcnt vmcnt(12)
	ds_write_b128 v100, v[12:15] offset:23040
	s_waitcnt vmcnt(11)
	ds_write_b128 v100, v[16:19] offset:9216
	s_waitcnt vmcnt(10)
	ds_write_b128 v100, v[20:23] offset:27648
	s_waitcnt vmcnt(9)
	ds_write_b128 v100, v[24:27] offset:13824
	s_waitcnt vmcnt(8)
	ds_write_b128 v100, v[28:31] offset:32256
	global_load_dwordx4 v[136:139], v[84:85], off offset:256
	global_load_dwordx4 v[64:67], v[86:87], off offset:256
	global_load_dwordx4 v[140:143], v[88:89], off offset:256
	global_load_dwordx4 v[68:71], v[90:91], off offset:256
	global_load_dwordx4 v[144:147], v[92:93], off offset:256
	global_load_dwordx4 v[72:75], v[94:95], off offset:256
	global_load_dwordx4 v[148:151], v[96:97], off offset:256
	global_load_dwordx4 v[76:79], v[98:99], off offset:256
	v_lshrrev_b32_e32 v0, 2, v34
	v_lshrrev_b32_e32 v2, 1, v34
	v_and_b32_e32 v3, 31, v34
	v_and_b32_e32 v1, 0x5f, v34
	v_and_b32_e32 v0, 8, v0
	v_and_or_b32 v2, v2, s80, v3
	v_mad_u64_u32 v[2:3], s[8:9], v2, s72, v[0:1]
	v_lshl_add_u32 v101, v2, 1, 32
	v_mad_u32_u24 v0, v1, s72, v0
	s_waitcnt lgkmcnt(0)
	s_barrier
	v_lshl_add_u32 v102, v0, 1, 32
	ds_read_b128 v[0:3], v101
	ds_read_b128 v[4:7], v102 offset:18432
	ds_read_b128 v[16:19], v102 offset:23040
	ds_read_b128 v[20:23], v101 offset:4608
	s_waitcnt lgkmcnt(2)
	v_mfma_f32_32x32x16_bf16 v[48:63], v[0:3], v[4:7], 0
	ds_read_b128 v[152:155], v102 offset:18464
	ds_read_b128 v[156:159], v102 offset:23072
	ds_read_b128 v[160:163], v101 offset:32
	ds_read_b128 v[164:167], v101 offset:4640
	s_waitcnt lgkmcnt(5)
	v_mfma_f32_32x32x16_bf16 v[32:47], v[0:3], v[16:19], 0
	s_waitcnt lgkmcnt(4)
	v_mfma_f32_32x32x16_bf16 v[0:15], v[20:23], v[4:7], 0
	v_mfma_f32_32x32x16_bf16 v[16:31], v[20:23], v[16:19], 0
	s_waitcnt lgkmcnt(1)
	v_mfma_f32_32x32x16_bf16 v[48:63], v[160:163], v[152:155], v[48:63]
	v_mfma_f32_32x32x16_bf16 v[32:47], v[160:163], v[156:159], v[32:47]
	s_waitcnt lgkmcnt(0)
	v_mfma_f32_32x32x16_bf16 v[0:15], v[164:167], v[152:155], v[0:15]
	ds_read_b128 v[152:155], v102 offset:18496
	ds_read_b128 v[160:163], v102 offset:23104
	ds_read_b128 v[168:171], v101 offset:64
	ds_read_b128 v[172:175], v101 offset:4672
	s_waitcnt vmcnt(15)
	ds_write_b128 v100, v[104:107] offset:36864
	s_waitcnt vmcnt(13)
	ds_write_b128 v100, v[108:111] offset:41472
	s_waitcnt vmcnt(11)
	ds_write_b128 v100, v[116:119] offset:46080
	s_waitcnt vmcnt(9)
	ds_write_b128 v100, v[128:131] offset:50688
	v_mfma_f32_32x32x16_bf16 v[16:31], v[164:167], v[156:159], v[16:31]
	s_waitcnt lgkmcnt(5)
	v_mfma_f32_32x32x16_bf16 v[48:63], v[168:171], v[152:155], v[48:63]
	ds_read_b128 v[104:107], v102 offset:18528
	ds_read_b128 v[108:111], v102 offset:23136
	ds_read_b128 v[116:119], v101 offset:96
	ds_read_b128 v[128:131], v101 offset:4704
	ds_write_b128 v100, v[80:83] offset:55296
	ds_write_b128 v100, v[112:115] offset:59904
	ds_write_b128 v100, v[124:127] offset:64512
	s_waitcnt vmcnt(8)
	ds_write_b128 v103, v[132:135] offset:13824
	v_mfma_f32_32x32x16_bf16 v[32:47], v[168:171], v[160:163], v[32:47]
	s_waitcnt lgkmcnt(12)
	v_mfma_f32_32x32x16_bf16 v[0:15], v[172:175], v[152:155], v[0:15]
	v_mfma_f32_32x32x16_bf16 v[16:31], v[172:175], v[160:163], v[16:31]
	s_waitcnt lgkmcnt(0)
	s_barrier
; template <bool SWAP>
; DI void gemm_tile(const bf16_t* __restrict__ A, int lda, const bf16_t* __restrict__ Bt, int ldb, int K, f32x16 (&acc)[2][2], bf16_t* As, bf16_t* Bs_unused) {
;     ...
;   auto step = [&](int buf, u32x4 (&ra)[4], u32x4 (&rb)[4], bool do_write, bool do_load, int tload) __attribute__((always_inline)) {
;     const bf16_t* pa = As + buf * 2 * GT_IMG + pao; const bf16_t* pb = As + buf * 2 * GT_IMG + pbo;
;     bf16_t* Ad = As + (buf ^ 1) * 2 * GT_IMG; bf16_t* Bd = Ad + GT_IMG;
;     bf16x8 F0[4], F1[4];
;     frag_read(F0, pa, pb, 0);
;     __builtin_amdgcn_sched_barrier(0);
;     frag_read(F1, pa, pb, 16);
;     mfma4(F0);
;     __builtin_amdgcn_sched_barrier(0);
;     frag_read(F0, pa, pb, 32);
;     mfma4(F1);
;     if (do_write) {
; #pragma unroll
;       for (int i = 0; i < 4; ++i) *(u32x4*)(Ad + (lr + 32 * i) * 72 + lc) = ra[i];
;     }
;     __builtin_amdgcn_sched_barrier(0);
;     frag_read(F1, pa, pb, 48);
;     mfma4(F0);
;     if (do_write) {
; #pragma unroll
;       for (int i = 0; i < 4; ++i) *(u32x4*)(Bd + (lr + 32 * i) * 72 + lc) = rb[i];
;     }
;     __builtin_amdgcn_sched_barrier(0);
;     mfma4(F1);
;     if (do_load) load_stage(ra, rb, tload);
;     __builtin_amdgcn_sched_barrier(0);
;   };
;   const int nk = K >> 6;
;   load_stage(ra0, rb0, 0); load_stage(ra1, rb1, 1);
;   __syncthreads();
;   write_stage(ra0, rb0, 0);
;   load_stage(ra0, rb0, 2);
;   __syncthreads();
;   for (int kt = 0; kt < nk; kt += 2) {
;     step(0, ra1, rb1, true, kt + 3 < nk, kt + 3);
;     __syncthreads();
;     step(1, ra0, rb0, kt + 2 < nk, kt + 4 < nk, kt + 4);
;     __syncthreads();
	ds_read_b128 v[152:155], v102 offset:55296
	ds_read_b128 v[156:159], v102 offset:59904
	ds_read_b128 v[160:163], v101 offset:36864
	ds_read_b128 v[164:167], v101 offset:41472
	v_mfma_f32_32x32x16_bf16 v[48:63], v[116:119], v[104:107], v[48:63]
	v_mfma_f32_32x32x16_bf16 v[32:47], v[116:119], v[108:111], v[32:47]
	v_mfma_f32_32x32x16_bf16 v[0:15], v[128:131], v[104:107], v[0:15]
	v_mfma_f32_32x32x16_bf16 v[16:31], v[128:131], v[108:111], v[16:31]
	global_load_dwordx4 v[80:83], v[84:85], off offset:384
	global_load_dwordx4 v[104:107], v[86:87], off offset:384
	global_load_dwordx4 v[108:111], v[88:89], off offset:384
	global_load_dwordx4 v[112:115], v[90:91], off offset:384
	global_load_dwordx4 v[116:119], v[92:93], off offset:384
	global_load_dwordx4 v[124:127], v[94:95], off offset:384
	global_load_dwordx4 v[128:131], v[96:97], off offset:384
	global_load_dwordx4 v[132:135], v[98:99], off offset:384
	s_waitcnt lgkmcnt(1)
	v_mfma_f32_32x32x16_bf16 v[48:63], v[160:163], v[152:155], v[48:63]
	v_mfma_f32_32x32x16_bf16 v[32:47], v[160:163], v[156:159], v[32:47]
	s_waitcnt lgkmcnt(0)
	v_mfma_f32_32x32x16_bf16 v[0:15], v[164:167], v[152:155], v[0:15]
	ds_read_b128 v[152:155], v102 offset:55328
	ds_read_b128 v[160:163], v102 offset:59936
	ds_read_b128 v[168:171], v101 offset:36896
	ds_read_b128 v[172:175], v101 offset:41504
	v_mfma_f32_32x32x16_bf16 v[16:31], v[164:167], v[156:159], v[16:31]
	s_waitcnt lgkmcnt(1)
	v_mfma_f32_32x32x16_bf16 v[48:63], v[168:171], v[152:155], v[48:63]
	v_mfma_f32_32x32x16_bf16 v[32:47], v[168:171], v[160:163], v[32:47]
	s_waitcnt lgkmcnt(0)
	v_mfma_f32_32x32x16_bf16 v[0:15], v[172:175], v[152:155], v[0:15]
	ds_read_b128 v[152:155], v102 offset:55360
	ds_read_b128 v[156:159], v102 offset:59968
	ds_read_b128 v[164:167], v101 offset:36928
	ds_read_b128 v[168:171], v101 offset:41536
	s_waitcnt vmcnt(15)
	ds_write_b128 v100, v[136:139]
	s_waitcnt vmcnt(13)
	ds_write_b128 v100, v[140:143] offset:4608
	s_waitcnt vmcnt(11)
	ds_write_b128 v100, v[144:147] offset:9216
	s_waitcnt vmcnt(9)
	ds_write_b128 v100, v[148:151] offset:13824
	v_mfma_f32_32x32x16_bf16 v[16:31], v[172:175], v[160:163], v[16:31]
	s_waitcnt lgkmcnt(5)
	v_mfma_f32_32x32x16_bf16 v[48:63], v[164:167], v[152:155], v[48:63]
	ds_read_b128 v[136:139], v102 offset:55392
	ds_read_b128 v[140:143], v102 offset:60000
	ds_read_b128 v[144:147], v101 offset:36960
	ds_read_b128 v[148:151], v101 offset:41568
	ds_write_b128 v100, v[64:67] offset:18432
	ds_write_b128 v100, v[68:71] offset:23040
	ds_write_b128 v100, v[72:75] offset:27648
	s_waitcnt vmcnt(8)
	ds_write_b128 v100, v[76:79] offset:32256
	v_mfma_f32_32x32x16_bf16 v[32:47], v[164:167], v[156:159], v[32:47]
	s_waitcnt lgkmcnt(12)
	v_mfma_f32_32x32x16_bf16 v[0:15], v[168:171], v[152:155], v[0:15]
	v_mfma_f32_32x32x16_bf16 v[16:31], v[168:171], v[156:159], v[16:31]
	s_waitcnt lgkmcnt(0)
	s_barrier
	ds_read_b128 v[152:155], v102 offset:18432
	ds_read_b128 v[156:159], v102 offset:23040
	ds_read_b128 v[160:163], v101
	ds_read_b128 v[164:167], v101 offset:4608
	v_mfma_f32_32x32x16_bf16 v[48:63], v[144:147], v[136:139], v[48:63]
	v_mfma_f32_32x32x16_bf16 v[32:47], v[144:147], v[140:143], v[32:47]
	v_mfma_f32_32x32x16_bf16 v[0:15], v[148:151], v[136:139], v[0:15]
	v_mfma_f32_32x32x16_bf16 v[16:31], v[148:151], v[140:143], v[16:31]
	global_load_dwordx4 v[64:67], v[84:85], off offset:512
	global_load_dwordx4 v[68:71], v[86:87], off offset:512
	global_load_dwordx4 v[72:75], v[88:89], off offset:512
	global_load_dwordx4 v[76:79], v[90:91], off offset:512
	global_load_dwordx4 v[136:139], v[92:93], off offset:512
	global_load_dwordx4 v[140:143], v[94:95], off offset:512
	global_load_dwordx4 v[144:147], v[96:97], off offset:512
	global_load_dwordx4 v[148:151], v[98:99], off offset:512
	s_waitcnt lgkmcnt(1)
	v_mfma_f32_32x32x16_bf16 v[48:63], v[160:163], v[152:155], v[48:63]
	v_mfma_f32_32x32x16_bf16 v[32:47], v[160:163], v[156:159], v[32:47]
	s_waitcnt lgkmcnt(0)
	v_mfma_f32_32x32x16_bf16 v[0:15], v[164:167], v[152:155], v[0:15]
	ds_read_b128 v[152:155], v102 offset:18464
	ds_read_b128 v[160:163], v102 offset:23072
	ds_read_b128 v[168:171], v101 offset:32
	ds_read_b128 v[172:175], v101 offset:4640
	v_mfma_f32_32x32x16_bf16 v[16:31], v[164:167], v[156:159], v[16:31]
	s_waitcnt lgkmcnt(1)
	v_mfma_f32_32x32x16_bf16 v[48:63], v[168:171], v[152:155], v[48:63]
	v_mfma_f32_32x32x16_bf16 v[32:47], v[168:171], v[160:163], v[32:47]
	s_waitcnt lgkmcnt(0)
	v_mfma_f32_32x32x16_bf16 v[0:15], v[172:175], v[152:155], v[0:15]
	ds_read_b128 v[152:155], v102 offset:18496
	ds_read_b128 v[156:159], v102 offset:23104
	ds_read_b128 v[164:167], v101 offset:64
	ds_read_b128 v[168:171], v101 offset:4672
	s_waitcnt vmcnt(15)
	ds_write_b128 v100, v[80:83] offset:36864
	s_waitcnt vmcnt(13)
	ds_write_b128 v100, v[108:111] offset:41472
	s_waitcnt vmcnt(11)
	ds_write_b128 v100, v[116:119] offset:46080
	s_waitcnt vmcnt(9)
	ds_write_b128 v100, v[128:131] offset:50688
	v_mfma_f32_32x32x16_bf16 v[16:31], v[172:175], v[160:163], v[16:31]
	s_waitcnt lgkmcnt(5)
	v_mfma_f32_32x32x16_bf16 v[48:63], v[164:167], v[152:155], v[48:63]
	ds_read_b128 v[80:83], v102 offset:18528
	ds_read_b128 v[108:111], v102 offset:23136
	ds_read_b128 v[116:119], v101 offset:96
	ds_read_b128 v[128:131], v101 offset:4704
	ds_write_b128 v100, v[104:107] offset:55296
	ds_write_b128 v100, v[112:115] offset:59904
	ds_write_b128 v100, v[124:127] offset:64512
	s_waitcnt vmcnt(8)
	ds_write_b128 v103, v[132:135] offset:13824
	v_mfma_f32_32x32x16_bf16 v[32:47], v[164:167], v[156:159], v[32:47]
	s_waitcnt lgkmcnt(12)
	v_mfma_f32_32x32x16_bf16 v[0:15], v[168:171], v[152:155], v[0:15]
	v_mfma_f32_32x32x16_bf16 v[16:31], v[168:171], v[156:159], v[16:31]
	s_waitcnt lgkmcnt(0)
	s_barrier
; template <bool SWAP>
; DI void gemm_tile(const bf16_t* __restrict__ A, int lda, const bf16_t* __restrict__ Bt, int ldb, int K, f32x16 (&acc)[2][2], bf16_t* As, bf16_t* Bs_unused) {
;     ...
;   auto step = [&](int buf, u32x4 (&ra)[4], u32x4 (&rb)[4], bool do_write, bool do_load, int tload) __attribute__((always_inline)) {
;     const bf16_t* pa = As + buf * 2 * GT_IMG + pao; const bf16_t* pb = As + buf * 2 * GT_IMG + pbo;
;     bf16_t* Ad = As + (buf ^ 1) * 2 * GT_IMG; bf16_t* Bd = Ad + GT_IMG;
;     bf16x8 F0[4], F1[4];
;     frag_read(F0, pa, pb, 0);
;     __builtin_amdgcn_sched_barrier(0);
;     frag_read(F1, pa, pb, 16);
;     mfma4(F0);
;     __builtin_amdgcn_sched_barrier(0);
;     frag_read(F0, pa, pb, 32);
;     mfma4(F1);
;     if (do_write) {
; #pragma unroll
;       for (int i = 0; i < 4; ++i) *(u32x4*)(Ad + (lr + 32 * i) * 72 + lc) = ra[i];
;     }
;     __builtin_amdgcn_sched_barrier(0);
;     frag_read(F1, pa, pb, 48);
;     mfma4(F0);
;     if (do_write) {
; #pragma unroll
;       for (int i = 0; i < 4; ++i) *(u32x4*)(Bd + (lr + 32 * i) * 72 + lc) = rb[i];
;     }
;     __builtin_amdgcn_sched_barrier(0);
;     mfma4(F1);
;     if (do_load) load_stage(ra, rb, tload);
;     __builtin_amdgcn_sched_barrier(0);
;   };
;   const int nk = K >> 6;
;   load_stage(ra0, rb0, 0); load_stage(ra1, rb1, 1);
;   __syncthreads();
;   write_stage(ra0, rb0, 0);
;   load_stage(ra0, rb0, 2);
;   __syncthreads();
;   for (int kt = 0; kt < nk; kt += 2) {
;     step(0, ra1, rb1, true, kt + 3 < nk, kt + 3);
;     __syncthreads();
;     step(1, ra0, rb0, kt + 2 < nk, kt + 4 < nk, kt + 4);
;     __syncthreads();
	ds_read_b128 v[152:155], v102 offset:55296
	ds_read_b128 v[156:159], v102 offset:59904
	ds_read_b128 v[160:163], v101 offset:36864
	ds_read_b128 v[164:167], v101 offset:41472
	v_mfma_f32_32x32x16_bf16 v[48:63], v[116:119], v[80:83], v[48:63]
	v_mfma_f32_32x32x16_bf16 v[32:47], v[116:119], v[108:111], v[32:47]
	v_mfma_f32_32x32x16_bf16 v[0:15], v[128:131], v[80:83], v[0:15]
	v_mfma_f32_32x32x16_bf16 v[16:31], v[128:131], v[108:111], v[16:31]
	global_load_dwordx4 v[80:83], v[84:85], off offset:640
	global_load_dwordx4 v[104:107], v[86:87], off offset:640
	global_load_dwordx4 v[108:111], v[88:89], off offset:640
	global_load_dwordx4 v[112:115], v[90:91], off offset:640
	global_load_dwordx4 v[116:119], v[92:93], off offset:640
	global_load_dwordx4 v[124:127], v[94:95], off offset:640
	global_load_dwordx4 v[128:131], v[96:97], off offset:640
	global_load_dwordx4 v[132:135], v[98:99], off offset:640
	s_waitcnt lgkmcnt(1)
	v_mfma_f32_32x32x16_bf16 v[48:63], v[160:163], v[152:155], v[48:63]
	v_mfma_f32_32x32x16_bf16 v[32:47], v[160:163], v[156:159], v[32:47]
	s_waitcnt lgkmcnt(0)
	v_mfma_f32_32x32x16_bf16 v[0:15], v[164:167], v[152:155], v[0:15]
	ds_read_b128 v[152:155], v102 offset:55328
	ds_read_b128 v[160:163], v102 offset:59936
	ds_read_b128 v[168:171], v101 offset:36896
	ds_read_b128 v[172:175], v101 offset:41504
	v_mfma_f32_32x32x16_bf16 v[16:31], v[164:167], v[156:159], v[16:31]
	s_waitcnt lgkmcnt(1)
	v_mfma_f32_32x32x16_bf16 v[48:63], v[168:171], v[152:155], v[48:63]
	v_mfma_f32_32x32x16_bf16 v[32:47], v[168:171], v[160:163], v[32:47]
	s_waitcnt lgkmcnt(0)
	v_mfma_f32_32x32x16_bf16 v[0:15], v[172:175], v[152:155], v[0:15]
	ds_read_b128 v[152:155], v102 offset:55360
	ds_read_b128 v[156:159], v102 offset:59968
	ds_read_b128 v[164:167], v101 offset:36928
	ds_read_b128 v[168:171], v101 offset:41536
	s_waitcnt vmcnt(15)
	ds_write_b128 v100, v[64:67]
	s_waitcnt vmcnt(13)
	ds_write_b128 v100, v[72:75] offset:4608
	s_waitcnt vmcnt(11)
	ds_write_b128 v100, v[136:139] offset:9216
	s_waitcnt vmcnt(9)
	ds_write_b128 v100, v[144:147] offset:13824
	v_mfma_f32_32x32x16_bf16 v[16:31], v[172:175], v[160:163], v[16:31]
	s_waitcnt lgkmcnt(5)
	v_mfma_f32_32x32x16_bf16 v[48:63], v[164:167], v[152:155], v[48:63]
	ds_read_b128 v[64:67], v102 offset:55392
	ds_read_b128 v[72:75], v102 offset:60000
	ds_read_b128 v[136:139], v101 offset:36960
	ds_read_b128 v[144:147], v101 offset:41568
	ds_write_b128 v100, v[68:71] offset:18432
	ds_write_b128 v100, v[76:79] offset:23040
	ds_write_b128 v100, v[140:143] offset:27648
	s_waitcnt vmcnt(8)
	ds_write_b128 v100, v[148:151] offset:32256
	v_mfma_f32_32x32x16_bf16 v[32:47], v[164:167], v[156:159], v[32:47]
	s_waitcnt lgkmcnt(12)
	v_mfma_f32_32x32x16_bf16 v[0:15], v[168:171], v[152:155], v[0:15]
	v_mfma_f32_32x32x16_bf16 v[16:31], v[168:171], v[156:159], v[16:31]
	s_waitcnt lgkmcnt(0)
	s_barrier
	ds_read_b128 v[152:155], v102 offset:18432
	ds_read_b128 v[156:159], v102 offset:23040
	ds_read_b128 v[160:163], v101
	ds_read_b128 v[164:167], v101 offset:4608
	v_mfma_f32_32x32x16_bf16 v[48:63], v[136:139], v[64:67], v[48:63]
	v_mfma_f32_32x32x16_bf16 v[32:47], v[136:139], v[72:75], v[32:47]
	v_mfma_f32_32x32x16_bf16 v[0:15], v[144:147], v[64:67], v[0:15]
	v_mfma_f32_32x32x16_bf16 v[16:31], v[144:147], v[72:75], v[16:31]
	global_load_dwordx4 v[64:67], v[84:85], off offset:768
	global_load_dwordx4 v[68:71], v[86:87], off offset:768
	global_load_dwordx4 v[72:75], v[88:89], off offset:768
	global_load_dwordx4 v[76:79], v[90:91], off offset:768
	global_load_dwordx4 v[136:139], v[92:93], off offset:768
	global_load_dwordx4 v[140:143], v[94:95], off offset:768
	global_load_dwordx4 v[144:147], v[96:97], off offset:768
	global_load_dwordx4 v[148:151], v[98:99], off offset:768
	s_waitcnt lgkmcnt(1)
	v_mfma_f32_32x32x16_bf16 v[48:63], v[160:163], v[152:155], v[48:63]
	v_mfma_f32_32x32x16_bf16 v[32:47], v[160:163], v[156:159], v[32:47]
	s_waitcnt lgkmcnt(0)
	v_mfma_f32_32x32x16_bf16 v[0:15], v[164:167], v[152:155], v[0:15]
	ds_read_b128 v[152:155], v102 offset:18464
	ds_read_b128 v[160:163], v102 offset:23072
	ds_read_b128 v[168:171], v101 offset:32
	ds_read_b128 v[172:175], v101 offset:4640
	v_mfma_f32_32x32x16_bf16 v[16:31], v[164:167], v[156:159], v[16:31]
	s_waitcnt lgkmcnt(1)
	v_mfma_f32_32x32x16_bf16 v[48:63], v[168:171], v[152:155], v[48:63]
	v_mfma_f32_32x32x16_bf16 v[32:47], v[168:171], v[160:163], v[32:47]
	s_waitcnt lgkmcnt(0)
	v_mfma_f32_32x32x16_bf16 v[0:15], v[172:175], v[152:155], v[0:15]
	ds_read_b128 v[152:155], v102 offset:18496
	ds_read_b128 v[156:159], v102 offset:23104
	ds_read_b128 v[164:167], v101 offset:64
	ds_read_b128 v[168:171], v101 offset:4672
	s_waitcnt vmcnt(15)
	ds_write_b128 v100, v[80:83] offset:36864
	s_waitcnt vmcnt(13)
	ds_write_b128 v100, v[108:111] offset:41472
	s_waitcnt vmcnt(11)
	ds_write_b128 v100, v[116:119] offset:46080
	s_waitcnt vmcnt(9)
	ds_write_b128 v100, v[128:131] offset:50688
	v_mfma_f32_32x32x16_bf16 v[16:31], v[172:175], v[160:163], v[16:31]
	s_waitcnt lgkmcnt(5)
	v_mfma_f32_32x32x16_bf16 v[48:63], v[164:167], v[152:155], v[48:63]
	ds_read_b128 v[80:83], v102 offset:18528
	ds_read_b128 v[108:111], v102 offset:23136
	ds_read_b128 v[116:119], v101 offset:96
	ds_read_b128 v[128:131], v101 offset:4704
	ds_write_b128 v100, v[104:107] offset:55296
	ds_write_b128 v100, v[112:115] offset:59904
	ds_write_b128 v100, v[124:127] offset:64512
	s_waitcnt vmcnt(8)
	ds_write_b128 v103, v[132:135] offset:13824
	v_mfma_f32_32x32x16_bf16 v[32:47], v[164:167], v[156:159], v[32:47]
	s_waitcnt lgkmcnt(12)
	v_mfma_f32_32x32x16_bf16 v[0:15], v[168:171], v[152:155], v[0:15]
	v_mfma_f32_32x32x16_bf16 v[16:31], v[168:171], v[156:159], v[16:31]
	s_waitcnt lgkmcnt(0)
	s_barrier
; template <bool SWAP>
; DI void gemm_tile(const bf16_t* __restrict__ A, int lda, const bf16_t* __restrict__ Bt, int ldb, int K, f32x16 (&acc)[2][2], bf16_t* As, bf16_t* Bs_unused) {
;     ...
;   auto step = [&](int buf, u32x4 (&ra)[4], u32x4 (&rb)[4], bool do_write, bool do_load, int tload) __attribute__((always_inline)) {
;     const bf16_t* pa = As + buf * 2 * GT_IMG + pao; const bf16_t* pb = As + buf * 2 * GT_IMG + pbo;
;     bf16_t* Ad = As + (buf ^ 1) * 2 * GT_IMG; bf16_t* Bd = Ad + GT_IMG;
;     bf16x8 F0[4], F1[4];
;     frag_read(F0, pa, pb, 0);
;     __builtin_amdgcn_sched_barrier(0);
;     frag_read(F1, pa, pb, 16);
;     mfma4(F0);
;     __builtin_amdgcn_sched_barrier(0);
;     frag_read(F0, pa, pb, 32);
;     mfma4(F1);
;     if (do_write) {
; #pragma unroll
;       for (int i = 0; i < 4; ++i) *(u32x4*)(Ad + (lr + 32 * i) * 72 + lc) = ra[i];
;     }
;     __builtin_amdgcn_sched_barrier(0);
;     frag_read(F1, pa, pb, 48);
;     mfma4(F0);
;     if (do_write) {
; #pragma unroll
;       for (int i = 0; i < 4; ++i) *(u32x4*)(Bd + (lr + 32 * i) * 72 + lc) = rb[i];
;     }
;     __builtin_amdgcn_sched_barrier(0);
;     mfma4(F1);
;     if (do_load) load_stage(ra, rb, tload);
;     __builtin_amdgcn_sched_barrier(0);
;   };
;   const int nk = K >> 6;
;   load_stage(ra0, rb0, 0); load_stage(ra1, rb1, 1);
;   __syncthreads();
;   write_stage(ra0, rb0, 0);
;   load_stage(ra0, rb0, 2);
;   __syncthreads();
;   for (int kt = 0; kt < nk; kt += 2) {
;     step(0, ra1, rb1, true, kt + 3 < nk, kt + 3);
;     __syncthreads();
;     step(1, ra0, rb0, kt + 2 < nk, kt + 4 < nk, kt + 4);
;     __syncthreads();
	ds_read_b128 v[152:155], v102 offset:55296
	ds_read_b128 v[156:159], v102 offset:59904
	ds_read_b128 v[160:163], v101 offset:36864
	ds_read_b128 v[164:167], v101 offset:41472
	v_mfma_f32_32x32x16_bf16 v[48:63], v[116:119], v[80:83], v[48:63]
	v_mfma_f32_32x32x16_bf16 v[32:47], v[116:119], v[108:111], v[32:47]
	v_mfma_f32_32x32x16_bf16 v[0:15], v[128:131], v[80:83], v[0:15]
	v_mfma_f32_32x32x16_bf16 v[16:31], v[128:131], v[108:111], v[16:31]
	global_load_dwordx4 v[80:83], v[84:85], off offset:896
	global_load_dwordx4 v[104:107], v[86:87], off offset:896
	global_load_dwordx4 v[108:111], v[88:89], off offset:896
	global_load_dwordx4 v[112:115], v[90:91], off offset:896
	global_load_dwordx4 v[116:119], v[92:93], off offset:896
	global_load_dwordx4 v[124:127], v[94:95], off offset:896
	global_load_dwordx4 v[128:131], v[96:97], off offset:896
	global_load_dwordx4 v[132:135], v[98:99], off offset:896
	s_waitcnt lgkmcnt(1)
	v_mfma_f32_32x32x16_bf16 v[48:63], v[160:163], v[152:155], v[48:63]
	v_mfma_f32_32x32x16_bf16 v[32:47], v[160:163], v[156:159], v[32:47]
	s_waitcnt lgkmcnt(0)
	v_mfma_f32_32x32x16_bf16 v[0:15], v[164:167], v[152:155], v[0:15]
	ds_read_b128 v[152:155], v102 offset:55328
	ds_read_b128 v[160:163], v102 offset:59936
	ds_read_b128 v[168:171], v101 offset:36896
	ds_read_b128 v[172:175], v101 offset:41504
	v_mfma_f32_32x32x16_bf16 v[16:31], v[164:167], v[156:159], v[16:31]
	s_waitcnt lgkmcnt(1)
	v_mfma_f32_32x32x16_bf16 v[48:63], v[168:171], v[152:155], v[48:63]
	v_mfma_f32_32x32x16_bf16 v[32:47], v[168:171], v[160:163], v[32:47]
	s_waitcnt lgkmcnt(0)
	v_mfma_f32_32x32x16_bf16 v[0:15], v[172:175], v[152:155], v[0:15]
	ds_read_b128 v[152:155], v102 offset:55360
	ds_read_b128 v[156:159], v102 offset:59968
	ds_read_b128 v[164:167], v101 offset:36928
	ds_read_b128 v[168:171], v101 offset:41536
	s_waitcnt vmcnt(15)
	ds_write_b128 v100, v[64:67]
	s_waitcnt vmcnt(13)
	ds_write_b128 v100, v[72:75] offset:4608
	s_waitcnt vmcnt(11)
	ds_write_b128 v100, v[136:139] offset:9216
	s_waitcnt vmcnt(9)
	ds_write_b128 v100, v[144:147] offset:13824
	v_mfma_f32_32x32x16_bf16 v[16:31], v[172:175], v[160:163], v[16:31]
	s_waitcnt lgkmcnt(5)
	v_mfma_f32_32x32x16_bf16 v[48:63], v[164:167], v[152:155], v[48:63]
	ds_read_b128 v[64:67], v102 offset:55392
	ds_read_b128 v[72:75], v102 offset:60000
	ds_read_b128 v[136:139], v101 offset:36960
	ds_read_b128 v[144:147], v101 offset:41568
	ds_write_b128 v100, v[68:71] offset:18432
	ds_write_b128 v100, v[76:79] offset:23040
	ds_write_b128 v100, v[140:143] offset:27648
	s_waitcnt vmcnt(8)
	ds_write_b128 v100, v[148:151] offset:32256
	v_mfma_f32_32x32x16_bf16 v[32:47], v[164:167], v[156:159], v[32:47]
	s_waitcnt lgkmcnt(12)
	v_mfma_f32_32x32x16_bf16 v[0:15], v[168:171], v[152:155], v[0:15]
	v_mfma_f32_32x32x16_bf16 v[16:31], v[168:171], v[156:159], v[16:31]
	s_waitcnt lgkmcnt(0)
	s_barrier
	ds_read_b128 v[152:155], v102 offset:18432
	ds_read_b128 v[156:159], v102 offset:23040
	ds_read_b128 v[160:163], v101
	ds_read_b128 v[164:167], v101 offset:4608
	v_mfma_f32_32x32x16_bf16 v[48:63], v[136:139], v[64:67], v[48:63]
	v_mfma_f32_32x32x16_bf16 v[32:47], v[136:139], v[72:75], v[32:47]
	v_mfma_f32_32x32x16_bf16 v[0:15], v[144:147], v[64:67], v[0:15]
	v_mfma_f32_32x32x16_bf16 v[16:31], v[144:147], v[72:75], v[16:31]
	global_load_dwordx4 v[64:67], v[84:85], off offset:1024
	global_load_dwordx4 v[68:71], v[86:87], off offset:1024
	global_load_dwordx4 v[72:75], v[88:89], off offset:1024
	global_load_dwordx4 v[76:79], v[90:91], off offset:1024
	global_load_dwordx4 v[136:139], v[92:93], off offset:1024
	global_load_dwordx4 v[140:143], v[94:95], off offset:1024
	global_load_dwordx4 v[144:147], v[96:97], off offset:1024
	global_load_dwordx4 v[148:151], v[98:99], off offset:1024
	s_waitcnt lgkmcnt(1)
	v_mfma_f32_32x32x16_bf16 v[48:63], v[160:163], v[152:155], v[48:63]
	v_mfma_f32_32x32x16_bf16 v[32:47], v[160:163], v[156:159], v[32:47]
	s_waitcnt lgkmcnt(0)
	v_mfma_f32_32x32x16_bf16 v[0:15], v[164:167], v[152:155], v[0:15]
	ds_read_b128 v[152:155], v102 offset:18464
	ds_read_b128 v[160:163], v102 offset:23072
	ds_read_b128 v[168:171], v101 offset:32
	ds_read_b128 v[172:175], v101 offset:4640
	v_mfma_f32_32x32x16_bf16 v[16:31], v[164:167], v[156:159], v[16:31]
	s_waitcnt lgkmcnt(1)
	v_mfma_f32_32x32x16_bf16 v[48:63], v[168:171], v[152:155], v[48:63]
	v_mfma_f32_32x32x16_bf16 v[32:47], v[168:171], v[160:163], v[32:47]
	s_waitcnt lgkmcnt(0)
	v_mfma_f32_32x32x16_bf16 v[0:15], v[172:175], v[152:155], v[0:15]
	ds_read_b128 v[152:155], v102 offset:18496
	ds_read_b128 v[156:159], v102 offset:23104
	ds_read_b128 v[164:167], v101 offset:64
	ds_read_b128 v[168:171], v101 offset:4672
	s_waitcnt vmcnt(15)
	ds_write_b128 v100, v[80:83] offset:36864
	s_waitcnt vmcnt(13)
	ds_write_b128 v100, v[108:111] offset:41472
	s_waitcnt vmcnt(11)
	ds_write_b128 v100, v[116:119] offset:46080
	s_waitcnt vmcnt(9)
	ds_write_b128 v100, v[128:131] offset:50688
	v_mfma_f32_32x32x16_bf16 v[16:31], v[172:175], v[160:163], v[16:31]
	s_waitcnt lgkmcnt(5)
	v_mfma_f32_32x32x16_bf16 v[48:63], v[164:167], v[152:155], v[48:63]
	ds_read_b128 v[80:83], v102 offset:18528
	ds_read_b128 v[108:111], v102 offset:23136
	ds_read_b128 v[116:119], v101 offset:96
	ds_read_b128 v[128:131], v101 offset:4704
	ds_write_b128 v100, v[104:107] offset:55296
	ds_write_b128 v100, v[112:115] offset:59904
	ds_write_b128 v100, v[124:127] offset:64512
	s_waitcnt vmcnt(8)
	ds_write_b128 v103, v[132:135] offset:13824
	v_mfma_f32_32x32x16_bf16 v[32:47], v[164:167], v[156:159], v[32:47]
	s_waitcnt lgkmcnt(12)
	v_mfma_f32_32x32x16_bf16 v[0:15], v[168:171], v[152:155], v[0:15]
	v_mfma_f32_32x32x16_bf16 v[16:31], v[168:171], v[156:159], v[16:31]
	s_waitcnt lgkmcnt(0)
	s_barrier
; template <bool SWAP>
; DI void gemm_tile(const bf16_t* __restrict__ A, int lda, const bf16_t* __restrict__ Bt, int ldb, int K, f32x16 (&acc)[2][2], bf16_t* As, bf16_t* Bs_unused) {
;     ...
;   auto step = [&](int buf, u32x4 (&ra)[4], u32x4 (&rb)[4], bool do_write, bool do_load, int tload) __attribute__((always_inline)) {
;     const bf16_t* pa = As + buf * 2 * GT_IMG + pao; const bf16_t* pb = As + buf * 2 * GT_IMG + pbo;
;     bf16_t* Ad = As + (buf ^ 1) * 2 * GT_IMG; bf16_t* Bd = Ad + GT_IMG;
;     bf16x8 F0[4], F1[4];
;     frag_read(F0, pa, pb, 0);
;     __builtin_amdgcn_sched_barrier(0);
;     frag_read(F1, pa, pb, 16);
;     mfma4(F0);
;     __builtin_amdgcn_sched_barrier(0);
;     frag_read(F0, pa, pb, 32);
;     mfma4(F1);
;     if (do_write) {
; #pragma unroll
;       for (int i = 0; i < 4; ++i) *(u32x4*)(Ad + (lr + 32 * i) * 72 + lc) = ra[i];
;     }
;     __builtin_amdgcn_sched_barrier(0);
;     frag_read(F1, pa, pb, 48);
;     mfma4(F0);
;     if (do_write) {
; #pragma unroll
;       for (int i = 0; i < 4; ++i) *(u32x4*)(Bd + (lr + 32 * i) * 72 + lc) = rb[i];
;     }
;     __builtin_amdgcn_sched_barrier(0);
;     mfma4(F1);
;     if (do_load) load_stage(ra, rb, tload);
;     __builtin_amdgcn_sched_barrier(0);
;   };
;   const int nk = K >> 6;
;   load_stage(ra0, rb0, 0); load_stage(ra1, rb1, 1);
;   __syncthreads();
;   write_stage(ra0, rb0, 0);
;   load_stage(ra0, rb0, 2);
;   __syncthreads();
;   for (int kt = 0; kt < nk; kt += 2) {
;     step(0, ra1, rb1, true, kt + 3 < nk, kt + 3);
;     __syncthreads();
;     step(1, ra0, rb0, kt + 2 < nk, kt + 4 < nk, kt + 4);
;     __syncthreads();
	ds_read_b128 v[152:155], v102 offset:55296
	ds_read_b128 v[156:159], v102 offset:59904
	ds_read_b128 v[160:163], v101 offset:36864
	ds_read_b128 v[164:167], v101 offset:41472
	v_mfma_f32_32x32x16_bf16 v[48:63], v[116:119], v[80:83], v[48:63]
	v_mfma_f32_32x32x16_bf16 v[32:47], v[116:119], v[108:111], v[32:47]
	v_mfma_f32_32x32x16_bf16 v[0:15], v[128:131], v[80:83], v[0:15]
	v_mfma_f32_32x32x16_bf16 v[16:31], v[128:131], v[108:111], v[16:31]
	global_load_dwordx4 v[80:83], v[84:85], off offset:1152
	global_load_dwordx4 v[104:107], v[86:87], off offset:1152
	global_load_dwordx4 v[108:111], v[88:89], off offset:1152
	global_load_dwordx4 v[112:115], v[90:91], off offset:1152
	global_load_dwordx4 v[116:119], v[92:93], off offset:1152
	global_load_dwordx4 v[124:127], v[94:95], off offset:1152
	global_load_dwordx4 v[128:131], v[96:97], off offset:1152
	global_load_dwordx4 v[132:135], v[98:99], off offset:1152
	s_waitcnt lgkmcnt(1)
	v_mfma_f32_32x32x16_bf16 v[48:63], v[160:163], v[152:155], v[48:63]
	v_mfma_f32_32x32x16_bf16 v[32:47], v[160:163], v[156:159], v[32:47]
	s_waitcnt lgkmcnt(0)
	v_mfma_f32_32x32x16_bf16 v[0:15], v[164:167], v[152:155], v[0:15]
	ds_read_b128 v[152:155], v102 offset:55328
	ds_read_b128 v[160:163], v102 offset:59936
	ds_read_b128 v[168:171], v101 offset:36896
	ds_read_b128 v[172:175], v101 offset:41504
	v_mfma_f32_32x32x16_bf16 v[16:31], v[164:167], v[156:159], v[16:31]
	s_waitcnt lgkmcnt(1)
	v_mfma_f32_32x32x16_bf16 v[48:63], v[168:171], v[152:155], v[48:63]
	v_mfma_f32_32x32x16_bf16 v[32:47], v[168:171], v[160:163], v[32:47]
	s_waitcnt lgkmcnt(0)
	v_mfma_f32_32x32x16_bf16 v[0:15], v[172:175], v[152:155], v[0:15]
	ds_read_b128 v[152:155], v102 offset:55360
	ds_read_b128 v[156:159], v102 offset:59968
	ds_read_b128 v[164:167], v101 offset:36928
	ds_read_b128 v[168:171], v101 offset:41536
	s_waitcnt vmcnt(15)
	ds_write_b128 v100, v[64:67]
	s_waitcnt vmcnt(13)
	ds_write_b128 v100, v[72:75] offset:4608
	s_waitcnt vmcnt(11)
	ds_write_b128 v100, v[136:139] offset:9216
	s_waitcnt vmcnt(9)
	ds_write_b128 v100, v[144:147] offset:13824
	v_mfma_f32_32x32x16_bf16 v[16:31], v[172:175], v[160:163], v[16:31]
	s_waitcnt lgkmcnt(5)
	v_mfma_f32_32x32x16_bf16 v[48:63], v[164:167], v[152:155], v[48:63]
	ds_read_b128 v[64:67], v102 offset:55392
	ds_read_b128 v[72:75], v102 offset:60000
	ds_read_b128 v[136:139], v101 offset:36960
	ds_read_b128 v[144:147], v101 offset:41568
	ds_write_b128 v100, v[68:71] offset:18432
	ds_write_b128 v100, v[76:79] offset:23040
	ds_write_b128 v100, v[140:143] offset:27648
	s_waitcnt vmcnt(8)
	ds_write_b128 v100, v[148:151] offset:32256
	v_mfma_f32_32x32x16_bf16 v[32:47], v[164:167], v[156:159], v[32:47]
	s_waitcnt lgkmcnt(12)
	v_mfma_f32_32x32x16_bf16 v[0:15], v[168:171], v[152:155], v[0:15]
	v_mfma_f32_32x32x16_bf16 v[16:31], v[168:171], v[156:159], v[16:31]
	s_waitcnt lgkmcnt(0)
	s_barrier
	ds_read_b128 v[152:155], v102 offset:18432
	ds_read_b128 v[156:159], v102 offset:23040
	ds_read_b128 v[160:163], v101
	ds_read_b128 v[164:167], v101 offset:4608
	v_mfma_f32_32x32x16_bf16 v[48:63], v[136:139], v[64:67], v[48:63]
	v_mfma_f32_32x32x16_bf16 v[32:47], v[136:139], v[72:75], v[32:47]
	v_mfma_f32_32x32x16_bf16 v[0:15], v[144:147], v[64:67], v[0:15]
	v_mfma_f32_32x32x16_bf16 v[16:31], v[144:147], v[72:75], v[16:31]
	global_load_dwordx4 v[64:67], v[84:85], off offset:1280
	global_load_dwordx4 v[68:71], v[86:87], off offset:1280
	global_load_dwordx4 v[72:75], v[88:89], off offset:1280
	global_load_dwordx4 v[76:79], v[90:91], off offset:1280
	global_load_dwordx4 v[136:139], v[92:93], off offset:1280
	global_load_dwordx4 v[140:143], v[94:95], off offset:1280
	global_load_dwordx4 v[144:147], v[96:97], off offset:1280
	global_load_dwordx4 v[148:151], v[98:99], off offset:1280
	s_waitcnt lgkmcnt(1)
	v_mfma_f32_32x32x16_bf16 v[48:63], v[160:163], v[152:155], v[48:63]
	v_mfma_f32_32x32x16_bf16 v[32:47], v[160:163], v[156:159], v[32:47]
	s_waitcnt lgkmcnt(0)
	v_mfma_f32_32x32x16_bf16 v[0:15], v[164:167], v[152:155], v[0:15]
	ds_read_b128 v[152:155], v102 offset:18464
	ds_read_b128 v[160:163], v102 offset:23072
	ds_read_b128 v[168:171], v101 offset:32
	ds_read_b128 v[172:175], v101 offset:4640
	v_mfma_f32_32x32x16_bf16 v[16:31], v[164:167], v[156:159], v[16:31]
	s_waitcnt lgkmcnt(1)
	v_mfma_f32_32x32x16_bf16 v[48:63], v[168:171], v[152:155], v[48:63]
	v_mfma_f32_32x32x16_bf16 v[32:47], v[168:171], v[160:163], v[32:47]
	s_waitcnt lgkmcnt(0)
	v_mfma_f32_32x32x16_bf16 v[0:15], v[172:175], v[152:155], v[0:15]
	ds_read_b128 v[152:155], v102 offset:18496
	ds_read_b128 v[156:159], v102 offset:23104
	ds_read_b128 v[164:167], v101 offset:64
	ds_read_b128 v[168:171], v101 offset:4672
	s_waitcnt vmcnt(15)
	ds_write_b128 v100, v[80:83] offset:36864
	s_waitcnt vmcnt(13)
	ds_write_b128 v100, v[108:111] offset:41472
	s_waitcnt vmcnt(11)
	ds_write_b128 v100, v[116:119] offset:46080
	s_waitcnt vmcnt(9)
	ds_write_b128 v100, v[128:131] offset:50688
	v_mfma_f32_32x32x16_bf16 v[16:31], v[172:175], v[160:163], v[16:31]
	s_waitcnt lgkmcnt(5)
	v_mfma_f32_32x32x16_bf16 v[48:63], v[164:167], v[152:155], v[48:63]
	ds_read_b128 v[80:83], v102 offset:18528
	ds_read_b128 v[108:111], v102 offset:23136
	ds_read_b128 v[116:119], v101 offset:96
	ds_read_b128 v[128:131], v101 offset:4704
	ds_write_b128 v100, v[104:107] offset:55296
	ds_write_b128 v100, v[112:115] offset:59904
	ds_write_b128 v100, v[124:127] offset:64512
	s_waitcnt vmcnt(8)
	ds_write_b128 v103, v[132:135] offset:13824
	v_mfma_f32_32x32x16_bf16 v[32:47], v[164:167], v[156:159], v[32:47]
	s_waitcnt lgkmcnt(12)
	v_mfma_f32_32x32x16_bf16 v[0:15], v[168:171], v[152:155], v[0:15]
	v_mfma_f32_32x32x16_bf16 v[16:31], v[168:171], v[156:159], v[16:31]
	s_waitcnt lgkmcnt(0)
	s_barrier
; template <bool SWAP>
; DI void gemm_tile(const bf16_t* __restrict__ A, int lda, const bf16_t* __restrict__ Bt, int ldb, int K, f32x16 (&acc)[2][2], bf16_t* As, bf16_t* Bs_unused) {
;     ...
;   auto step = [&](int buf, u32x4 (&ra)[4], u32x4 (&rb)[4], bool do_write, bool do_load, int tload) __attribute__((always_inline)) {
;     const bf16_t* pa = As + buf * 2 * GT_IMG + pao; const bf16_t* pb = As + buf * 2 * GT_IMG + pbo;
;     bf16_t* Ad = As + (buf ^ 1) * 2 * GT_IMG; bf16_t* Bd = Ad + GT_IMG;
;     bf16x8 F0[4], F1[4];
;     frag_read(F0, pa, pb, 0);
;     __builtin_amdgcn_sched_barrier(0);
;     frag_read(F1, pa, pb, 16);
;     mfma4(F0);
;     __builtin_amdgcn_sched_barrier(0);
;     frag_read(F0, pa, pb, 32);
;     mfma4(F1);
;     if (do_write) {
; #pragma unroll
;       for (int i = 0; i < 4; ++i) *(u32x4*)(Ad + (lr + 32 * i) * 72 + lc) = ra[i];
;     }
;     __builtin_amdgcn_sched_barrier(0);
;     frag_read(F1, pa, pb, 48);
;     mfma4(F0);
;     if (do_write) {
; #pragma unroll
;       for (int i = 0; i < 4; ++i) *(u32x4*)(Bd + (lr + 32 * i) * 72 + lc) = rb[i];
;     }
;     __builtin_amdgcn_sched_barrier(0);
;     mfma4(F1);
;     if (do_load) load_stage(ra, rb, tload);
;     __builtin_amdgcn_sched_barrier(0);
;   };
;   const int nk = K >> 6;
;   load_stage(ra0, rb0, 0); load_stage(ra1, rb1, 1);
;   __syncthreads();
;   write_stage(ra0, rb0, 0);
;   load_stage(ra0, rb0, 2);
;   __syncthreads();
;   for (int kt = 0; kt < nk; kt += 2) {
;     step(0, ra1, rb1, true, kt + 3 < nk, kt + 3);
;     __syncthreads();
;     step(1, ra0, rb0, kt + 2 < nk, kt + 4 < nk, kt + 4);
;     __syncthreads();
	ds_read_b128 v[152:155], v102 offset:55296
	ds_read_b128 v[156:159], v102 offset:59904
	ds_read_b128 v[160:163], v101 offset:36864
	ds_read_b128 v[164:167], v101 offset:41472
	v_mfma_f32_32x32x16_bf16 v[48:63], v[116:119], v[80:83], v[48:63]
	v_mfma_f32_32x32x16_bf16 v[32:47], v[116:119], v[108:111], v[32:47]
	v_mfma_f32_32x32x16_bf16 v[0:15], v[128:131], v[80:83], v[0:15]
	v_mfma_f32_32x32x16_bf16 v[16:31], v[128:131], v[108:111], v[16:31]
	global_load_dwordx4 v[80:83], v[84:85], off offset:1408
	global_load_dwordx4 v[104:107], v[86:87], off offset:1408
	global_load_dwordx4 v[108:111], v[88:89], off offset:1408
	global_load_dwordx4 v[112:115], v[90:91], off offset:1408
	global_load_dwordx4 v[116:119], v[92:93], off offset:1408
	global_load_dwordx4 v[124:127], v[94:95], off offset:1408
	global_load_dwordx4 v[128:131], v[96:97], off offset:1408
	global_load_dwordx4 v[132:135], v[98:99], off offset:1408
	s_waitcnt lgkmcnt(1)
	v_mfma_f32_32x32x16_bf16 v[48:63], v[160:163], v[152:155], v[48:63]
	v_mfma_f32_32x32x16_bf16 v[32:47], v[160:163], v[156:159], v[32:47]
	s_waitcnt lgkmcnt(0)
	v_mfma_f32_32x32x16_bf16 v[0:15], v[164:167], v[152:155], v[0:15]
	ds_read_b128 v[152:155], v102 offset:55328
	ds_read_b128 v[160:163], v102 offset:59936
	ds_read_b128 v[168:171], v101 offset:36896
	ds_read_b128 v[172:175], v101 offset:41504
	v_mfma_f32_32x32x16_bf16 v[16:31], v[164:167], v[156:159], v[16:31]
	s_waitcnt lgkmcnt(1)
	v_mfma_f32_32x32x16_bf16 v[48:63], v[168:171], v[152:155], v[48:63]
	v_mfma_f32_32x32x16_bf16 v[32:47], v[168:171], v[160:163], v[32:47]
	s_waitcnt lgkmcnt(0)
	v_mfma_f32_32x32x16_bf16 v[0:15], v[172:175], v[152:155], v[0:15]
	ds_read_b128 v[152:155], v102 offset:55360
	ds_read_b128 v[156:159], v102 offset:59968
	ds_read_b128 v[164:167], v101 offset:36928
	ds_read_b128 v[168:171], v101 offset:41536
	s_waitcnt vmcnt(15)
	ds_write_b128 v100, v[64:67]
	s_waitcnt vmcnt(13)
	ds_write_b128 v100, v[72:75] offset:4608
	s_waitcnt vmcnt(11)
	ds_write_b128 v100, v[136:139] offset:9216
	s_waitcnt vmcnt(9)
	ds_write_b128 v100, v[144:147] offset:13824
	v_mfma_f32_32x32x16_bf16 v[16:31], v[172:175], v[160:163], v[16:31]
	s_waitcnt lgkmcnt(5)
	v_mfma_f32_32x32x16_bf16 v[48:63], v[164:167], v[152:155], v[48:63]
	ds_read_b128 v[64:67], v102 offset:55392
	ds_read_b128 v[72:75], v102 offset:60000
	ds_read_b128 v[136:139], v101 offset:36960
	ds_read_b128 v[144:147], v101 offset:41568
	ds_write_b128 v100, v[68:71] offset:18432
	ds_write_b128 v100, v[76:79] offset:23040
	ds_write_b128 v100, v[140:143] offset:27648
	s_waitcnt vmcnt(8)
	ds_write_b128 v100, v[148:151] offset:32256
	v_mfma_f32_32x32x16_bf16 v[32:47], v[164:167], v[156:159], v[32:47]
	s_waitcnt lgkmcnt(12)
	v_mfma_f32_32x32x16_bf16 v[0:15], v[168:171], v[152:155], v[0:15]
	v_mfma_f32_32x32x16_bf16 v[16:31], v[168:171], v[156:159], v[16:31]
	s_waitcnt lgkmcnt(0)
	s_barrier
	ds_read_b128 v[152:155], v102 offset:18432
	ds_read_b128 v[156:159], v102 offset:23040
	ds_read_b128 v[160:163], v101
	ds_read_b128 v[164:167], v101 offset:4608
	v_mfma_f32_32x32x16_bf16 v[48:63], v[136:139], v[64:67], v[48:63]
	v_mfma_f32_32x32x16_bf16 v[32:47], v[136:139], v[72:75], v[32:47]
	v_mfma_f32_32x32x16_bf16 v[0:15], v[144:147], v[64:67], v[0:15]
	v_mfma_f32_32x32x16_bf16 v[16:31], v[144:147], v[72:75], v[16:31]
	global_load_dwordx4 v[64:67], v[84:85], off offset:1536
	global_load_dwordx4 v[68:71], v[86:87], off offset:1536
	global_load_dwordx4 v[72:75], v[88:89], off offset:1536
	global_load_dwordx4 v[76:79], v[90:91], off offset:1536
	global_load_dwordx4 v[136:139], v[92:93], off offset:1536
	global_load_dwordx4 v[140:143], v[94:95], off offset:1536
	global_load_dwordx4 v[144:147], v[96:97], off offset:1536
	global_load_dwordx4 v[148:151], v[98:99], off offset:1536
	s_waitcnt lgkmcnt(1)
	v_mfma_f32_32x32x16_bf16 v[48:63], v[160:163], v[152:155], v[48:63]
	v_mfma_f32_32x32x16_bf16 v[32:47], v[160:163], v[156:159], v[32:47]
	s_waitcnt lgkmcnt(0)
	v_mfma_f32_32x32x16_bf16 v[0:15], v[164:167], v[152:155], v[0:15]
	ds_read_b128 v[152:155], v102 offset:18464
	ds_read_b128 v[160:163], v102 offset:23072
	ds_read_b128 v[168:171], v101 offset:32
	ds_read_b128 v[172:175], v101 offset:4640
	v_mfma_f32_32x32x16_bf16 v[16:31], v[164:167], v[156:159], v[16:31]
	s_waitcnt lgkmcnt(1)
	v_mfma_f32_32x32x16_bf16 v[48:63], v[168:171], v[152:155], v[48:63]
	v_mfma_f32_32x32x16_bf16 v[32:47], v[168:171], v[160:163], v[32:47]
	s_waitcnt lgkmcnt(0)
	v_mfma_f32_32x32x16_bf16 v[0:15], v[172:175], v[152:155], v[0:15]
	ds_read_b128 v[152:155], v102 offset:18496
	ds_read_b128 v[156:159], v102 offset:23104
	ds_read_b128 v[164:167], v101 offset:64
	ds_read_b128 v[168:171], v101 offset:4672
	s_waitcnt vmcnt(15)
	ds_write_b128 v100, v[80:83] offset:36864
	s_waitcnt vmcnt(13)
	ds_write_b128 v100, v[108:111] offset:41472
	s_waitcnt vmcnt(11)
	ds_write_b128 v100, v[116:119] offset:46080
	s_waitcnt vmcnt(9)
	ds_write_b128 v100, v[128:131] offset:50688
	v_mfma_f32_32x32x16_bf16 v[16:31], v[172:175], v[160:163], v[16:31]
	s_waitcnt lgkmcnt(5)
	v_mfma_f32_32x32x16_bf16 v[48:63], v[164:167], v[152:155], v[48:63]
	ds_read_b128 v[80:83], v102 offset:18528
	ds_read_b128 v[108:111], v102 offset:23136
	ds_read_b128 v[116:119], v101 offset:96
	ds_read_b128 v[128:131], v101 offset:4704
	ds_write_b128 v100, v[104:107] offset:55296
	ds_write_b128 v100, v[112:115] offset:59904
	ds_write_b128 v100, v[124:127] offset:64512
	s_waitcnt vmcnt(8)
	ds_write_b128 v103, v[132:135] offset:13824
	v_mfma_f32_32x32x16_bf16 v[32:47], v[164:167], v[156:159], v[32:47]
	s_waitcnt lgkmcnt(12)
	v_mfma_f32_32x32x16_bf16 v[0:15], v[168:171], v[152:155], v[0:15]
	v_mfma_f32_32x32x16_bf16 v[16:31], v[168:171], v[156:159], v[16:31]
	s_waitcnt lgkmcnt(0)
	s_barrier
; template <bool SWAP>
; DI void gemm_tile(const bf16_t* __restrict__ A, int lda, const bf16_t* __restrict__ Bt, int ldb, int K, f32x16 (&acc)[2][2], bf16_t* As, bf16_t* Bs_unused) {
;     ...
;   auto step = [&](int buf, u32x4 (&ra)[4], u32x4 (&rb)[4], bool do_write, bool do_load, int tload) __attribute__((always_inline)) {
;     const bf16_t* pa = As + buf * 2 * GT_IMG + pao; const bf16_t* pb = As + buf * 2 * GT_IMG + pbo;
;     bf16_t* Ad = As + (buf ^ 1) * 2 * GT_IMG; bf16_t* Bd = Ad + GT_IMG;
;     bf16x8 F0[4], F1[4];
;     frag_read(F0, pa, pb, 0);
;     __builtin_amdgcn_sched_barrier(0);
;     frag_read(F1, pa, pb, 16);
;     mfma4(F0);
;     __builtin_amdgcn_sched_barrier(0);
;     frag_read(F0, pa, pb, 32);
;     mfma4(F1);
;     if (do_write) {
; #pragma unroll
;       for (int i = 0; i < 4; ++i) *(u32x4*)(Ad + (lr + 32 * i) * 72 + lc) = ra[i];
;     }
;     __builtin_amdgcn_sched_barrier(0);
;     frag_read(F1, pa, pb, 48);
;     mfma4(F0);
;     if (do_write) {
; #pragma unroll
;       for (int i = 0; i < 4; ++i) *(u32x4*)(Bd + (lr + 32 * i) * 72 + lc) = rb[i];
;     }
;     __builtin_amdgcn_sched_barrier(0);
;     mfma4(F1);
;     if (do_load) load_stage(ra, rb, tload);
;     __builtin_amdgcn_sched_barrier(0);
;   };
;   const int nk = K >> 6;
;   load_stage(ra0, rb0, 0); load_stage(ra1, rb1, 1);
;   __syncthreads();
;   write_stage(ra0, rb0, 0);
;   load_stage(ra0, rb0, 2);
;   __syncthreads();
;   for (int kt = 0; kt < nk; kt += 2) {
;     step(0, ra1, rb1, true, kt + 3 < nk, kt + 3);
;     __syncthreads();
;     step(1, ra0, rb0, kt + 2 < nk, kt + 4 < nk, kt + 4);
;     __syncthreads();
	ds_read_b128 v[152:155], v102 offset:55296
	ds_read_b128 v[156:159], v102 offset:59904
	ds_read_b128 v[160:163], v101 offset:36864
	ds_read_b128 v[164:167], v101 offset:41472
	v_mfma_f32_32x32x16_bf16 v[48:63], v[116:119], v[80:83], v[48:63]
	v_mfma_f32_32x32x16_bf16 v[32:47], v[116:119], v[108:111], v[32:47]
	v_mfma_f32_32x32x16_bf16 v[0:15], v[128:131], v[80:83], v[0:15]
	v_mfma_f32_32x32x16_bf16 v[16:31], v[128:131], v[108:111], v[16:31]
	global_load_dwordx4 v[80:83], v[84:85], off offset:1664
	global_load_dwordx4 v[104:107], v[86:87], off offset:1664
	global_load_dwordx4 v[108:111], v[88:89], off offset:1664
	global_load_dwordx4 v[112:115], v[90:91], off offset:1664
	global_load_dwordx4 v[116:119], v[92:93], off offset:1664
	global_load_dwordx4 v[124:127], v[94:95], off offset:1664
	global_load_dwordx4 v[128:131], v[96:97], off offset:1664
	global_load_dwordx4 v[132:135], v[98:99], off offset:1664
	s_waitcnt lgkmcnt(1)
	v_mfma_f32_32x32x16_bf16 v[48:63], v[160:163], v[152:155], v[48:63]
	v_mfma_f32_32x32x16_bf16 v[32:47], v[160:163], v[156:159], v[32:47]
	s_waitcnt lgkmcnt(0)
	v_mfma_f32_32x32x16_bf16 v[0:15], v[164:167], v[152:155], v[0:15]
	ds_read_b128 v[152:155], v102 offset:55328
	ds_read_b128 v[160:163], v102 offset:59936
	ds_read_b128 v[168:171], v101 offset:36896
	ds_read_b128 v[172:175], v101 offset:41504
	v_mfma_f32_32x32x16_bf16 v[16:31], v[164:167], v[156:159], v[16:31]
	s_waitcnt lgkmcnt(1)
	v_mfma_f32_32x32x16_bf16 v[48:63], v[168:171], v[152:155], v[48:63]
	v_mfma_f32_32x32x16_bf16 v[32:47], v[168:171], v[160:163], v[32:47]
	s_waitcnt lgkmcnt(0)
	v_mfma_f32_32x32x16_bf16 v[0:15], v[172:175], v[152:155], v[0:15]
	ds_read_b128 v[152:155], v102 offset:55360
	ds_read_b128 v[156:159], v102 offset:59968
	ds_read_b128 v[164:167], v101 offset:36928
	ds_read_b128 v[168:171], v101 offset:41536
	s_waitcnt vmcnt(15)
	ds_write_b128 v100, v[64:67]
	s_waitcnt vmcnt(13)
	ds_write_b128 v100, v[72:75] offset:4608
	s_waitcnt vmcnt(11)
	ds_write_b128 v100, v[136:139] offset:9216
	s_waitcnt vmcnt(9)
	ds_write_b128 v100, v[144:147] offset:13824
	v_mfma_f32_32x32x16_bf16 v[16:31], v[172:175], v[160:163], v[16:31]
	s_waitcnt lgkmcnt(5)
	v_mfma_f32_32x32x16_bf16 v[48:63], v[164:167], v[152:155], v[48:63]
	ds_read_b128 v[64:67], v102 offset:55392
	ds_read_b128 v[72:75], v102 offset:60000
	ds_read_b128 v[136:139], v101 offset:36960
	ds_read_b128 v[144:147], v101 offset:41568
	ds_write_b128 v100, v[68:71] offset:18432
	ds_write_b128 v100, v[76:79] offset:23040
	ds_write_b128 v100, v[140:143] offset:27648
	s_waitcnt vmcnt(8)
	ds_write_b128 v100, v[148:151] offset:32256
	v_mfma_f32_32x32x16_bf16 v[32:47], v[164:167], v[156:159], v[32:47]
	s_waitcnt lgkmcnt(12)
	v_mfma_f32_32x32x16_bf16 v[0:15], v[168:171], v[152:155], v[0:15]
	v_mfma_f32_32x32x16_bf16 v[16:31], v[168:171], v[156:159], v[16:31]
	s_waitcnt lgkmcnt(0)
	s_barrier
	ds_read_b128 v[152:155], v102 offset:18432
	ds_read_b128 v[156:159], v102 offset:23040
	ds_read_b128 v[160:163], v101
	ds_read_b128 v[164:167], v101 offset:4608
	v_mfma_f32_32x32x16_bf16 v[48:63], v[136:139], v[64:67], v[48:63]
	v_mfma_f32_32x32x16_bf16 v[32:47], v[136:139], v[72:75], v[32:47]
	v_mfma_f32_32x32x16_bf16 v[0:15], v[144:147], v[64:67], v[0:15]
	v_mfma_f32_32x32x16_bf16 v[16:31], v[144:147], v[72:75], v[16:31]
	global_load_dwordx4 v[64:67], v[84:85], off offset:1792
	global_load_dwordx4 v[68:71], v[86:87], off offset:1792
	global_load_dwordx4 v[72:75], v[88:89], off offset:1792
	global_load_dwordx4 v[76:79], v[90:91], off offset:1792
	global_load_dwordx4 v[136:139], v[92:93], off offset:1792
	global_load_dwordx4 v[140:143], v[94:95], off offset:1792
	global_load_dwordx4 v[144:147], v[96:97], off offset:1792
	global_load_dwordx4 v[148:151], v[98:99], off offset:1792
	s_waitcnt lgkmcnt(1)
	v_mfma_f32_32x32x16_bf16 v[48:63], v[160:163], v[152:155], v[48:63]
	v_mfma_f32_32x32x16_bf16 v[32:47], v[160:163], v[156:159], v[32:47]
	s_waitcnt lgkmcnt(0)
	v_mfma_f32_32x32x16_bf16 v[0:15], v[164:167], v[152:155], v[0:15]
	ds_read_b128 v[152:155], v102 offset:18464
	ds_read_b128 v[160:163], v102 offset:23072
	ds_read_b128 v[168:171], v101 offset:32
	ds_read_b128 v[172:175], v101 offset:4640
	v_mfma_f32_32x32x16_bf16 v[16:31], v[164:167], v[156:159], v[16:31]
	s_waitcnt lgkmcnt(1)
	v_mfma_f32_32x32x16_bf16 v[48:63], v[168:171], v[152:155], v[48:63]
	v_mfma_f32_32x32x16_bf16 v[32:47], v[168:171], v[160:163], v[32:47]
	s_waitcnt lgkmcnt(0)
	v_mfma_f32_32x32x16_bf16 v[0:15], v[172:175], v[152:155], v[0:15]
	ds_read_b128 v[152:155], v102 offset:18496
	ds_read_b128 v[156:159], v102 offset:23104
	ds_read_b128 v[164:167], v101 offset:64
	ds_read_b128 v[168:171], v101 offset:4672
	s_waitcnt vmcnt(15)
	ds_write_b128 v100, v[80:83] offset:36864
	s_waitcnt vmcnt(13)
	ds_write_b128 v100, v[108:111] offset:41472
	s_waitcnt vmcnt(11)
	ds_write_b128 v100, v[116:119] offset:46080
	s_waitcnt vmcnt(9)
	ds_write_b128 v100, v[128:131] offset:50688
	v_mfma_f32_32x32x16_bf16 v[16:31], v[172:175], v[160:163], v[16:31]
	s_waitcnt lgkmcnt(5)
	v_mfma_f32_32x32x16_bf16 v[48:63], v[164:167], v[152:155], v[48:63]
	ds_read_b128 v[80:83], v102 offset:18528
	ds_read_b128 v[108:111], v102 offset:23136
	ds_read_b128 v[116:119], v101 offset:96
	ds_read_b128 v[128:131], v101 offset:4704
	ds_write_b128 v100, v[104:107] offset:55296
	ds_write_b128 v100, v[112:115] offset:59904
	ds_write_b128 v100, v[124:127] offset:64512
	s_waitcnt vmcnt(8)
	ds_write_b128 v103, v[132:135] offset:13824
	v_mfma_f32_32x32x16_bf16 v[32:47], v[164:167], v[156:159], v[32:47]
	s_waitcnt lgkmcnt(12)
	v_mfma_f32_32x32x16_bf16 v[0:15], v[168:171], v[152:155], v[0:15]
	v_mfma_f32_32x32x16_bf16 v[16:31], v[168:171], v[156:159], v[16:31]
	s_waitcnt lgkmcnt(5)
	v_mfma_f32_32x32x16_bf16 v[48:63], v[116:119], v[80:83], v[48:63]
	v_mfma_f32_32x32x16_bf16 v[32:47], v[116:119], v[108:111], v[32:47]
	s_waitcnt lgkmcnt(4)
	v_mfma_f32_32x32x16_bf16 v[0:15], v[128:131], v[80:83], v[0:15]
	v_mfma_f32_32x32x16_bf16 v[16:31], v[128:131], v[108:111], v[16:31]
	global_load_dwordx4 v[80:83], v[84:85], off offset:1920
	s_nop 0
	global_load_dwordx4 v[84:87], v[86:87], off offset:1920
	s_nop 0
	global_load_dwordx4 v[104:107], v[88:89], off offset:1920
	s_nop 0
	global_load_dwordx4 v[88:91], v[90:91], off offset:1920
	s_nop 0
	global_load_dwordx4 v[108:111], v[92:93], off offset:1920
	s_nop 0
	global_load_dwordx4 v[92:95], v[94:95], off offset:1920
	s_nop 0
	global_load_dwordx4 v[112:115], v[96:97], off offset:1920
	s_nop 0
	global_load_dwordx4 v[96:99], v[98:99], off offset:1920
	s_waitcnt lgkmcnt(0)
	s_barrier
; template <bool SWAP>
; DI void gemm_tile(const bf16_t* __restrict__ A, int lda, const bf16_t* __restrict__ Bt, int ldb, int K, f32x16 (&acc)[2][2], bf16_t* As, bf16_t* Bs_unused) {
;     ...
;   auto step = [&](int buf, u32x4 (&ra)[4], u32x4 (&rb)[4], bool do_write, bool do_load, int tload) __attribute__((always_inline)) {
;     const bf16_t* pa = As + buf * 2 * GT_IMG + pao; const bf16_t* pb = As + buf * 2 * GT_IMG + pbo;
;     bf16_t* Ad = As + (buf ^ 1) * 2 * GT_IMG; bf16_t* Bd = Ad + GT_IMG;
;     bf16x8 F0[4], F1[4];
;     frag_read(F0, pa, pb, 0);
;     __builtin_amdgcn_sched_barrier(0);
;     frag_read(F1, pa, pb, 16);
;     mfma4(F0);
;     __builtin_amdgcn_sched_barrier(0);
;     frag_read(F0, pa, pb, 32);
;     mfma4(F1);
;     if (do_write) {
; #pragma unroll
;       for (int i = 0; i < 4; ++i) *(u32x4*)(Ad + (lr + 32 * i) * 72 + lc) = ra[i];
;     }
;     __builtin_amdgcn_sched_barrier(0);
;     frag_read(F1, pa, pb, 48);
;     mfma4(F0);
;     if (do_write) {
; #pragma unroll
;       for (int i = 0; i < 4; ++i) *(u32x4*)(Bd + (lr + 32 * i) * 72 + lc) = rb[i];
;     }
;     __builtin_amdgcn_sched_barrier(0);
;     mfma4(F1);
;     if (do_load) load_stage(ra, rb, tload);
;     __builtin_amdgcn_sched_barrier(0);
;   };
;   const int nk = K >> 6;
;   load_stage(ra0, rb0, 0); load_stage(ra1, rb1, 1);
;   __syncthreads();
;   write_stage(ra0, rb0, 0);
;   load_stage(ra0, rb0, 2);
;   __syncthreads();
;   for (int kt = 0; kt < nk; kt += 2) {
;     step(0, ra1, rb1, true, kt + 3 < nk, kt + 3);
;     __syncthreads();
;     step(1, ra0, rb0, kt + 2 < nk, kt + 4 < nk, kt + 4);
;     __syncthreads();
;   }
	ds_read_b128 v[116:119], v102 offset:55296
	ds_read_b128 v[124:127], v102 offset:59904
	ds_read_b128 v[128:131], v101 offset:36864
	ds_read_b128 v[132:135], v101 offset:41472
	s_waitcnt lgkmcnt(1)
	v_mfma_f32_32x32x16_bf16 v[48:63], v[128:131], v[116:119], v[48:63]
	v_mfma_f32_32x32x16_bf16 v[32:47], v[128:131], v[124:127], v[32:47]
	s_waitcnt lgkmcnt(0)
	v_mfma_f32_32x32x16_bf16 v[0:15], v[132:135], v[116:119], v[0:15]
	ds_read_b128 v[116:119], v102 offset:55328
	ds_read_b128 v[128:131], v102 offset:59936
	ds_read_b128 v[152:155], v101 offset:36896
	ds_read_b128 v[156:159], v101 offset:41504
	v_mfma_f32_32x32x16_bf16 v[16:31], v[132:135], v[124:127], v[16:31]
	s_waitcnt lgkmcnt(1)
	v_mfma_f32_32x32x16_bf16 v[48:63], v[152:155], v[116:119], v[48:63]
	v_mfma_f32_32x32x16_bf16 v[32:47], v[152:155], v[128:131], v[32:47]
	s_waitcnt lgkmcnt(0)
	v_mfma_f32_32x32x16_bf16 v[0:15], v[156:159], v[116:119], v[0:15]
	ds_read_b128 v[116:119], v102 offset:55360
	ds_read_b128 v[124:127], v102 offset:59968
	ds_read_b128 v[132:135], v101 offset:36928
	ds_read_b128 v[152:155], v101 offset:41536
	s_waitcnt vmcnt(15)
	ds_write_b128 v100, v[64:67]
	s_waitcnt vmcnt(13)
	ds_write_b128 v100, v[72:75] offset:4608
	s_waitcnt vmcnt(11)
	ds_write_b128 v100, v[136:139] offset:9216
	s_waitcnt vmcnt(9)
	ds_write_b128 v100, v[144:147] offset:13824
	v_mfma_f32_32x32x16_bf16 v[16:31], v[156:159], v[128:131], v[16:31]
	s_waitcnt lgkmcnt(5)
	v_mfma_f32_32x32x16_bf16 v[48:63], v[132:135], v[116:119], v[48:63]
	v_mfma_f32_32x32x16_bf16 v[32:47], v[132:135], v[124:127], v[32:47]
	s_waitcnt lgkmcnt(4)
	v_mfma_f32_32x32x16_bf16 v[0:15], v[152:155], v[116:119], v[0:15]
	ds_read_b128 v[64:67], v102 offset:55392
	ds_read_b128 v[72:75], v102 offset:60000
	ds_read_b128 v[116:119], v101 offset:36960
	ds_read_b128 v[128:131], v101 offset:41568
	ds_write_b128 v100, v[68:71] offset:18432
	ds_write_b128 v100, v[76:79] offset:23040
	ds_write_b128 v100, v[140:143] offset:27648
	s_waitcnt vmcnt(8)
	ds_write_b128 v100, v[148:151] offset:32256
	v_mfma_f32_32x32x16_bf16 v[16:31], v[152:155], v[124:127], v[16:31]
	s_waitcnt lgkmcnt(5)
	v_mfma_f32_32x32x16_bf16 v[48:63], v[116:119], v[64:67], v[48:63]
	v_mfma_f32_32x32x16_bf16 v[32:47], v[116:119], v[72:75], v[32:47]
	s_waitcnt lgkmcnt(4)
	v_mfma_f32_32x32x16_bf16 v[0:15], v[128:131], v[64:67], v[0:15]
	v_mfma_f32_32x32x16_bf16 v[16:31], v[128:131], v[72:75], v[16:31]
	s_waitcnt lgkmcnt(0)
	s_barrier
	ds_read_b128 v[64:67], v102 offset:18432
	ds_read_b128 v[68:71], v102 offset:23040
	ds_read_b128 v[72:75], v101
	ds_read_b128 v[76:79], v101 offset:4608
	s_waitcnt lgkmcnt(1)
	v_mfma_f32_32x32x16_bf16 v[48:63], v[72:75], v[64:67], v[48:63]
	v_mfma_f32_32x32x16_bf16 v[32:47], v[72:75], v[68:71], v[32:47]
	s_waitcnt lgkmcnt(0)
	v_mfma_f32_32x32x16_bf16 v[0:15], v[76:79], v[64:67], v[0:15]
	ds_read_b128 v[64:67], v102 offset:18464
	ds_read_b128 v[72:75], v102 offset:23072
	ds_read_b128 v[116:119], v101 offset:32
	ds_read_b128 v[124:127], v101 offset:4640
	v_mfma_f32_32x32x16_bf16 v[16:31], v[76:79], v[68:71], v[16:31]
	s_waitcnt lgkmcnt(1)
	v_mfma_f32_32x32x16_bf16 v[48:63], v[116:119], v[64:67], v[48:63]
	v_mfma_f32_32x32x16_bf16 v[32:47], v[116:119], v[72:75], v[32:47]
	s_waitcnt lgkmcnt(0)
	v_mfma_f32_32x32x16_bf16 v[0:15], v[124:127], v[64:67], v[0:15]
	ds_read_b128 v[64:67], v102 offset:18496
	ds_read_b128 v[68:71], v102 offset:23104
	ds_read_b128 v[76:79], v101 offset:64
	ds_read_b128 v[116:119], v101 offset:4672
	s_waitcnt vmcnt(7)
	ds_write_b128 v100, v[80:83] offset:36864
	s_waitcnt vmcnt(5)
	ds_write_b128 v100, v[104:107] offset:41472
	s_waitcnt vmcnt(3)
	ds_write_b128 v100, v[108:111] offset:46080
	s_waitcnt vmcnt(1)
	ds_write_b128 v100, v[112:115] offset:50688
	v_mfma_f32_32x32x16_bf16 v[16:31], v[124:127], v[72:75], v[16:31]
	s_waitcnt lgkmcnt(5)
	v_mfma_f32_32x32x16_bf16 v[48:63], v[76:79], v[64:67], v[48:63]
	v_mfma_f32_32x32x16_bf16 v[32:47], v[76:79], v[68:71], v[32:47]
	s_waitcnt lgkmcnt(4)
	v_mfma_f32_32x32x16_bf16 v[0:15], v[116:119], v[64:67], v[0:15]
	ds_read_b128 v[64:67], v102 offset:18528
	ds_read_b128 v[72:75], v102 offset:23136
	ds_read_b128 v[76:79], v101 offset:96
	ds_read_b128 v[80:83], v101 offset:4704
	ds_write_b128 v100, v[84:87] offset:55296
	ds_write_b128 v100, v[88:91] offset:59904
	ds_write_b128 v100, v[92:95] offset:64512
	s_waitcnt vmcnt(0)
	ds_write_b128 v103, v[96:99] offset:13824
	v_mfma_f32_32x32x16_bf16 v[16:31], v[116:119], v[68:71], v[16:31]
	s_waitcnt lgkmcnt(5)
	v_mfma_f32_32x32x16_bf16 v[48:63], v[76:79], v[64:67], v[48:63]
	v_mfma_f32_32x32x16_bf16 v[32:47], v[76:79], v[72:75], v[32:47]
	s_waitcnt lgkmcnt(4)
	v_mfma_f32_32x32x16_bf16 v[0:15], v[80:83], v[64:67], v[0:15]
	v_mfma_f32_32x32x16_bf16 v[16:31], v[80:83], v[72:75], v[16:31]
	s_waitcnt lgkmcnt(0)
	s_barrier
	ds_read_b128 v[64:67], v102 offset:55296
	ds_read_b128 v[68:71], v102 offset:59904
	ds_read_b128 v[72:75], v101 offset:36864
	ds_read_b128 v[76:79], v101 offset:41472
	s_waitcnt lgkmcnt(1)
	v_mfma_f32_32x32x16_bf16 v[48:63], v[72:75], v[64:67], v[48:63]
	v_mfma_f32_32x32x16_bf16 v[32:47], v[72:75], v[68:71], v[32:47]
	s_waitcnt lgkmcnt(0)
	v_mfma_f32_32x32x16_bf16 v[0:15], v[76:79], v[64:67], v[0:15]
	ds_read_b128 v[64:67], v102 offset:55328
	ds_read_b128 v[72:75], v102 offset:59936
	ds_read_b128 v[80:83], v101 offset:36896
	ds_read_b128 v[84:87], v101 offset:41504
	v_mfma_f32_32x32x16_bf16 v[16:31], v[76:79], v[68:71], v[16:31]
	s_waitcnt lgkmcnt(1)
	v_mfma_f32_32x32x16_bf16 v[48:63], v[80:83], v[64:67], v[48:63]
	v_mfma_f32_32x32x16_bf16 v[32:47], v[80:83], v[72:75], v[32:47]
	s_waitcnt lgkmcnt(0)
	v_mfma_f32_32x32x16_bf16 v[0:15], v[84:87], v[64:67], v[0:15]
	v_mfma_f32_32x32x16_bf16 v[16:31], v[84:87], v[72:75], v[16:31]
	ds_read_b128 v[64:67], v101 offset:41536
	ds_read_b128 v[68:71], v102 offset:59968
	ds_read_b128 v[72:75], v102 offset:55360
	ds_read_b128 v[76:79], v101 offset:36928
	s_waitcnt lgkmcnt(0)
	v_mfma_f32_32x32x16_bf16 v[48:63], v[76:79], v[72:75], v[48:63]
	v_mfma_f32_32x32x16_bf16 v[32:47], v[76:79], v[68:71], v[32:47]
	v_mfma_f32_32x32x16_bf16 v[0:15], v[64:67], v[72:75], v[0:15]
	v_mfma_f32_32x32x16_bf16 v[16:31], v[64:67], v[68:71], v[16:31]
	ds_read_b128 v[64:67], v101 offset:41568
	ds_read_b128 v[68:71], v102 offset:60000
	ds_read_b128 v[72:75], v102 offset:55392
	ds_read_b128 v[76:79], v101 offset:36960
	s_waitcnt lgkmcnt(0)
	v_mfma_f32_32x32x16_bf16 v[48:63], v[76:79], v[72:75], v[48:63]
	v_mfma_f32_32x32x16_bf16 v[32:47], v[76:79], v[68:71], v[32:47]
	v_mfma_f32_32x32x16_bf16 v[0:15], v[64:67], v[72:75], v[0:15]
	v_mfma_f32_32x32x16_bf16 v[16:31], v[64:67], v[68:71], v[16:31]
	s_barrier
	s_mov_b64 s[8:9], 0
; template <bool SWAP>
; DI void gemm_tile(const bf16_t* __restrict__ A, int lda, const bf16_t* __restrict__ Bt, int ldb, int K, f32x16 (&acc)[2][2], bf16_t* As, bf16_t* Bs_unused) {
;     ...
;   auto load_stage = [&](u32x4 (&ra)[4], u32x4 (&rb)[4], int t) __attribute__((always_inline)) {
; #pragma unroll
;     for (int i = 0; i < 4; ++i) { ra[i] = *(const u32x4*)(ga + (size_t)(32 * i) * lda + t * 64); rb[i] = *(const u32x4*)(gb + (size_t)(32 * i) * ldb + t * 64); }
;   };
;   auto write_stage = [&](const u32x4 (&ra)[4], const u32x4 (&rb)[4], int buf) __attribute__((always_inline)) {
;     bf16_t* Ad = As + buf * 2 * GT_IMG; bf16_t* Bd = Ad + GT_IMG;
; #pragma unroll
;     for (int i = 0; i < 4; ++i) { *(u32x4*)(Ad + (lr + 32 * i) * 72 + lc) = ra[i]; *(u32x4*)(Bd + (lr + 32 * i) * 72 + lc) = rb[i]; }
;   };
;   const int fr = lane & 31, fk = (lane >> 5) * 8;
;   const int pao = (wm * 64 + fr) * 72 + fk, pbo = GT_IMG + (wn * 64 + fr) * 72 + fk;
;   auto frag_read = [&](bf16x8 (&f)[4], const bf16_t* pa, const bf16_t* pb, int so) __attribute__((always_inline)) {
;     f[0] = *(const bf16x8*)(pa + so); f[1] = *(const bf16x8*)(pb + so); f[2] = *(const bf16x8*)(pb + 32 * 72 + so); f[3] = *(const bf16x8*)(pa + 32 * 72 + so);
;   };
;   auto mfma4 = [&](const bf16x8 (&f)[4]) __attribute__((always_inline)) {
;     if (SWAP) {
;       acc[0][0] = MFMA32(f[1], f[0], acc[0][0]); acc[0][1] = MFMA32(f[2], f[0], acc[0][1]);
;       acc[1][0] = MFMA32(f[1], f[3], acc[1][0]); acc[1][1] = MFMA32(f[2], f[3], acc[1][1]);
;     } else {
;       acc[0][0] = MFMA32(f[0], f[1], acc[0][0]); acc[0][1] = MFMA32(f[0], f[2], acc[0][1]);
;       acc[1][0] = MFMA32(f[3], f[1], acc[1][0]); acc[1][1] = MFMA32(f[3], f[2], acc[1][1]);
;     }
;   };
;   auto step = [&](int buf, u32x4 (&ra)[4], u32x4 (&rb)[4], bool do_write, bool do_load, int tload) __attribute__((always_inline)) {
;     const bf16_t* pa = As + buf * 2 * GT_IMG + pao; const bf16_t* pb = As + buf * 2 * GT_IMG + pbo;
; DI void phase_gemm1(const Params& p, int g, char* smem, int bid, int nb) {
;     ...
;     const bool swp = (nt >= 16 && nt < 24) || (nt >= 32 && nt < 40);
;     const bf16_t* A = H + (size_t)mt * 128 * 1024; const bf16_t* B = W + (size_t)nt * 128 * 1024;
;     if (swp) gemm_tile<true>(A, 1024, B, 1024, 1024, acc, As, Bs); else gemm_tile<false>(A, 1024, B, 1024, 1024, acc, As, Bs);
.LBB0_369:
	v_readlane_b32 s22, v231, 53
	s_andn2_b64 vcc, exec, s[8:9]
	v_readlane_b32 s23, v231, 54
	s_cbranch_vccnz .LBB0_371
	s_waitcnt lgkmcnt(0)
	s_nop 3
	v_mov_b32_e32 v4, v195
	s_nop 0
	v_ashrrev_i32_e32 v32, 3, v4
	v_ashrrev_i32_e32 v33, 31, v32
	v_lshlrev_b64 v[0:1], 11, v[32:33]
	v_lshlrev_b32_e32 v5, 4, v4
	v_lshl_add_u64 v[2:3], s[0:1], 0, v[0:1]
	v_and_b32_e32 v192, 0x70, v5
	v_lshl_add_u64 v[0:1], s[6:7], 0, v[0:1]
	v_lshl_add_u64 v[106:107], v[0:1], 0, v[192:193]
	v_lshrrev_b32_e32 v1, 2, v4
	v_and_b32_e32 v0, 31, v4
	v_and_b32_e32 v34, 8, v1
	v_lshrrev_b32_e32 v1, 1, v4
	v_and_or_b32 v0, v1, s80, v0
	v_mad_u64_u32 v[36:37], s[0:1], v0, s72, v[34:35]
	s_waitcnt vmcnt(0)
	v_lshl_add_u64 v[104:105], v[2:3], 0, v[192:193]
	s_mov_b32 s0, 0x10000
	v_add_co_u32_e32 v108, vcc, s0, v104
	v_and_b32_e32 v33, 0x5f, v4
	s_nop 0
	v_addc_co_u32_e32 v109, vcc, 0, v105, vcc
	v_add_co_u32_e32 v110, vcc, s0, v106
	s_mov_b32 s0, 0x20000
	s_nop 0
	v_addc_co_u32_e32 v111, vcc, 0, v107, vcc
	global_load_dwordx4 v[0:3], v[104:105], off
	global_load_dwordx4 v[4:7], v[106:107], off
	v_add_co_u32_e32 v112, vcc, s0, v104
	global_load_dwordx4 v[8:11], v[108:109], off
	global_load_dwordx4 v[12:15], v[110:111], off
	v_addc_co_u32_e32 v113, vcc, 0, v105, vcc
	v_add_co_u32_e32 v114, vcc, s0, v106
	s_mov_b32 s0, 0x30000
	s_nop 0
	v_addc_co_u32_e32 v115, vcc, 0, v107, vcc
	global_load_dwordx4 v[16:19], v[112:113], off
	global_load_dwordx4 v[20:23], v[114:115], off
	v_add_co_u32_e32 v116, vcc, s0, v104
	v_mul_lo_u32 v32, v32, s71
	s_nop 0
	v_addc_co_u32_e32 v117, vcc, 0, v105, vcc
	global_load_dwordx4 v[24:27], v[116:117], off
	v_add_co_u32_e32 v118, vcc, s0, v106
	v_add3_u32 v125, 32, v32, v192
	s_nop 0
	v_addc_co_u32_e32 v119, vcc, 0, v107, vcc
	global_load_dwordx4 v[28:31], v[118:119], off
	global_load_dwordx4 v[128:131], v[104:105], off offset:128
	global_load_dwordx4 v[80:83], v[106:107], off offset:128
	global_load_dwordx4 v[132:135], v[108:109], off offset:128
	global_load_dwordx4 v[92:95], v[110:111], off offset:128
	global_load_dwordx4 v[136:139], v[112:113], off offset:128
	global_load_dwordx4 v[140:143], v[114:115], off offset:128
	global_load_dwordx4 v[144:147], v[116:117], off offset:128
	global_load_dwordx4 v[148:151], v[118:119], off offset:128
	s_waitcnt lgkmcnt(0)
	s_barrier
	v_lshl_add_u32 v124, v36, 1, 32
	v_add_u32_e32 v127, 0xd800, v125
	s_waitcnt vmcnt(15)
	ds_write_b128 v125, v[0:3]
	s_waitcnt vmcnt(14)
	ds_write_b128 v125, v[4:7] offset:18432
	s_waitcnt vmcnt(13)
	ds_write_b128 v125, v[8:11] offset:4608
	s_waitcnt vmcnt(12)
	ds_write_b128 v125, v[12:15] offset:23040
	s_waitcnt vmcnt(11)
	ds_write_b128 v125, v[16:19] offset:9216
	s_waitcnt vmcnt(10)
	ds_write_b128 v125, v[20:23] offset:27648
	s_waitcnt vmcnt(9)
	ds_write_b128 v125, v[24:27] offset:13824
	s_waitcnt vmcnt(8)
	ds_write_b128 v125, v[28:31] offset:32256
	global_load_dwordx4 v[84:87], v[104:105], off offset:256
	global_load_dwordx4 v[64:67], v[106:107], off offset:256
	global_load_dwordx4 v[88:91], v[108:109], off offset:256
	global_load_dwordx4 v[68:71], v[110:111], off offset:256
	global_load_dwordx4 v[96:99], v[112:113], off offset:256
	global_load_dwordx4 v[72:75], v[114:115], off offset:256
	global_load_dwordx4 v[100:103], v[116:117], off offset:256
	global_load_dwordx4 v[76:79], v[118:119], off offset:256
	v_mad_u32_u24 v0, v33, s72, v34
	s_waitcnt lgkmcnt(0)
	s_barrier
	v_lshl_add_u32 v126, v0, 1, 32
	ds_read_b128 v[0:3], v124
	ds_read_b128 v[4:7], v126 offset:18432
	ds_read_b128 v[16:19], v126 offset:23040
	ds_read_b128 v[20:23], v124 offset:4608
	s_waitcnt lgkmcnt(2)
	v_mfma_f32_32x32x16_bf16 v[48:63], v[4:7], v[0:3], 0
	ds_read_b128 v[152:155], v126 offset:18464
	ds_read_b128 v[156:159], v126 offset:23072
	ds_read_b128 v[160:163], v124 offset:32
	ds_read_b128 v[164:167], v124 offset:4640
	s_waitcnt lgkmcnt(5)
	v_mfma_f32_32x32x16_bf16 v[32:47], v[16:19], v[0:3], 0
	s_waitcnt lgkmcnt(4)
	v_mfma_f32_32x32x16_bf16 v[0:15], v[4:7], v[20:23], 0
	v_mfma_f32_32x32x16_bf16 v[16:31], v[16:19], v[20:23], 0
	s_waitcnt lgkmcnt(1)
	v_mfma_f32_32x32x16_bf16 v[48:63], v[152:155], v[160:163], v[48:63]
	v_mfma_f32_32x32x16_bf16 v[32:47], v[156:159], v[160:163], v[32:47]
	s_waitcnt lgkmcnt(0)
	v_mfma_f32_32x32x16_bf16 v[0:15], v[152:155], v[164:167], v[0:15]
	ds_read_b128 v[152:155], v126 offset:18496
	ds_read_b128 v[160:163], v126 offset:23104
	ds_read_b128 v[168:171], v124 offset:64
	ds_read_b128 v[172:175], v124 offset:4672
	s_waitcnt vmcnt(15)
	ds_write_b128 v125, v[128:131] offset:36864
	s_waitcnt vmcnt(13)
	ds_write_b128 v125, v[132:135] offset:41472
	s_waitcnt vmcnt(11)
	ds_write_b128 v125, v[136:139] offset:46080
	s_waitcnt vmcnt(9)
	ds_write_b128 v125, v[144:147] offset:50688
	v_mfma_f32_32x32x16_bf16 v[16:31], v[156:159], v[164:167], v[16:31]
	s_waitcnt lgkmcnt(5)
	v_mfma_f32_32x32x16_bf16 v[48:63], v[152:155], v[168:171], v[48:63]
	ds_read_b128 v[128:131], v126 offset:18528
	ds_read_b128 v[132:135], v126 offset:23136
	ds_read_b128 v[136:139], v124 offset:96
	ds_read_b128 v[144:147], v124 offset:4704
	ds_write_b128 v125, v[80:83] offset:55296
	ds_write_b128 v125, v[92:95] offset:59904
	ds_write_b128 v125, v[140:143] offset:64512
	s_waitcnt vmcnt(8)
	ds_write_b128 v127, v[148:151] offset:13824
	v_mfma_f32_32x32x16_bf16 v[32:47], v[160:163], v[168:171], v[32:47]
	s_waitcnt lgkmcnt(12)
	v_mfma_f32_32x32x16_bf16 v[0:15], v[152:155], v[172:175], v[0:15]
	v_mfma_f32_32x32x16_bf16 v[16:31], v[160:163], v[172:175], v[16:31]
	s_waitcnt lgkmcnt(0)
	s_barrier
; template <bool SWAP>
; DI void gemm_tile(const bf16_t* __restrict__ A, int lda, const bf16_t* __restrict__ Bt, int ldb, int K, f32x16 (&acc)[2][2], bf16_t* As, bf16_t* Bs_unused) {
;     ...
;   auto step = [&](int buf, u32x4 (&ra)[4], u32x4 (&rb)[4], bool do_write, bool do_load, int tload) __attribute__((always_inline)) {
;     const bf16_t* pa = As + buf * 2 * GT_IMG + pao; const bf16_t* pb = As + buf * 2 * GT_IMG + pbo;
;     bf16_t* Ad = As + (buf ^ 1) * 2 * GT_IMG; bf16_t* Bd = Ad + GT_IMG;
;     bf16x8 F0[4], F1[4];
;     frag_read(F0, pa, pb, 0);
;     __builtin_amdgcn_sched_barrier(0);
;     frag_read(F1, pa, pb, 16);
;     mfma4(F0);
;     __builtin_amdgcn_sched_barrier(0);
;     frag_read(F0, pa, pb, 32);
;     mfma4(F1);
;     if (do_write) {
; #pragma unroll
;       for (int i = 0; i < 4; ++i) *(u32x4*)(Ad + (lr + 32 * i) * 72 + lc) = ra[i];
;     }
;     __builtin_amdgcn_sched_barrier(0);
;     frag_read(F1, pa, pb, 48);
;     mfma4(F0);
;     if (do_write) {
; #pragma unroll
;       for (int i = 0; i < 4; ++i) *(u32x4*)(Bd + (lr + 32 * i) * 72 + lc) = rb[i];
;     }
;     __builtin_amdgcn_sched_barrier(0);
;     mfma4(F1);
;     if (do_load) load_stage(ra, rb, tload);
;     __builtin_amdgcn_sched_barrier(0);
;   };
;   const int nk = K >> 6;
;   load_stage(ra0, rb0, 0); load_stage(ra1, rb1, 1);
;   __syncthreads();
;   write_stage(ra0, rb0, 0);
;   load_stage(ra0, rb0, 2);
;   __syncthreads();
;   for (int kt = 0; kt < nk; kt += 2) {
;     step(0, ra1, rb1, true, kt + 3 < nk, kt + 3);
;     __syncthreads();
;     step(1, ra0, rb0, kt + 2 < nk, kt + 4 < nk, kt + 4);
;     __syncthreads();
	ds_read_b128 v[152:155], v126 offset:55296
	ds_read_b128 v[156:159], v126 offset:59904
	ds_read_b128 v[160:163], v124 offset:36864
	ds_read_b128 v[164:167], v124 offset:41472
	v_mfma_f32_32x32x16_bf16 v[48:63], v[128:131], v[136:139], v[48:63]
	v_mfma_f32_32x32x16_bf16 v[32:47], v[132:135], v[136:139], v[32:47]
	v_mfma_f32_32x32x16_bf16 v[0:15], v[128:131], v[144:147], v[0:15]
	v_mfma_f32_32x32x16_bf16 v[16:31], v[132:135], v[144:147], v[16:31]
	global_load_dwordx4 v[80:83], v[104:105], off offset:384
	global_load_dwordx4 v[92:95], v[106:107], off offset:384
	global_load_dwordx4 v[128:131], v[108:109], off offset:384
	global_load_dwordx4 v[132:135], v[110:111], off offset:384
	global_load_dwordx4 v[136:139], v[112:113], off offset:384
	global_load_dwordx4 v[140:143], v[114:115], off offset:384
	global_load_dwordx4 v[144:147], v[116:117], off offset:384
	global_load_dwordx4 v[148:151], v[118:119], off offset:384
	s_waitcnt lgkmcnt(1)
	v_mfma_f32_32x32x16_bf16 v[48:63], v[152:155], v[160:163], v[48:63]
	v_mfma_f32_32x32x16_bf16 v[32:47], v[156:159], v[160:163], v[32:47]
	s_waitcnt lgkmcnt(0)
	v_mfma_f32_32x32x16_bf16 v[0:15], v[152:155], v[164:167], v[0:15]
	ds_read_b128 v[152:155], v126 offset:55328
	ds_read_b128 v[160:163], v126 offset:59936
	ds_read_b128 v[168:171], v124 offset:36896
	ds_read_b128 v[172:175], v124 offset:41504
	v_mfma_f32_32x32x16_bf16 v[16:31], v[156:159], v[164:167], v[16:31]
	s_waitcnt lgkmcnt(1)
	v_mfma_f32_32x32x16_bf16 v[48:63], v[152:155], v[168:171], v[48:63]
	v_mfma_f32_32x32x16_bf16 v[32:47], v[160:163], v[168:171], v[32:47]
	s_waitcnt lgkmcnt(0)
	v_mfma_f32_32x32x16_bf16 v[0:15], v[152:155], v[172:175], v[0:15]
	ds_read_b128 v[152:155], v126 offset:55360
	ds_read_b128 v[156:159], v126 offset:59968
	ds_read_b128 v[164:167], v124 offset:36928
	ds_read_b128 v[168:171], v124 offset:41536
	s_waitcnt vmcnt(15)
	ds_write_b128 v125, v[84:87]
	s_waitcnt vmcnt(13)
	ds_write_b128 v125, v[88:91] offset:4608
	s_waitcnt vmcnt(11)
	ds_write_b128 v125, v[96:99] offset:9216
	s_waitcnt vmcnt(9)
	ds_write_b128 v125, v[100:103] offset:13824
	v_mfma_f32_32x32x16_bf16 v[16:31], v[160:163], v[172:175], v[16:31]
	s_waitcnt lgkmcnt(5)
	v_mfma_f32_32x32x16_bf16 v[48:63], v[152:155], v[164:167], v[48:63]
	ds_read_b128 v[84:87], v126 offset:55392
	ds_read_b128 v[88:91], v126 offset:60000
	ds_read_b128 v[96:99], v124 offset:36960
	ds_read_b128 v[100:103], v124 offset:41568
	ds_write_b128 v125, v[64:67] offset:18432
	ds_write_b128 v125, v[68:71] offset:23040
	ds_write_b128 v125, v[72:75] offset:27648
	s_waitcnt vmcnt(8)
	ds_write_b128 v125, v[76:79] offset:32256
	v_mfma_f32_32x32x16_bf16 v[32:47], v[156:159], v[164:167], v[32:47]
	s_waitcnt lgkmcnt(12)
	v_mfma_f32_32x32x16_bf16 v[0:15], v[152:155], v[168:171], v[0:15]
	v_mfma_f32_32x32x16_bf16 v[16:31], v[156:159], v[168:171], v[16:31]
	s_waitcnt lgkmcnt(0)
	s_barrier
	ds_read_b128 v[152:155], v126 offset:18432
	ds_read_b128 v[156:159], v126 offset:23040
	ds_read_b128 v[160:163], v124
	ds_read_b128 v[164:167], v124 offset:4608
	v_mfma_f32_32x32x16_bf16 v[48:63], v[84:87], v[96:99], v[48:63]
	v_mfma_f32_32x32x16_bf16 v[32:47], v[88:91], v[96:99], v[32:47]
	v_mfma_f32_32x32x16_bf16 v[0:15], v[84:87], v[100:103], v[0:15]
	v_mfma_f32_32x32x16_bf16 v[16:31], v[88:91], v[100:103], v[16:31]
	global_load_dwordx4 v[64:67], v[104:105], off offset:512
	global_load_dwordx4 v[68:71], v[106:107], off offset:512
	global_load_dwordx4 v[72:75], v[108:109], off offset:512
	global_load_dwordx4 v[76:79], v[110:111], off offset:512
	global_load_dwordx4 v[84:87], v[112:113], off offset:512
	global_load_dwordx4 v[88:91], v[114:115], off offset:512
	global_load_dwordx4 v[96:99], v[116:117], off offset:512
	global_load_dwordx4 v[100:103], v[118:119], off offset:512
	s_waitcnt lgkmcnt(1)
	v_mfma_f32_32x32x16_bf16 v[48:63], v[152:155], v[160:163], v[48:63]
	v_mfma_f32_32x32x16_bf16 v[32:47], v[156:159], v[160:163], v[32:47]
	s_waitcnt lgkmcnt(0)
	v_mfma_f32_32x32x16_bf16 v[0:15], v[152:155], v[164:167], v[0:15]
	ds_read_b128 v[152:155], v126 offset:18464
	ds_read_b128 v[160:163], v126 offset:23072
	ds_read_b128 v[168:171], v124 offset:32
	ds_read_b128 v[172:175], v124 offset:4640
	v_mfma_f32_32x32x16_bf16 v[16:31], v[156:159], v[164:167], v[16:31]
	s_waitcnt lgkmcnt(1)
	v_mfma_f32_32x32x16_bf16 v[48:63], v[152:155], v[168:171], v[48:63]
	v_mfma_f32_32x32x16_bf16 v[32:47], v[160:163], v[168:171], v[32:47]
	s_waitcnt lgkmcnt(0)
	v_mfma_f32_32x32x16_bf16 v[0:15], v[152:155], v[172:175], v[0:15]
	ds_read_b128 v[152:155], v126 offset:18496
	ds_read_b128 v[156:159], v126 offset:23104
	ds_read_b128 v[164:167], v124 offset:64
	ds_read_b128 v[168:171], v124 offset:4672
	s_waitcnt vmcnt(15)
	ds_write_b128 v125, v[80:83] offset:36864
	s_waitcnt vmcnt(13)
	ds_write_b128 v125, v[128:131] offset:41472
	s_waitcnt vmcnt(11)
	ds_write_b128 v125, v[136:139] offset:46080
	s_waitcnt vmcnt(9)
	ds_write_b128 v125, v[144:147] offset:50688
	v_mfma_f32_32x32x16_bf16 v[16:31], v[160:163], v[172:175], v[16:31]
	s_waitcnt lgkmcnt(5)
	v_mfma_f32_32x32x16_bf16 v[48:63], v[152:155], v[164:167], v[48:63]
	ds_read_b128 v[80:83], v126 offset:18528
	ds_read_b128 v[128:131], v126 offset:23136
	ds_read_b128 v[136:139], v124 offset:96
	ds_read_b128 v[144:147], v124 offset:4704
	ds_write_b128 v125, v[92:95] offset:55296
	ds_write_b128 v125, v[132:135] offset:59904
	ds_write_b128 v125, v[140:143] offset:64512
	s_waitcnt vmcnt(8)
	ds_write_b128 v127, v[148:151] offset:13824
	v_mfma_f32_32x32x16_bf16 v[32:47], v[156:159], v[164:167], v[32:47]
	s_waitcnt lgkmcnt(12)
	v_mfma_f32_32x32x16_bf16 v[0:15], v[152:155], v[168:171], v[0:15]
	v_mfma_f32_32x32x16_bf16 v[16:31], v[156:159], v[168:171], v[16:31]
	s_waitcnt lgkmcnt(0)
	s_barrier
; template <bool SWAP>
; DI void gemm_tile(const bf16_t* __restrict__ A, int lda, const bf16_t* __restrict__ Bt, int ldb, int K, f32x16 (&acc)[2][2], bf16_t* As, bf16_t* Bs_unused) {
;     ...
;   auto step = [&](int buf, u32x4 (&ra)[4], u32x4 (&rb)[4], bool do_write, bool do_load, int tload) __attribute__((always_inline)) {
;     const bf16_t* pa = As + buf * 2 * GT_IMG + pao; const bf16_t* pb = As + buf * 2 * GT_IMG + pbo;
;     bf16_t* Ad = As + (buf ^ 1) * 2 * GT_IMG; bf16_t* Bd = Ad + GT_IMG;
;     bf16x8 F0[4], F1[4];
;     frag_read(F0, pa, pb, 0);
;     __builtin_amdgcn_sched_barrier(0);
;     frag_read(F1, pa, pb, 16);
;     mfma4(F0);
;     __builtin_amdgcn_sched_barrier(0);
;     frag_read(F0, pa, pb, 32);
;     mfma4(F1);
;     if (do_write) {
; #pragma unroll
;       for (int i = 0; i < 4; ++i) *(u32x4*)(Ad + (lr + 32 * i) * 72 + lc) = ra[i];
;     }
;     __builtin_amdgcn_sched_barrier(0);
;     frag_read(F1, pa, pb, 48);
;     mfma4(F0);
;     if (do_write) {
; #pragma unroll
;       for (int i = 0; i < 4; ++i) *(u32x4*)(Bd + (lr + 32 * i) * 72 + lc) = rb[i];
;     }
;     __builtin_amdgcn_sched_barrier(0);
;     mfma4(F1);
;     if (do_load) load_stage(ra, rb, tload);
;     __builtin_amdgcn_sched_barrier(0);
;   };
;   const int nk = K >> 6;
;   load_stage(ra0, rb0, 0); load_stage(ra1, rb1, 1);
;   __syncthreads();
;   write_stage(ra0, rb0, 0);
;   load_stage(ra0, rb0, 2);
;   __syncthreads();
;   for (int kt = 0; kt < nk; kt += 2) {
;     step(0, ra1, rb1, true, kt + 3 < nk, kt + 3);
;     __syncthreads();
;     step(1, ra0, rb0, kt + 2 < nk, kt + 4 < nk, kt + 4);
;     __syncthreads();
	ds_read_b128 v[152:155], v126 offset:55296
	ds_read_b128 v[156:159], v126 offset:59904
	ds_read_b128 v[160:163], v124 offset:36864
	ds_read_b128 v[164:167], v124 offset:41472
	v_mfma_f32_32x32x16_bf16 v[48:63], v[80:83], v[136:139], v[48:63]
	v_mfma_f32_32x32x16_bf16 v[32:47], v[128:131], v[136:139], v[32:47]
	v_mfma_f32_32x32x16_bf16 v[0:15], v[80:83], v[144:147], v[0:15]
	v_mfma_f32_32x32x16_bf16 v[16:31], v[128:131], v[144:147], v[16:31]
	global_load_dwordx4 v[80:83], v[104:105], off offset:640
	global_load_dwordx4 v[92:95], v[106:107], off offset:640
	global_load_dwordx4 v[128:131], v[108:109], off offset:640
	global_load_dwordx4 v[132:135], v[110:111], off offset:640
	global_load_dwordx4 v[136:139], v[112:113], off offset:640
	global_load_dwordx4 v[140:143], v[114:115], off offset:640
	global_load_dwordx4 v[144:147], v[116:117], off offset:640
	global_load_dwordx4 v[148:151], v[118:119], off offset:640
	s_waitcnt lgkmcnt(1)
	v_mfma_f32_32x32x16_bf16 v[48:63], v[152:155], v[160:163], v[48:63]
	v_mfma_f32_32x32x16_bf16 v[32:47], v[156:159], v[160:163], v[32:47]
	s_waitcnt lgkmcnt(0)
	v_mfma_f32_32x32x16_bf16 v[0:15], v[152:155], v[164:167], v[0:15]
	ds_read_b128 v[152:155], v126 offset:55328
	ds_read_b128 v[160:163], v126 offset:59936
	ds_read_b128 v[168:171], v124 offset:36896
	ds_read_b128 v[172:175], v124 offset:41504
	v_mfma_f32_32x32x16_bf16 v[16:31], v[156:159], v[164:167], v[16:31]
	s_waitcnt lgkmcnt(1)
	v_mfma_f32_32x32x16_bf16 v[48:63], v[152:155], v[168:171], v[48:63]
	v_mfma_f32_32x32x16_bf16 v[32:47], v[160:163], v[168:171], v[32:47]
	s_waitcnt lgkmcnt(0)
	v_mfma_f32_32x32x16_bf16 v[0:15], v[152:155], v[172:175], v[0:15]
	ds_read_b128 v[152:155], v126 offset:55360
	ds_read_b128 v[156:159], v126 offset:59968
	ds_read_b128 v[164:167], v124 offset:36928
	ds_read_b128 v[168:171], v124 offset:41536
	s_waitcnt vmcnt(15)
	ds_write_b128 v125, v[64:67]
	s_waitcnt vmcnt(13)
	ds_write_b128 v125, v[72:75] offset:4608
	s_waitcnt vmcnt(11)
	ds_write_b128 v125, v[84:87] offset:9216
	s_waitcnt vmcnt(9)
	ds_write_b128 v125, v[96:99] offset:13824
	v_mfma_f32_32x32x16_bf16 v[16:31], v[160:163], v[172:175], v[16:31]
	s_waitcnt lgkmcnt(5)
	v_mfma_f32_32x32x16_bf16 v[48:63], v[152:155], v[164:167], v[48:63]
	ds_read_b128 v[64:67], v126 offset:55392
	ds_read_b128 v[72:75], v126 offset:60000
	ds_read_b128 v[84:87], v124 offset:36960
	ds_read_b128 v[96:99], v124 offset:41568
	ds_write_b128 v125, v[68:71] offset:18432
	ds_write_b128 v125, v[76:79] offset:23040
	ds_write_b128 v125, v[88:91] offset:27648
	s_waitcnt vmcnt(8)
	ds_write_b128 v125, v[100:103] offset:32256
	v_mfma_f32_32x32x16_bf16 v[32:47], v[156:159], v[164:167], v[32:47]
	s_waitcnt lgkmcnt(12)
	v_mfma_f32_32x32x16_bf16 v[0:15], v[152:155], v[168:171], v[0:15]
	v_mfma_f32_32x32x16_bf16 v[16:31], v[156:159], v[168:171], v[16:31]
	s_waitcnt lgkmcnt(0)
	s_barrier
	ds_read_b128 v[152:155], v126 offset:18432
	ds_read_b128 v[156:159], v126 offset:23040
	ds_read_b128 v[160:163], v124
	ds_read_b128 v[164:167], v124 offset:4608
	v_mfma_f32_32x32x16_bf16 v[48:63], v[64:67], v[84:87], v[48:63]
	v_mfma_f32_32x32x16_bf16 v[32:47], v[72:75], v[84:87], v[32:47]
	v_mfma_f32_32x32x16_bf16 v[0:15], v[64:67], v[96:99], v[0:15]
	v_mfma_f32_32x32x16_bf16 v[16:31], v[72:75], v[96:99], v[16:31]
	global_load_dwordx4 v[64:67], v[104:105], off offset:768
	global_load_dwordx4 v[68:71], v[106:107], off offset:768
	global_load_dwordx4 v[72:75], v[108:109], off offset:768
	global_load_dwordx4 v[76:79], v[110:111], off offset:768
	global_load_dwordx4 v[84:87], v[112:113], off offset:768
	global_load_dwordx4 v[88:91], v[114:115], off offset:768
	global_load_dwordx4 v[96:99], v[116:117], off offset:768
	global_load_dwordx4 v[100:103], v[118:119], off offset:768
	s_waitcnt lgkmcnt(1)
	v_mfma_f32_32x32x16_bf16 v[48:63], v[152:155], v[160:163], v[48:63]
	v_mfma_f32_32x32x16_bf16 v[32:47], v[156:159], v[160:163], v[32:47]
	s_waitcnt lgkmcnt(0)
	v_mfma_f32_32x32x16_bf16 v[0:15], v[152:155], v[164:167], v[0:15]
	ds_read_b128 v[152:155], v126 offset:18464
	ds_read_b128 v[160:163], v126 offset:23072
	ds_read_b128 v[168:171], v124 offset:32
	ds_read_b128 v[172:175], v124 offset:4640
	v_mfma_f32_32x32x16_bf16 v[16:31], v[156:159], v[164:167], v[16:31]
	s_waitcnt lgkmcnt(1)
	v_mfma_f32_32x32x16_bf16 v[48:63], v[152:155], v[168:171], v[48:63]
	v_mfma_f32_32x32x16_bf16 v[32:47], v[160:163], v[168:171], v[32:47]
	s_waitcnt lgkmcnt(0)
	v_mfma_f32_32x32x16_bf16 v[0:15], v[152:155], v[172:175], v[0:15]
	ds_read_b128 v[152:155], v126 offset:18496
	ds_read_b128 v[156:159], v126 offset:23104
	ds_read_b128 v[164:167], v124 offset:64
	ds_read_b128 v[168:171], v124 offset:4672
	s_waitcnt vmcnt(15)
	ds_write_b128 v125, v[80:83] offset:36864
	s_waitcnt vmcnt(13)
	ds_write_b128 v125, v[128:131] offset:41472
	s_waitcnt vmcnt(11)
	ds_write_b128 v125, v[136:139] offset:46080
	s_waitcnt vmcnt(9)
	ds_write_b128 v125, v[144:147] offset:50688
	v_mfma_f32_32x32x16_bf16 v[16:31], v[160:163], v[172:175], v[16:31]
	s_waitcnt lgkmcnt(5)
	v_mfma_f32_32x32x16_bf16 v[48:63], v[152:155], v[164:167], v[48:63]
	ds_read_b128 v[80:83], v126 offset:18528
	ds_read_b128 v[128:131], v126 offset:23136
	ds_read_b128 v[136:139], v124 offset:96
	ds_read_b128 v[144:147], v124 offset:4704
	ds_write_b128 v125, v[92:95] offset:55296
	ds_write_b128 v125, v[132:135] offset:59904
	ds_write_b128 v125, v[140:143] offset:64512
	s_waitcnt vmcnt(8)
	ds_write_b128 v127, v[148:151] offset:13824
	v_mfma_f32_32x32x16_bf16 v[32:47], v[156:159], v[164:167], v[32:47]
	s_waitcnt lgkmcnt(12)
	v_mfma_f32_32x32x16_bf16 v[0:15], v[152:155], v[168:171], v[0:15]
	v_mfma_f32_32x32x16_bf16 v[16:31], v[156:159], v[168:171], v[16:31]
	s_waitcnt lgkmcnt(0)
	s_barrier
; template <bool SWAP>
; DI void gemm_tile(const bf16_t* __restrict__ A, int lda, const bf16_t* __restrict__ Bt, int ldb, int K, f32x16 (&acc)[2][2], bf16_t* As, bf16_t* Bs_unused) {
;     ...
;   auto step = [&](int buf, u32x4 (&ra)[4], u32x4 (&rb)[4], bool do_write, bool do_load, int tload) __attribute__((always_inline)) {
;     const bf16_t* pa = As + buf * 2 * GT_IMG + pao; const bf16_t* pb = As + buf * 2 * GT_IMG + pbo;
;     bf16_t* Ad = As + (buf ^ 1) * 2 * GT_IMG; bf16_t* Bd = Ad + GT_IMG;
;     bf16x8 F0[4], F1[4];
;     frag_read(F0, pa, pb, 0);
;     __builtin_amdgcn_sched_barrier(0);
;     frag_read(F1, pa, pb, 16);
;     mfma4(F0);
;     __builtin_amdgcn_sched_barrier(0);
;     frag_read(F0, pa, pb, 32);
;     mfma4(F1);
;     if (do_write) {
; #pragma unroll
;       for (int i = 0; i < 4; ++i) *(u32x4*)(Ad + (lr + 32 * i) * 72 + lc) = ra[i];
;     }
;     __builtin_amdgcn_sched_barrier(0);
;     frag_read(F1, pa, pb, 48);
;     mfma4(F0);
;     if (do_write) {
; #pragma unroll
;       for (int i = 0; i < 4; ++i) *(u32x4*)(Bd + (lr + 32 * i) * 72 + lc) = rb[i];
;     }
;     __builtin_amdgcn_sched_barrier(0);
;     mfma4(F1);
;     if (do_load) load_stage(ra, rb, tload);
;     __builtin_amdgcn_sched_barrier(0);
;   };
;   const int nk = K >> 6;
;   load_stage(ra0, rb0, 0); load_stage(ra1, rb1, 1);
;   __syncthreads();
;   write_stage(ra0, rb0, 0);
;   load_stage(ra0, rb0, 2);
;   __syncthreads();
;   for (int kt = 0; kt < nk; kt += 2) {
;     step(0, ra1, rb1, true, kt + 3 < nk, kt + 3);
;     __syncthreads();
;     step(1, ra0, rb0, kt + 2 < nk, kt + 4 < nk, kt + 4);
;     __syncthreads();
	ds_read_b128 v[152:155], v126 offset:55296
	ds_read_b128 v[156:159], v126 offset:59904
	ds_read_b128 v[160:163], v124 offset:36864
	ds_read_b128 v[164:167], v124 offset:41472
	v_mfma_f32_32x32x16_bf16 v[48:63], v[80:83], v[136:139], v[48:63]
	v_mfma_f32_32x32x16_bf16 v[32:47], v[128:131], v[136:139], v[32:47]
	v_mfma_f32_32x32x16_bf16 v[0:15], v[80:83], v[144:147], v[0:15]
	v_mfma_f32_32x32x16_bf16 v[16:31], v[128:131], v[144:147], v[16:31]
	global_load_dwordx4 v[80:83], v[104:105], off offset:896
	global_load_dwordx4 v[92:95], v[106:107], off offset:896
	global_load_dwordx4 v[128:131], v[108:109], off offset:896
	global_load_dwordx4 v[132:135], v[110:111], off offset:896
	global_load_dwordx4 v[136:139], v[112:113], off offset:896
	global_load_dwordx4 v[140:143], v[114:115], off offset:896
	global_load_dwordx4 v[144:147], v[116:117], off offset:896
	global_load_dwordx4 v[148:151], v[118:119], off offset:896
	s_waitcnt lgkmcnt(1)
	v_mfma_f32_32x32x16_bf16 v[48:63], v[152:155], v[160:163], v[48:63]
	v_mfma_f32_32x32x16_bf16 v[32:47], v[156:159], v[160:163], v[32:47]
	s_waitcnt lgkmcnt(0)
	v_mfma_f32_32x32x16_bf16 v[0:15], v[152:155], v[164:167], v[0:15]
	ds_read_b128 v[152:155], v126 offset:55328
	ds_read_b128 v[160:163], v126 offset:59936
	ds_read_b128 v[168:171], v124 offset:36896
	ds_read_b128 v[172:175], v124 offset:41504
	v_mfma_f32_32x32x16_bf16 v[16:31], v[156:159], v[164:167], v[16:31]
	s_waitcnt lgkmcnt(1)
	v_mfma_f32_32x32x16_bf16 v[48:63], v[152:155], v[168:171], v[48:63]
	v_mfma_f32_32x32x16_bf16 v[32:47], v[160:163], v[168:171], v[32:47]
	s_waitcnt lgkmcnt(0)
	v_mfma_f32_32x32x16_bf16 v[0:15], v[152:155], v[172:175], v[0:15]
	ds_read_b128 v[152:155], v126 offset:55360
	ds_read_b128 v[156:159], v126 offset:59968
	ds_read_b128 v[164:167], v124 offset:36928
	ds_read_b128 v[168:171], v124 offset:41536
	s_waitcnt vmcnt(15)
	ds_write_b128 v125, v[64:67]
	s_waitcnt vmcnt(13)
	ds_write_b128 v125, v[72:75] offset:4608
	s_waitcnt vmcnt(11)
	ds_write_b128 v125, v[84:87] offset:9216
	s_waitcnt vmcnt(9)
	ds_write_b128 v125, v[96:99] offset:13824
	v_mfma_f32_32x32x16_bf16 v[16:31], v[160:163], v[172:175], v[16:31]
	s_waitcnt lgkmcnt(5)
	v_mfma_f32_32x32x16_bf16 v[48:63], v[152:155], v[164:167], v[48:63]
	ds_read_b128 v[64:67], v126 offset:55392
	ds_read_b128 v[72:75], v126 offset:60000
	ds_read_b128 v[84:87], v124 offset:36960
	ds_read_b128 v[96:99], v124 offset:41568
	ds_write_b128 v125, v[68:71] offset:18432
	ds_write_b128 v125, v[76:79] offset:23040
	ds_write_b128 v125, v[88:91] offset:27648
	s_waitcnt vmcnt(8)
	ds_write_b128 v125, v[100:103] offset:32256
	v_mfma_f32_32x32x16_bf16 v[32:47], v[156:159], v[164:167], v[32:47]
	s_waitcnt lgkmcnt(12)
	v_mfma_f32_32x32x16_bf16 v[0:15], v[152:155], v[168:171], v[0:15]
	v_mfma_f32_32x32x16_bf16 v[16:31], v[156:159], v[168:171], v[16:31]
	s_waitcnt lgkmcnt(0)
	s_barrier
	ds_read_b128 v[152:155], v126 offset:18432
	ds_read_b128 v[156:159], v126 offset:23040
	ds_read_b128 v[160:163], v124
	ds_read_b128 v[164:167], v124 offset:4608
	v_mfma_f32_32x32x16_bf16 v[48:63], v[64:67], v[84:87], v[48:63]
	v_mfma_f32_32x32x16_bf16 v[32:47], v[72:75], v[84:87], v[32:47]
	v_mfma_f32_32x32x16_bf16 v[0:15], v[64:67], v[96:99], v[0:15]
	v_mfma_f32_32x32x16_bf16 v[16:31], v[72:75], v[96:99], v[16:31]
	global_load_dwordx4 v[64:67], v[104:105], off offset:1024
	global_load_dwordx4 v[68:71], v[106:107], off offset:1024
	global_load_dwordx4 v[72:75], v[108:109], off offset:1024
	global_load_dwordx4 v[76:79], v[110:111], off offset:1024
	global_load_dwordx4 v[84:87], v[112:113], off offset:1024
	global_load_dwordx4 v[88:91], v[114:115], off offset:1024
	global_load_dwordx4 v[96:99], v[116:117], off offset:1024
	global_load_dwordx4 v[100:103], v[118:119], off offset:1024
	s_waitcnt lgkmcnt(1)
	v_mfma_f32_32x32x16_bf16 v[48:63], v[152:155], v[160:163], v[48:63]
	v_mfma_f32_32x32x16_bf16 v[32:47], v[156:159], v[160:163], v[32:47]
	s_waitcnt lgkmcnt(0)
	v_mfma_f32_32x32x16_bf16 v[0:15], v[152:155], v[164:167], v[0:15]
	ds_read_b128 v[152:155], v126 offset:18464
	ds_read_b128 v[160:163], v126 offset:23072
	ds_read_b128 v[168:171], v124 offset:32
	ds_read_b128 v[172:175], v124 offset:4640
	v_mfma_f32_32x32x16_bf16 v[16:31], v[156:159], v[164:167], v[16:31]
	s_waitcnt lgkmcnt(1)
	v_mfma_f32_32x32x16_bf16 v[48:63], v[152:155], v[168:171], v[48:63]
	v_mfma_f32_32x32x16_bf16 v[32:47], v[160:163], v[168:171], v[32:47]
	s_waitcnt lgkmcnt(0)
	v_mfma_f32_32x32x16_bf16 v[0:15], v[152:155], v[172:175], v[0:15]
	ds_read_b128 v[152:155], v126 offset:18496
	ds_read_b128 v[156:159], v126 offset:23104
	ds_read_b128 v[164:167], v124 offset:64
	ds_read_b128 v[168:171], v124 offset:4672
	s_waitcnt vmcnt(15)
	ds_write_b128 v125, v[80:83] offset:36864
	s_waitcnt vmcnt(13)
	ds_write_b128 v125, v[128:131] offset:41472
	s_waitcnt vmcnt(11)
	ds_write_b128 v125, v[136:139] offset:46080
	s_waitcnt vmcnt(9)
	ds_write_b128 v125, v[144:147] offset:50688
	v_mfma_f32_32x32x16_bf16 v[16:31], v[160:163], v[172:175], v[16:31]
	s_waitcnt lgkmcnt(5)
	v_mfma_f32_32x32x16_bf16 v[48:63], v[152:155], v[164:167], v[48:63]
	ds_read_b128 v[80:83], v126 offset:18528
	ds_read_b128 v[128:131], v126 offset:23136
	ds_read_b128 v[136:139], v124 offset:96
	ds_read_b128 v[144:147], v124 offset:4704
	ds_write_b128 v125, v[92:95] offset:55296
	ds_write_b128 v125, v[132:135] offset:59904
	ds_write_b128 v125, v[140:143] offset:64512
	s_waitcnt vmcnt(8)
	ds_write_b128 v127, v[148:151] offset:13824
	v_mfma_f32_32x32x16_bf16 v[32:47], v[156:159], v[164:167], v[32:47]
	s_waitcnt lgkmcnt(12)
	v_mfma_f32_32x32x16_bf16 v[0:15], v[152:155], v[168:171], v[0:15]
	v_mfma_f32_32x32x16_bf16 v[16:31], v[156:159], v[168:171], v[16:31]
	s_waitcnt lgkmcnt(0)
	s_barrier
; template <bool SWAP>
; DI void gemm_tile(const bf16_t* __restrict__ A, int lda, const bf16_t* __restrict__ Bt, int ldb, int K, f32x16 (&acc)[2][2], bf16_t* As, bf16_t* Bs_unused) {
;     ...
;   auto step = [&](int buf, u32x4 (&ra)[4], u32x4 (&rb)[4], bool do_write, bool do_load, int tload) __attribute__((always_inline)) {
;     const bf16_t* pa = As + buf * 2 * GT_IMG + pao; const bf16_t* pb = As + buf * 2 * GT_IMG + pbo;
;     bf16_t* Ad = As + (buf ^ 1) * 2 * GT_IMG; bf16_t* Bd = Ad + GT_IMG;
;     bf16x8 F0[4], F1[4];
;     frag_read(F0, pa, pb, 0);
;     __builtin_amdgcn_sched_barrier(0);
;     frag_read(F1, pa, pb, 16);
;     mfma4(F0);
;     __builtin_amdgcn_sched_barrier(0);
;     frag_read(F0, pa, pb, 32);
;     mfma4(F1);
;     if (do_write) {
; #pragma unroll
;       for (int i = 0; i < 4; ++i) *(u32x4*)(Ad + (lr + 32 * i) * 72 + lc) = ra[i];
;     }
;     __builtin_amdgcn_sched_barrier(0);
;     frag_read(F1, pa, pb, 48);
;     mfma4(F0);
;     if (do_write) {
; #pragma unroll
;       for (int i = 0; i < 4; ++i) *(u32x4*)(Bd + (lr + 32 * i) * 72 + lc) = rb[i];
;     }
;     __builtin_amdgcn_sched_barrier(0);
;     mfma4(F1);
;     if (do_load) load_stage(ra, rb, tload);
;     __builtin_amdgcn_sched_barrier(0);
;   };
;   const int nk = K >> 6;
;   load_stage(ra0, rb0, 0); load_stage(ra1, rb1, 1);
;   __syncthreads();
;   write_stage(ra0, rb0, 0);
;   load_stage(ra0, rb0, 2);
;   __syncthreads();
;   for (int kt = 0; kt < nk; kt += 2) {
;     step(0, ra1, rb1, true, kt + 3 < nk, kt + 3);
;     __syncthreads();
;     step(1, ra0, rb0, kt + 2 < nk, kt + 4 < nk, kt + 4);
;     __syncthreads();
	ds_read_b128 v[152:155], v126 offset:55296
	ds_read_b128 v[156:159], v126 offset:59904
	ds_read_b128 v[160:163], v124 offset:36864
	ds_read_b128 v[164:167], v124 offset:41472
	v_mfma_f32_32x32x16_bf16 v[48:63], v[80:83], v[136:139], v[48:63]
	v_mfma_f32_32x32x16_bf16 v[32:47], v[128:131], v[136:139], v[32:47]
	v_mfma_f32_32x32x16_bf16 v[0:15], v[80:83], v[144:147], v[0:15]
	v_mfma_f32_32x32x16_bf16 v[16:31], v[128:131], v[144:147], v[16:31]
	global_load_dwordx4 v[80:83], v[104:105], off offset:1152
	global_load_dwordx4 v[92:95], v[106:107], off offset:1152
	global_load_dwordx4 v[128:131], v[108:109], off offset:1152
	global_load_dwordx4 v[132:135], v[110:111], off offset:1152
	global_load_dwordx4 v[136:139], v[112:113], off offset:1152
	global_load_dwordx4 v[140:143], v[114:115], off offset:1152
	global_load_dwordx4 v[144:147], v[116:117], off offset:1152
	global_load_dwordx4 v[148:151], v[118:119], off offset:1152
	s_waitcnt lgkmcnt(1)
	v_mfma_f32_32x32x16_bf16 v[48:63], v[152:155], v[160:163], v[48:63]
	v_mfma_f32_32x32x16_bf16 v[32:47], v[156:159], v[160:163], v[32:47]
	s_waitcnt lgkmcnt(0)
	v_mfma_f32_32x32x16_bf16 v[0:15], v[152:155], v[164:167], v[0:15]
	ds_read_b128 v[152:155], v126 offset:55328
	ds_read_b128 v[160:163], v126 offset:59936
	ds_read_b128 v[168:171], v124 offset:36896
	ds_read_b128 v[172:175], v124 offset:41504
	v_mfma_f32_32x32x16_bf16 v[16:31], v[156:159], v[164:167], v[16:31]
	s_waitcnt lgkmcnt(1)
	v_mfma_f32_32x32x16_bf16 v[48:63], v[152:155], v[168:171], v[48:63]
	v_mfma_f32_32x32x16_bf16 v[32:47], v[160:163], v[168:171], v[32:47]
	s_waitcnt lgkmcnt(0)
	v_mfma_f32_32x32x16_bf16 v[0:15], v[152:155], v[172:175], v[0:15]
	ds_read_b128 v[152:155], v126 offset:55360
	ds_read_b128 v[156:159], v126 offset:59968
	ds_read_b128 v[164:167], v124 offset:36928
	ds_read_b128 v[168:171], v124 offset:41536
	s_waitcnt vmcnt(15)
	ds_write_b128 v125, v[64:67]
	s_waitcnt vmcnt(13)
	ds_write_b128 v125, v[72:75] offset:4608
	s_waitcnt vmcnt(11)
	ds_write_b128 v125, v[84:87] offset:9216
	s_waitcnt vmcnt(9)
	ds_write_b128 v125, v[96:99] offset:13824
	v_mfma_f32_32x32x16_bf16 v[16:31], v[160:163], v[172:175], v[16:31]
	s_waitcnt lgkmcnt(5)
	v_mfma_f32_32x32x16_bf16 v[48:63], v[152:155], v[164:167], v[48:63]
	ds_read_b128 v[64:67], v126 offset:55392
	ds_read_b128 v[72:75], v126 offset:60000
	ds_read_b128 v[84:87], v124 offset:36960
	ds_read_b128 v[96:99], v124 offset:41568
	ds_write_b128 v125, v[68:71] offset:18432
	ds_write_b128 v125, v[76:79] offset:23040
	ds_write_b128 v125, v[88:91] offset:27648
	s_waitcnt vmcnt(8)
	ds_write_b128 v125, v[100:103] offset:32256
	v_mfma_f32_32x32x16_bf16 v[32:47], v[156:159], v[164:167], v[32:47]
	s_waitcnt lgkmcnt(12)
	v_mfma_f32_32x32x16_bf16 v[0:15], v[152:155], v[168:171], v[0:15]
	v_mfma_f32_32x32x16_bf16 v[16:31], v[156:159], v[168:171], v[16:31]
	s_waitcnt lgkmcnt(0)
	s_barrier
	ds_read_b128 v[152:155], v126 offset:18432
	ds_read_b128 v[156:159], v126 offset:23040
	ds_read_b128 v[160:163], v124
	ds_read_b128 v[164:167], v124 offset:4608
	v_mfma_f32_32x32x16_bf16 v[48:63], v[64:67], v[84:87], v[48:63]
	v_mfma_f32_32x32x16_bf16 v[32:47], v[72:75], v[84:87], v[32:47]
	v_mfma_f32_32x32x16_bf16 v[0:15], v[64:67], v[96:99], v[0:15]
	v_mfma_f32_32x32x16_bf16 v[16:31], v[72:75], v[96:99], v[16:31]
	global_load_dwordx4 v[64:67], v[104:105], off offset:1280
	global_load_dwordx4 v[68:71], v[106:107], off offset:1280
	global_load_dwordx4 v[72:75], v[108:109], off offset:1280
	global_load_dwordx4 v[76:79], v[110:111], off offset:1280
	global_load_dwordx4 v[84:87], v[112:113], off offset:1280
	global_load_dwordx4 v[88:91], v[114:115], off offset:1280
	global_load_dwordx4 v[96:99], v[116:117], off offset:1280
	global_load_dwordx4 v[100:103], v[118:119], off offset:1280
	s_waitcnt lgkmcnt(1)
	v_mfma_f32_32x32x16_bf16 v[48:63], v[152:155], v[160:163], v[48:63]
	v_mfma_f32_32x32x16_bf16 v[32:47], v[156:159], v[160:163], v[32:47]
	s_waitcnt lgkmcnt(0)
	v_mfma_f32_32x32x16_bf16 v[0:15], v[152:155], v[164:167], v[0:15]
	ds_read_b128 v[152:155], v126 offset:18464
	ds_read_b128 v[160:163], v126 offset:23072
	ds_read_b128 v[168:171], v124 offset:32
	ds_read_b128 v[172:175], v124 offset:4640
	v_mfma_f32_32x32x16_bf16 v[16:31], v[156:159], v[164:167], v[16:31]
	s_waitcnt lgkmcnt(1)
	v_mfma_f32_32x32x16_bf16 v[48:63], v[152:155], v[168:171], v[48:63]
	v_mfma_f32_32x32x16_bf16 v[32:47], v[160:163], v[168:171], v[32:47]
	s_waitcnt lgkmcnt(0)
	v_mfma_f32_32x32x16_bf16 v[0:15], v[152:155], v[172:175], v[0:15]
	ds_read_b128 v[152:155], v126 offset:18496
	ds_read_b128 v[156:159], v126 offset:23104
	ds_read_b128 v[164:167], v124 offset:64
	ds_read_b128 v[168:171], v124 offset:4672
	s_waitcnt vmcnt(15)
	ds_write_b128 v125, v[80:83] offset:36864
	s_waitcnt vmcnt(13)
	ds_write_b128 v125, v[128:131] offset:41472
	s_waitcnt vmcnt(11)
	ds_write_b128 v125, v[136:139] offset:46080
	s_waitcnt vmcnt(9)
	ds_write_b128 v125, v[144:147] offset:50688
	v_mfma_f32_32x32x16_bf16 v[16:31], v[160:163], v[172:175], v[16:31]
	s_waitcnt lgkmcnt(5)
	v_mfma_f32_32x32x16_bf16 v[48:63], v[152:155], v[164:167], v[48:63]
	ds_read_b128 v[80:83], v126 offset:18528
	ds_read_b128 v[128:131], v126 offset:23136
	ds_read_b128 v[136:139], v124 offset:96
	ds_read_b128 v[144:147], v124 offset:4704
	ds_write_b128 v125, v[92:95] offset:55296
	ds_write_b128 v125, v[132:135] offset:59904
	ds_write_b128 v125, v[140:143] offset:64512
	s_waitcnt vmcnt(8)
	ds_write_b128 v127, v[148:151] offset:13824
	v_mfma_f32_32x32x16_bf16 v[32:47], v[156:159], v[164:167], v[32:47]
	s_waitcnt lgkmcnt(12)
	v_mfma_f32_32x32x16_bf16 v[0:15], v[152:155], v[168:171], v[0:15]
	v_mfma_f32_32x32x16_bf16 v[16:31], v[156:159], v[168:171], v[16:31]
	s_waitcnt lgkmcnt(0)
	s_barrier
; template <bool SWAP>
; DI void gemm_tile(const bf16_t* __restrict__ A, int lda, const bf16_t* __restrict__ Bt, int ldb, int K, f32x16 (&acc)[2][2], bf16_t* As, bf16_t* Bs_unused) {
;     ...
;   auto step = [&](int buf, u32x4 (&ra)[4], u32x4 (&rb)[4], bool do_write, bool do_load, int tload) __attribute__((always_inline)) {
;     const bf16_t* pa = As + buf * 2 * GT_IMG + pao; const bf16_t* pb = As + buf * 2 * GT_IMG + pbo;
;     bf16_t* Ad = As + (buf ^ 1) * 2 * GT_IMG; bf16_t* Bd = Ad + GT_IMG;
;     bf16x8 F0[4], F1[4];
;     frag_read(F0, pa, pb, 0);
;     __builtin_amdgcn_sched_barrier(0);
;     frag_read(F1, pa, pb, 16);
;     mfma4(F0);
;     __builtin_amdgcn_sched_barrier(0);
;     frag_read(F0, pa, pb, 32);
;     mfma4(F1);
;     if (do_write) {
; #pragma unroll
;       for (int i = 0; i < 4; ++i) *(u32x4*)(Ad + (lr + 32 * i) * 72 + lc) = ra[i];
;     }
;     __builtin_amdgcn_sched_barrier(0);
;     frag_read(F1, pa, pb, 48);
;     mfma4(F0);
;     if (do_write) {
; #pragma unroll
;       for (int i = 0; i < 4; ++i) *(u32x4*)(Bd + (lr + 32 * i) * 72 + lc) = rb[i];
;     }
;     __builtin_amdgcn_sched_barrier(0);
;     mfma4(F1);
;     if (do_load) load_stage(ra, rb, tload);
;     __builtin_amdgcn_sched_barrier(0);
;   };
;   const int nk = K >> 6;
;   load_stage(ra0, rb0, 0); load_stage(ra1, rb1, 1);
;   __syncthreads();
;   write_stage(ra0, rb0, 0);
;   load_stage(ra0, rb0, 2);
;   __syncthreads();
;   for (int kt = 0; kt < nk; kt += 2) {
;     step(0, ra1, rb1, true, kt + 3 < nk, kt + 3);
;     __syncthreads();
;     step(1, ra0, rb0, kt + 2 < nk, kt + 4 < nk, kt + 4);
;     __syncthreads();
	ds_read_b128 v[152:155], v126 offset:55296
	ds_read_b128 v[156:159], v126 offset:59904
	ds_read_b128 v[160:163], v124 offset:36864
	ds_read_b128 v[164:167], v124 offset:41472
	v_mfma_f32_32x32x16_bf16 v[48:63], v[80:83], v[136:139], v[48:63]
	v_mfma_f32_32x32x16_bf16 v[32:47], v[128:131], v[136:139], v[32:47]
	v_mfma_f32_32x32x16_bf16 v[0:15], v[80:83], v[144:147], v[0:15]
	v_mfma_f32_32x32x16_bf16 v[16:31], v[128:131], v[144:147], v[16:31]
	global_load_dwordx4 v[80:83], v[104:105], off offset:1408
	global_load_dwordx4 v[92:95], v[106:107], off offset:1408
	global_load_dwordx4 v[128:131], v[108:109], off offset:1408
	global_load_dwordx4 v[132:135], v[110:111], off offset:1408
	global_load_dwordx4 v[136:139], v[112:113], off offset:1408
	global_load_dwordx4 v[140:143], v[114:115], off offset:1408
	global_load_dwordx4 v[144:147], v[116:117], off offset:1408
	global_load_dwordx4 v[148:151], v[118:119], off offset:1408
	s_waitcnt lgkmcnt(1)
	v_mfma_f32_32x32x16_bf16 v[48:63], v[152:155], v[160:163], v[48:63]
	v_mfma_f32_32x32x16_bf16 v[32:47], v[156:159], v[160:163], v[32:47]
	s_waitcnt lgkmcnt(0)
	v_mfma_f32_32x32x16_bf16 v[0:15], v[152:155], v[164:167], v[0:15]
	ds_read_b128 v[152:155], v126 offset:55328
	ds_read_b128 v[160:163], v126 offset:59936
	ds_read_b128 v[168:171], v124 offset:36896
	ds_read_b128 v[172:175], v124 offset:41504
	v_mfma_f32_32x32x16_bf16 v[16:31], v[156:159], v[164:167], v[16:31]
	s_waitcnt lgkmcnt(1)
	v_mfma_f32_32x32x16_bf16 v[48:63], v[152:155], v[168:171], v[48:63]
	v_mfma_f32_32x32x16_bf16 v[32:47], v[160:163], v[168:171], v[32:47]
	s_waitcnt lgkmcnt(0)
	v_mfma_f32_32x32x16_bf16 v[0:15], v[152:155], v[172:175], v[0:15]
	ds_read_b128 v[152:155], v126 offset:55360
	ds_read_b128 v[156:159], v126 offset:59968
	ds_read_b128 v[164:167], v124 offset:36928
	ds_read_b128 v[168:171], v124 offset:41536
	s_waitcnt vmcnt(15)
	ds_write_b128 v125, v[64:67]
	s_waitcnt vmcnt(13)
	ds_write_b128 v125, v[72:75] offset:4608
	s_waitcnt vmcnt(11)
	ds_write_b128 v125, v[84:87] offset:9216
	s_waitcnt vmcnt(9)
	ds_write_b128 v125, v[96:99] offset:13824
	v_mfma_f32_32x32x16_bf16 v[16:31], v[160:163], v[172:175], v[16:31]
	s_waitcnt lgkmcnt(5)
	v_mfma_f32_32x32x16_bf16 v[48:63], v[152:155], v[164:167], v[48:63]
	ds_read_b128 v[64:67], v126 offset:55392
	ds_read_b128 v[72:75], v126 offset:60000
	ds_read_b128 v[84:87], v124 offset:36960
	ds_read_b128 v[96:99], v124 offset:41568
	ds_write_b128 v125, v[68:71] offset:18432
	ds_write_b128 v125, v[76:79] offset:23040
	ds_write_b128 v125, v[88:91] offset:27648
	s_waitcnt vmcnt(8)
	ds_write_b128 v125, v[100:103] offset:32256
	v_mfma_f32_32x32x16_bf16 v[32:47], v[156:159], v[164:167], v[32:47]
	s_waitcnt lgkmcnt(12)
	v_mfma_f32_32x32x16_bf16 v[0:15], v[152:155], v[168:171], v[0:15]
	v_mfma_f32_32x32x16_bf16 v[16:31], v[156:159], v[168:171], v[16:31]
	s_waitcnt lgkmcnt(0)
	s_barrier
	ds_read_b128 v[152:155], v126 offset:18432
	ds_read_b128 v[156:159], v126 offset:23040
	ds_read_b128 v[160:163], v124
	ds_read_b128 v[164:167], v124 offset:4608
	v_mfma_f32_32x32x16_bf16 v[48:63], v[64:67], v[84:87], v[48:63]
	v_mfma_f32_32x32x16_bf16 v[32:47], v[72:75], v[84:87], v[32:47]
	v_mfma_f32_32x32x16_bf16 v[0:15], v[64:67], v[96:99], v[0:15]
	v_mfma_f32_32x32x16_bf16 v[16:31], v[72:75], v[96:99], v[16:31]
	global_load_dwordx4 v[64:67], v[104:105], off offset:1536
	global_load_dwordx4 v[68:71], v[106:107], off offset:1536
	global_load_dwordx4 v[72:75], v[108:109], off offset:1536
	global_load_dwordx4 v[76:79], v[110:111], off offset:1536
	global_load_dwordx4 v[84:87], v[112:113], off offset:1536
	global_load_dwordx4 v[88:91], v[114:115], off offset:1536
	global_load_dwordx4 v[96:99], v[116:117], off offset:1536
	global_load_dwordx4 v[100:103], v[118:119], off offset:1536
	s_waitcnt lgkmcnt(1)
	v_mfma_f32_32x32x16_bf16 v[48:63], v[152:155], v[160:163], v[48:63]
	v_mfma_f32_32x32x16_bf16 v[32:47], v[156:159], v[160:163], v[32:47]
	s_waitcnt lgkmcnt(0)
	v_mfma_f32_32x32x16_bf16 v[0:15], v[152:155], v[164:167], v[0:15]
	ds_read_b128 v[152:155], v126 offset:18464
	ds_read_b128 v[160:163], v126 offset:23072
	ds_read_b128 v[168:171], v124 offset:32
	ds_read_b128 v[172:175], v124 offset:4640
	v_mfma_f32_32x32x16_bf16 v[16:31], v[156:159], v[164:167], v[16:31]
	s_waitcnt lgkmcnt(1)
	v_mfma_f32_32x32x16_bf16 v[48:63], v[152:155], v[168:171], v[48:63]
	v_mfma_f32_32x32x16_bf16 v[32:47], v[160:163], v[168:171], v[32:47]
	s_waitcnt lgkmcnt(0)
	v_mfma_f32_32x32x16_bf16 v[0:15], v[152:155], v[172:175], v[0:15]
	ds_read_b128 v[152:155], v126 offset:18496
	ds_read_b128 v[156:159], v126 offset:23104
	ds_read_b128 v[164:167], v124 offset:64
	ds_read_b128 v[168:171], v124 offset:4672
	s_waitcnt vmcnt(15)
	ds_write_b128 v125, v[80:83] offset:36864
	s_waitcnt vmcnt(13)
	ds_write_b128 v125, v[128:131] offset:41472
	s_waitcnt vmcnt(11)
	ds_write_b128 v125, v[136:139] offset:46080
	s_waitcnt vmcnt(9)
	ds_write_b128 v125, v[144:147] offset:50688
	v_mfma_f32_32x32x16_bf16 v[16:31], v[160:163], v[172:175], v[16:31]
	s_waitcnt lgkmcnt(5)
	v_mfma_f32_32x32x16_bf16 v[48:63], v[152:155], v[164:167], v[48:63]
	ds_read_b128 v[80:83], v126 offset:18528
	ds_read_b128 v[128:131], v126 offset:23136
	ds_read_b128 v[136:139], v124 offset:96
	ds_read_b128 v[144:147], v124 offset:4704
	ds_write_b128 v125, v[92:95] offset:55296
	ds_write_b128 v125, v[132:135] offset:59904
	ds_write_b128 v125, v[140:143] offset:64512
	s_waitcnt vmcnt(8)
	ds_write_b128 v127, v[148:151] offset:13824
	v_mfma_f32_32x32x16_bf16 v[32:47], v[156:159], v[164:167], v[32:47]
	s_waitcnt lgkmcnt(12)
	v_mfma_f32_32x32x16_bf16 v[0:15], v[152:155], v[168:171], v[0:15]
	v_mfma_f32_32x32x16_bf16 v[16:31], v[156:159], v[168:171], v[16:31]
	s_waitcnt lgkmcnt(0)
	s_barrier
; template <bool SWAP>
; DI void gemm_tile(const bf16_t* __restrict__ A, int lda, const bf16_t* __restrict__ Bt, int ldb, int K, f32x16 (&acc)[2][2], bf16_t* As, bf16_t* Bs_unused) {
;     ...
;   auto step = [&](int buf, u32x4 (&ra)[4], u32x4 (&rb)[4], bool do_write, bool do_load, int tload) __attribute__((always_inline)) {
;     const bf16_t* pa = As + buf * 2 * GT_IMG + pao; const bf16_t* pb = As + buf * 2 * GT_IMG + pbo;
;     bf16_t* Ad = As + (buf ^ 1) * 2 * GT_IMG; bf16_t* Bd = Ad + GT_IMG;
;     bf16x8 F0[4], F1[4];
;     frag_read(F0, pa, pb, 0);
;     __builtin_amdgcn_sched_barrier(0);
;     frag_read(F1, pa, pb, 16);
;     mfma4(F0);
;     __builtin_amdgcn_sched_barrier(0);
;     frag_read(F0, pa, pb, 32);
;     mfma4(F1);
;     if (do_write) {
; #pragma unroll
;       for (int i = 0; i < 4; ++i) *(u32x4*)(Ad + (lr + 32 * i) * 72 + lc) = ra[i];
;     }
;     __builtin_amdgcn_sched_barrier(0);
;     frag_read(F1, pa, pb, 48);
;     mfma4(F0);
;     if (do_write) {
; #pragma unroll
;       for (int i = 0; i < 4; ++i) *(u32x4*)(Bd + (lr + 32 * i) * 72 + lc) = rb[i];
;     }
;     __builtin_amdgcn_sched_barrier(0);
;     mfma4(F1);
;     if (do_load) load_stage(ra, rb, tload);
;     __builtin_amdgcn_sched_barrier(0);
;   };
;   const int nk = K >> 6;
;   load_stage(ra0, rb0, 0); load_stage(ra1, rb1, 1);
;   __syncthreads();
;   write_stage(ra0, rb0, 0);
;   load_stage(ra0, rb0, 2);
;   __syncthreads();
;   for (int kt = 0; kt < nk; kt += 2) {
;     step(0, ra1, rb1, true, kt + 3 < nk, kt + 3);
;     __syncthreads();
;     step(1, ra0, rb0, kt + 2 < nk, kt + 4 < nk, kt + 4);
;     __syncthreads();
	ds_read_b128 v[152:155], v126 offset:55296
	ds_read_b128 v[156:159], v126 offset:59904
	ds_read_b128 v[160:163], v124 offset:36864
	ds_read_b128 v[164:167], v124 offset:41472
	v_mfma_f32_32x32x16_bf16 v[48:63], v[80:83], v[136:139], v[48:63]
	v_mfma_f32_32x32x16_bf16 v[32:47], v[128:131], v[136:139], v[32:47]
	v_mfma_f32_32x32x16_bf16 v[0:15], v[80:83], v[144:147], v[0:15]
	v_mfma_f32_32x32x16_bf16 v[16:31], v[128:131], v[144:147], v[16:31]
	global_load_dwordx4 v[80:83], v[104:105], off offset:1664
	global_load_dwordx4 v[92:95], v[106:107], off offset:1664
	global_load_dwordx4 v[128:131], v[108:109], off offset:1664
	global_load_dwordx4 v[132:135], v[110:111], off offset:1664
	global_load_dwordx4 v[136:139], v[112:113], off offset:1664
	global_load_dwordx4 v[140:143], v[114:115], off offset:1664
	global_load_dwordx4 v[144:147], v[116:117], off offset:1664
	global_load_dwordx4 v[148:151], v[118:119], off offset:1664
	s_waitcnt lgkmcnt(1)
	v_mfma_f32_32x32x16_bf16 v[48:63], v[152:155], v[160:163], v[48:63]
	v_mfma_f32_32x32x16_bf16 v[32:47], v[156:159], v[160:163], v[32:47]
	s_waitcnt lgkmcnt(0)
	v_mfma_f32_32x32x16_bf16 v[0:15], v[152:155], v[164:167], v[0:15]
	ds_read_b128 v[152:155], v126 offset:55328
	ds_read_b128 v[160:163], v126 offset:59936
	ds_read_b128 v[168:171], v124 offset:36896
	ds_read_b128 v[172:175], v124 offset:41504
	v_mfma_f32_32x32x16_bf16 v[16:31], v[156:159], v[164:167], v[16:31]
	s_waitcnt lgkmcnt(1)
	v_mfma_f32_32x32x16_bf16 v[48:63], v[152:155], v[168:171], v[48:63]
	v_mfma_f32_32x32x16_bf16 v[32:47], v[160:163], v[168:171], v[32:47]
	s_waitcnt lgkmcnt(0)
	v_mfma_f32_32x32x16_bf16 v[0:15], v[152:155], v[172:175], v[0:15]
	ds_read_b128 v[152:155], v126 offset:55360
	ds_read_b128 v[156:159], v126 offset:59968
	ds_read_b128 v[164:167], v124 offset:36928
	ds_read_b128 v[168:171], v124 offset:41536
	s_waitcnt vmcnt(15)
	ds_write_b128 v125, v[64:67]
	s_waitcnt vmcnt(13)
	ds_write_b128 v125, v[72:75] offset:4608
	s_waitcnt vmcnt(11)
	ds_write_b128 v125, v[84:87] offset:9216
	s_waitcnt vmcnt(9)
	ds_write_b128 v125, v[96:99] offset:13824
	v_mfma_f32_32x32x16_bf16 v[16:31], v[160:163], v[172:175], v[16:31]
	s_waitcnt lgkmcnt(5)
	v_mfma_f32_32x32x16_bf16 v[48:63], v[152:155], v[164:167], v[48:63]
	ds_read_b128 v[64:67], v126 offset:55392
	ds_read_b128 v[72:75], v126 offset:60000
	ds_read_b128 v[84:87], v124 offset:36960
	ds_read_b128 v[96:99], v124 offset:41568
	ds_write_b128 v125, v[68:71] offset:18432
	ds_write_b128 v125, v[76:79] offset:23040
	ds_write_b128 v125, v[88:91] offset:27648
	s_waitcnt vmcnt(8)
	ds_write_b128 v125, v[100:103] offset:32256
	v_mfma_f32_32x32x16_bf16 v[32:47], v[156:159], v[164:167], v[32:47]
	s_waitcnt lgkmcnt(12)
	v_mfma_f32_32x32x16_bf16 v[0:15], v[152:155], v[168:171], v[0:15]
	v_mfma_f32_32x32x16_bf16 v[16:31], v[156:159], v[168:171], v[16:31]
	s_waitcnt lgkmcnt(0)
	s_barrier
	ds_read_b128 v[152:155], v126 offset:18432
	ds_read_b128 v[156:159], v126 offset:23040
	ds_read_b128 v[160:163], v124
	ds_read_b128 v[164:167], v124 offset:4608
	v_mfma_f32_32x32x16_bf16 v[48:63], v[64:67], v[84:87], v[48:63]
	v_mfma_f32_32x32x16_bf16 v[32:47], v[72:75], v[84:87], v[32:47]
	v_mfma_f32_32x32x16_bf16 v[0:15], v[64:67], v[96:99], v[0:15]
	v_mfma_f32_32x32x16_bf16 v[16:31], v[72:75], v[96:99], v[16:31]
	global_load_dwordx4 v[64:67], v[104:105], off offset:1792
	global_load_dwordx4 v[68:71], v[106:107], off offset:1792
	global_load_dwordx4 v[72:75], v[108:109], off offset:1792
	global_load_dwordx4 v[76:79], v[110:111], off offset:1792
	global_load_dwordx4 v[84:87], v[112:113], off offset:1792
	global_load_dwordx4 v[88:91], v[114:115], off offset:1792
	global_load_dwordx4 v[96:99], v[116:117], off offset:1792
	global_load_dwordx4 v[100:103], v[118:119], off offset:1792
	s_waitcnt lgkmcnt(1)
	v_mfma_f32_32x32x16_bf16 v[48:63], v[152:155], v[160:163], v[48:63]
	v_mfma_f32_32x32x16_bf16 v[32:47], v[156:159], v[160:163], v[32:47]
	s_waitcnt lgkmcnt(0)
	v_mfma_f32_32x32x16_bf16 v[0:15], v[152:155], v[164:167], v[0:15]
	ds_read_b128 v[152:155], v126 offset:18464
	ds_read_b128 v[160:163], v126 offset:23072
	ds_read_b128 v[168:171], v124 offset:32
	ds_read_b128 v[172:175], v124 offset:4640
	v_mfma_f32_32x32x16_bf16 v[16:31], v[156:159], v[164:167], v[16:31]
	s_waitcnt lgkmcnt(1)
	v_mfma_f32_32x32x16_bf16 v[48:63], v[152:155], v[168:171], v[48:63]
	v_mfma_f32_32x32x16_bf16 v[32:47], v[160:163], v[168:171], v[32:47]
	s_waitcnt lgkmcnt(0)
	v_mfma_f32_32x32x16_bf16 v[0:15], v[152:155], v[172:175], v[0:15]
	ds_read_b128 v[152:155], v126 offset:18496
	ds_read_b128 v[156:159], v126 offset:23104
	ds_read_b128 v[164:167], v124 offset:64
	ds_read_b128 v[168:171], v124 offset:4672
	s_waitcnt vmcnt(15)
	ds_write_b128 v125, v[80:83] offset:36864
	s_waitcnt vmcnt(13)
	ds_write_b128 v125, v[128:131] offset:41472
	s_waitcnt vmcnt(11)
	ds_write_b128 v125, v[136:139] offset:46080
	s_waitcnt vmcnt(9)
	ds_write_b128 v125, v[144:147] offset:50688
	v_mfma_f32_32x32x16_bf16 v[16:31], v[160:163], v[172:175], v[16:31]
	s_waitcnt lgkmcnt(5)
	v_mfma_f32_32x32x16_bf16 v[48:63], v[152:155], v[164:167], v[48:63]
	ds_read_b128 v[80:83], v126 offset:18528
	ds_read_b128 v[128:131], v126 offset:23136
	ds_read_b128 v[136:139], v124 offset:96
	ds_read_b128 v[144:147], v124 offset:4704
	ds_write_b128 v125, v[92:95] offset:55296
	ds_write_b128 v125, v[132:135] offset:59904
	ds_write_b128 v125, v[140:143] offset:64512
	s_waitcnt vmcnt(8)
	ds_write_b128 v127, v[148:151] offset:13824
	v_mfma_f32_32x32x16_bf16 v[32:47], v[156:159], v[164:167], v[32:47]
	s_waitcnt lgkmcnt(12)
	v_mfma_f32_32x32x16_bf16 v[0:15], v[152:155], v[168:171], v[0:15]
	v_mfma_f32_32x32x16_bf16 v[16:31], v[156:159], v[168:171], v[16:31]
	s_waitcnt lgkmcnt(5)
	v_mfma_f32_32x32x16_bf16 v[48:63], v[80:83], v[136:139], v[48:63]
	v_mfma_f32_32x32x16_bf16 v[32:47], v[128:131], v[136:139], v[32:47]
	s_waitcnt lgkmcnt(4)
	v_mfma_f32_32x32x16_bf16 v[0:15], v[80:83], v[144:147], v[0:15]
	v_mfma_f32_32x32x16_bf16 v[16:31], v[128:131], v[144:147], v[16:31]
	global_load_dwordx4 v[80:83], v[104:105], off offset:1920
	global_load_dwordx4 v[92:95], v[106:107], off offset:1920
	s_nop 0
	global_load_dwordx4 v[104:107], v[108:109], off offset:1920
	s_nop 0
	global_load_dwordx4 v[108:111], v[110:111], off offset:1920
	s_nop 0
	global_load_dwordx4 v[128:131], v[112:113], off offset:1920
	s_nop 0
	global_load_dwordx4 v[112:115], v[114:115], off offset:1920
	s_nop 0
	global_load_dwordx4 v[132:135], v[116:117], off offset:1920
	s_nop 0
	global_load_dwordx4 v[116:119], v[118:119], off offset:1920
	s_waitcnt lgkmcnt(0)
	s_barrier
; template <bool SWAP>
; DI void gemm_tile(const bf16_t* __restrict__ A, int lda, const bf16_t* __restrict__ Bt, int ldb, int K, f32x16 (&acc)[2][2], bf16_t* As, bf16_t* Bs_unused) {
;     ...
;   auto step = [&](int buf, u32x4 (&ra)[4], u32x4 (&rb)[4], bool do_write, bool do_load, int tload) __attribute__((always_inline)) {
;     const bf16_t* pa = As + buf * 2 * GT_IMG + pao; const bf16_t* pb = As + buf * 2 * GT_IMG + pbo;
;     bf16_t* Ad = As + (buf ^ 1) * 2 * GT_IMG; bf16_t* Bd = Ad + GT_IMG;
;     bf16x8 F0[4], F1[4];
;     frag_read(F0, pa, pb, 0);
;     __builtin_amdgcn_sched_barrier(0);
;     frag_read(F1, pa, pb, 16);
;     mfma4(F0);
;     __builtin_amdgcn_sched_barrier(0);
;     frag_read(F0, pa, pb, 32);
;     mfma4(F1);
;     if (do_write) {
; #pragma unroll
;       for (int i = 0; i < 4; ++i) *(u32x4*)(Ad + (lr + 32 * i) * 72 + lc) = ra[i];
;     }
;     __builtin_amdgcn_sched_barrier(0);
;     frag_read(F1, pa, pb, 48);
;     mfma4(F0);
;     if (do_write) {
; #pragma unroll
;       for (int i = 0; i < 4; ++i) *(u32x4*)(Bd + (lr + 32 * i) * 72 + lc) = rb[i];
;     }
;     __builtin_amdgcn_sched_barrier(0);
;     mfma4(F1);
;     if (do_load) load_stage(ra, rb, tload);
;     __builtin_amdgcn_sched_barrier(0);
;   };
;   const int nk = K >> 6;
;   load_stage(ra0, rb0, 0); load_stage(ra1, rb1, 1);
;   __syncthreads();
;   write_stage(ra0, rb0, 0);
;   load_stage(ra0, rb0, 2);
;   __syncthreads();
;   for (int kt = 0; kt < nk; kt += 2) {
;     step(0, ra1, rb1, true, kt + 3 < nk, kt + 3);
;     __syncthreads();
;     step(1, ra0, rb0, kt + 2 < nk, kt + 4 < nk, kt + 4);
;     __syncthreads();
;   }
	ds_read_b128 v[136:139], v126 offset:55296
	ds_read_b128 v[140:143], v126 offset:59904
	ds_read_b128 v[144:147], v124 offset:36864
	ds_read_b128 v[148:151], v124 offset:41472
	s_waitcnt lgkmcnt(1)
	v_mfma_f32_32x32x16_bf16 v[48:63], v[136:139], v[144:147], v[48:63]
	v_mfma_f32_32x32x16_bf16 v[32:47], v[140:143], v[144:147], v[32:47]
	s_waitcnt lgkmcnt(0)
	v_mfma_f32_32x32x16_bf16 v[0:15], v[136:139], v[148:151], v[0:15]
	ds_read_b128 v[136:139], v126 offset:55328
	ds_read_b128 v[144:147], v126 offset:59936
	ds_read_b128 v[152:155], v124 offset:36896
	ds_read_b128 v[156:159], v124 offset:41504
	v_mfma_f32_32x32x16_bf16 v[16:31], v[140:143], v[148:151], v[16:31]
	s_waitcnt lgkmcnt(1)
	v_mfma_f32_32x32x16_bf16 v[48:63], v[136:139], v[152:155], v[48:63]
	v_mfma_f32_32x32x16_bf16 v[32:47], v[144:147], v[152:155], v[32:47]
	s_waitcnt lgkmcnt(0)
	v_mfma_f32_32x32x16_bf16 v[0:15], v[136:139], v[156:159], v[0:15]
	ds_read_b128 v[136:139], v126 offset:55360
	ds_read_b128 v[140:143], v126 offset:59968
	ds_read_b128 v[148:151], v124 offset:36928
	ds_read_b128 v[152:155], v124 offset:41536
	s_waitcnt vmcnt(15)
	ds_write_b128 v125, v[64:67]
	s_waitcnt vmcnt(13)
	ds_write_b128 v125, v[72:75] offset:4608
	s_waitcnt vmcnt(11)
	ds_write_b128 v125, v[84:87] offset:9216
	s_waitcnt vmcnt(9)
	ds_write_b128 v125, v[96:99] offset:13824
	v_mfma_f32_32x32x16_bf16 v[16:31], v[144:147], v[156:159], v[16:31]
	s_waitcnt lgkmcnt(5)
	v_mfma_f32_32x32x16_bf16 v[48:63], v[136:139], v[148:151], v[48:63]
	ds_read_b128 v[64:67], v126 offset:55392
	ds_read_b128 v[72:75], v126 offset:60000
	ds_read_b128 v[84:87], v124 offset:36960
	ds_read_b128 v[96:99], v124 offset:41568
	ds_write_b128 v125, v[68:71] offset:18432
	ds_write_b128 v125, v[76:79] offset:23040
	ds_write_b128 v125, v[88:91] offset:27648
	s_waitcnt vmcnt(8)
	ds_write_b128 v125, v[100:103] offset:32256
	v_mfma_f32_32x32x16_bf16 v[32:47], v[140:143], v[148:151], v[32:47]
	s_waitcnt lgkmcnt(12)
	v_mfma_f32_32x32x16_bf16 v[0:15], v[136:139], v[152:155], v[0:15]
	v_mfma_f32_32x32x16_bf16 v[16:31], v[140:143], v[152:155], v[16:31]
	s_waitcnt lgkmcnt(5)
	v_mfma_f32_32x32x16_bf16 v[48:63], v[64:67], v[84:87], v[48:63]
	v_mfma_f32_32x32x16_bf16 v[32:47], v[72:75], v[84:87], v[32:47]
	s_waitcnt lgkmcnt(4)
	v_mfma_f32_32x32x16_bf16 v[0:15], v[64:67], v[96:99], v[0:15]
	v_mfma_f32_32x32x16_bf16 v[16:31], v[72:75], v[96:99], v[16:31]
	s_waitcnt lgkmcnt(0)
	s_barrier
	ds_read_b128 v[64:67], v126 offset:18432
	ds_read_b128 v[68:71], v126 offset:23040
	ds_read_b128 v[72:75], v124
	ds_read_b128 v[76:79], v124 offset:4608
	s_waitcnt lgkmcnt(1)
	v_mfma_f32_32x32x16_bf16 v[48:63], v[64:67], v[72:75], v[48:63]
	v_mfma_f32_32x32x16_bf16 v[32:47], v[68:71], v[72:75], v[32:47]
	s_waitcnt lgkmcnt(0)
	v_mfma_f32_32x32x16_bf16 v[0:15], v[64:67], v[76:79], v[0:15]
	ds_read_b128 v[64:67], v126 offset:18464
	ds_read_b128 v[72:75], v126 offset:23072
	ds_read_b128 v[84:87], v124 offset:32
	ds_read_b128 v[88:91], v124 offset:4640
	v_mfma_f32_32x32x16_bf16 v[16:31], v[68:71], v[76:79], v[16:31]
	s_waitcnt lgkmcnt(1)
	v_mfma_f32_32x32x16_bf16 v[48:63], v[64:67], v[84:87], v[48:63]
	v_mfma_f32_32x32x16_bf16 v[32:47], v[72:75], v[84:87], v[32:47]
	s_waitcnt lgkmcnt(0)
	v_mfma_f32_32x32x16_bf16 v[0:15], v[64:67], v[88:91], v[0:15]
	ds_read_b128 v[64:67], v126 offset:18496
	ds_read_b128 v[68:71], v126 offset:23104
	ds_read_b128 v[76:79], v124 offset:64
	ds_read_b128 v[84:87], v124 offset:4672
	s_waitcnt vmcnt(7)
	ds_write_b128 v125, v[80:83] offset:36864
	s_waitcnt vmcnt(5)
	ds_write_b128 v125, v[104:107] offset:41472
	s_waitcnt vmcnt(3)
	ds_write_b128 v125, v[128:131] offset:46080
	s_waitcnt vmcnt(1)
	ds_write_b128 v125, v[132:135] offset:50688
	v_mfma_f32_32x32x16_bf16 v[16:31], v[72:75], v[88:91], v[16:31]
	s_waitcnt lgkmcnt(5)
	v_mfma_f32_32x32x16_bf16 v[48:63], v[64:67], v[76:79], v[48:63]
	v_mfma_f32_32x32x16_bf16 v[32:47], v[68:71], v[76:79], v[32:47]
	s_waitcnt lgkmcnt(4)
	v_mfma_f32_32x32x16_bf16 v[0:15], v[64:67], v[84:87], v[0:15]
	ds_read_b128 v[64:67], v126 offset:18528
	ds_read_b128 v[72:75], v126 offset:23136
	ds_read_b128 v[76:79], v124 offset:96
	ds_read_b128 v[80:83], v124 offset:4704
	ds_write_b128 v125, v[92:95] offset:55296
	ds_write_b128 v125, v[108:111] offset:59904
	ds_write_b128 v125, v[112:115] offset:64512
	s_waitcnt vmcnt(0)
	ds_write_b128 v127, v[116:119] offset:13824
	v_mfma_f32_32x32x16_bf16 v[16:31], v[68:71], v[84:87], v[16:31]
	s_waitcnt lgkmcnt(5)
	v_mfma_f32_32x32x16_bf16 v[48:63], v[64:67], v[76:79], v[48:63]
	v_mfma_f32_32x32x16_bf16 v[32:47], v[72:75], v[76:79], v[32:47]
	s_waitcnt lgkmcnt(4)
	v_mfma_f32_32x32x16_bf16 v[0:15], v[64:67], v[80:83], v[0:15]
	v_mfma_f32_32x32x16_bf16 v[16:31], v[72:75], v[80:83], v[16:31]
	s_waitcnt lgkmcnt(0)
	s_barrier
	ds_read_b128 v[64:67], v126 offset:55296
	ds_read_b128 v[68:71], v126 offset:59904
	ds_read_b128 v[72:75], v124 offset:36864
	ds_read_b128 v[76:79], v124 offset:41472
	s_waitcnt lgkmcnt(1)
	v_mfma_f32_32x32x16_bf16 v[48:63], v[64:67], v[72:75], v[48:63]
	v_mfma_f32_32x32x16_bf16 v[32:47], v[68:71], v[72:75], v[32:47]
	s_waitcnt lgkmcnt(0)
	v_mfma_f32_32x32x16_bf16 v[0:15], v[64:67], v[76:79], v[0:15]
	ds_read_b128 v[64:67], v126 offset:55328
	ds_read_b128 v[72:75], v126 offset:59936
	ds_read_b128 v[80:83], v124 offset:36896
	ds_read_b128 v[84:87], v124 offset:41504
	v_mfma_f32_32x32x16_bf16 v[16:31], v[68:71], v[76:79], v[16:31]
	s_waitcnt lgkmcnt(1)
	v_mfma_f32_32x32x16_bf16 v[48:63], v[64:67], v[80:83], v[48:63]
	v_mfma_f32_32x32x16_bf16 v[32:47], v[72:75], v[80:83], v[32:47]
	s_waitcnt lgkmcnt(0)
	v_mfma_f32_32x32x16_bf16 v[0:15], v[64:67], v[84:87], v[0:15]
	ds_read_b128 v[64:67], v126 offset:59968
	ds_read_b128 v[68:71], v126 offset:55360
	ds_read_b128 v[76:79], v124 offset:41536
	ds_read_b128 v[80:83], v124 offset:36928
	v_mfma_f32_32x32x16_bf16 v[16:31], v[72:75], v[84:87], v[16:31]
	s_waitcnt lgkmcnt(0)
	v_mfma_f32_32x32x16_bf16 v[48:63], v[68:71], v[80:83], v[48:63]
	v_mfma_f32_32x32x16_bf16 v[32:47], v[64:67], v[80:83], v[32:47]
	v_mfma_f32_32x32x16_bf16 v[0:15], v[68:71], v[76:79], v[0:15]
	ds_read_b128 v[68:71], v126 offset:60000
	ds_read_b128 v[72:75], v126 offset:55392
	ds_read_b128 v[80:83], v124 offset:41568
	ds_read_b128 v[84:87], v124 offset:36960
	v_mfma_f32_32x32x16_bf16 v[16:31], v[64:67], v[76:79], v[16:31]
	s_waitcnt lgkmcnt(0)
	v_mfma_f32_32x32x16_bf16 v[48:63], v[72:75], v[84:87], v[48:63]
	v_mfma_f32_32x32x16_bf16 v[32:47], v[68:71], v[84:87], v[32:47]
	v_mfma_f32_32x32x16_bf16 v[0:15], v[72:75], v[80:83], v[0:15]
	v_mfma_f32_32x32x16_bf16 v[16:31], v[68:71], v[80:83], v[16:31]
	s_barrier
